# fix: dead preamble writes no longer clobber prefetched K tile; combine with 2 accumulators and B-operand prefetch; V loads issued during QK
# speedup vs baseline: 1.0473x; 1.0015x over previous
; #define LAS __attribute__((address_space(3)))
; __device__ __forceinline__ void scan_combine(LAS unsigned char* lds, CArgsP a) {
;     if (blockIdx.x >= 64) return;
;     const int tid = threadIdx.x, h = blockIdx.x >> 3, rw = tid >> 6, v = (blockIdx.x & 7) * 8 + rw, kq = tid & 63;
;     const float* PM = (const float*)(a->ws + WS_PM); const float* UM = (const float*)(a->ws + WS_UM); float* SS = (float*)(a->ws + WS_SS);
;     LAS float* Sl = (LAS float*)lds;
;     LAS float* Pl = (LAS float*)(lds + 4096);
;     constexpr int GL = NSEG - 2;
;     float cur = SS[((size_t)(1 * 8 + h) * 64 + v) * 64 + kq];
;     f32x4 pa, pb;
;     float u1, u2;
;     {
;         const f32x4* P1 = (const f32x4*)(PM + (size_t)(1 * 8 + h) * 4096);
;         *(LAS f32x4*)(Pl + 1 * 4096 + 4 * tid) = P1[tid]; *(LAS f32x4*)(Pl + 1 * 4096 + 2048 + 4 * tid) = P1[512 + tid];
;         if (GL >= 2) { const f32x4* P2 = (const f32x4*)(PM + (size_t)(2 * 8 + h) * 4096);
;             *(LAS f32x4*)(Pl + 2 * 4096 + 4 * tid) = P2[tid]; *(LAS f32x4*)(Pl + 2 * 4096 + 2048 + 4 * tid) = P2[512 + tid]; }
;         u1 = UM[((size_t)(1 * 8 + h) * 64 + v) * 64 + kq];
;         u2 = GL >= 2 ? UM[((size_t)(2 * 8 + h) * 64 + v) * 64 + kq] : 0.f;
;     }
;     for (int g = 1; g <= GL; ++g) {
;         const bool pf = (g + 2 <= GL);
;         float u3 = 0.f;
;         if (pf) { const f32x4* Pn = (const f32x4*)(PM + (size_t)((g + 2) * 8 + h) * 4096); pa = Pn[tid]; pb = Pn[512 + tid]; u3 = UM[((size_t)((g + 2) * 8 + h) * 64 + v) * 64 + kq]; }
;         asm volatile("s_waitcnt lgkmcnt(0)\n\ts_barrier" ::: "memory");
.LBB0_1217:
	s_or_b64 exec, exec, s[8:9]
	s_mov_b64 s[20:21], s[92:93]
	s_cmp_gt_u32 s2, 63
	v_lshrrev_b32_e32 v50, 6, v164
	s_waitcnt lgkmcnt(0)
	s_barrier
	s_cbranch_scc1 .LBB0_1224
	s_load_dwordx2 s[4:5], s[20:21], 0xf8
	v_readfirstlane_b32 s3, v50
	s_lshr_b32 s12, s2, 3
	s_and_b32 s13, s2, 7
	s_lshl_b32 s12, s12, 14
	s_lshl_b32 s13, s13, 11
	s_add_u32 s13, s13, s12
	v_lshlrev_b32_e32 v0, 4, v164
	v_add_u32_e32 v1, 0x2000, v0
	v_lshrrev_b32_e32 v3, 4, v164
	v_and_b32_e32 v4, 15, v164
	v_mul_u32_u24_e32 v3, 0x140, v3
	v_lshl_add_u32 v3, v4, 4, v3
	v_add_u32_e32 v2, 4352, v3
	v_lshlrev_b32_e32 v3, 8, v50
	v_lshl_add_u32 v3, v148, 2, v3
	v_mul_u32_u24_e32 v5, 0x110, v50
	v_lshl_add_u32 v5, v148, 2, v5
	s_waitcnt lgkmcnt(0)
	s_add_u32 s0, s4, 0xf600000
	s_addc_u32 s1, s5, 0
	s_add_u32 s0, s0, s12
	s_addc_u32 s1, s1, 0
	s_add_u32 s6, s4, 0x300000
	s_addc_u32 s7, s5, 0
	s_add_u32 s6, s6, s13
	s_addc_u32 s7, s7, 0
	s_add_u32 s8, s4, 0xbc00000
	s_addc_u32 s9, s5, 0
	s_add_u32 s8, s8, s13
	s_addc_u32 s9, s9, 0
	s_add_u32 s16, s8, 0x20000
	s_addc_u32 s17, s9, 0
	global_load_dword v4, v3, s[16:17]
	s_add_u32 s10, s0, 0x20000
	s_addc_u32 s11, s1, 0
	global_load_dwordx4 v[60:63], v0, s[10:11]
	global_load_dwordx4 v[64:67], v1, s[10:11]
	s_add_u32 s10, s0, 0x40000
	s_addc_u32 s11, s1, 0
	global_load_dwordx4 v[68:71], v0, s[10:11]
	global_load_dwordx4 v[72:75], v1, s[10:11]
	s_add_u32 s10, s0, 0x60000
	s_addc_u32 s11, s1, 0
	global_load_dwordx4 v[76:79], v0, s[10:11]
	global_load_dwordx4 v[80:83], v1, s[10:11]
	s_add_u32 s10, s0, 0x80000
	s_addc_u32 s11, s1, 0
	global_load_dwordx4 v[84:87], v0, s[10:11]
	global_load_dwordx4 v[88:91], v1, s[10:11]
	s_add_u32 s10, s0, 0xa0000
	s_addc_u32 s11, s1, 0
	global_load_dwordx4 v[92:95], v0, s[10:11]
	global_load_dwordx4 v[96:99], v1, s[10:11]
	s_add_u32 s10, s0, 0xc0000
	s_addc_u32 s11, s1, 0
	global_load_dwordx4 v[52:55], v0, s[10:11]
	global_load_dwordx4 v[56:59], v1, s[10:11]
	v_lshrrev_b32_e32 v6, 4, v148
	v_and_b32_e32 v7, 15, v148
	v_and_b32_e32 v14, 7, v148
	v_mul_u32_u24_e32 v14, 0x110, v14
	v_lshl_add_u32 v8, v6, 2, v14
	v_add_u32_e32 v9, 2176, v8
	s_lshl_b32 s12, s3, 6
	v_lshl_add_u32 v15, v7, 2, s12
	v_mul_u32_u24_e32 v14, 0x140, v6
	v_add_u32_e32 v14, v14, v15
	v_add_u32_e32 v10, 0x1100, v14
	v_add_u32_e32 v11, 0x5000, v10
	v_and_b32_e32 v14, 1, v6
	v_lshl_add_u32 v12, v14, 10, v15
	v_mul_u32_u24_e32 v14, 0x440, v14
	v_add_u32_e32 v13, v14, v15
	s_waitcnt vmcnt(12)
	ds_write_b32 v5, v4 offset:2176
	s_waitcnt vmcnt(10)
	ds_write_b128 v2, v[60:63] offset:20480
	ds_write_b128 v2, v[64:67] offset:30720
	s_add_u32 s10, s0, 0xe0000
	s_addc_u32 s11, s1, 0
	global_load_dwordx4 v[60:63], v0, s[10:11]
	global_load_dwordx4 v[64:67], v1, s[10:11]
	s_waitcnt vmcnt(10)
	ds_write_b128 v2, v[68:71] offset:0
	ds_write_b128 v2, v[72:75] offset:10240
	s_add_u32 s10, s0, 0x100000
	s_addc_u32 s11, s1, 0
	global_load_dwordx4 v[68:71], v0, s[10:11]
	global_load_dwordx4 v[72:75], v1, s[10:11]
	s_cmp_gt_u32 s3, 3
	s_cbranch_scc1 .Lcmb_loader
	s_add_u32 s14, s6, 0x20000
	s_addc_u32 s15, s7, 0
	global_load_dword v208, v12, s[14:15] offset:0
	global_load_dword v209, v12, s[14:15] offset:256
	global_load_dword v210, v12, s[14:15] offset:512
	global_load_dword v211, v12, s[14:15] offset:768
	s_add_u32 s14, s6, 0x40000
	s_addc_u32 s15, s7, 0
	global_load_dword v212, v12, s[14:15] offset:0
	global_load_dword v213, v12, s[14:15] offset:256
	global_load_dword v214, v12, s[14:15] offset:512
	global_load_dword v215, v12, s[14:15] offset:768
	s_add_u32 s14, s6, 0x60000
	s_addc_u32 s15, s7, 0
	global_load_dword v216, v12, s[14:15] offset:0
	global_load_dword v217, v12, s[14:15] offset:256
	global_load_dword v218, v12, s[14:15] offset:512
	global_load_dword v219, v12, s[14:15] offset:768
	s_add_u32 s14, s6, 0x80000
	s_addc_u32 s15, s7, 0
	global_load_dword v220, v12, s[14:15] offset:0
	global_load_dword v221, v12, s[14:15] offset:256
	global_load_dword v222, v12, s[14:15] offset:512
	global_load_dword v223, v12, s[14:15] offset:768
	s_add_u32 s14, s6, 0xa0000
	s_addc_u32 s15, s7, 0
	global_load_dword v224, v12, s[14:15] offset:0
	global_load_dword v225, v12, s[14:15] offset:256
	global_load_dword v226, v12, s[14:15] offset:512
	global_load_dword v227, v12, s[14:15] offset:768
	s_add_u32 s14, s6, 0xc0000
	s_addc_u32 s15, s7, 0
	global_load_dword v204, v12, s[14:15] offset:0
	global_load_dword v205, v12, s[14:15] offset:256
	global_load_dword v206, v12, s[14:15] offset:512
	global_load_dword v207, v12, s[14:15] offset:768
	s_waitcnt lgkmcnt(0)
	s_barrier
	ds_read2st64_b32 v[228:229], v11 offset0:0 offset1:5
	ds_read2st64_b32 v[230:231], v11 offset0:10 offset1:15
	ds_read2st64_b32 v[232:233], v11 offset0:20 offset1:25
	ds_read2st64_b32 v[234:235], v11 offset0:30 offset1:35
	ds_read2st64_b32 v[236:237], v11 offset0:40 offset1:45
	ds_read2st64_b32 v[238:239], v11 offset0:50 offset1:55
	ds_read2st64_b32 v[240:241], v11 offset0:60 offset1:65
	ds_read2st64_b32 v[242:243], v11 offset0:70 offset1:75
	s_waitcnt lgkmcnt(0)
	s_barrier
; #define LAS __attribute__((address_space(3)))
; __device__ __forceinline__ void scan_combine(LAS unsigned char* lds, CArgsP a) {
;     ...
;     for (int g = 1; g <= GL; ++g) {
;         const bool pf = (g + 2 <= GL);
;         float u3 = 0.f;
;         if (pf) { const f32x4* Pn = (const f32x4*)(PM + (size_t)((g + 2) * 8 + h) * 4096); pa = Pn[tid]; pb = Pn[512 + tid]; u3 = UM[((size_t)((g + 2) * 8 + h) * 64 + v) * 64 + kq]; }
;         asm volatile("s_waitcnt lgkmcnt(0)\n\ts_barrier" ::: "memory");
;         const LAS float* Pg = Pl + (g % 3) * 4096 + kq;
;         float acc0 = u1, acc1 = 0.f, acc2 = 0.f, acc3 = 0.f;
;         const int curi = __builtin_bit_cast(int, cur);
; #pragma unroll
;         for (int k = 0; k < 64; k += 4) {
;             const float s0 = __builtin_bit_cast(float, __builtin_amdgcn_readlane(curi, k)), s1 = __builtin_bit_cast(float, __builtin_amdgcn_readlane(curi, k + 1));
;             const float s2 = __builtin_bit_cast(float, __builtin_amdgcn_readlane(curi, k + 2)), s3 = __builtin_bit_cast(float, __builtin_amdgcn_readlane(curi, k + 3));
;             acc0 += s0 * Pg[(k + 0) * 64]; acc1 += s1 * Pg[(k + 1) * 64]; acc2 += s2 * Pg[(k + 2) * 64]; acc3 += s3 * Pg[(k + 3) * 64];
;         }
;         cur = (acc0 + acc1) + (acc2 + acc3);
;         SS[((size_t)((g + 1) * 8 + h) * 64 + v) * 64 + kq] = cur;
;         if (pf) { LAS float* dst = Pl + ((g + 2) % 3) * 4096; *(LAS f32x4*)(dst + 4 * tid) = pa; *(LAS f32x4*)(dst + 2048 + 4 * tid) = pb; }
;         u1 = u2; u2 = u3;
;     }
	ds_read2_b32 v[104:105], v9 offset0:0 offset1:4
	ds_read2_b32 v[106:107], v9 offset0:8 offset1:12
	ds_read2_b32 v[108:109], v9 offset0:16 offset1:20
	ds_read2_b32 v[110:111], v9 offset0:24 offset1:28
	ds_read2_b32 v[112:113], v9 offset0:32 offset1:36
	ds_read2_b32 v[114:115], v9 offset0:40 offset1:44
	ds_read2_b32 v[116:117], v9 offset0:48 offset1:52
	ds_read2_b32 v[118:119], v9 offset0:56 offset1:60
	s_waitcnt vmcnt(20)
	s_waitcnt lgkmcnt(7)
	v_mfma_f32_16x16x4_f32 v[136:139], v104, v228, v[208:211]
	v_mfma_f32_16x16x4_f32 v[140:143], v105, v229, 0
	ds_read2st64_b32 v[120:121], v10 offset0:0 offset1:5
	ds_read2st64_b32 v[122:123], v10 offset0:10 offset1:15
	s_waitcnt lgkmcnt(8)
	v_mfma_f32_16x16x4_f32 v[136:139], v106, v230, v[136:139]
	v_mfma_f32_16x16x4_f32 v[140:143], v107, v231, v[140:143]
	ds_read2st64_b32 v[124:125], v10 offset0:20 offset1:25
	ds_read2st64_b32 v[126:127], v10 offset0:30 offset1:35
	s_waitcnt lgkmcnt(9)
	v_mfma_f32_16x16x4_f32 v[136:139], v108, v232, v[136:139]
	v_mfma_f32_16x16x4_f32 v[140:143], v109, v233, v[140:143]
	ds_read2st64_b32 v[128:129], v10 offset0:40 offset1:45
	ds_read2st64_b32 v[130:131], v10 offset0:50 offset1:55
	s_waitcnt lgkmcnt(10)
	v_mfma_f32_16x16x4_f32 v[136:139], v110, v234, v[136:139]
	v_mfma_f32_16x16x4_f32 v[140:143], v111, v235, v[140:143]
	ds_read2st64_b32 v[132:133], v10 offset0:60 offset1:65
	ds_read2st64_b32 v[134:135], v10 offset0:70 offset1:75
	s_waitcnt lgkmcnt(11)
	v_mfma_f32_16x16x4_f32 v[136:139], v112, v236, v[136:139]
	v_mfma_f32_16x16x4_f32 v[140:143], v113, v237, v[140:143]
	s_add_u32 s14, s6, 0xe0000
	s_addc_u32 s15, s7, 0
	global_load_dword v208, v12, s[14:15] offset:0
	global_load_dword v209, v12, s[14:15] offset:256
	global_load_dword v210, v12, s[14:15] offset:512
	global_load_dword v211, v12, s[14:15] offset:768
	s_waitcnt lgkmcnt(10)
	v_mfma_f32_16x16x4_f32 v[136:139], v114, v238, v[136:139]
	v_mfma_f32_16x16x4_f32 v[140:143], v115, v239, v[140:143]
	ds_write_b128 v2, v[76:79] offset:20480
	ds_write_b128 v2, v[80:83] offset:30720
	s_add_u32 s10, s0, 0x120000
	s_addc_u32 s11, s1, 0
	global_load_dwordx4 v[76:79], v0, s[10:11]
	global_load_dwordx4 v[80:83], v1, s[10:11]
	s_waitcnt lgkmcnt(11)
	v_mfma_f32_16x16x4_f32 v[136:139], v116, v240, v[136:139]
	v_mfma_f32_16x16x4_f32 v[140:143], v117, v241, v[140:143]
	s_waitcnt lgkmcnt(10)
	v_mfma_f32_16x16x4_f32 v[136:139], v118, v242, v[136:139]
	v_mfma_f32_16x16x4_f32 v[140:143], v119, v243, v[140:143]
	s_add_u32 s16, s8, 0x40000
	s_addc_u32 s17, s9, 0
	s_nop 9
	v_add_f32_e32 v136, v136, v140
	v_add_f32_e32 v137, v137, v141
	v_add_f32_e32 v138, v138, v142
	v_add_f32_e32 v139, v139, v143
	ds_write_b32 v13, v136 offset:0
	ds_write_b32 v13, v137 offset:272
	ds_write_b32 v13, v138 offset:544
	ds_write_b32 v13, v139 offset:816
	global_store_dword v12, v136, s[16:17] offset:0
	global_store_dword v12, v137, s[16:17] offset:256
	global_store_dword v12, v138, s[16:17] offset:512
	global_store_dword v12, v139, s[16:17] offset:768
	s_waitcnt lgkmcnt(0)
	s_barrier
	ds_read2_b32 v[104:105], v8 offset0:0 offset1:4
	ds_read2_b32 v[106:107], v8 offset0:8 offset1:12
	ds_read2_b32 v[108:109], v8 offset0:16 offset1:20
	ds_read2_b32 v[110:111], v8 offset0:24 offset1:28
	ds_read2_b32 v[112:113], v8 offset0:32 offset1:36
	ds_read2_b32 v[114:115], v8 offset0:40 offset1:44
	ds_read2_b32 v[116:117], v8 offset0:48 offset1:52
	ds_read2_b32 v[118:119], v8 offset0:56 offset1:60
	s_waitcnt vmcnt(26)
	s_waitcnt lgkmcnt(7)
	v_mfma_f32_16x16x4_f32 v[136:139], v104, v120, v[212:215]
	v_mfma_f32_16x16x4_f32 v[140:143], v105, v121, 0
	ds_read2st64_b32 v[228:229], v11 offset0:0 offset1:5
	ds_read2st64_b32 v[230:231], v11 offset0:10 offset1:15
	s_waitcnt lgkmcnt(8)
	v_mfma_f32_16x16x4_f32 v[136:139], v106, v122, v[136:139]
	v_mfma_f32_16x16x4_f32 v[140:143], v107, v123, v[140:143]
	ds_read2st64_b32 v[232:233], v11 offset0:20 offset1:25
	ds_read2st64_b32 v[234:235], v11 offset0:30 offset1:35
	s_waitcnt lgkmcnt(9)
	v_mfma_f32_16x16x4_f32 v[136:139], v108, v124, v[136:139]
	v_mfma_f32_16x16x4_f32 v[140:143], v109, v125, v[140:143]
	ds_read2st64_b32 v[236:237], v11 offset0:40 offset1:45
	ds_read2st64_b32 v[238:239], v11 offset0:50 offset1:55
	s_waitcnt lgkmcnt(10)
	v_mfma_f32_16x16x4_f32 v[136:139], v110, v126, v[136:139]
	v_mfma_f32_16x16x4_f32 v[140:143], v111, v127, v[140:143]
	ds_read2st64_b32 v[240:241], v11 offset0:60 offset1:65
	ds_read2st64_b32 v[242:243], v11 offset0:70 offset1:75
	s_waitcnt lgkmcnt(11)
	v_mfma_f32_16x16x4_f32 v[136:139], v112, v128, v[136:139]
	v_mfma_f32_16x16x4_f32 v[140:143], v113, v129, v[140:143]
	s_add_u32 s14, s6, 0x100000
	s_addc_u32 s15, s7, 0
	global_load_dword v212, v12, s[14:15] offset:0
	global_load_dword v213, v12, s[14:15] offset:256
	global_load_dword v214, v12, s[14:15] offset:512
	global_load_dword v215, v12, s[14:15] offset:768
	s_waitcnt lgkmcnt(10)
	v_mfma_f32_16x16x4_f32 v[136:139], v114, v130, v[136:139]
	v_mfma_f32_16x16x4_f32 v[140:143], v115, v131, v[140:143]
	ds_write_b128 v2, v[84:87] offset:0
	ds_write_b128 v2, v[88:91] offset:10240
	s_add_u32 s10, s0, 0x140000
	s_addc_u32 s11, s1, 0
	global_load_dwordx4 v[84:87], v0, s[10:11]
	global_load_dwordx4 v[88:91], v1, s[10:11]
	s_waitcnt lgkmcnt(11)
	v_mfma_f32_16x16x4_f32 v[136:139], v116, v132, v[136:139]
	v_mfma_f32_16x16x4_f32 v[140:143], v117, v133, v[140:143]
	s_waitcnt lgkmcnt(10)
	v_mfma_f32_16x16x4_f32 v[136:139], v118, v134, v[136:139]
	v_mfma_f32_16x16x4_f32 v[140:143], v119, v135, v[140:143]
	s_add_u32 s16, s8, 0x60000
	s_addc_u32 s17, s9, 0
	s_nop 9
	v_add_f32_e32 v136, v136, v140
	v_add_f32_e32 v137, v137, v141
	v_add_f32_e32 v138, v138, v142
	v_add_f32_e32 v139, v139, v143
	ds_write_b32 v13, v136 offset:2176
	ds_write_b32 v13, v137 offset:2448
	ds_write_b32 v13, v138 offset:2720
	ds_write_b32 v13, v139 offset:2992
	global_store_dword v12, v136, s[16:17] offset:0
	global_store_dword v12, v137, s[16:17] offset:256
	global_store_dword v12, v138, s[16:17] offset:512
	global_store_dword v12, v139, s[16:17] offset:768
	s_waitcnt lgkmcnt(0)
	s_barrier
; #define LAS __attribute__((address_space(3)))
; __device__ __forceinline__ void scan_combine(LAS unsigned char* lds, CArgsP a) {
;     ...
;     for (int g = 1; g <= GL; ++g) {
;         const bool pf = (g + 2 <= GL);
;         float u3 = 0.f;
;         if (pf) { const f32x4* Pn = (const f32x4*)(PM + (size_t)((g + 2) * 8 + h) * 4096); pa = Pn[tid]; pb = Pn[512 + tid]; u3 = UM[((size_t)((g + 2) * 8 + h) * 64 + v) * 64 + kq]; }
;         asm volatile("s_waitcnt lgkmcnt(0)\n\ts_barrier" ::: "memory");
;         const LAS float* Pg = Pl + (g % 3) * 4096 + kq;
;         float acc0 = u1, acc1 = 0.f, acc2 = 0.f, acc3 = 0.f;
;         const int curi = __builtin_bit_cast(int, cur);
; #pragma unroll
;         for (int k = 0; k < 64; k += 4) {
;             const float s0 = __builtin_bit_cast(float, __builtin_amdgcn_readlane(curi, k)), s1 = __builtin_bit_cast(float, __builtin_amdgcn_readlane(curi, k + 1));
;             const float s2 = __builtin_bit_cast(float, __builtin_amdgcn_readlane(curi, k + 2)), s3 = __builtin_bit_cast(float, __builtin_amdgcn_readlane(curi, k + 3));
;             acc0 += s0 * Pg[(k + 0) * 64]; acc1 += s1 * Pg[(k + 1) * 64]; acc2 += s2 * Pg[(k + 2) * 64]; acc3 += s3 * Pg[(k + 3) * 64];
;         }
;         cur = (acc0 + acc1) + (acc2 + acc3);
;         SS[((size_t)((g + 1) * 8 + h) * 64 + v) * 64 + kq] = cur;
;         if (pf) { LAS float* dst = Pl + ((g + 2) % 3) * 4096; *(LAS f32x4*)(dst + 4 * tid) = pa; *(LAS f32x4*)(dst + 2048 + 4 * tid) = pb; }
;         u1 = u2; u2 = u3;
;     }
	ds_read2_b32 v[104:105], v9 offset0:0 offset1:4
	ds_read2_b32 v[106:107], v9 offset0:8 offset1:12
	ds_read2_b32 v[108:109], v9 offset0:16 offset1:20
	ds_read2_b32 v[110:111], v9 offset0:24 offset1:28
	ds_read2_b32 v[112:113], v9 offset0:32 offset1:36
	ds_read2_b32 v[114:115], v9 offset0:40 offset1:44
	ds_read2_b32 v[116:117], v9 offset0:48 offset1:52
	ds_read2_b32 v[118:119], v9 offset0:56 offset1:60
	s_waitcnt vmcnt(32)
	s_waitcnt lgkmcnt(7)
	v_mfma_f32_16x16x4_f32 v[136:139], v104, v228, v[216:219]
	v_mfma_f32_16x16x4_f32 v[140:143], v105, v229, 0
	ds_read2st64_b32 v[120:121], v10 offset0:0 offset1:5
	ds_read2st64_b32 v[122:123], v10 offset0:10 offset1:15
	s_waitcnt lgkmcnt(8)
	v_mfma_f32_16x16x4_f32 v[136:139], v106, v230, v[136:139]
	v_mfma_f32_16x16x4_f32 v[140:143], v107, v231, v[140:143]
	ds_read2st64_b32 v[124:125], v10 offset0:20 offset1:25
	ds_read2st64_b32 v[126:127], v10 offset0:30 offset1:35
	s_waitcnt lgkmcnt(9)
	v_mfma_f32_16x16x4_f32 v[136:139], v108, v232, v[136:139]
	v_mfma_f32_16x16x4_f32 v[140:143], v109, v233, v[140:143]
	ds_read2st64_b32 v[128:129], v10 offset0:40 offset1:45
	ds_read2st64_b32 v[130:131], v10 offset0:50 offset1:55
	s_waitcnt lgkmcnt(10)
	v_mfma_f32_16x16x4_f32 v[136:139], v110, v234, v[136:139]
	v_mfma_f32_16x16x4_f32 v[140:143], v111, v235, v[140:143]
	ds_read2st64_b32 v[132:133], v10 offset0:60 offset1:65
	ds_read2st64_b32 v[134:135], v10 offset0:70 offset1:75
	s_waitcnt lgkmcnt(11)
	v_mfma_f32_16x16x4_f32 v[136:139], v112, v236, v[136:139]
	v_mfma_f32_16x16x4_f32 v[140:143], v113, v237, v[140:143]
	s_add_u32 s14, s6, 0x120000
	s_addc_u32 s15, s7, 0
	global_load_dword v216, v12, s[14:15] offset:0
	global_load_dword v217, v12, s[14:15] offset:256
	global_load_dword v218, v12, s[14:15] offset:512
	global_load_dword v219, v12, s[14:15] offset:768
	s_waitcnt lgkmcnt(10)
	v_mfma_f32_16x16x4_f32 v[136:139], v114, v238, v[136:139]
	v_mfma_f32_16x16x4_f32 v[140:143], v115, v239, v[140:143]
	ds_write_b128 v2, v[92:95] offset:20480
	ds_write_b128 v2, v[96:99] offset:30720
	s_add_u32 s10, s0, 0x160000
	s_addc_u32 s11, s1, 0
	global_load_dwordx4 v[92:95], v0, s[10:11]
	global_load_dwordx4 v[96:99], v1, s[10:11]
	s_waitcnt lgkmcnt(11)
	v_mfma_f32_16x16x4_f32 v[136:139], v116, v240, v[136:139]
	v_mfma_f32_16x16x4_f32 v[140:143], v117, v241, v[140:143]
	s_waitcnt lgkmcnt(10)
	v_mfma_f32_16x16x4_f32 v[136:139], v118, v242, v[136:139]
	v_mfma_f32_16x16x4_f32 v[140:143], v119, v243, v[140:143]
	s_add_u32 s16, s8, 0x80000
	s_addc_u32 s17, s9, 0
	s_nop 9
	v_add_f32_e32 v136, v136, v140
	v_add_f32_e32 v137, v137, v141
	v_add_f32_e32 v138, v138, v142
	v_add_f32_e32 v139, v139, v143
	ds_write_b32 v13, v136 offset:0
	ds_write_b32 v13, v137 offset:272
	ds_write_b32 v13, v138 offset:544
	ds_write_b32 v13, v139 offset:816
	global_store_dword v12, v136, s[16:17] offset:0
	global_store_dword v12, v137, s[16:17] offset:256
	global_store_dword v12, v138, s[16:17] offset:512
	global_store_dword v12, v139, s[16:17] offset:768
	s_waitcnt lgkmcnt(0)
	s_barrier
	ds_read2_b32 v[104:105], v8 offset0:0 offset1:4
	ds_read2_b32 v[106:107], v8 offset0:8 offset1:12
	ds_read2_b32 v[108:109], v8 offset0:16 offset1:20
	ds_read2_b32 v[110:111], v8 offset0:24 offset1:28
	ds_read2_b32 v[112:113], v8 offset0:32 offset1:36
	ds_read2_b32 v[114:115], v8 offset0:40 offset1:44
	ds_read2_b32 v[116:117], v8 offset0:48 offset1:52
	ds_read2_b32 v[118:119], v8 offset0:56 offset1:60
	s_waitcnt vmcnt(38)
	s_waitcnt lgkmcnt(7)
	v_mfma_f32_16x16x4_f32 v[136:139], v104, v120, v[220:223]
	v_mfma_f32_16x16x4_f32 v[140:143], v105, v121, 0
	ds_read2st64_b32 v[228:229], v11 offset0:0 offset1:5
	ds_read2st64_b32 v[230:231], v11 offset0:10 offset1:15
	s_waitcnt lgkmcnt(8)
	v_mfma_f32_16x16x4_f32 v[136:139], v106, v122, v[136:139]
	v_mfma_f32_16x16x4_f32 v[140:143], v107, v123, v[140:143]
	ds_read2st64_b32 v[232:233], v11 offset0:20 offset1:25
	ds_read2st64_b32 v[234:235], v11 offset0:30 offset1:35
	s_waitcnt lgkmcnt(9)
	v_mfma_f32_16x16x4_f32 v[136:139], v108, v124, v[136:139]
	v_mfma_f32_16x16x4_f32 v[140:143], v109, v125, v[140:143]
	ds_read2st64_b32 v[236:237], v11 offset0:40 offset1:45
	ds_read2st64_b32 v[238:239], v11 offset0:50 offset1:55
	s_waitcnt lgkmcnt(10)
	v_mfma_f32_16x16x4_f32 v[136:139], v110, v126, v[136:139]
	v_mfma_f32_16x16x4_f32 v[140:143], v111, v127, v[140:143]
	ds_read2st64_b32 v[240:241], v11 offset0:60 offset1:65
	ds_read2st64_b32 v[242:243], v11 offset0:70 offset1:75
	s_waitcnt lgkmcnt(11)
	v_mfma_f32_16x16x4_f32 v[136:139], v112, v128, v[136:139]
	v_mfma_f32_16x16x4_f32 v[140:143], v113, v129, v[140:143]
	s_add_u32 s14, s6, 0x140000
	s_addc_u32 s15, s7, 0
	global_load_dword v220, v12, s[14:15] offset:0
	global_load_dword v221, v12, s[14:15] offset:256
	global_load_dword v222, v12, s[14:15] offset:512
	global_load_dword v223, v12, s[14:15] offset:768
	s_waitcnt lgkmcnt(10)
	v_mfma_f32_16x16x4_f32 v[136:139], v114, v130, v[136:139]
	v_mfma_f32_16x16x4_f32 v[140:143], v115, v131, v[140:143]
	ds_write_b128 v2, v[52:55] offset:0
	ds_write_b128 v2, v[56:59] offset:10240
	s_add_u32 s10, s0, 0x180000
	s_addc_u32 s11, s1, 0
	global_load_dwordx4 v[52:55], v0, s[10:11]
	global_load_dwordx4 v[56:59], v1, s[10:11]
	s_waitcnt lgkmcnt(11)
	v_mfma_f32_16x16x4_f32 v[136:139], v116, v132, v[136:139]
	v_mfma_f32_16x16x4_f32 v[140:143], v117, v133, v[140:143]
	s_waitcnt lgkmcnt(10)
	v_mfma_f32_16x16x4_f32 v[136:139], v118, v134, v[136:139]
	v_mfma_f32_16x16x4_f32 v[140:143], v119, v135, v[140:143]
	s_add_u32 s16, s8, 0xa0000
	s_addc_u32 s17, s9, 0
	s_nop 9
	v_add_f32_e32 v136, v136, v140
	v_add_f32_e32 v137, v137, v141
	v_add_f32_e32 v138, v138, v142
	v_add_f32_e32 v139, v139, v143
	ds_write_b32 v13, v136 offset:2176
	ds_write_b32 v13, v137 offset:2448
	ds_write_b32 v13, v138 offset:2720
	ds_write_b32 v13, v139 offset:2992
	global_store_dword v12, v136, s[16:17] offset:0
	global_store_dword v12, v137, s[16:17] offset:256
	global_store_dword v12, v138, s[16:17] offset:512
	global_store_dword v12, v139, s[16:17] offset:768
	s_waitcnt lgkmcnt(0)
	s_barrier
; #define LAS __attribute__((address_space(3)))
; __device__ __forceinline__ void scan_combine(LAS unsigned char* lds, CArgsP a) {
;     ...
;     for (int g = 1; g <= GL; ++g) {
;         const bool pf = (g + 2 <= GL);
;         float u3 = 0.f;
;         if (pf) { const f32x4* Pn = (const f32x4*)(PM + (size_t)((g + 2) * 8 + h) * 4096); pa = Pn[tid]; pb = Pn[512 + tid]; u3 = UM[((size_t)((g + 2) * 8 + h) * 64 + v) * 64 + kq]; }
;         asm volatile("s_waitcnt lgkmcnt(0)\n\ts_barrier" ::: "memory");
;         const LAS float* Pg = Pl + (g % 3) * 4096 + kq;
;         float acc0 = u1, acc1 = 0.f, acc2 = 0.f, acc3 = 0.f;
;         const int curi = __builtin_bit_cast(int, cur);
; #pragma unroll
;         for (int k = 0; k < 64; k += 4) {
;             const float s0 = __builtin_bit_cast(float, __builtin_amdgcn_readlane(curi, k)), s1 = __builtin_bit_cast(float, __builtin_amdgcn_readlane(curi, k + 1));
;             const float s2 = __builtin_bit_cast(float, __builtin_amdgcn_readlane(curi, k + 2)), s3 = __builtin_bit_cast(float, __builtin_amdgcn_readlane(curi, k + 3));
;             acc0 += s0 * Pg[(k + 0) * 64]; acc1 += s1 * Pg[(k + 1) * 64]; acc2 += s2 * Pg[(k + 2) * 64]; acc3 += s3 * Pg[(k + 3) * 64];
;         }
;         cur = (acc0 + acc1) + (acc2 + acc3);
;         SS[((size_t)((g + 1) * 8 + h) * 64 + v) * 64 + kq] = cur;
;         if (pf) { LAS float* dst = Pl + ((g + 2) % 3) * 4096; *(LAS f32x4*)(dst + 4 * tid) = pa; *(LAS f32x4*)(dst + 2048 + 4 * tid) = pb; }
;         u1 = u2; u2 = u3;
;     }
	ds_read2_b32 v[104:105], v9 offset0:0 offset1:4
	ds_read2_b32 v[106:107], v9 offset0:8 offset1:12
	ds_read2_b32 v[108:109], v9 offset0:16 offset1:20
	ds_read2_b32 v[110:111], v9 offset0:24 offset1:28
	ds_read2_b32 v[112:113], v9 offset0:32 offset1:36
	ds_read2_b32 v[114:115], v9 offset0:40 offset1:44
	ds_read2_b32 v[116:117], v9 offset0:48 offset1:52
	ds_read2_b32 v[118:119], v9 offset0:56 offset1:60
	s_waitcnt vmcnt(44)
	s_waitcnt lgkmcnt(7)
	v_mfma_f32_16x16x4_f32 v[136:139], v104, v228, v[224:227]
	v_mfma_f32_16x16x4_f32 v[140:143], v105, v229, 0
	ds_read2st64_b32 v[120:121], v10 offset0:0 offset1:5
	ds_read2st64_b32 v[122:123], v10 offset0:10 offset1:15
	s_waitcnt lgkmcnt(8)
	v_mfma_f32_16x16x4_f32 v[136:139], v106, v230, v[136:139]
	v_mfma_f32_16x16x4_f32 v[140:143], v107, v231, v[140:143]
	ds_read2st64_b32 v[124:125], v10 offset0:20 offset1:25
	ds_read2st64_b32 v[126:127], v10 offset0:30 offset1:35
	s_waitcnt lgkmcnt(9)
	v_mfma_f32_16x16x4_f32 v[136:139], v108, v232, v[136:139]
	v_mfma_f32_16x16x4_f32 v[140:143], v109, v233, v[140:143]
	ds_read2st64_b32 v[128:129], v10 offset0:40 offset1:45
	ds_read2st64_b32 v[130:131], v10 offset0:50 offset1:55
	s_waitcnt lgkmcnt(10)
	v_mfma_f32_16x16x4_f32 v[136:139], v110, v234, v[136:139]
	v_mfma_f32_16x16x4_f32 v[140:143], v111, v235, v[140:143]
	ds_read2st64_b32 v[132:133], v10 offset0:60 offset1:65
	ds_read2st64_b32 v[134:135], v10 offset0:70 offset1:75
	s_waitcnt lgkmcnt(11)
	v_mfma_f32_16x16x4_f32 v[136:139], v112, v236, v[136:139]
	v_mfma_f32_16x16x4_f32 v[140:143], v113, v237, v[140:143]
	s_add_u32 s14, s6, 0x160000
	s_addc_u32 s15, s7, 0
	global_load_dword v224, v12, s[14:15] offset:0
	global_load_dword v225, v12, s[14:15] offset:256
	global_load_dword v226, v12, s[14:15] offset:512
	global_load_dword v227, v12, s[14:15] offset:768
	s_waitcnt lgkmcnt(10)
	v_mfma_f32_16x16x4_f32 v[136:139], v114, v238, v[136:139]
	v_mfma_f32_16x16x4_f32 v[140:143], v115, v239, v[140:143]
	ds_write_b128 v2, v[60:63] offset:20480
	ds_write_b128 v2, v[64:67] offset:30720
	s_add_u32 s10, s0, 0x1a0000
	s_addc_u32 s11, s1, 0
	global_load_dwordx4 v[60:63], v0, s[10:11]
	global_load_dwordx4 v[64:67], v1, s[10:11]
	s_waitcnt lgkmcnt(11)
	v_mfma_f32_16x16x4_f32 v[136:139], v116, v240, v[136:139]
	v_mfma_f32_16x16x4_f32 v[140:143], v117, v241, v[140:143]
	s_waitcnt lgkmcnt(10)
	v_mfma_f32_16x16x4_f32 v[136:139], v118, v242, v[136:139]
	v_mfma_f32_16x16x4_f32 v[140:143], v119, v243, v[140:143]
	s_add_u32 s16, s8, 0xc0000
	s_addc_u32 s17, s9, 0
	s_nop 9
	v_add_f32_e32 v136, v136, v140
	v_add_f32_e32 v137, v137, v141
	v_add_f32_e32 v138, v138, v142
	v_add_f32_e32 v139, v139, v143
	ds_write_b32 v13, v136 offset:0
	ds_write_b32 v13, v137 offset:272
	ds_write_b32 v13, v138 offset:544
	ds_write_b32 v13, v139 offset:816
	global_store_dword v12, v136, s[16:17] offset:0
	global_store_dword v12, v137, s[16:17] offset:256
	global_store_dword v12, v138, s[16:17] offset:512
	global_store_dword v12, v139, s[16:17] offset:768
	s_waitcnt lgkmcnt(0)
	s_barrier
	ds_read2_b32 v[104:105], v8 offset0:0 offset1:4
	ds_read2_b32 v[106:107], v8 offset0:8 offset1:12
	ds_read2_b32 v[108:109], v8 offset0:16 offset1:20
	ds_read2_b32 v[110:111], v8 offset0:24 offset1:28
	ds_read2_b32 v[112:113], v8 offset0:32 offset1:36
	ds_read2_b32 v[114:115], v8 offset0:40 offset1:44
	ds_read2_b32 v[116:117], v8 offset0:48 offset1:52
	ds_read2_b32 v[118:119], v8 offset0:56 offset1:60
	s_waitcnt vmcnt(50)
	s_waitcnt lgkmcnt(7)
	v_mfma_f32_16x16x4_f32 v[136:139], v104, v120, v[204:207]
	v_mfma_f32_16x16x4_f32 v[140:143], v105, v121, 0
	ds_read2st64_b32 v[228:229], v11 offset0:0 offset1:5
	ds_read2st64_b32 v[230:231], v11 offset0:10 offset1:15
	s_waitcnt lgkmcnt(8)
	v_mfma_f32_16x16x4_f32 v[136:139], v106, v122, v[136:139]
	v_mfma_f32_16x16x4_f32 v[140:143], v107, v123, v[140:143]
	ds_read2st64_b32 v[232:233], v11 offset0:20 offset1:25
	ds_read2st64_b32 v[234:235], v11 offset0:30 offset1:35
	s_waitcnt lgkmcnt(9)
	v_mfma_f32_16x16x4_f32 v[136:139], v108, v124, v[136:139]
	v_mfma_f32_16x16x4_f32 v[140:143], v109, v125, v[140:143]
	ds_read2st64_b32 v[236:237], v11 offset0:40 offset1:45
	ds_read2st64_b32 v[238:239], v11 offset0:50 offset1:55
	s_waitcnt lgkmcnt(10)
	v_mfma_f32_16x16x4_f32 v[136:139], v110, v126, v[136:139]
	v_mfma_f32_16x16x4_f32 v[140:143], v111, v127, v[140:143]
	ds_read2st64_b32 v[240:241], v11 offset0:60 offset1:65
	ds_read2st64_b32 v[242:243], v11 offset0:70 offset1:75
	s_waitcnt lgkmcnt(11)
	v_mfma_f32_16x16x4_f32 v[136:139], v112, v128, v[136:139]
	v_mfma_f32_16x16x4_f32 v[140:143], v113, v129, v[140:143]
	s_add_u32 s14, s6, 0x180000
	s_addc_u32 s15, s7, 0
	global_load_dword v204, v12, s[14:15] offset:0
	global_load_dword v205, v12, s[14:15] offset:256
	global_load_dword v206, v12, s[14:15] offset:512
	global_load_dword v207, v12, s[14:15] offset:768
	s_waitcnt lgkmcnt(10)
	v_mfma_f32_16x16x4_f32 v[136:139], v114, v130, v[136:139]
	v_mfma_f32_16x16x4_f32 v[140:143], v115, v131, v[140:143]
	ds_write_b128 v2, v[68:71] offset:0
	ds_write_b128 v2, v[72:75] offset:10240
	s_add_u32 s10, s0, 0x1c0000
	s_addc_u32 s11, s1, 0
	global_load_dwordx4 v[68:71], v0, s[10:11]
	global_load_dwordx4 v[72:75], v1, s[10:11]
	s_waitcnt lgkmcnt(11)
	v_mfma_f32_16x16x4_f32 v[136:139], v116, v132, v[136:139]
	v_mfma_f32_16x16x4_f32 v[140:143], v117, v133, v[140:143]
	s_waitcnt lgkmcnt(10)
	v_mfma_f32_16x16x4_f32 v[136:139], v118, v134, v[136:139]
	v_mfma_f32_16x16x4_f32 v[140:143], v119, v135, v[140:143]
	s_add_u32 s16, s8, 0xe0000
	s_addc_u32 s17, s9, 0
	s_nop 9
	v_add_f32_e32 v136, v136, v140
	v_add_f32_e32 v137, v137, v141
	v_add_f32_e32 v138, v138, v142
	v_add_f32_e32 v139, v139, v143
	ds_write_b32 v13, v136 offset:2176
	ds_write_b32 v13, v137 offset:2448
	ds_write_b32 v13, v138 offset:2720
	ds_write_b32 v13, v139 offset:2992
	global_store_dword v12, v136, s[16:17] offset:0
	global_store_dword v12, v137, s[16:17] offset:256
	global_store_dword v12, v138, s[16:17] offset:512
	global_store_dword v12, v139, s[16:17] offset:768
	s_waitcnt lgkmcnt(0)
	s_barrier
; #define LAS __attribute__((address_space(3)))
; __device__ __forceinline__ void scan_combine(LAS unsigned char* lds, CArgsP a) {
;     ...
;     for (int g = 1; g <= GL; ++g) {
;         const bool pf = (g + 2 <= GL);
;         float u3 = 0.f;
;         if (pf) { const f32x4* Pn = (const f32x4*)(PM + (size_t)((g + 2) * 8 + h) * 4096); pa = Pn[tid]; pb = Pn[512 + tid]; u3 = UM[((size_t)((g + 2) * 8 + h) * 64 + v) * 64 + kq]; }
;         asm volatile("s_waitcnt lgkmcnt(0)\n\ts_barrier" ::: "memory");
;         const LAS float* Pg = Pl + (g % 3) * 4096 + kq;
;         float acc0 = u1, acc1 = 0.f, acc2 = 0.f, acc3 = 0.f;
;         const int curi = __builtin_bit_cast(int, cur);
; #pragma unroll
;         for (int k = 0; k < 64; k += 4) {
;             const float s0 = __builtin_bit_cast(float, __builtin_amdgcn_readlane(curi, k)), s1 = __builtin_bit_cast(float, __builtin_amdgcn_readlane(curi, k + 1));
;             const float s2 = __builtin_bit_cast(float, __builtin_amdgcn_readlane(curi, k + 2)), s3 = __builtin_bit_cast(float, __builtin_amdgcn_readlane(curi, k + 3));
;             acc0 += s0 * Pg[(k + 0) * 64]; acc1 += s1 * Pg[(k + 1) * 64]; acc2 += s2 * Pg[(k + 2) * 64]; acc3 += s3 * Pg[(k + 3) * 64];
;         }
;         cur = (acc0 + acc1) + (acc2 + acc3);
;         SS[((size_t)((g + 1) * 8 + h) * 64 + v) * 64 + kq] = cur;
;         if (pf) { LAS float* dst = Pl + ((g + 2) % 3) * 4096; *(LAS f32x4*)(dst + 4 * tid) = pa; *(LAS f32x4*)(dst + 2048 + 4 * tid) = pb; }
;         u1 = u2; u2 = u3;
;     }
	ds_read2_b32 v[104:105], v9 offset0:0 offset1:4
	ds_read2_b32 v[106:107], v9 offset0:8 offset1:12
	ds_read2_b32 v[108:109], v9 offset0:16 offset1:20
	ds_read2_b32 v[110:111], v9 offset0:24 offset1:28
	ds_read2_b32 v[112:113], v9 offset0:32 offset1:36
	ds_read2_b32 v[114:115], v9 offset0:40 offset1:44
	ds_read2_b32 v[116:117], v9 offset0:48 offset1:52
	ds_read2_b32 v[118:119], v9 offset0:56 offset1:60
	s_waitcnt vmcnt(56)
	s_waitcnt lgkmcnt(7)
	v_mfma_f32_16x16x4_f32 v[136:139], v104, v228, v[208:211]
	v_mfma_f32_16x16x4_f32 v[140:143], v105, v229, 0
	ds_read2st64_b32 v[120:121], v10 offset0:0 offset1:5
	ds_read2st64_b32 v[122:123], v10 offset0:10 offset1:15
	s_waitcnt lgkmcnt(8)
	v_mfma_f32_16x16x4_f32 v[136:139], v106, v230, v[136:139]
	v_mfma_f32_16x16x4_f32 v[140:143], v107, v231, v[140:143]
	ds_read2st64_b32 v[124:125], v10 offset0:20 offset1:25
	ds_read2st64_b32 v[126:127], v10 offset0:30 offset1:35
	s_waitcnt lgkmcnt(9)
	v_mfma_f32_16x16x4_f32 v[136:139], v108, v232, v[136:139]
	v_mfma_f32_16x16x4_f32 v[140:143], v109, v233, v[140:143]
	ds_read2st64_b32 v[128:129], v10 offset0:40 offset1:45
	ds_read2st64_b32 v[130:131], v10 offset0:50 offset1:55
	s_waitcnt lgkmcnt(10)
	v_mfma_f32_16x16x4_f32 v[136:139], v110, v234, v[136:139]
	v_mfma_f32_16x16x4_f32 v[140:143], v111, v235, v[140:143]
	ds_read2st64_b32 v[132:133], v10 offset0:60 offset1:65
	ds_read2st64_b32 v[134:135], v10 offset0:70 offset1:75
	s_waitcnt lgkmcnt(11)
	v_mfma_f32_16x16x4_f32 v[136:139], v112, v236, v[136:139]
	v_mfma_f32_16x16x4_f32 v[140:143], v113, v237, v[140:143]
	s_add_u32 s14, s6, 0x1a0000
	s_addc_u32 s15, s7, 0
	global_load_dword v208, v12, s[14:15] offset:0
	global_load_dword v209, v12, s[14:15] offset:256
	global_load_dword v210, v12, s[14:15] offset:512
	global_load_dword v211, v12, s[14:15] offset:768
	s_waitcnt lgkmcnt(10)
	v_mfma_f32_16x16x4_f32 v[136:139], v114, v238, v[136:139]
	v_mfma_f32_16x16x4_f32 v[140:143], v115, v239, v[140:143]
	s_waitcnt vmcnt(58)
	ds_write_b128 v2, v[76:79] offset:20480
	ds_write_b128 v2, v[80:83] offset:30720
	s_add_u32 s10, s0, 0x1e0000
	s_addc_u32 s11, s1, 0
	global_load_dwordx4 v[76:79], v0, s[10:11]
	global_load_dwordx4 v[80:83], v1, s[10:11]
	s_waitcnt lgkmcnt(11)
	v_mfma_f32_16x16x4_f32 v[136:139], v116, v240, v[136:139]
	v_mfma_f32_16x16x4_f32 v[140:143], v117, v241, v[140:143]
	s_waitcnt lgkmcnt(10)
	v_mfma_f32_16x16x4_f32 v[136:139], v118, v242, v[136:139]
	v_mfma_f32_16x16x4_f32 v[140:143], v119, v243, v[140:143]
	s_add_u32 s16, s8, 0x100000
	s_addc_u32 s17, s9, 0
	s_nop 9
	v_add_f32_e32 v136, v136, v140
	v_add_f32_e32 v137, v137, v141
	v_add_f32_e32 v138, v138, v142
	v_add_f32_e32 v139, v139, v143
	ds_write_b32 v13, v136 offset:0
	ds_write_b32 v13, v137 offset:272
	ds_write_b32 v13, v138 offset:544
	ds_write_b32 v13, v139 offset:816
	global_store_dword v12, v136, s[16:17] offset:0
	global_store_dword v12, v137, s[16:17] offset:256
	global_store_dword v12, v138, s[16:17] offset:512
	global_store_dword v12, v139, s[16:17] offset:768
	s_waitcnt lgkmcnt(0)
	s_barrier
	ds_read2_b32 v[104:105], v8 offset0:0 offset1:4
	ds_read2_b32 v[106:107], v8 offset0:8 offset1:12
	ds_read2_b32 v[108:109], v8 offset0:16 offset1:20
	ds_read2_b32 v[110:111], v8 offset0:24 offset1:28
	ds_read2_b32 v[112:113], v8 offset0:32 offset1:36
	ds_read2_b32 v[114:115], v8 offset0:40 offset1:44
	ds_read2_b32 v[116:117], v8 offset0:48 offset1:52
	ds_read2_b32 v[118:119], v8 offset0:56 offset1:60
	s_waitcnt vmcnt(56)
	s_waitcnt lgkmcnt(7)
	v_mfma_f32_16x16x4_f32 v[136:139], v104, v120, v[212:215]
	v_mfma_f32_16x16x4_f32 v[140:143], v105, v121, 0
	ds_read2st64_b32 v[228:229], v11 offset0:0 offset1:5
	ds_read2st64_b32 v[230:231], v11 offset0:10 offset1:15
	s_waitcnt lgkmcnt(8)
	v_mfma_f32_16x16x4_f32 v[136:139], v106, v122, v[136:139]
	v_mfma_f32_16x16x4_f32 v[140:143], v107, v123, v[140:143]
	ds_read2st64_b32 v[232:233], v11 offset0:20 offset1:25
	ds_read2st64_b32 v[234:235], v11 offset0:30 offset1:35
	s_waitcnt lgkmcnt(9)
	v_mfma_f32_16x16x4_f32 v[136:139], v108, v124, v[136:139]
	v_mfma_f32_16x16x4_f32 v[140:143], v109, v125, v[140:143]
	ds_read2st64_b32 v[236:237], v11 offset0:40 offset1:45
	ds_read2st64_b32 v[238:239], v11 offset0:50 offset1:55
	s_waitcnt lgkmcnt(10)
	v_mfma_f32_16x16x4_f32 v[136:139], v110, v126, v[136:139]
	v_mfma_f32_16x16x4_f32 v[140:143], v111, v127, v[140:143]
	ds_read2st64_b32 v[240:241], v11 offset0:60 offset1:65
	ds_read2st64_b32 v[242:243], v11 offset0:70 offset1:75
	s_waitcnt lgkmcnt(11)
	v_mfma_f32_16x16x4_f32 v[136:139], v112, v128, v[136:139]
	v_mfma_f32_16x16x4_f32 v[140:143], v113, v129, v[140:143]
	s_add_u32 s14, s6, 0x1c0000
	s_addc_u32 s15, s7, 0
	global_load_dword v212, v12, s[14:15] offset:0
	global_load_dword v213, v12, s[14:15] offset:256
	global_load_dword v214, v12, s[14:15] offset:512
	global_load_dword v215, v12, s[14:15] offset:768
	s_waitcnt lgkmcnt(10)
	v_mfma_f32_16x16x4_f32 v[136:139], v114, v130, v[136:139]
	v_mfma_f32_16x16x4_f32 v[140:143], v115, v131, v[140:143]
	s_waitcnt vmcnt(58)
	ds_write_b128 v2, v[84:87] offset:0
	ds_write_b128 v2, v[88:91] offset:10240
	s_add_u32 s10, s0, 0x200000
	s_addc_u32 s11, s1, 0
	global_load_dwordx4 v[84:87], v0, s[10:11]
	global_load_dwordx4 v[88:91], v1, s[10:11]
	s_waitcnt lgkmcnt(11)
	v_mfma_f32_16x16x4_f32 v[136:139], v116, v132, v[136:139]
	v_mfma_f32_16x16x4_f32 v[140:143], v117, v133, v[140:143]
	s_waitcnt lgkmcnt(10)
	v_mfma_f32_16x16x4_f32 v[136:139], v118, v134, v[136:139]
	v_mfma_f32_16x16x4_f32 v[140:143], v119, v135, v[140:143]
	s_add_u32 s16, s8, 0x120000
	s_addc_u32 s17, s9, 0
	s_nop 9
	v_add_f32_e32 v136, v136, v140
	v_add_f32_e32 v137, v137, v141
	v_add_f32_e32 v138, v138, v142
	v_add_f32_e32 v139, v139, v143
	ds_write_b32 v13, v136 offset:2176
	ds_write_b32 v13, v137 offset:2448
	ds_write_b32 v13, v138 offset:2720
	ds_write_b32 v13, v139 offset:2992
	global_store_dword v12, v136, s[16:17] offset:0
	global_store_dword v12, v137, s[16:17] offset:256
	global_store_dword v12, v138, s[16:17] offset:512
	global_store_dword v12, v139, s[16:17] offset:768
	s_waitcnt lgkmcnt(0)
	s_barrier
; #define LAS __attribute__((address_space(3)))
; __device__ __forceinline__ void scan_combine(LAS unsigned char* lds, CArgsP a) {
;     ...
;     for (int g = 1; g <= GL; ++g) {
;         const bool pf = (g + 2 <= GL);
;         float u3 = 0.f;
;         if (pf) { const f32x4* Pn = (const f32x4*)(PM + (size_t)((g + 2) * 8 + h) * 4096); pa = Pn[tid]; pb = Pn[512 + tid]; u3 = UM[((size_t)((g + 2) * 8 + h) * 64 + v) * 64 + kq]; }
;         asm volatile("s_waitcnt lgkmcnt(0)\n\ts_barrier" ::: "memory");
;         const LAS float* Pg = Pl + (g % 3) * 4096 + kq;
;         float acc0 = u1, acc1 = 0.f, acc2 = 0.f, acc3 = 0.f;
;         const int curi = __builtin_bit_cast(int, cur);
; #pragma unroll
;         for (int k = 0; k < 64; k += 4) {
;             const float s0 = __builtin_bit_cast(float, __builtin_amdgcn_readlane(curi, k)), s1 = __builtin_bit_cast(float, __builtin_amdgcn_readlane(curi, k + 1));
;             const float s2 = __builtin_bit_cast(float, __builtin_amdgcn_readlane(curi, k + 2)), s3 = __builtin_bit_cast(float, __builtin_amdgcn_readlane(curi, k + 3));
;             acc0 += s0 * Pg[(k + 0) * 64]; acc1 += s1 * Pg[(k + 1) * 64]; acc2 += s2 * Pg[(k + 2) * 64]; acc3 += s3 * Pg[(k + 3) * 64];
;         }
;         cur = (acc0 + acc1) + (acc2 + acc3);
;         SS[((size_t)((g + 1) * 8 + h) * 64 + v) * 64 + kq] = cur;
;         if (pf) { LAS float* dst = Pl + ((g + 2) % 3) * 4096; *(LAS f32x4*)(dst + 4 * tid) = pa; *(LAS f32x4*)(dst + 2048 + 4 * tid) = pb; }
;         u1 = u2; u2 = u3;
;     }
	ds_read2_b32 v[104:105], v9 offset0:0 offset1:4
	ds_read2_b32 v[106:107], v9 offset0:8 offset1:12
	ds_read2_b32 v[108:109], v9 offset0:16 offset1:20
	ds_read2_b32 v[110:111], v9 offset0:24 offset1:28
	ds_read2_b32 v[112:113], v9 offset0:32 offset1:36
	ds_read2_b32 v[114:115], v9 offset0:40 offset1:44
	ds_read2_b32 v[116:117], v9 offset0:48 offset1:52
	ds_read2_b32 v[118:119], v9 offset0:56 offset1:60
	s_waitcnt vmcnt(56)
	s_waitcnt lgkmcnt(7)
	v_mfma_f32_16x16x4_f32 v[136:139], v104, v228, v[216:219]
	v_mfma_f32_16x16x4_f32 v[140:143], v105, v229, 0
	ds_read2st64_b32 v[120:121], v10 offset0:0 offset1:5
	ds_read2st64_b32 v[122:123], v10 offset0:10 offset1:15
	s_waitcnt lgkmcnt(8)
	v_mfma_f32_16x16x4_f32 v[136:139], v106, v230, v[136:139]
	v_mfma_f32_16x16x4_f32 v[140:143], v107, v231, v[140:143]
	ds_read2st64_b32 v[124:125], v10 offset0:20 offset1:25
	ds_read2st64_b32 v[126:127], v10 offset0:30 offset1:35
	s_waitcnt lgkmcnt(9)
	v_mfma_f32_16x16x4_f32 v[136:139], v108, v232, v[136:139]
	v_mfma_f32_16x16x4_f32 v[140:143], v109, v233, v[140:143]
	ds_read2st64_b32 v[128:129], v10 offset0:40 offset1:45
	ds_read2st64_b32 v[130:131], v10 offset0:50 offset1:55
	s_waitcnt lgkmcnt(10)
	v_mfma_f32_16x16x4_f32 v[136:139], v110, v234, v[136:139]
	v_mfma_f32_16x16x4_f32 v[140:143], v111, v235, v[140:143]
	ds_read2st64_b32 v[132:133], v10 offset0:60 offset1:65
	ds_read2st64_b32 v[134:135], v10 offset0:70 offset1:75
	s_waitcnt lgkmcnt(11)
	v_mfma_f32_16x16x4_f32 v[136:139], v112, v236, v[136:139]
	v_mfma_f32_16x16x4_f32 v[140:143], v113, v237, v[140:143]
	s_add_u32 s14, s6, 0x1e0000
	s_addc_u32 s15, s7, 0
	global_load_dword v216, v12, s[14:15] offset:0
	global_load_dword v217, v12, s[14:15] offset:256
	global_load_dword v218, v12, s[14:15] offset:512
	global_load_dword v219, v12, s[14:15] offset:768
	s_waitcnt lgkmcnt(10)
	v_mfma_f32_16x16x4_f32 v[136:139], v114, v238, v[136:139]
	v_mfma_f32_16x16x4_f32 v[140:143], v115, v239, v[140:143]
	s_waitcnt vmcnt(58)
	ds_write_b128 v2, v[92:95] offset:20480
	ds_write_b128 v2, v[96:99] offset:30720
	s_add_u32 s10, s0, 0x220000
	s_addc_u32 s11, s1, 0
	global_load_dwordx4 v[92:95], v0, s[10:11]
	global_load_dwordx4 v[96:99], v1, s[10:11]
	s_waitcnt lgkmcnt(11)
	v_mfma_f32_16x16x4_f32 v[136:139], v116, v240, v[136:139]
	v_mfma_f32_16x16x4_f32 v[140:143], v117, v241, v[140:143]
	s_waitcnt lgkmcnt(10)
	v_mfma_f32_16x16x4_f32 v[136:139], v118, v242, v[136:139]
	v_mfma_f32_16x16x4_f32 v[140:143], v119, v243, v[140:143]
	s_add_u32 s16, s8, 0x140000
	s_addc_u32 s17, s9, 0
	s_nop 9
	v_add_f32_e32 v136, v136, v140
	v_add_f32_e32 v137, v137, v141
	v_add_f32_e32 v138, v138, v142
	v_add_f32_e32 v139, v139, v143
	ds_write_b32 v13, v136 offset:0
	ds_write_b32 v13, v137 offset:272
	ds_write_b32 v13, v138 offset:544
	ds_write_b32 v13, v139 offset:816
	global_store_dword v12, v136, s[16:17] offset:0
	global_store_dword v12, v137, s[16:17] offset:256
	global_store_dword v12, v138, s[16:17] offset:512
	global_store_dword v12, v139, s[16:17] offset:768
	s_waitcnt lgkmcnt(0)
	s_barrier
	ds_read2_b32 v[104:105], v8 offset0:0 offset1:4
	ds_read2_b32 v[106:107], v8 offset0:8 offset1:12
	ds_read2_b32 v[108:109], v8 offset0:16 offset1:20
	ds_read2_b32 v[110:111], v8 offset0:24 offset1:28
	ds_read2_b32 v[112:113], v8 offset0:32 offset1:36
	ds_read2_b32 v[114:115], v8 offset0:40 offset1:44
	ds_read2_b32 v[116:117], v8 offset0:48 offset1:52
	ds_read2_b32 v[118:119], v8 offset0:56 offset1:60
	s_waitcnt vmcnt(56)
	s_waitcnt lgkmcnt(7)
	v_mfma_f32_16x16x4_f32 v[136:139], v104, v120, v[220:223]
	v_mfma_f32_16x16x4_f32 v[140:143], v105, v121, 0
	ds_read2st64_b32 v[228:229], v11 offset0:0 offset1:5
	ds_read2st64_b32 v[230:231], v11 offset0:10 offset1:15
	s_waitcnt lgkmcnt(8)
	v_mfma_f32_16x16x4_f32 v[136:139], v106, v122, v[136:139]
	v_mfma_f32_16x16x4_f32 v[140:143], v107, v123, v[140:143]
	ds_read2st64_b32 v[232:233], v11 offset0:20 offset1:25
	ds_read2st64_b32 v[234:235], v11 offset0:30 offset1:35
	s_waitcnt lgkmcnt(9)
	v_mfma_f32_16x16x4_f32 v[136:139], v108, v124, v[136:139]
	v_mfma_f32_16x16x4_f32 v[140:143], v109, v125, v[140:143]
	ds_read2st64_b32 v[236:237], v11 offset0:40 offset1:45
	ds_read2st64_b32 v[238:239], v11 offset0:50 offset1:55
	s_waitcnt lgkmcnt(10)
	v_mfma_f32_16x16x4_f32 v[136:139], v110, v126, v[136:139]
	v_mfma_f32_16x16x4_f32 v[140:143], v111, v127, v[140:143]
	ds_read2st64_b32 v[240:241], v11 offset0:60 offset1:65
	ds_read2st64_b32 v[242:243], v11 offset0:70 offset1:75
	s_waitcnt lgkmcnt(11)
	v_mfma_f32_16x16x4_f32 v[136:139], v112, v128, v[136:139]
	v_mfma_f32_16x16x4_f32 v[140:143], v113, v129, v[140:143]
	s_add_u32 s14, s6, 0x200000
	s_addc_u32 s15, s7, 0
	global_load_dword v220, v12, s[14:15] offset:0
	global_load_dword v221, v12, s[14:15] offset:256
	global_load_dword v222, v12, s[14:15] offset:512
	global_load_dword v223, v12, s[14:15] offset:768
	s_waitcnt lgkmcnt(10)
	v_mfma_f32_16x16x4_f32 v[136:139], v114, v130, v[136:139]
	v_mfma_f32_16x16x4_f32 v[140:143], v115, v131, v[140:143]
	s_waitcnt vmcnt(58)
	ds_write_b128 v2, v[52:55] offset:0
	ds_write_b128 v2, v[56:59] offset:10240
	s_add_u32 s10, s0, 0x240000
	s_addc_u32 s11, s1, 0
	global_load_dwordx4 v[52:55], v0, s[10:11]
	global_load_dwordx4 v[56:59], v1, s[10:11]
	s_waitcnt lgkmcnt(11)
	v_mfma_f32_16x16x4_f32 v[136:139], v116, v132, v[136:139]
	v_mfma_f32_16x16x4_f32 v[140:143], v117, v133, v[140:143]
	s_waitcnt lgkmcnt(10)
	v_mfma_f32_16x16x4_f32 v[136:139], v118, v134, v[136:139]
	v_mfma_f32_16x16x4_f32 v[140:143], v119, v135, v[140:143]
	s_add_u32 s16, s8, 0x160000
	s_addc_u32 s17, s9, 0
	s_nop 9
	v_add_f32_e32 v136, v136, v140
	v_add_f32_e32 v137, v137, v141
	v_add_f32_e32 v138, v138, v142
	v_add_f32_e32 v139, v139, v143
	ds_write_b32 v13, v136 offset:2176
	ds_write_b32 v13, v137 offset:2448
	ds_write_b32 v13, v138 offset:2720
	ds_write_b32 v13, v139 offset:2992
	global_store_dword v12, v136, s[16:17] offset:0
	global_store_dword v12, v137, s[16:17] offset:256
	global_store_dword v12, v138, s[16:17] offset:512
	global_store_dword v12, v139, s[16:17] offset:768
	s_waitcnt lgkmcnt(0)
	s_barrier
; #define LAS __attribute__((address_space(3)))
; __device__ __forceinline__ void scan_combine(LAS unsigned char* lds, CArgsP a) {
;     ...
;     for (int g = 1; g <= GL; ++g) {
;         const bool pf = (g + 2 <= GL);
;         float u3 = 0.f;
;         if (pf) { const f32x4* Pn = (const f32x4*)(PM + (size_t)((g + 2) * 8 + h) * 4096); pa = Pn[tid]; pb = Pn[512 + tid]; u3 = UM[((size_t)((g + 2) * 8 + h) * 64 + v) * 64 + kq]; }
;         asm volatile("s_waitcnt lgkmcnt(0)\n\ts_barrier" ::: "memory");
;         const LAS float* Pg = Pl + (g % 3) * 4096 + kq;
;         float acc0 = u1, acc1 = 0.f, acc2 = 0.f, acc3 = 0.f;
;         const int curi = __builtin_bit_cast(int, cur);
; #pragma unroll
;         for (int k = 0; k < 64; k += 4) {
;             const float s0 = __builtin_bit_cast(float, __builtin_amdgcn_readlane(curi, k)), s1 = __builtin_bit_cast(float, __builtin_amdgcn_readlane(curi, k + 1));
;             const float s2 = __builtin_bit_cast(float, __builtin_amdgcn_readlane(curi, k + 2)), s3 = __builtin_bit_cast(float, __builtin_amdgcn_readlane(curi, k + 3));
;             acc0 += s0 * Pg[(k + 0) * 64]; acc1 += s1 * Pg[(k + 1) * 64]; acc2 += s2 * Pg[(k + 2) * 64]; acc3 += s3 * Pg[(k + 3) * 64];
;         }
;         cur = (acc0 + acc1) + (acc2 + acc3);
;         SS[((size_t)((g + 1) * 8 + h) * 64 + v) * 64 + kq] = cur;
;         if (pf) { LAS float* dst = Pl + ((g + 2) % 3) * 4096; *(LAS f32x4*)(dst + 4 * tid) = pa; *(LAS f32x4*)(dst + 2048 + 4 * tid) = pb; }
;         u1 = u2; u2 = u3;
;     }
	ds_read2_b32 v[104:105], v9 offset0:0 offset1:4
	ds_read2_b32 v[106:107], v9 offset0:8 offset1:12
	ds_read2_b32 v[108:109], v9 offset0:16 offset1:20
	ds_read2_b32 v[110:111], v9 offset0:24 offset1:28
	ds_read2_b32 v[112:113], v9 offset0:32 offset1:36
	ds_read2_b32 v[114:115], v9 offset0:40 offset1:44
	ds_read2_b32 v[116:117], v9 offset0:48 offset1:52
	ds_read2_b32 v[118:119], v9 offset0:56 offset1:60
	s_waitcnt vmcnt(56)
	s_waitcnt lgkmcnt(7)
	v_mfma_f32_16x16x4_f32 v[136:139], v104, v228, v[224:227]
	v_mfma_f32_16x16x4_f32 v[140:143], v105, v229, 0
	ds_read2st64_b32 v[120:121], v10 offset0:0 offset1:5
	ds_read2st64_b32 v[122:123], v10 offset0:10 offset1:15
	s_waitcnt lgkmcnt(8)
	v_mfma_f32_16x16x4_f32 v[136:139], v106, v230, v[136:139]
	v_mfma_f32_16x16x4_f32 v[140:143], v107, v231, v[140:143]
	ds_read2st64_b32 v[124:125], v10 offset0:20 offset1:25
	ds_read2st64_b32 v[126:127], v10 offset0:30 offset1:35
	s_waitcnt lgkmcnt(9)
	v_mfma_f32_16x16x4_f32 v[136:139], v108, v232, v[136:139]
	v_mfma_f32_16x16x4_f32 v[140:143], v109, v233, v[140:143]
	ds_read2st64_b32 v[128:129], v10 offset0:40 offset1:45
	ds_read2st64_b32 v[130:131], v10 offset0:50 offset1:55
	s_waitcnt lgkmcnt(10)
	v_mfma_f32_16x16x4_f32 v[136:139], v110, v234, v[136:139]
	v_mfma_f32_16x16x4_f32 v[140:143], v111, v235, v[140:143]
	ds_read2st64_b32 v[132:133], v10 offset0:60 offset1:65
	ds_read2st64_b32 v[134:135], v10 offset0:70 offset1:75
	s_waitcnt lgkmcnt(11)
	v_mfma_f32_16x16x4_f32 v[136:139], v112, v236, v[136:139]
	v_mfma_f32_16x16x4_f32 v[140:143], v113, v237, v[140:143]
	s_add_u32 s14, s6, 0x220000
	s_addc_u32 s15, s7, 0
	global_load_dword v224, v12, s[14:15] offset:0
	global_load_dword v225, v12, s[14:15] offset:256
	global_load_dword v226, v12, s[14:15] offset:512
	global_load_dword v227, v12, s[14:15] offset:768
	s_waitcnt lgkmcnt(10)
	v_mfma_f32_16x16x4_f32 v[136:139], v114, v238, v[136:139]
	v_mfma_f32_16x16x4_f32 v[140:143], v115, v239, v[140:143]
	s_waitcnt vmcnt(58)
	ds_write_b128 v2, v[60:63] offset:20480
	ds_write_b128 v2, v[64:67] offset:30720
	s_add_u32 s10, s0, 0x260000
	s_addc_u32 s11, s1, 0
	global_load_dwordx4 v[60:63], v0, s[10:11]
	global_load_dwordx4 v[64:67], v1, s[10:11]
	s_waitcnt lgkmcnt(11)
	v_mfma_f32_16x16x4_f32 v[136:139], v116, v240, v[136:139]
	v_mfma_f32_16x16x4_f32 v[140:143], v117, v241, v[140:143]
	s_waitcnt lgkmcnt(10)
	v_mfma_f32_16x16x4_f32 v[136:139], v118, v242, v[136:139]
	v_mfma_f32_16x16x4_f32 v[140:143], v119, v243, v[140:143]
	s_add_u32 s16, s8, 0x180000
	s_addc_u32 s17, s9, 0
	s_nop 9
	v_add_f32_e32 v136, v136, v140
	v_add_f32_e32 v137, v137, v141
	v_add_f32_e32 v138, v138, v142
	v_add_f32_e32 v139, v139, v143
	ds_write_b32 v13, v136 offset:0
	ds_write_b32 v13, v137 offset:272
	ds_write_b32 v13, v138 offset:544
	ds_write_b32 v13, v139 offset:816
	global_store_dword v12, v136, s[16:17] offset:0
	global_store_dword v12, v137, s[16:17] offset:256
	global_store_dword v12, v138, s[16:17] offset:512
	global_store_dword v12, v139, s[16:17] offset:768
	s_waitcnt lgkmcnt(0)
	s_barrier
	ds_read2_b32 v[104:105], v8 offset0:0 offset1:4
	ds_read2_b32 v[106:107], v8 offset0:8 offset1:12
	ds_read2_b32 v[108:109], v8 offset0:16 offset1:20
	ds_read2_b32 v[110:111], v8 offset0:24 offset1:28
	ds_read2_b32 v[112:113], v8 offset0:32 offset1:36
	ds_read2_b32 v[114:115], v8 offset0:40 offset1:44
	ds_read2_b32 v[116:117], v8 offset0:48 offset1:52
	ds_read2_b32 v[118:119], v8 offset0:56 offset1:60
	s_waitcnt vmcnt(56)
	s_waitcnt lgkmcnt(7)
	v_mfma_f32_16x16x4_f32 v[136:139], v104, v120, v[204:207]
	v_mfma_f32_16x16x4_f32 v[140:143], v105, v121, 0
	ds_read2st64_b32 v[228:229], v11 offset0:0 offset1:5
	ds_read2st64_b32 v[230:231], v11 offset0:10 offset1:15
	s_waitcnt lgkmcnt(8)
	v_mfma_f32_16x16x4_f32 v[136:139], v106, v122, v[136:139]
	v_mfma_f32_16x16x4_f32 v[140:143], v107, v123, v[140:143]
	ds_read2st64_b32 v[232:233], v11 offset0:20 offset1:25
	ds_read2st64_b32 v[234:235], v11 offset0:30 offset1:35
	s_waitcnt lgkmcnt(9)
	v_mfma_f32_16x16x4_f32 v[136:139], v108, v124, v[136:139]
	v_mfma_f32_16x16x4_f32 v[140:143], v109, v125, v[140:143]
	ds_read2st64_b32 v[236:237], v11 offset0:40 offset1:45
	ds_read2st64_b32 v[238:239], v11 offset0:50 offset1:55
	s_waitcnt lgkmcnt(10)
	v_mfma_f32_16x16x4_f32 v[136:139], v110, v126, v[136:139]
	v_mfma_f32_16x16x4_f32 v[140:143], v111, v127, v[140:143]
	ds_read2st64_b32 v[240:241], v11 offset0:60 offset1:65
	ds_read2st64_b32 v[242:243], v11 offset0:70 offset1:75
	s_waitcnt lgkmcnt(11)
	v_mfma_f32_16x16x4_f32 v[136:139], v112, v128, v[136:139]
	v_mfma_f32_16x16x4_f32 v[140:143], v113, v129, v[140:143]
	s_add_u32 s14, s6, 0x240000
	s_addc_u32 s15, s7, 0
	global_load_dword v204, v12, s[14:15] offset:0
	global_load_dword v205, v12, s[14:15] offset:256
	global_load_dword v206, v12, s[14:15] offset:512
	global_load_dword v207, v12, s[14:15] offset:768
	s_waitcnt lgkmcnt(10)
	v_mfma_f32_16x16x4_f32 v[136:139], v114, v130, v[136:139]
	v_mfma_f32_16x16x4_f32 v[140:143], v115, v131, v[140:143]
	s_waitcnt vmcnt(58)
	ds_write_b128 v2, v[68:71] offset:0
	ds_write_b128 v2, v[72:75] offset:10240
	s_add_u32 s10, s0, 0x280000
	s_addc_u32 s11, s1, 0
	global_load_dwordx4 v[68:71], v0, s[10:11]
	global_load_dwordx4 v[72:75], v1, s[10:11]
	s_waitcnt lgkmcnt(11)
	v_mfma_f32_16x16x4_f32 v[136:139], v116, v132, v[136:139]
	v_mfma_f32_16x16x4_f32 v[140:143], v117, v133, v[140:143]
	s_waitcnt lgkmcnt(10)
	v_mfma_f32_16x16x4_f32 v[136:139], v118, v134, v[136:139]
	v_mfma_f32_16x16x4_f32 v[140:143], v119, v135, v[140:143]
	s_add_u32 s16, s8, 0x1a0000
	s_addc_u32 s17, s9, 0
	s_nop 9
	v_add_f32_e32 v136, v136, v140
	v_add_f32_e32 v137, v137, v141
	v_add_f32_e32 v138, v138, v142
	v_add_f32_e32 v139, v139, v143
	ds_write_b32 v13, v136 offset:2176
	ds_write_b32 v13, v137 offset:2448
	ds_write_b32 v13, v138 offset:2720
	ds_write_b32 v13, v139 offset:2992
	global_store_dword v12, v136, s[16:17] offset:0
	global_store_dword v12, v137, s[16:17] offset:256
	global_store_dword v12, v138, s[16:17] offset:512
	global_store_dword v12, v139, s[16:17] offset:768
	s_waitcnt lgkmcnt(0)
	s_barrier
; #define LAS __attribute__((address_space(3)))
; __device__ __forceinline__ void scan_combine(LAS unsigned char* lds, CArgsP a) {
;     ...
;     for (int g = 1; g <= GL; ++g) {
;         const bool pf = (g + 2 <= GL);
;         float u3 = 0.f;
;         if (pf) { const f32x4* Pn = (const f32x4*)(PM + (size_t)((g + 2) * 8 + h) * 4096); pa = Pn[tid]; pb = Pn[512 + tid]; u3 = UM[((size_t)((g + 2) * 8 + h) * 64 + v) * 64 + kq]; }
;         asm volatile("s_waitcnt lgkmcnt(0)\n\ts_barrier" ::: "memory");
;         const LAS float* Pg = Pl + (g % 3) * 4096 + kq;
;         float acc0 = u1, acc1 = 0.f, acc2 = 0.f, acc3 = 0.f;
;         const int curi = __builtin_bit_cast(int, cur);
; #pragma unroll
;         for (int k = 0; k < 64; k += 4) {
;             const float s0 = __builtin_bit_cast(float, __builtin_amdgcn_readlane(curi, k)), s1 = __builtin_bit_cast(float, __builtin_amdgcn_readlane(curi, k + 1));
;             const float s2 = __builtin_bit_cast(float, __builtin_amdgcn_readlane(curi, k + 2)), s3 = __builtin_bit_cast(float, __builtin_amdgcn_readlane(curi, k + 3));
;             acc0 += s0 * Pg[(k + 0) * 64]; acc1 += s1 * Pg[(k + 1) * 64]; acc2 += s2 * Pg[(k + 2) * 64]; acc3 += s3 * Pg[(k + 3) * 64];
;         }
;         cur = (acc0 + acc1) + (acc2 + acc3);
;         SS[((size_t)((g + 1) * 8 + h) * 64 + v) * 64 + kq] = cur;
;         if (pf) { LAS float* dst = Pl + ((g + 2) % 3) * 4096; *(LAS f32x4*)(dst + 4 * tid) = pa; *(LAS f32x4*)(dst + 2048 + 4 * tid) = pb; }
;         u1 = u2; u2 = u3;
;     }
	ds_read2_b32 v[104:105], v9 offset0:0 offset1:4
	ds_read2_b32 v[106:107], v9 offset0:8 offset1:12
	ds_read2_b32 v[108:109], v9 offset0:16 offset1:20
	ds_read2_b32 v[110:111], v9 offset0:24 offset1:28
	ds_read2_b32 v[112:113], v9 offset0:32 offset1:36
	ds_read2_b32 v[114:115], v9 offset0:40 offset1:44
	ds_read2_b32 v[116:117], v9 offset0:48 offset1:52
	ds_read2_b32 v[118:119], v9 offset0:56 offset1:60
	s_waitcnt vmcnt(56)
	s_waitcnt lgkmcnt(7)
	v_mfma_f32_16x16x4_f32 v[136:139], v104, v228, v[208:211]
	v_mfma_f32_16x16x4_f32 v[140:143], v105, v229, 0
	ds_read2st64_b32 v[120:121], v10 offset0:0 offset1:5
	ds_read2st64_b32 v[122:123], v10 offset0:10 offset1:15
	s_waitcnt lgkmcnt(8)
	v_mfma_f32_16x16x4_f32 v[136:139], v106, v230, v[136:139]
	v_mfma_f32_16x16x4_f32 v[140:143], v107, v231, v[140:143]
	ds_read2st64_b32 v[124:125], v10 offset0:20 offset1:25
	ds_read2st64_b32 v[126:127], v10 offset0:30 offset1:35
	s_waitcnt lgkmcnt(9)
	v_mfma_f32_16x16x4_f32 v[136:139], v108, v232, v[136:139]
	v_mfma_f32_16x16x4_f32 v[140:143], v109, v233, v[140:143]
	ds_read2st64_b32 v[128:129], v10 offset0:40 offset1:45
	ds_read2st64_b32 v[130:131], v10 offset0:50 offset1:55
	s_waitcnt lgkmcnt(10)
	v_mfma_f32_16x16x4_f32 v[136:139], v110, v234, v[136:139]
	v_mfma_f32_16x16x4_f32 v[140:143], v111, v235, v[140:143]
	ds_read2st64_b32 v[132:133], v10 offset0:60 offset1:65
	ds_read2st64_b32 v[134:135], v10 offset0:70 offset1:75
	s_waitcnt lgkmcnt(11)
	v_mfma_f32_16x16x4_f32 v[136:139], v112, v236, v[136:139]
	v_mfma_f32_16x16x4_f32 v[140:143], v113, v237, v[140:143]
	s_add_u32 s14, s6, 0x260000
	s_addc_u32 s15, s7, 0
	global_load_dword v208, v12, s[14:15] offset:0
	global_load_dword v209, v12, s[14:15] offset:256
	global_load_dword v210, v12, s[14:15] offset:512
	global_load_dword v211, v12, s[14:15] offset:768
	s_waitcnt lgkmcnt(10)
	v_mfma_f32_16x16x4_f32 v[136:139], v114, v238, v[136:139]
	v_mfma_f32_16x16x4_f32 v[140:143], v115, v239, v[140:143]
	s_waitcnt vmcnt(58)
	ds_write_b128 v2, v[76:79] offset:20480
	ds_write_b128 v2, v[80:83] offset:30720
	s_add_u32 s10, s0, 0x2a0000
	s_addc_u32 s11, s1, 0
	global_load_dwordx4 v[76:79], v0, s[10:11]
	global_load_dwordx4 v[80:83], v1, s[10:11]
	s_waitcnt lgkmcnt(11)
	v_mfma_f32_16x16x4_f32 v[136:139], v116, v240, v[136:139]
	v_mfma_f32_16x16x4_f32 v[140:143], v117, v241, v[140:143]
	s_waitcnt lgkmcnt(10)
	v_mfma_f32_16x16x4_f32 v[136:139], v118, v242, v[136:139]
	v_mfma_f32_16x16x4_f32 v[140:143], v119, v243, v[140:143]
	s_add_u32 s16, s8, 0x1c0000
	s_addc_u32 s17, s9, 0
	s_nop 9
	v_add_f32_e32 v136, v136, v140
	v_add_f32_e32 v137, v137, v141
	v_add_f32_e32 v138, v138, v142
	v_add_f32_e32 v139, v139, v143
	ds_write_b32 v13, v136 offset:0
	ds_write_b32 v13, v137 offset:272
	ds_write_b32 v13, v138 offset:544
	ds_write_b32 v13, v139 offset:816
	global_store_dword v12, v136, s[16:17] offset:0
	global_store_dword v12, v137, s[16:17] offset:256
	global_store_dword v12, v138, s[16:17] offset:512
	global_store_dword v12, v139, s[16:17] offset:768
	s_waitcnt lgkmcnt(0)
	s_barrier
	ds_read2_b32 v[104:105], v8 offset0:0 offset1:4
	ds_read2_b32 v[106:107], v8 offset0:8 offset1:12
	ds_read2_b32 v[108:109], v8 offset0:16 offset1:20
	ds_read2_b32 v[110:111], v8 offset0:24 offset1:28
	ds_read2_b32 v[112:113], v8 offset0:32 offset1:36
	ds_read2_b32 v[114:115], v8 offset0:40 offset1:44
	ds_read2_b32 v[116:117], v8 offset0:48 offset1:52
	ds_read2_b32 v[118:119], v8 offset0:56 offset1:60
	s_waitcnt vmcnt(56)
	s_waitcnt lgkmcnt(7)
	v_mfma_f32_16x16x4_f32 v[136:139], v104, v120, v[212:215]
	v_mfma_f32_16x16x4_f32 v[140:143], v105, v121, 0
	ds_read2st64_b32 v[228:229], v11 offset0:0 offset1:5
	ds_read2st64_b32 v[230:231], v11 offset0:10 offset1:15
	s_waitcnt lgkmcnt(8)
	v_mfma_f32_16x16x4_f32 v[136:139], v106, v122, v[136:139]
	v_mfma_f32_16x16x4_f32 v[140:143], v107, v123, v[140:143]
	ds_read2st64_b32 v[232:233], v11 offset0:20 offset1:25
	ds_read2st64_b32 v[234:235], v11 offset0:30 offset1:35
	s_waitcnt lgkmcnt(9)
	v_mfma_f32_16x16x4_f32 v[136:139], v108, v124, v[136:139]
	v_mfma_f32_16x16x4_f32 v[140:143], v109, v125, v[140:143]
	ds_read2st64_b32 v[236:237], v11 offset0:40 offset1:45
	ds_read2st64_b32 v[238:239], v11 offset0:50 offset1:55
	s_waitcnt lgkmcnt(10)
	v_mfma_f32_16x16x4_f32 v[136:139], v110, v126, v[136:139]
	v_mfma_f32_16x16x4_f32 v[140:143], v111, v127, v[140:143]
	ds_read2st64_b32 v[240:241], v11 offset0:60 offset1:65
	ds_read2st64_b32 v[242:243], v11 offset0:70 offset1:75
	s_waitcnt lgkmcnt(11)
	v_mfma_f32_16x16x4_f32 v[136:139], v112, v128, v[136:139]
	v_mfma_f32_16x16x4_f32 v[140:143], v113, v129, v[140:143]
	s_add_u32 s14, s6, 0x280000
	s_addc_u32 s15, s7, 0
	global_load_dword v212, v12, s[14:15] offset:0
	global_load_dword v213, v12, s[14:15] offset:256
	global_load_dword v214, v12, s[14:15] offset:512
	global_load_dword v215, v12, s[14:15] offset:768
	s_waitcnt lgkmcnt(10)
	v_mfma_f32_16x16x4_f32 v[136:139], v114, v130, v[136:139]
	v_mfma_f32_16x16x4_f32 v[140:143], v115, v131, v[140:143]
	s_waitcnt vmcnt(58)
	ds_write_b128 v2, v[84:87] offset:0
	ds_write_b128 v2, v[88:91] offset:10240
	s_add_u32 s10, s0, 0x2c0000
	s_addc_u32 s11, s1, 0
	global_load_dwordx4 v[84:87], v0, s[10:11]
	global_load_dwordx4 v[88:91], v1, s[10:11]
	s_waitcnt lgkmcnt(11)
	v_mfma_f32_16x16x4_f32 v[136:139], v116, v132, v[136:139]
	v_mfma_f32_16x16x4_f32 v[140:143], v117, v133, v[140:143]
	s_waitcnt lgkmcnt(10)
	v_mfma_f32_16x16x4_f32 v[136:139], v118, v134, v[136:139]
	v_mfma_f32_16x16x4_f32 v[140:143], v119, v135, v[140:143]
	s_add_u32 s16, s8, 0x1e0000
	s_addc_u32 s17, s9, 0
	s_nop 9
	v_add_f32_e32 v136, v136, v140
	v_add_f32_e32 v137, v137, v141
	v_add_f32_e32 v138, v138, v142
	v_add_f32_e32 v139, v139, v143
	ds_write_b32 v13, v136 offset:2176
	ds_write_b32 v13, v137 offset:2448
	ds_write_b32 v13, v138 offset:2720
	ds_write_b32 v13, v139 offset:2992
	global_store_dword v12, v136, s[16:17] offset:0
	global_store_dword v12, v137, s[16:17] offset:256
	global_store_dword v12, v138, s[16:17] offset:512
	global_store_dword v12, v139, s[16:17] offset:768
	s_waitcnt lgkmcnt(0)
	s_barrier
; #define LAS __attribute__((address_space(3)))
; __device__ __forceinline__ void scan_combine(LAS unsigned char* lds, CArgsP a) {
;     ...
;     for (int g = 1; g <= GL; ++g) {
;         const bool pf = (g + 2 <= GL);
;         float u3 = 0.f;
;         if (pf) { const f32x4* Pn = (const f32x4*)(PM + (size_t)((g + 2) * 8 + h) * 4096); pa = Pn[tid]; pb = Pn[512 + tid]; u3 = UM[((size_t)((g + 2) * 8 + h) * 64 + v) * 64 + kq]; }
;         asm volatile("s_waitcnt lgkmcnt(0)\n\ts_barrier" ::: "memory");
;         const LAS float* Pg = Pl + (g % 3) * 4096 + kq;
;         float acc0 = u1, acc1 = 0.f, acc2 = 0.f, acc3 = 0.f;
;         const int curi = __builtin_bit_cast(int, cur);
; #pragma unroll
;         for (int k = 0; k < 64; k += 4) {
;             const float s0 = __builtin_bit_cast(float, __builtin_amdgcn_readlane(curi, k)), s1 = __builtin_bit_cast(float, __builtin_amdgcn_readlane(curi, k + 1));
;             const float s2 = __builtin_bit_cast(float, __builtin_amdgcn_readlane(curi, k + 2)), s3 = __builtin_bit_cast(float, __builtin_amdgcn_readlane(curi, k + 3));
;             acc0 += s0 * Pg[(k + 0) * 64]; acc1 += s1 * Pg[(k + 1) * 64]; acc2 += s2 * Pg[(k + 2) * 64]; acc3 += s3 * Pg[(k + 3) * 64];
;         }
;         cur = (acc0 + acc1) + (acc2 + acc3);
;         SS[((size_t)((g + 1) * 8 + h) * 64 + v) * 64 + kq] = cur;
;         if (pf) { LAS float* dst = Pl + ((g + 2) % 3) * 4096; *(LAS f32x4*)(dst + 4 * tid) = pa; *(LAS f32x4*)(dst + 2048 + 4 * tid) = pb; }
;         u1 = u2; u2 = u3;
;     }
	ds_read2_b32 v[104:105], v9 offset0:0 offset1:4
	ds_read2_b32 v[106:107], v9 offset0:8 offset1:12
	ds_read2_b32 v[108:109], v9 offset0:16 offset1:20
	ds_read2_b32 v[110:111], v9 offset0:24 offset1:28
	ds_read2_b32 v[112:113], v9 offset0:32 offset1:36
	ds_read2_b32 v[114:115], v9 offset0:40 offset1:44
	ds_read2_b32 v[116:117], v9 offset0:48 offset1:52
	ds_read2_b32 v[118:119], v9 offset0:56 offset1:60
	s_waitcnt vmcnt(56)
	s_waitcnt lgkmcnt(7)
	v_mfma_f32_16x16x4_f32 v[136:139], v104, v228, v[216:219]
	v_mfma_f32_16x16x4_f32 v[140:143], v105, v229, 0
	ds_read2st64_b32 v[120:121], v10 offset0:0 offset1:5
	ds_read2st64_b32 v[122:123], v10 offset0:10 offset1:15
	s_waitcnt lgkmcnt(8)
	v_mfma_f32_16x16x4_f32 v[136:139], v106, v230, v[136:139]
	v_mfma_f32_16x16x4_f32 v[140:143], v107, v231, v[140:143]
	ds_read2st64_b32 v[124:125], v10 offset0:20 offset1:25
	ds_read2st64_b32 v[126:127], v10 offset0:30 offset1:35
	s_waitcnt lgkmcnt(9)
	v_mfma_f32_16x16x4_f32 v[136:139], v108, v232, v[136:139]
	v_mfma_f32_16x16x4_f32 v[140:143], v109, v233, v[140:143]
	ds_read2st64_b32 v[128:129], v10 offset0:40 offset1:45
	ds_read2st64_b32 v[130:131], v10 offset0:50 offset1:55
	s_waitcnt lgkmcnt(10)
	v_mfma_f32_16x16x4_f32 v[136:139], v110, v234, v[136:139]
	v_mfma_f32_16x16x4_f32 v[140:143], v111, v235, v[140:143]
	ds_read2st64_b32 v[132:133], v10 offset0:60 offset1:65
	ds_read2st64_b32 v[134:135], v10 offset0:70 offset1:75
	s_waitcnt lgkmcnt(11)
	v_mfma_f32_16x16x4_f32 v[136:139], v112, v236, v[136:139]
	v_mfma_f32_16x16x4_f32 v[140:143], v113, v237, v[140:143]
	s_add_u32 s14, s6, 0x2a0000
	s_addc_u32 s15, s7, 0
	global_load_dword v216, v12, s[14:15] offset:0
	global_load_dword v217, v12, s[14:15] offset:256
	global_load_dword v218, v12, s[14:15] offset:512
	global_load_dword v219, v12, s[14:15] offset:768
	s_waitcnt lgkmcnt(10)
	v_mfma_f32_16x16x4_f32 v[136:139], v114, v238, v[136:139]
	v_mfma_f32_16x16x4_f32 v[140:143], v115, v239, v[140:143]
	s_waitcnt vmcnt(58)
	ds_write_b128 v2, v[92:95] offset:20480
	ds_write_b128 v2, v[96:99] offset:30720
	s_add_u32 s10, s0, 0x2e0000
	s_addc_u32 s11, s1, 0
	global_load_dwordx4 v[92:95], v0, s[10:11]
	global_load_dwordx4 v[96:99], v1, s[10:11]
	s_waitcnt lgkmcnt(11)
	v_mfma_f32_16x16x4_f32 v[136:139], v116, v240, v[136:139]
	v_mfma_f32_16x16x4_f32 v[140:143], v117, v241, v[140:143]
	s_waitcnt lgkmcnt(10)
	v_mfma_f32_16x16x4_f32 v[136:139], v118, v242, v[136:139]
	v_mfma_f32_16x16x4_f32 v[140:143], v119, v243, v[140:143]
	s_add_u32 s16, s8, 0x200000
	s_addc_u32 s17, s9, 0
	s_nop 9
	v_add_f32_e32 v136, v136, v140
	v_add_f32_e32 v137, v137, v141
	v_add_f32_e32 v138, v138, v142
	v_add_f32_e32 v139, v139, v143
	ds_write_b32 v13, v136 offset:0
	ds_write_b32 v13, v137 offset:272
	ds_write_b32 v13, v138 offset:544
	ds_write_b32 v13, v139 offset:816
	global_store_dword v12, v136, s[16:17] offset:0
	global_store_dword v12, v137, s[16:17] offset:256
	global_store_dword v12, v138, s[16:17] offset:512
	global_store_dword v12, v139, s[16:17] offset:768
	s_waitcnt lgkmcnt(0)
	s_barrier
	ds_read2_b32 v[104:105], v8 offset0:0 offset1:4
	ds_read2_b32 v[106:107], v8 offset0:8 offset1:12
	ds_read2_b32 v[108:109], v8 offset0:16 offset1:20
	ds_read2_b32 v[110:111], v8 offset0:24 offset1:28
	ds_read2_b32 v[112:113], v8 offset0:32 offset1:36
	ds_read2_b32 v[114:115], v8 offset0:40 offset1:44
	ds_read2_b32 v[116:117], v8 offset0:48 offset1:52
	ds_read2_b32 v[118:119], v8 offset0:56 offset1:60
	s_waitcnt vmcnt(56)
	s_waitcnt lgkmcnt(7)
	v_mfma_f32_16x16x4_f32 v[136:139], v104, v120, v[220:223]
	v_mfma_f32_16x16x4_f32 v[140:143], v105, v121, 0
	ds_read2st64_b32 v[228:229], v11 offset0:0 offset1:5
	ds_read2st64_b32 v[230:231], v11 offset0:10 offset1:15
	s_waitcnt lgkmcnt(8)
	v_mfma_f32_16x16x4_f32 v[136:139], v106, v122, v[136:139]
	v_mfma_f32_16x16x4_f32 v[140:143], v107, v123, v[140:143]
	ds_read2st64_b32 v[232:233], v11 offset0:20 offset1:25
	ds_read2st64_b32 v[234:235], v11 offset0:30 offset1:35
	s_waitcnt lgkmcnt(9)
	v_mfma_f32_16x16x4_f32 v[136:139], v108, v124, v[136:139]
	v_mfma_f32_16x16x4_f32 v[140:143], v109, v125, v[140:143]
	ds_read2st64_b32 v[236:237], v11 offset0:40 offset1:45
	ds_read2st64_b32 v[238:239], v11 offset0:50 offset1:55
	s_waitcnt lgkmcnt(10)
	v_mfma_f32_16x16x4_f32 v[136:139], v110, v126, v[136:139]
	v_mfma_f32_16x16x4_f32 v[140:143], v111, v127, v[140:143]
	ds_read2st64_b32 v[240:241], v11 offset0:60 offset1:65
	ds_read2st64_b32 v[242:243], v11 offset0:70 offset1:75
	s_waitcnt lgkmcnt(11)
	v_mfma_f32_16x16x4_f32 v[136:139], v112, v128, v[136:139]
	v_mfma_f32_16x16x4_f32 v[140:143], v113, v129, v[140:143]
	s_add_u32 s14, s6, 0x2c0000
	s_addc_u32 s15, s7, 0
	global_load_dword v220, v12, s[14:15] offset:0
	global_load_dword v221, v12, s[14:15] offset:256
	global_load_dword v222, v12, s[14:15] offset:512
	global_load_dword v223, v12, s[14:15] offset:768
	s_waitcnt lgkmcnt(10)
	v_mfma_f32_16x16x4_f32 v[136:139], v114, v130, v[136:139]
	v_mfma_f32_16x16x4_f32 v[140:143], v115, v131, v[140:143]
	s_waitcnt vmcnt(58)
	ds_write_b128 v2, v[52:55] offset:0
	ds_write_b128 v2, v[56:59] offset:10240
	s_add_u32 s10, s0, 0x300000
	s_addc_u32 s11, s1, 0
	global_load_dwordx4 v[52:55], v0, s[10:11]
	global_load_dwordx4 v[56:59], v1, s[10:11]
	s_waitcnt lgkmcnt(11)
	v_mfma_f32_16x16x4_f32 v[136:139], v116, v132, v[136:139]
	v_mfma_f32_16x16x4_f32 v[140:143], v117, v133, v[140:143]
	s_waitcnt lgkmcnt(10)
	v_mfma_f32_16x16x4_f32 v[136:139], v118, v134, v[136:139]
	v_mfma_f32_16x16x4_f32 v[140:143], v119, v135, v[140:143]
	s_add_u32 s16, s8, 0x220000
	s_addc_u32 s17, s9, 0
	s_nop 9
	v_add_f32_e32 v136, v136, v140
	v_add_f32_e32 v137, v137, v141
	v_add_f32_e32 v138, v138, v142
	v_add_f32_e32 v139, v139, v143
	ds_write_b32 v13, v136 offset:2176
	ds_write_b32 v13, v137 offset:2448
	ds_write_b32 v13, v138 offset:2720
	ds_write_b32 v13, v139 offset:2992
	global_store_dword v12, v136, s[16:17] offset:0
	global_store_dword v12, v137, s[16:17] offset:256
	global_store_dword v12, v138, s[16:17] offset:512
	global_store_dword v12, v139, s[16:17] offset:768
	s_waitcnt lgkmcnt(0)
	s_barrier
; #define LAS __attribute__((address_space(3)))
; __device__ __forceinline__ void scan_combine(LAS unsigned char* lds, CArgsP a) {
;     ...
;     for (int g = 1; g <= GL; ++g) {
;         const bool pf = (g + 2 <= GL);
;         float u3 = 0.f;
;         if (pf) { const f32x4* Pn = (const f32x4*)(PM + (size_t)((g + 2) * 8 + h) * 4096); pa = Pn[tid]; pb = Pn[512 + tid]; u3 = UM[((size_t)((g + 2) * 8 + h) * 64 + v) * 64 + kq]; }
;         asm volatile("s_waitcnt lgkmcnt(0)\n\ts_barrier" ::: "memory");
;         const LAS float* Pg = Pl + (g % 3) * 4096 + kq;
;         float acc0 = u1, acc1 = 0.f, acc2 = 0.f, acc3 = 0.f;
;         const int curi = __builtin_bit_cast(int, cur);
; #pragma unroll
;         for (int k = 0; k < 64; k += 4) {
;             const float s0 = __builtin_bit_cast(float, __builtin_amdgcn_readlane(curi, k)), s1 = __builtin_bit_cast(float, __builtin_amdgcn_readlane(curi, k + 1));
;             const float s2 = __builtin_bit_cast(float, __builtin_amdgcn_readlane(curi, k + 2)), s3 = __builtin_bit_cast(float, __builtin_amdgcn_readlane(curi, k + 3));
;             acc0 += s0 * Pg[(k + 0) * 64]; acc1 += s1 * Pg[(k + 1) * 64]; acc2 += s2 * Pg[(k + 2) * 64]; acc3 += s3 * Pg[(k + 3) * 64];
;         }
;         cur = (acc0 + acc1) + (acc2 + acc3);
;         SS[((size_t)((g + 1) * 8 + h) * 64 + v) * 64 + kq] = cur;
;         if (pf) { LAS float* dst = Pl + ((g + 2) % 3) * 4096; *(LAS f32x4*)(dst + 4 * tid) = pa; *(LAS f32x4*)(dst + 2048 + 4 * tid) = pb; }
;         u1 = u2; u2 = u3;
	ds_read2_b32 v[104:105], v9 offset0:0 offset1:4
	ds_read2_b32 v[106:107], v9 offset0:8 offset1:12
	ds_read2_b32 v[108:109], v9 offset0:16 offset1:20
	ds_read2_b32 v[110:111], v9 offset0:24 offset1:28
	ds_read2_b32 v[112:113], v9 offset0:32 offset1:36
	ds_read2_b32 v[114:115], v9 offset0:40 offset1:44
	ds_read2_b32 v[116:117], v9 offset0:48 offset1:52
	ds_read2_b32 v[118:119], v9 offset0:56 offset1:60
	s_waitcnt vmcnt(56)
	s_waitcnt lgkmcnt(7)
	v_mfma_f32_16x16x4_f32 v[136:139], v104, v228, v[224:227]
	v_mfma_f32_16x16x4_f32 v[140:143], v105, v229, 0
	ds_read2st64_b32 v[120:121], v10 offset0:0 offset1:5
	ds_read2st64_b32 v[122:123], v10 offset0:10 offset1:15
	s_waitcnt lgkmcnt(8)
	v_mfma_f32_16x16x4_f32 v[136:139], v106, v230, v[136:139]
	v_mfma_f32_16x16x4_f32 v[140:143], v107, v231, v[140:143]
	ds_read2st64_b32 v[124:125], v10 offset0:20 offset1:25
	ds_read2st64_b32 v[126:127], v10 offset0:30 offset1:35
	s_waitcnt lgkmcnt(9)
	v_mfma_f32_16x16x4_f32 v[136:139], v108, v232, v[136:139]
	v_mfma_f32_16x16x4_f32 v[140:143], v109, v233, v[140:143]
	ds_read2st64_b32 v[128:129], v10 offset0:40 offset1:45
	ds_read2st64_b32 v[130:131], v10 offset0:50 offset1:55
	s_waitcnt lgkmcnt(10)
	v_mfma_f32_16x16x4_f32 v[136:139], v110, v234, v[136:139]
	v_mfma_f32_16x16x4_f32 v[140:143], v111, v235, v[140:143]
	ds_read2st64_b32 v[132:133], v10 offset0:60 offset1:65
	ds_read2st64_b32 v[134:135], v10 offset0:70 offset1:75
	s_waitcnt lgkmcnt(11)
	v_mfma_f32_16x16x4_f32 v[136:139], v112, v236, v[136:139]
	v_mfma_f32_16x16x4_f32 v[140:143], v113, v237, v[140:143]
	s_add_u32 s14, s6, 0x2e0000
	s_addc_u32 s15, s7, 0
	global_load_dword v224, v12, s[14:15] offset:0
	global_load_dword v225, v12, s[14:15] offset:256
	global_load_dword v226, v12, s[14:15] offset:512
	global_load_dword v227, v12, s[14:15] offset:768
	s_waitcnt lgkmcnt(10)
	v_mfma_f32_16x16x4_f32 v[136:139], v114, v238, v[136:139]
	v_mfma_f32_16x16x4_f32 v[140:143], v115, v239, v[140:143]
	s_waitcnt vmcnt(58)
	ds_write_b128 v2, v[60:63] offset:20480
	ds_write_b128 v2, v[64:67] offset:30720
	s_add_u32 s10, s0, 0x320000
	s_addc_u32 s11, s1, 0
	global_load_dwordx4 v[60:63], v0, s[10:11]
	global_load_dwordx4 v[64:67], v1, s[10:11]
	s_waitcnt lgkmcnt(11)
	v_mfma_f32_16x16x4_f32 v[136:139], v116, v240, v[136:139]
	v_mfma_f32_16x16x4_f32 v[140:143], v117, v241, v[140:143]
	s_waitcnt lgkmcnt(10)
	v_mfma_f32_16x16x4_f32 v[136:139], v118, v242, v[136:139]
	v_mfma_f32_16x16x4_f32 v[140:143], v119, v243, v[140:143]
	s_add_u32 s16, s8, 0x240000
	s_addc_u32 s17, s9, 0
	s_nop 9
	v_add_f32_e32 v136, v136, v140
	v_add_f32_e32 v137, v137, v141
	v_add_f32_e32 v138, v138, v142
	v_add_f32_e32 v139, v139, v143
	ds_write_b32 v13, v136 offset:0
	ds_write_b32 v13, v137 offset:272
	ds_write_b32 v13, v138 offset:544
	ds_write_b32 v13, v139 offset:816
	global_store_dword v12, v136, s[16:17] offset:0
	global_store_dword v12, v137, s[16:17] offset:256
	global_store_dword v12, v138, s[16:17] offset:512
	global_store_dword v12, v139, s[16:17] offset:768
	s_waitcnt lgkmcnt(0)
	s_barrier
	ds_read2_b32 v[104:105], v8 offset0:0 offset1:4
	ds_read2_b32 v[106:107], v8 offset0:8 offset1:12
	ds_read2_b32 v[108:109], v8 offset0:16 offset1:20
	ds_read2_b32 v[110:111], v8 offset0:24 offset1:28
	ds_read2_b32 v[112:113], v8 offset0:32 offset1:36
	ds_read2_b32 v[114:115], v8 offset0:40 offset1:44
	ds_read2_b32 v[116:117], v8 offset0:48 offset1:52
	ds_read2_b32 v[118:119], v8 offset0:56 offset1:60
	s_waitcnt vmcnt(56)
	s_waitcnt lgkmcnt(7)
	v_mfma_f32_16x16x4_f32 v[136:139], v104, v120, v[204:207]
	v_mfma_f32_16x16x4_f32 v[140:143], v105, v121, 0
	ds_read2st64_b32 v[228:229], v11 offset0:0 offset1:5
	ds_read2st64_b32 v[230:231], v11 offset0:10 offset1:15
	s_waitcnt lgkmcnt(8)
	v_mfma_f32_16x16x4_f32 v[136:139], v106, v122, v[136:139]
	v_mfma_f32_16x16x4_f32 v[140:143], v107, v123, v[140:143]
	ds_read2st64_b32 v[232:233], v11 offset0:20 offset1:25
	ds_read2st64_b32 v[234:235], v11 offset0:30 offset1:35
	s_waitcnt lgkmcnt(9)
	v_mfma_f32_16x16x4_f32 v[136:139], v108, v124, v[136:139]
	v_mfma_f32_16x16x4_f32 v[140:143], v109, v125, v[140:143]
	ds_read2st64_b32 v[236:237], v11 offset0:40 offset1:45
	ds_read2st64_b32 v[238:239], v11 offset0:50 offset1:55
	s_waitcnt lgkmcnt(10)
	v_mfma_f32_16x16x4_f32 v[136:139], v110, v126, v[136:139]
	v_mfma_f32_16x16x4_f32 v[140:143], v111, v127, v[140:143]
	ds_read2st64_b32 v[240:241], v11 offset0:60 offset1:65
	ds_read2st64_b32 v[242:243], v11 offset0:70 offset1:75
	s_waitcnt lgkmcnt(11)
	v_mfma_f32_16x16x4_f32 v[136:139], v112, v128, v[136:139]
	v_mfma_f32_16x16x4_f32 v[140:143], v113, v129, v[140:143]
	s_add_u32 s14, s6, 0x300000
	s_addc_u32 s15, s7, 0
	global_load_dword v204, v12, s[14:15] offset:0
	global_load_dword v205, v12, s[14:15] offset:256
	global_load_dword v206, v12, s[14:15] offset:512
	global_load_dword v207, v12, s[14:15] offset:768
	s_waitcnt lgkmcnt(10)
	v_mfma_f32_16x16x4_f32 v[136:139], v114, v130, v[136:139]
	v_mfma_f32_16x16x4_f32 v[140:143], v115, v131, v[140:143]
	s_waitcnt vmcnt(58)
	ds_write_b128 v2, v[68:71] offset:0
	ds_write_b128 v2, v[72:75] offset:10240
	s_add_u32 s10, s0, 0x340000
	s_addc_u32 s11, s1, 0
	global_load_dwordx4 v[68:71], v0, s[10:11]
	global_load_dwordx4 v[72:75], v1, s[10:11]
	s_waitcnt lgkmcnt(11)
	v_mfma_f32_16x16x4_f32 v[136:139], v116, v132, v[136:139]
	v_mfma_f32_16x16x4_f32 v[140:143], v117, v133, v[140:143]
	s_waitcnt lgkmcnt(10)
	v_mfma_f32_16x16x4_f32 v[136:139], v118, v134, v[136:139]
	v_mfma_f32_16x16x4_f32 v[140:143], v119, v135, v[140:143]
	s_add_u32 s16, s8, 0x260000
	s_addc_u32 s17, s9, 0
	s_nop 9
	v_add_f32_e32 v136, v136, v140
	v_add_f32_e32 v137, v137, v141
	v_add_f32_e32 v138, v138, v142
	v_add_f32_e32 v139, v139, v143
	ds_write_b32 v13, v136 offset:2176
	ds_write_b32 v13, v137 offset:2448
	ds_write_b32 v13, v138 offset:2720
	ds_write_b32 v13, v139 offset:2992
	global_store_dword v12, v136, s[16:17] offset:0
	global_store_dword v12, v137, s[16:17] offset:256
	global_store_dword v12, v138, s[16:17] offset:512
	global_store_dword v12, v139, s[16:17] offset:768
	s_waitcnt lgkmcnt(0)
	s_barrier
; #define LAS __attribute__((address_space(3)))
; __device__ __forceinline__ void scan_combine(LAS unsigned char* lds, CArgsP a) {
;     ...
;     for (int g = 1; g <= GL; ++g) {
;         const bool pf = (g + 2 <= GL);
;         float u3 = 0.f;
;         if (pf) { const f32x4* Pn = (const f32x4*)(PM + (size_t)((g + 2) * 8 + h) * 4096); pa = Pn[tid]; pb = Pn[512 + tid]; u3 = UM[((size_t)((g + 2) * 8 + h) * 64 + v) * 64 + kq]; }
;         asm volatile("s_waitcnt lgkmcnt(0)\n\ts_barrier" ::: "memory");
;         const LAS float* Pg = Pl + (g % 3) * 4096 + kq;
;         float acc0 = u1, acc1 = 0.f, acc2 = 0.f, acc3 = 0.f;
;         const int curi = __builtin_bit_cast(int, cur);
; #pragma unroll
;         for (int k = 0; k < 64; k += 4) {
;             const float s0 = __builtin_bit_cast(float, __builtin_amdgcn_readlane(curi, k)), s1 = __builtin_bit_cast(float, __builtin_amdgcn_readlane(curi, k + 1));
;             const float s2 = __builtin_bit_cast(float, __builtin_amdgcn_readlane(curi, k + 2)), s3 = __builtin_bit_cast(float, __builtin_amdgcn_readlane(curi, k + 3));
;             acc0 += s0 * Pg[(k + 0) * 64]; acc1 += s1 * Pg[(k + 1) * 64]; acc2 += s2 * Pg[(k + 2) * 64]; acc3 += s3 * Pg[(k + 3) * 64];
;         }
;         cur = (acc0 + acc1) + (acc2 + acc3);
;         SS[((size_t)((g + 1) * 8 + h) * 64 + v) * 64 + kq] = cur;
;         if (pf) { LAS float* dst = Pl + ((g + 2) % 3) * 4096; *(LAS f32x4*)(dst + 4 * tid) = pa; *(LAS f32x4*)(dst + 2048 + 4 * tid) = pb; }
;         u1 = u2; u2 = u3;
	ds_read2_b32 v[104:105], v9 offset0:0 offset1:4
	ds_read2_b32 v[106:107], v9 offset0:8 offset1:12
	ds_read2_b32 v[108:109], v9 offset0:16 offset1:20
	ds_read2_b32 v[110:111], v9 offset0:24 offset1:28
	ds_read2_b32 v[112:113], v9 offset0:32 offset1:36
	ds_read2_b32 v[114:115], v9 offset0:40 offset1:44
	ds_read2_b32 v[116:117], v9 offset0:48 offset1:52
	ds_read2_b32 v[118:119], v9 offset0:56 offset1:60
	s_waitcnt vmcnt(56)
	s_waitcnt lgkmcnt(7)
	v_mfma_f32_16x16x4_f32 v[136:139], v104, v228, v[208:211]
	v_mfma_f32_16x16x4_f32 v[140:143], v105, v229, 0
	ds_read2st64_b32 v[120:121], v10 offset0:0 offset1:5
	ds_read2st64_b32 v[122:123], v10 offset0:10 offset1:15
	s_waitcnt lgkmcnt(8)
	v_mfma_f32_16x16x4_f32 v[136:139], v106, v230, v[136:139]
	v_mfma_f32_16x16x4_f32 v[140:143], v107, v231, v[140:143]
	ds_read2st64_b32 v[124:125], v10 offset0:20 offset1:25
	ds_read2st64_b32 v[126:127], v10 offset0:30 offset1:35
	s_waitcnt lgkmcnt(9)
	v_mfma_f32_16x16x4_f32 v[136:139], v108, v232, v[136:139]
	v_mfma_f32_16x16x4_f32 v[140:143], v109, v233, v[140:143]
	ds_read2st64_b32 v[128:129], v10 offset0:40 offset1:45
	ds_read2st64_b32 v[130:131], v10 offset0:50 offset1:55
	s_waitcnt lgkmcnt(10)
	v_mfma_f32_16x16x4_f32 v[136:139], v110, v234, v[136:139]
	v_mfma_f32_16x16x4_f32 v[140:143], v111, v235, v[140:143]
	ds_read2st64_b32 v[132:133], v10 offset0:60 offset1:65
	ds_read2st64_b32 v[134:135], v10 offset0:70 offset1:75
	s_waitcnt lgkmcnt(11)
	v_mfma_f32_16x16x4_f32 v[136:139], v112, v236, v[136:139]
	v_mfma_f32_16x16x4_f32 v[140:143], v113, v237, v[140:143]
	s_add_u32 s14, s6, 0x320000
	s_addc_u32 s15, s7, 0
	global_load_dword v208, v12, s[14:15] offset:0
	global_load_dword v209, v12, s[14:15] offset:256
	global_load_dword v210, v12, s[14:15] offset:512
	global_load_dword v211, v12, s[14:15] offset:768
	s_waitcnt lgkmcnt(10)
	v_mfma_f32_16x16x4_f32 v[136:139], v114, v238, v[136:139]
	v_mfma_f32_16x16x4_f32 v[140:143], v115, v239, v[140:143]
	s_waitcnt vmcnt(58)
	ds_write_b128 v2, v[76:79] offset:20480
	ds_write_b128 v2, v[80:83] offset:30720
	s_add_u32 s10, s0, 0x360000
	s_addc_u32 s11, s1, 0
	global_load_dwordx4 v[76:79], v0, s[10:11]
	global_load_dwordx4 v[80:83], v1, s[10:11]
	s_waitcnt lgkmcnt(11)
	v_mfma_f32_16x16x4_f32 v[136:139], v116, v240, v[136:139]
	v_mfma_f32_16x16x4_f32 v[140:143], v117, v241, v[140:143]
	s_waitcnt lgkmcnt(10)
	v_mfma_f32_16x16x4_f32 v[136:139], v118, v242, v[136:139]
	v_mfma_f32_16x16x4_f32 v[140:143], v119, v243, v[140:143]
	s_add_u32 s16, s8, 0x280000
	s_addc_u32 s17, s9, 0
	s_nop 9
	v_add_f32_e32 v136, v136, v140
	v_add_f32_e32 v137, v137, v141
	v_add_f32_e32 v138, v138, v142
	v_add_f32_e32 v139, v139, v143
	ds_write_b32 v13, v136 offset:0
	ds_write_b32 v13, v137 offset:272
	ds_write_b32 v13, v138 offset:544
	ds_write_b32 v13, v139 offset:816
	global_store_dword v12, v136, s[16:17] offset:0
	global_store_dword v12, v137, s[16:17] offset:256
	global_store_dword v12, v138, s[16:17] offset:512
	global_store_dword v12, v139, s[16:17] offset:768
	s_waitcnt lgkmcnt(0)
	s_barrier
	ds_read2_b32 v[104:105], v8 offset0:0 offset1:4
	ds_read2_b32 v[106:107], v8 offset0:8 offset1:12
	ds_read2_b32 v[108:109], v8 offset0:16 offset1:20
	ds_read2_b32 v[110:111], v8 offset0:24 offset1:28
	ds_read2_b32 v[112:113], v8 offset0:32 offset1:36
	ds_read2_b32 v[114:115], v8 offset0:40 offset1:44
	ds_read2_b32 v[116:117], v8 offset0:48 offset1:52
	ds_read2_b32 v[118:119], v8 offset0:56 offset1:60
	s_waitcnt vmcnt(56)
	s_waitcnt lgkmcnt(7)
	v_mfma_f32_16x16x4_f32 v[136:139], v104, v120, v[212:215]
	v_mfma_f32_16x16x4_f32 v[140:143], v105, v121, 0
	ds_read2st64_b32 v[228:229], v11 offset0:0 offset1:5
	ds_read2st64_b32 v[230:231], v11 offset0:10 offset1:15
	s_waitcnt lgkmcnt(8)
	v_mfma_f32_16x16x4_f32 v[136:139], v106, v122, v[136:139]
	v_mfma_f32_16x16x4_f32 v[140:143], v107, v123, v[140:143]
	ds_read2st64_b32 v[232:233], v11 offset0:20 offset1:25
	ds_read2st64_b32 v[234:235], v11 offset0:30 offset1:35
	s_waitcnt lgkmcnt(9)
	v_mfma_f32_16x16x4_f32 v[136:139], v108, v124, v[136:139]
	v_mfma_f32_16x16x4_f32 v[140:143], v109, v125, v[140:143]
	ds_read2st64_b32 v[236:237], v11 offset0:40 offset1:45
	ds_read2st64_b32 v[238:239], v11 offset0:50 offset1:55
	s_waitcnt lgkmcnt(10)
	v_mfma_f32_16x16x4_f32 v[136:139], v110, v126, v[136:139]
	v_mfma_f32_16x16x4_f32 v[140:143], v111, v127, v[140:143]
	ds_read2st64_b32 v[240:241], v11 offset0:60 offset1:65
	ds_read2st64_b32 v[242:243], v11 offset0:70 offset1:75
	s_waitcnt lgkmcnt(11)
	v_mfma_f32_16x16x4_f32 v[136:139], v112, v128, v[136:139]
	v_mfma_f32_16x16x4_f32 v[140:143], v113, v129, v[140:143]
	s_add_u32 s14, s6, 0x340000
	s_addc_u32 s15, s7, 0
	global_load_dword v212, v12, s[14:15] offset:0
	global_load_dword v213, v12, s[14:15] offset:256
	global_load_dword v214, v12, s[14:15] offset:512
	global_load_dword v215, v12, s[14:15] offset:768
	s_waitcnt lgkmcnt(10)
	v_mfma_f32_16x16x4_f32 v[136:139], v114, v130, v[136:139]
	v_mfma_f32_16x16x4_f32 v[140:143], v115, v131, v[140:143]
	s_waitcnt vmcnt(58)
	ds_write_b128 v2, v[84:87] offset:0
	ds_write_b128 v2, v[88:91] offset:10240
	s_add_u32 s10, s0, 0x380000
	s_addc_u32 s11, s1, 0
	global_load_dwordx4 v[84:87], v0, s[10:11]
	global_load_dwordx4 v[88:91], v1, s[10:11]
	s_waitcnt lgkmcnt(11)
	v_mfma_f32_16x16x4_f32 v[136:139], v116, v132, v[136:139]
	v_mfma_f32_16x16x4_f32 v[140:143], v117, v133, v[140:143]
	s_waitcnt lgkmcnt(10)
	v_mfma_f32_16x16x4_f32 v[136:139], v118, v134, v[136:139]
	v_mfma_f32_16x16x4_f32 v[140:143], v119, v135, v[140:143]
	s_add_u32 s16, s8, 0x2a0000
	s_addc_u32 s17, s9, 0
	s_nop 9
	v_add_f32_e32 v136, v136, v140
	v_add_f32_e32 v137, v137, v141
	v_add_f32_e32 v138, v138, v142
	v_add_f32_e32 v139, v139, v143
	ds_write_b32 v13, v136 offset:2176
	ds_write_b32 v13, v137 offset:2448
	ds_write_b32 v13, v138 offset:2720
	ds_write_b32 v13, v139 offset:2992
	global_store_dword v12, v136, s[16:17] offset:0
	global_store_dword v12, v137, s[16:17] offset:256
	global_store_dword v12, v138, s[16:17] offset:512
	global_store_dword v12, v139, s[16:17] offset:768
	s_waitcnt lgkmcnt(0)
	s_barrier
; #define LAS __attribute__((address_space(3)))
; __device__ __forceinline__ void scan_combine(LAS unsigned char* lds, CArgsP a) {
;     ...
;     for (int g = 1; g <= GL; ++g) {
;         const bool pf = (g + 2 <= GL);
;         float u3 = 0.f;
;         if (pf) { const f32x4* Pn = (const f32x4*)(PM + (size_t)((g + 2) * 8 + h) * 4096); pa = Pn[tid]; pb = Pn[512 + tid]; u3 = UM[((size_t)((g + 2) * 8 + h) * 64 + v) * 64 + kq]; }
;         asm volatile("s_waitcnt lgkmcnt(0)\n\ts_barrier" ::: "memory");
;         const LAS float* Pg = Pl + (g % 3) * 4096 + kq;
;         float acc0 = u1, acc1 = 0.f, acc2 = 0.f, acc3 = 0.f;
;         const int curi = __builtin_bit_cast(int, cur);
; #pragma unroll
;         for (int k = 0; k < 64; k += 4) {
;             const float s0 = __builtin_bit_cast(float, __builtin_amdgcn_readlane(curi, k)), s1 = __builtin_bit_cast(float, __builtin_amdgcn_readlane(curi, k + 1));
;             const float s2 = __builtin_bit_cast(float, __builtin_amdgcn_readlane(curi, k + 2)), s3 = __builtin_bit_cast(float, __builtin_amdgcn_readlane(curi, k + 3));
;             acc0 += s0 * Pg[(k + 0) * 64]; acc1 += s1 * Pg[(k + 1) * 64]; acc2 += s2 * Pg[(k + 2) * 64]; acc3 += s3 * Pg[(k + 3) * 64];
;         }
;         cur = (acc0 + acc1) + (acc2 + acc3);
;         SS[((size_t)((g + 1) * 8 + h) * 64 + v) * 64 + kq] = cur;
;         if (pf) { LAS float* dst = Pl + ((g + 2) % 3) * 4096; *(LAS f32x4*)(dst + 4 * tid) = pa; *(LAS f32x4*)(dst + 2048 + 4 * tid) = pb; }
;         u1 = u2; u2 = u3;
	ds_read2_b32 v[104:105], v9 offset0:0 offset1:4
	ds_read2_b32 v[106:107], v9 offset0:8 offset1:12
	ds_read2_b32 v[108:109], v9 offset0:16 offset1:20
	ds_read2_b32 v[110:111], v9 offset0:24 offset1:28
	ds_read2_b32 v[112:113], v9 offset0:32 offset1:36
	ds_read2_b32 v[114:115], v9 offset0:40 offset1:44
	ds_read2_b32 v[116:117], v9 offset0:48 offset1:52
	ds_read2_b32 v[118:119], v9 offset0:56 offset1:60
	s_waitcnt vmcnt(56)
	s_waitcnt lgkmcnt(7)
	v_mfma_f32_16x16x4_f32 v[136:139], v104, v228, v[216:219]
	v_mfma_f32_16x16x4_f32 v[140:143], v105, v229, 0
	ds_read2st64_b32 v[120:121], v10 offset0:0 offset1:5
	ds_read2st64_b32 v[122:123], v10 offset0:10 offset1:15
	s_waitcnt lgkmcnt(8)
	v_mfma_f32_16x16x4_f32 v[136:139], v106, v230, v[136:139]
	v_mfma_f32_16x16x4_f32 v[140:143], v107, v231, v[140:143]
	ds_read2st64_b32 v[124:125], v10 offset0:20 offset1:25
	ds_read2st64_b32 v[126:127], v10 offset0:30 offset1:35
	s_waitcnt lgkmcnt(9)
	v_mfma_f32_16x16x4_f32 v[136:139], v108, v232, v[136:139]
	v_mfma_f32_16x16x4_f32 v[140:143], v109, v233, v[140:143]
	ds_read2st64_b32 v[128:129], v10 offset0:40 offset1:45
	ds_read2st64_b32 v[130:131], v10 offset0:50 offset1:55
	s_waitcnt lgkmcnt(10)
	v_mfma_f32_16x16x4_f32 v[136:139], v110, v234, v[136:139]
	v_mfma_f32_16x16x4_f32 v[140:143], v111, v235, v[140:143]
	ds_read2st64_b32 v[132:133], v10 offset0:60 offset1:65
	ds_read2st64_b32 v[134:135], v10 offset0:70 offset1:75
	s_waitcnt lgkmcnt(11)
	v_mfma_f32_16x16x4_f32 v[136:139], v112, v236, v[136:139]
	v_mfma_f32_16x16x4_f32 v[140:143], v113, v237, v[140:143]
	s_add_u32 s14, s6, 0x360000
	s_addc_u32 s15, s7, 0
	global_load_dword v216, v12, s[14:15] offset:0
	global_load_dword v217, v12, s[14:15] offset:256
	global_load_dword v218, v12, s[14:15] offset:512
	global_load_dword v219, v12, s[14:15] offset:768
	s_waitcnt lgkmcnt(10)
	v_mfma_f32_16x16x4_f32 v[136:139], v114, v238, v[136:139]
	v_mfma_f32_16x16x4_f32 v[140:143], v115, v239, v[140:143]
	s_waitcnt vmcnt(58)
	ds_write_b128 v2, v[92:95] offset:20480
	ds_write_b128 v2, v[96:99] offset:30720
	s_add_u32 s10, s0, 0x3a0000
	s_addc_u32 s11, s1, 0
	global_load_dwordx4 v[92:95], v0, s[10:11]
	global_load_dwordx4 v[96:99], v1, s[10:11]
	s_waitcnt lgkmcnt(11)
	v_mfma_f32_16x16x4_f32 v[136:139], v116, v240, v[136:139]
	v_mfma_f32_16x16x4_f32 v[140:143], v117, v241, v[140:143]
	s_waitcnt lgkmcnt(10)
	v_mfma_f32_16x16x4_f32 v[136:139], v118, v242, v[136:139]
	v_mfma_f32_16x16x4_f32 v[140:143], v119, v243, v[140:143]
	s_add_u32 s16, s8, 0x2c0000
	s_addc_u32 s17, s9, 0
	s_nop 9
	v_add_f32_e32 v136, v136, v140
	v_add_f32_e32 v137, v137, v141
	v_add_f32_e32 v138, v138, v142
	v_add_f32_e32 v139, v139, v143
	ds_write_b32 v13, v136 offset:0
	ds_write_b32 v13, v137 offset:272
	ds_write_b32 v13, v138 offset:544
	ds_write_b32 v13, v139 offset:816
	global_store_dword v12, v136, s[16:17] offset:0
	global_store_dword v12, v137, s[16:17] offset:256
	global_store_dword v12, v138, s[16:17] offset:512
	global_store_dword v12, v139, s[16:17] offset:768
	s_waitcnt lgkmcnt(0)
	s_barrier
	ds_read2_b32 v[104:105], v8 offset0:0 offset1:4
	ds_read2_b32 v[106:107], v8 offset0:8 offset1:12
	ds_read2_b32 v[108:109], v8 offset0:16 offset1:20
	ds_read2_b32 v[110:111], v8 offset0:24 offset1:28
	ds_read2_b32 v[112:113], v8 offset0:32 offset1:36
	ds_read2_b32 v[114:115], v8 offset0:40 offset1:44
	ds_read2_b32 v[116:117], v8 offset0:48 offset1:52
	ds_read2_b32 v[118:119], v8 offset0:56 offset1:60
	s_waitcnt vmcnt(56)
	s_waitcnt lgkmcnt(7)
	v_mfma_f32_16x16x4_f32 v[136:139], v104, v120, v[220:223]
	v_mfma_f32_16x16x4_f32 v[140:143], v105, v121, 0
	ds_read2st64_b32 v[228:229], v11 offset0:0 offset1:5
	ds_read2st64_b32 v[230:231], v11 offset0:10 offset1:15
	s_waitcnt lgkmcnt(8)
	v_mfma_f32_16x16x4_f32 v[136:139], v106, v122, v[136:139]
	v_mfma_f32_16x16x4_f32 v[140:143], v107, v123, v[140:143]
	ds_read2st64_b32 v[232:233], v11 offset0:20 offset1:25
	ds_read2st64_b32 v[234:235], v11 offset0:30 offset1:35
	s_waitcnt lgkmcnt(9)
	v_mfma_f32_16x16x4_f32 v[136:139], v108, v124, v[136:139]
	v_mfma_f32_16x16x4_f32 v[140:143], v109, v125, v[140:143]
	ds_read2st64_b32 v[236:237], v11 offset0:40 offset1:45
	ds_read2st64_b32 v[238:239], v11 offset0:50 offset1:55
	s_waitcnt lgkmcnt(10)
	v_mfma_f32_16x16x4_f32 v[136:139], v110, v126, v[136:139]
	v_mfma_f32_16x16x4_f32 v[140:143], v111, v127, v[140:143]
	ds_read2st64_b32 v[240:241], v11 offset0:60 offset1:65
	ds_read2st64_b32 v[242:243], v11 offset0:70 offset1:75
	s_waitcnt lgkmcnt(11)
	v_mfma_f32_16x16x4_f32 v[136:139], v112, v128, v[136:139]
	v_mfma_f32_16x16x4_f32 v[140:143], v113, v129, v[140:143]
	s_add_u32 s14, s6, 0x380000
	s_addc_u32 s15, s7, 0
	global_load_dword v220, v12, s[14:15] offset:0
	global_load_dword v221, v12, s[14:15] offset:256
	global_load_dword v222, v12, s[14:15] offset:512
	global_load_dword v223, v12, s[14:15] offset:768
	s_waitcnt lgkmcnt(10)
	v_mfma_f32_16x16x4_f32 v[136:139], v114, v130, v[136:139]
	v_mfma_f32_16x16x4_f32 v[140:143], v115, v131, v[140:143]
	s_waitcnt vmcnt(58)
	ds_write_b128 v2, v[52:55] offset:0
	ds_write_b128 v2, v[56:59] offset:10240
	s_add_u32 s10, s0, 0x3c0000
	s_addc_u32 s11, s1, 0
	global_load_dwordx4 v[52:55], v0, s[10:11]
	global_load_dwordx4 v[56:59], v1, s[10:11]
	s_waitcnt lgkmcnt(11)
	v_mfma_f32_16x16x4_f32 v[136:139], v116, v132, v[136:139]
	v_mfma_f32_16x16x4_f32 v[140:143], v117, v133, v[140:143]
	s_waitcnt lgkmcnt(10)
	v_mfma_f32_16x16x4_f32 v[136:139], v118, v134, v[136:139]
	v_mfma_f32_16x16x4_f32 v[140:143], v119, v135, v[140:143]
	s_add_u32 s16, s8, 0x2e0000
	s_addc_u32 s17, s9, 0
	s_nop 9
	v_add_f32_e32 v136, v136, v140
	v_add_f32_e32 v137, v137, v141
	v_add_f32_e32 v138, v138, v142
	v_add_f32_e32 v139, v139, v143
	ds_write_b32 v13, v136 offset:2176
	ds_write_b32 v13, v137 offset:2448
	ds_write_b32 v13, v138 offset:2720
	ds_write_b32 v13, v139 offset:2992
	global_store_dword v12, v136, s[16:17] offset:0
	global_store_dword v12, v137, s[16:17] offset:256
	global_store_dword v12, v138, s[16:17] offset:512
	global_store_dword v12, v139, s[16:17] offset:768
	s_waitcnt lgkmcnt(0)
	s_barrier
; #define LAS __attribute__((address_space(3)))
; __device__ __forceinline__ void scan_combine(LAS unsigned char* lds, CArgsP a) {
;     ...
;     for (int g = 1; g <= GL; ++g) {
;         const bool pf = (g + 2 <= GL);
;         float u3 = 0.f;
;         if (pf) { const f32x4* Pn = (const f32x4*)(PM + (size_t)((g + 2) * 8 + h) * 4096); pa = Pn[tid]; pb = Pn[512 + tid]; u3 = UM[((size_t)((g + 2) * 8 + h) * 64 + v) * 64 + kq]; }
;         asm volatile("s_waitcnt lgkmcnt(0)\n\ts_barrier" ::: "memory");
;         const LAS float* Pg = Pl + (g % 3) * 4096 + kq;
;         float acc0 = u1, acc1 = 0.f, acc2 = 0.f, acc3 = 0.f;
;         const int curi = __builtin_bit_cast(int, cur);
; #pragma unroll
;         for (int k = 0; k < 64; k += 4) {
;             const float s0 = __builtin_bit_cast(float, __builtin_amdgcn_readlane(curi, k)), s1 = __builtin_bit_cast(float, __builtin_amdgcn_readlane(curi, k + 1));
;             const float s2 = __builtin_bit_cast(float, __builtin_amdgcn_readlane(curi, k + 2)), s3 = __builtin_bit_cast(float, __builtin_amdgcn_readlane(curi, k + 3));
;             acc0 += s0 * Pg[(k + 0) * 64]; acc1 += s1 * Pg[(k + 1) * 64]; acc2 += s2 * Pg[(k + 2) * 64]; acc3 += s3 * Pg[(k + 3) * 64];
;         }
;         cur = (acc0 + acc1) + (acc2 + acc3);
;         SS[((size_t)((g + 1) * 8 + h) * 64 + v) * 64 + kq] = cur;
;         if (pf) { LAS float* dst = Pl + ((g + 2) % 3) * 4096; *(LAS f32x4*)(dst + 4 * tid) = pa; *(LAS f32x4*)(dst + 2048 + 4 * tid) = pb; }
;         u1 = u2; u2 = u3;
	ds_read2_b32 v[104:105], v9 offset0:0 offset1:4
	ds_read2_b32 v[106:107], v9 offset0:8 offset1:12
	ds_read2_b32 v[108:109], v9 offset0:16 offset1:20
	ds_read2_b32 v[110:111], v9 offset0:24 offset1:28
	ds_read2_b32 v[112:113], v9 offset0:32 offset1:36
	ds_read2_b32 v[114:115], v9 offset0:40 offset1:44
	ds_read2_b32 v[116:117], v9 offset0:48 offset1:52
	ds_read2_b32 v[118:119], v9 offset0:56 offset1:60
	s_waitcnt vmcnt(56)
	s_waitcnt lgkmcnt(7)
	v_mfma_f32_16x16x4_f32 v[136:139], v104, v228, v[224:227]
	v_mfma_f32_16x16x4_f32 v[140:143], v105, v229, 0
	ds_read2st64_b32 v[120:121], v10 offset0:0 offset1:5
	ds_read2st64_b32 v[122:123], v10 offset0:10 offset1:15
	s_waitcnt lgkmcnt(8)
	v_mfma_f32_16x16x4_f32 v[136:139], v106, v230, v[136:139]
	v_mfma_f32_16x16x4_f32 v[140:143], v107, v231, v[140:143]
	ds_read2st64_b32 v[124:125], v10 offset0:20 offset1:25
	ds_read2st64_b32 v[126:127], v10 offset0:30 offset1:35
	s_waitcnt lgkmcnt(9)
	v_mfma_f32_16x16x4_f32 v[136:139], v108, v232, v[136:139]
	v_mfma_f32_16x16x4_f32 v[140:143], v109, v233, v[140:143]
	ds_read2st64_b32 v[128:129], v10 offset0:40 offset1:45
	ds_read2st64_b32 v[130:131], v10 offset0:50 offset1:55
	s_waitcnt lgkmcnt(10)
	v_mfma_f32_16x16x4_f32 v[136:139], v110, v234, v[136:139]
	v_mfma_f32_16x16x4_f32 v[140:143], v111, v235, v[140:143]
	ds_read2st64_b32 v[132:133], v10 offset0:60 offset1:65
	ds_read2st64_b32 v[134:135], v10 offset0:70 offset1:75
	s_waitcnt lgkmcnt(11)
	v_mfma_f32_16x16x4_f32 v[136:139], v112, v236, v[136:139]
	v_mfma_f32_16x16x4_f32 v[140:143], v113, v237, v[140:143]
	s_add_u32 s14, s6, 0x3a0000
	s_addc_u32 s15, s7, 0
	global_load_dword v224, v12, s[14:15] offset:0
	global_load_dword v225, v12, s[14:15] offset:256
	global_load_dword v226, v12, s[14:15] offset:512
	global_load_dword v227, v12, s[14:15] offset:768
	s_waitcnt lgkmcnt(10)
	v_mfma_f32_16x16x4_f32 v[136:139], v114, v238, v[136:139]
	v_mfma_f32_16x16x4_f32 v[140:143], v115, v239, v[140:143]
	s_waitcnt vmcnt(58)
	ds_write_b128 v2, v[60:63] offset:20480
	ds_write_b128 v2, v[64:67] offset:30720
	s_add_u32 s10, s0, 0x3e0000
	s_addc_u32 s11, s1, 0
	global_load_dwordx4 v[60:63], v0, s[10:11]
	global_load_dwordx4 v[64:67], v1, s[10:11]
	s_waitcnt lgkmcnt(11)
	v_mfma_f32_16x16x4_f32 v[136:139], v116, v240, v[136:139]
	v_mfma_f32_16x16x4_f32 v[140:143], v117, v241, v[140:143]
	s_waitcnt lgkmcnt(10)
	v_mfma_f32_16x16x4_f32 v[136:139], v118, v242, v[136:139]
	v_mfma_f32_16x16x4_f32 v[140:143], v119, v243, v[140:143]
	s_add_u32 s16, s8, 0x300000
	s_addc_u32 s17, s9, 0
	s_nop 9
	v_add_f32_e32 v136, v136, v140
	v_add_f32_e32 v137, v137, v141
	v_add_f32_e32 v138, v138, v142
	v_add_f32_e32 v139, v139, v143
	ds_write_b32 v13, v136 offset:0
	ds_write_b32 v13, v137 offset:272
	ds_write_b32 v13, v138 offset:544
	ds_write_b32 v13, v139 offset:816
	global_store_dword v12, v136, s[16:17] offset:0
	global_store_dword v12, v137, s[16:17] offset:256
	global_store_dword v12, v138, s[16:17] offset:512
	global_store_dword v12, v139, s[16:17] offset:768
	s_waitcnt lgkmcnt(0)
	s_barrier
	ds_read2_b32 v[104:105], v8 offset0:0 offset1:4
	ds_read2_b32 v[106:107], v8 offset0:8 offset1:12
	ds_read2_b32 v[108:109], v8 offset0:16 offset1:20
	ds_read2_b32 v[110:111], v8 offset0:24 offset1:28
	ds_read2_b32 v[112:113], v8 offset0:32 offset1:36
	ds_read2_b32 v[114:115], v8 offset0:40 offset1:44
	ds_read2_b32 v[116:117], v8 offset0:48 offset1:52
	ds_read2_b32 v[118:119], v8 offset0:56 offset1:60
	s_waitcnt vmcnt(56)
	s_waitcnt lgkmcnt(7)
	v_mfma_f32_16x16x4_f32 v[136:139], v104, v120, v[204:207]
	v_mfma_f32_16x16x4_f32 v[140:143], v105, v121, 0
	ds_read2st64_b32 v[228:229], v11 offset0:0 offset1:5
	ds_read2st64_b32 v[230:231], v11 offset0:10 offset1:15
	s_waitcnt lgkmcnt(8)
	v_mfma_f32_16x16x4_f32 v[136:139], v106, v122, v[136:139]
	v_mfma_f32_16x16x4_f32 v[140:143], v107, v123, v[140:143]
	ds_read2st64_b32 v[232:233], v11 offset0:20 offset1:25
	ds_read2st64_b32 v[234:235], v11 offset0:30 offset1:35
	s_waitcnt lgkmcnt(9)
	v_mfma_f32_16x16x4_f32 v[136:139], v108, v124, v[136:139]
	v_mfma_f32_16x16x4_f32 v[140:143], v109, v125, v[140:143]
	ds_read2st64_b32 v[236:237], v11 offset0:40 offset1:45
	ds_read2st64_b32 v[238:239], v11 offset0:50 offset1:55
	s_waitcnt lgkmcnt(10)
	v_mfma_f32_16x16x4_f32 v[136:139], v110, v126, v[136:139]
	v_mfma_f32_16x16x4_f32 v[140:143], v111, v127, v[140:143]
	ds_read2st64_b32 v[240:241], v11 offset0:60 offset1:65
	ds_read2st64_b32 v[242:243], v11 offset0:70 offset1:75
	s_waitcnt lgkmcnt(11)
	v_mfma_f32_16x16x4_f32 v[136:139], v112, v128, v[136:139]
	v_mfma_f32_16x16x4_f32 v[140:143], v113, v129, v[140:143]
	s_add_u32 s14, s6, 0x3c0000
	s_addc_u32 s15, s7, 0
	global_load_dword v204, v12, s[14:15] offset:0
	global_load_dword v205, v12, s[14:15] offset:256
	global_load_dword v206, v12, s[14:15] offset:512
	global_load_dword v207, v12, s[14:15] offset:768
	s_waitcnt lgkmcnt(10)
	v_mfma_f32_16x16x4_f32 v[136:139], v114, v130, v[136:139]
	v_mfma_f32_16x16x4_f32 v[140:143], v115, v131, v[140:143]
	s_waitcnt vmcnt(58)
	ds_write_b128 v2, v[68:71] offset:0
	ds_write_b128 v2, v[72:75] offset:10240
	s_add_u32 s10, s0, 0x400000
	s_addc_u32 s11, s1, 0
	global_load_dwordx4 v[68:71], v0, s[10:11]
	global_load_dwordx4 v[72:75], v1, s[10:11]
	s_waitcnt lgkmcnt(11)
	v_mfma_f32_16x16x4_f32 v[136:139], v116, v132, v[136:139]
	v_mfma_f32_16x16x4_f32 v[140:143], v117, v133, v[140:143]
	s_waitcnt lgkmcnt(10)
	v_mfma_f32_16x16x4_f32 v[136:139], v118, v134, v[136:139]
	v_mfma_f32_16x16x4_f32 v[140:143], v119, v135, v[140:143]
	s_add_u32 s16, s8, 0x320000
	s_addc_u32 s17, s9, 0
	s_nop 9
	v_add_f32_e32 v136, v136, v140
	v_add_f32_e32 v137, v137, v141
	v_add_f32_e32 v138, v138, v142
	v_add_f32_e32 v139, v139, v143
	ds_write_b32 v13, v136 offset:2176
	ds_write_b32 v13, v137 offset:2448
	ds_write_b32 v13, v138 offset:2720
	ds_write_b32 v13, v139 offset:2992
	global_store_dword v12, v136, s[16:17] offset:0
	global_store_dword v12, v137, s[16:17] offset:256
	global_store_dword v12, v138, s[16:17] offset:512
	global_store_dword v12, v139, s[16:17] offset:768
	s_waitcnt lgkmcnt(0)
	s_barrier
; #define LAS __attribute__((address_space(3)))
; __device__ __forceinline__ void scan_combine(LAS unsigned char* lds, CArgsP a) {
;     ...
;     for (int g = 1; g <= GL; ++g) {
;         const bool pf = (g + 2 <= GL);
;         float u3 = 0.f;
;         if (pf) { const f32x4* Pn = (const f32x4*)(PM + (size_t)((g + 2) * 8 + h) * 4096); pa = Pn[tid]; pb = Pn[512 + tid]; u3 = UM[((size_t)((g + 2) * 8 + h) * 64 + v) * 64 + kq]; }
;         asm volatile("s_waitcnt lgkmcnt(0)\n\ts_barrier" ::: "memory");
;         const LAS float* Pg = Pl + (g % 3) * 4096 + kq;
;         float acc0 = u1, acc1 = 0.f, acc2 = 0.f, acc3 = 0.f;
;         const int curi = __builtin_bit_cast(int, cur);
; #pragma unroll
;         for (int k = 0; k < 64; k += 4) {
;             const float s0 = __builtin_bit_cast(float, __builtin_amdgcn_readlane(curi, k)), s1 = __builtin_bit_cast(float, __builtin_amdgcn_readlane(curi, k + 1));
;             const float s2 = __builtin_bit_cast(float, __builtin_amdgcn_readlane(curi, k + 2)), s3 = __builtin_bit_cast(float, __builtin_amdgcn_readlane(curi, k + 3));
;             acc0 += s0 * Pg[(k + 0) * 64]; acc1 += s1 * Pg[(k + 1) * 64]; acc2 += s2 * Pg[(k + 2) * 64]; acc3 += s3 * Pg[(k + 3) * 64];
;         }
;         cur = (acc0 + acc1) + (acc2 + acc3);
;         SS[((size_t)((g + 1) * 8 + h) * 64 + v) * 64 + kq] = cur;
;         if (pf) { LAS float* dst = Pl + ((g + 2) % 3) * 4096; *(LAS f32x4*)(dst + 4 * tid) = pa; *(LAS f32x4*)(dst + 2048 + 4 * tid) = pb; }
;         u1 = u2; u2 = u3;
	ds_read2_b32 v[104:105], v9 offset0:0 offset1:4
	ds_read2_b32 v[106:107], v9 offset0:8 offset1:12
	ds_read2_b32 v[108:109], v9 offset0:16 offset1:20
	ds_read2_b32 v[110:111], v9 offset0:24 offset1:28
	ds_read2_b32 v[112:113], v9 offset0:32 offset1:36
	ds_read2_b32 v[114:115], v9 offset0:40 offset1:44
	ds_read2_b32 v[116:117], v9 offset0:48 offset1:52
	ds_read2_b32 v[118:119], v9 offset0:56 offset1:60
	s_waitcnt vmcnt(56)
	s_waitcnt lgkmcnt(7)
	v_mfma_f32_16x16x4_f32 v[136:139], v104, v228, v[208:211]
	v_mfma_f32_16x16x4_f32 v[140:143], v105, v229, 0
	ds_read2st64_b32 v[120:121], v10 offset0:0 offset1:5
	ds_read2st64_b32 v[122:123], v10 offset0:10 offset1:15
	s_waitcnt lgkmcnt(8)
	v_mfma_f32_16x16x4_f32 v[136:139], v106, v230, v[136:139]
	v_mfma_f32_16x16x4_f32 v[140:143], v107, v231, v[140:143]
	ds_read2st64_b32 v[124:125], v10 offset0:20 offset1:25
	ds_read2st64_b32 v[126:127], v10 offset0:30 offset1:35
	s_waitcnt lgkmcnt(9)
	v_mfma_f32_16x16x4_f32 v[136:139], v108, v232, v[136:139]
	v_mfma_f32_16x16x4_f32 v[140:143], v109, v233, v[140:143]
	ds_read2st64_b32 v[128:129], v10 offset0:40 offset1:45
	ds_read2st64_b32 v[130:131], v10 offset0:50 offset1:55
	s_waitcnt lgkmcnt(10)
	v_mfma_f32_16x16x4_f32 v[136:139], v110, v234, v[136:139]
	v_mfma_f32_16x16x4_f32 v[140:143], v111, v235, v[140:143]
	ds_read2st64_b32 v[132:133], v10 offset0:60 offset1:65
	ds_read2st64_b32 v[134:135], v10 offset0:70 offset1:75
	s_waitcnt lgkmcnt(11)
	v_mfma_f32_16x16x4_f32 v[136:139], v112, v236, v[136:139]
	v_mfma_f32_16x16x4_f32 v[140:143], v113, v237, v[140:143]
	s_add_u32 s14, s6, 0x3e0000
	s_addc_u32 s15, s7, 0
	global_load_dword v208, v12, s[14:15] offset:0
	global_load_dword v209, v12, s[14:15] offset:256
	global_load_dword v210, v12, s[14:15] offset:512
	global_load_dword v211, v12, s[14:15] offset:768
	s_waitcnt lgkmcnt(10)
	v_mfma_f32_16x16x4_f32 v[136:139], v114, v238, v[136:139]
	v_mfma_f32_16x16x4_f32 v[140:143], v115, v239, v[140:143]
	s_waitcnt vmcnt(58)
	ds_write_b128 v2, v[76:79] offset:20480
	ds_write_b128 v2, v[80:83] offset:30720
	s_add_u32 s10, s0, 0x420000
	s_addc_u32 s11, s1, 0
	global_load_dwordx4 v[76:79], v0, s[10:11]
	global_load_dwordx4 v[80:83], v1, s[10:11]
	s_waitcnt lgkmcnt(11)
	v_mfma_f32_16x16x4_f32 v[136:139], v116, v240, v[136:139]
	v_mfma_f32_16x16x4_f32 v[140:143], v117, v241, v[140:143]
	s_waitcnt lgkmcnt(10)
	v_mfma_f32_16x16x4_f32 v[136:139], v118, v242, v[136:139]
	v_mfma_f32_16x16x4_f32 v[140:143], v119, v243, v[140:143]
	s_add_u32 s16, s8, 0x340000
	s_addc_u32 s17, s9, 0
	s_nop 9
	v_add_f32_e32 v136, v136, v140
	v_add_f32_e32 v137, v137, v141
	v_add_f32_e32 v138, v138, v142
	v_add_f32_e32 v139, v139, v143
	ds_write_b32 v13, v136 offset:0
	ds_write_b32 v13, v137 offset:272
	ds_write_b32 v13, v138 offset:544
	ds_write_b32 v13, v139 offset:816
	global_store_dword v12, v136, s[16:17] offset:0
	global_store_dword v12, v137, s[16:17] offset:256
	global_store_dword v12, v138, s[16:17] offset:512
	global_store_dword v12, v139, s[16:17] offset:768
	s_waitcnt lgkmcnt(0)
	s_barrier
	ds_read2_b32 v[104:105], v8 offset0:0 offset1:4
	ds_read2_b32 v[106:107], v8 offset0:8 offset1:12
	ds_read2_b32 v[108:109], v8 offset0:16 offset1:20
	ds_read2_b32 v[110:111], v8 offset0:24 offset1:28
	ds_read2_b32 v[112:113], v8 offset0:32 offset1:36
	ds_read2_b32 v[114:115], v8 offset0:40 offset1:44
	ds_read2_b32 v[116:117], v8 offset0:48 offset1:52
	ds_read2_b32 v[118:119], v8 offset0:56 offset1:60
	s_waitcnt vmcnt(56)
	s_waitcnt lgkmcnt(7)
	v_mfma_f32_16x16x4_f32 v[136:139], v104, v120, v[212:215]
	v_mfma_f32_16x16x4_f32 v[140:143], v105, v121, 0
	ds_read2st64_b32 v[228:229], v11 offset0:0 offset1:5
	ds_read2st64_b32 v[230:231], v11 offset0:10 offset1:15
	s_waitcnt lgkmcnt(8)
	v_mfma_f32_16x16x4_f32 v[136:139], v106, v122, v[136:139]
	v_mfma_f32_16x16x4_f32 v[140:143], v107, v123, v[140:143]
	ds_read2st64_b32 v[232:233], v11 offset0:20 offset1:25
	ds_read2st64_b32 v[234:235], v11 offset0:30 offset1:35
	s_waitcnt lgkmcnt(9)
	v_mfma_f32_16x16x4_f32 v[136:139], v108, v124, v[136:139]
	v_mfma_f32_16x16x4_f32 v[140:143], v109, v125, v[140:143]
	ds_read2st64_b32 v[236:237], v11 offset0:40 offset1:45
	ds_read2st64_b32 v[238:239], v11 offset0:50 offset1:55
	s_waitcnt lgkmcnt(10)
	v_mfma_f32_16x16x4_f32 v[136:139], v110, v126, v[136:139]
	v_mfma_f32_16x16x4_f32 v[140:143], v111, v127, v[140:143]
	ds_read2st64_b32 v[240:241], v11 offset0:60 offset1:65
	ds_read2st64_b32 v[242:243], v11 offset0:70 offset1:75
	s_waitcnt lgkmcnt(11)
	v_mfma_f32_16x16x4_f32 v[136:139], v112, v128, v[136:139]
	v_mfma_f32_16x16x4_f32 v[140:143], v113, v129, v[140:143]
	s_add_u32 s14, s6, 0x400000
	s_addc_u32 s15, s7, 0
	global_load_dword v212, v12, s[14:15] offset:0
	global_load_dword v213, v12, s[14:15] offset:256
	global_load_dword v214, v12, s[14:15] offset:512
	global_load_dword v215, v12, s[14:15] offset:768
	s_waitcnt lgkmcnt(10)
	v_mfma_f32_16x16x4_f32 v[136:139], v114, v130, v[136:139]
	v_mfma_f32_16x16x4_f32 v[140:143], v115, v131, v[140:143]
	s_waitcnt vmcnt(58)
	ds_write_b128 v2, v[84:87] offset:0
	ds_write_b128 v2, v[88:91] offset:10240
	s_add_u32 s10, s0, 0x440000
	s_addc_u32 s11, s1, 0
	global_load_dwordx4 v[84:87], v0, s[10:11]
	global_load_dwordx4 v[88:91], v1, s[10:11]
	s_waitcnt lgkmcnt(11)
	v_mfma_f32_16x16x4_f32 v[136:139], v116, v132, v[136:139]
	v_mfma_f32_16x16x4_f32 v[140:143], v117, v133, v[140:143]
	s_waitcnt lgkmcnt(10)
	v_mfma_f32_16x16x4_f32 v[136:139], v118, v134, v[136:139]
	v_mfma_f32_16x16x4_f32 v[140:143], v119, v135, v[140:143]
	s_add_u32 s16, s8, 0x360000
	s_addc_u32 s17, s9, 0
	s_nop 9
	v_add_f32_e32 v136, v136, v140
	v_add_f32_e32 v137, v137, v141
	v_add_f32_e32 v138, v138, v142
	v_add_f32_e32 v139, v139, v143
	ds_write_b32 v13, v136 offset:2176
	ds_write_b32 v13, v137 offset:2448
	ds_write_b32 v13, v138 offset:2720
	ds_write_b32 v13, v139 offset:2992
	global_store_dword v12, v136, s[16:17] offset:0
	global_store_dword v12, v137, s[16:17] offset:256
	global_store_dword v12, v138, s[16:17] offset:512
	global_store_dword v12, v139, s[16:17] offset:768
	s_waitcnt lgkmcnt(0)
	s_barrier
; #define LAS __attribute__((address_space(3)))
; __device__ __forceinline__ void scan_combine(LAS unsigned char* lds, CArgsP a) {
;     ...
;     for (int g = 1; g <= GL; ++g) {
;         const bool pf = (g + 2 <= GL);
;         float u3 = 0.f;
;         if (pf) { const f32x4* Pn = (const f32x4*)(PM + (size_t)((g + 2) * 8 + h) * 4096); pa = Pn[tid]; pb = Pn[512 + tid]; u3 = UM[((size_t)((g + 2) * 8 + h) * 64 + v) * 64 + kq]; }
;         asm volatile("s_waitcnt lgkmcnt(0)\n\ts_barrier" ::: "memory");
;         const LAS float* Pg = Pl + (g % 3) * 4096 + kq;
;         float acc0 = u1, acc1 = 0.f, acc2 = 0.f, acc3 = 0.f;
;         const int curi = __builtin_bit_cast(int, cur);
; #pragma unroll
;         for (int k = 0; k < 64; k += 4) {
;             const float s0 = __builtin_bit_cast(float, __builtin_amdgcn_readlane(curi, k)), s1 = __builtin_bit_cast(float, __builtin_amdgcn_readlane(curi, k + 1));
;             const float s2 = __builtin_bit_cast(float, __builtin_amdgcn_readlane(curi, k + 2)), s3 = __builtin_bit_cast(float, __builtin_amdgcn_readlane(curi, k + 3));
;             acc0 += s0 * Pg[(k + 0) * 64]; acc1 += s1 * Pg[(k + 1) * 64]; acc2 += s2 * Pg[(k + 2) * 64]; acc3 += s3 * Pg[(k + 3) * 64];
;         }
;         cur = (acc0 + acc1) + (acc2 + acc3);
;         SS[((size_t)((g + 1) * 8 + h) * 64 + v) * 64 + kq] = cur;
;         if (pf) { LAS float* dst = Pl + ((g + 2) % 3) * 4096; *(LAS f32x4*)(dst + 4 * tid) = pa; *(LAS f32x4*)(dst + 2048 + 4 * tid) = pb; }
;         u1 = u2; u2 = u3;
	ds_read2_b32 v[104:105], v9 offset0:0 offset1:4
	ds_read2_b32 v[106:107], v9 offset0:8 offset1:12
	ds_read2_b32 v[108:109], v9 offset0:16 offset1:20
	ds_read2_b32 v[110:111], v9 offset0:24 offset1:28
	ds_read2_b32 v[112:113], v9 offset0:32 offset1:36
	ds_read2_b32 v[114:115], v9 offset0:40 offset1:44
	ds_read2_b32 v[116:117], v9 offset0:48 offset1:52
	ds_read2_b32 v[118:119], v9 offset0:56 offset1:60
	s_waitcnt vmcnt(56)
	s_waitcnt lgkmcnt(7)
	v_mfma_f32_16x16x4_f32 v[136:139], v104, v228, v[216:219]
	v_mfma_f32_16x16x4_f32 v[140:143], v105, v229, 0
	ds_read2st64_b32 v[120:121], v10 offset0:0 offset1:5
	ds_read2st64_b32 v[122:123], v10 offset0:10 offset1:15
	s_waitcnt lgkmcnt(8)
	v_mfma_f32_16x16x4_f32 v[136:139], v106, v230, v[136:139]
	v_mfma_f32_16x16x4_f32 v[140:143], v107, v231, v[140:143]
	ds_read2st64_b32 v[124:125], v10 offset0:20 offset1:25
	ds_read2st64_b32 v[126:127], v10 offset0:30 offset1:35
	s_waitcnt lgkmcnt(9)
	v_mfma_f32_16x16x4_f32 v[136:139], v108, v232, v[136:139]
	v_mfma_f32_16x16x4_f32 v[140:143], v109, v233, v[140:143]
	ds_read2st64_b32 v[128:129], v10 offset0:40 offset1:45
	ds_read2st64_b32 v[130:131], v10 offset0:50 offset1:55
	s_waitcnt lgkmcnt(10)
	v_mfma_f32_16x16x4_f32 v[136:139], v110, v234, v[136:139]
	v_mfma_f32_16x16x4_f32 v[140:143], v111, v235, v[140:143]
	ds_read2st64_b32 v[132:133], v10 offset0:60 offset1:65
	ds_read2st64_b32 v[134:135], v10 offset0:70 offset1:75
	s_waitcnt lgkmcnt(11)
	v_mfma_f32_16x16x4_f32 v[136:139], v112, v236, v[136:139]
	v_mfma_f32_16x16x4_f32 v[140:143], v113, v237, v[140:143]
	s_add_u32 s14, s6, 0x420000
	s_addc_u32 s15, s7, 0
	global_load_dword v216, v12, s[14:15] offset:0
	global_load_dword v217, v12, s[14:15] offset:256
	global_load_dword v218, v12, s[14:15] offset:512
	global_load_dword v219, v12, s[14:15] offset:768
	s_waitcnt lgkmcnt(10)
	v_mfma_f32_16x16x4_f32 v[136:139], v114, v238, v[136:139]
	v_mfma_f32_16x16x4_f32 v[140:143], v115, v239, v[140:143]
	s_waitcnt vmcnt(58)
	ds_write_b128 v2, v[92:95] offset:20480
	ds_write_b128 v2, v[96:99] offset:30720
	s_add_u32 s10, s0, 0x460000
	s_addc_u32 s11, s1, 0
	global_load_dwordx4 v[92:95], v0, s[10:11]
	global_load_dwordx4 v[96:99], v1, s[10:11]
	s_waitcnt lgkmcnt(11)
	v_mfma_f32_16x16x4_f32 v[136:139], v116, v240, v[136:139]
	v_mfma_f32_16x16x4_f32 v[140:143], v117, v241, v[140:143]
	s_waitcnt lgkmcnt(10)
	v_mfma_f32_16x16x4_f32 v[136:139], v118, v242, v[136:139]
	v_mfma_f32_16x16x4_f32 v[140:143], v119, v243, v[140:143]
	s_add_u32 s16, s8, 0x380000
	s_addc_u32 s17, s9, 0
	s_nop 9
	v_add_f32_e32 v136, v136, v140
	v_add_f32_e32 v137, v137, v141
	v_add_f32_e32 v138, v138, v142
	v_add_f32_e32 v139, v139, v143
	ds_write_b32 v13, v136 offset:0
	ds_write_b32 v13, v137 offset:272
	ds_write_b32 v13, v138 offset:544
	ds_write_b32 v13, v139 offset:816
	global_store_dword v12, v136, s[16:17] offset:0
	global_store_dword v12, v137, s[16:17] offset:256
	global_store_dword v12, v138, s[16:17] offset:512
	global_store_dword v12, v139, s[16:17] offset:768
	s_waitcnt lgkmcnt(0)
	s_barrier
	ds_read2_b32 v[104:105], v8 offset0:0 offset1:4
	ds_read2_b32 v[106:107], v8 offset0:8 offset1:12
	ds_read2_b32 v[108:109], v8 offset0:16 offset1:20
	ds_read2_b32 v[110:111], v8 offset0:24 offset1:28
	ds_read2_b32 v[112:113], v8 offset0:32 offset1:36
	ds_read2_b32 v[114:115], v8 offset0:40 offset1:44
	ds_read2_b32 v[116:117], v8 offset0:48 offset1:52
	ds_read2_b32 v[118:119], v8 offset0:56 offset1:60
	s_waitcnt vmcnt(56)
	s_waitcnt lgkmcnt(7)
	v_mfma_f32_16x16x4_f32 v[136:139], v104, v120, v[220:223]
	v_mfma_f32_16x16x4_f32 v[140:143], v105, v121, 0
	ds_read2st64_b32 v[228:229], v11 offset0:0 offset1:5
	ds_read2st64_b32 v[230:231], v11 offset0:10 offset1:15
	s_waitcnt lgkmcnt(8)
	v_mfma_f32_16x16x4_f32 v[136:139], v106, v122, v[136:139]
	v_mfma_f32_16x16x4_f32 v[140:143], v107, v123, v[140:143]
	ds_read2st64_b32 v[232:233], v11 offset0:20 offset1:25
	ds_read2st64_b32 v[234:235], v11 offset0:30 offset1:35
	s_waitcnt lgkmcnt(9)
	v_mfma_f32_16x16x4_f32 v[136:139], v108, v124, v[136:139]
	v_mfma_f32_16x16x4_f32 v[140:143], v109, v125, v[140:143]
	ds_read2st64_b32 v[236:237], v11 offset0:40 offset1:45
	ds_read2st64_b32 v[238:239], v11 offset0:50 offset1:55
	s_waitcnt lgkmcnt(10)
	v_mfma_f32_16x16x4_f32 v[136:139], v110, v126, v[136:139]
	v_mfma_f32_16x16x4_f32 v[140:143], v111, v127, v[140:143]
	ds_read2st64_b32 v[240:241], v11 offset0:60 offset1:65
	ds_read2st64_b32 v[242:243], v11 offset0:70 offset1:75
	s_waitcnt lgkmcnt(11)
	v_mfma_f32_16x16x4_f32 v[136:139], v112, v128, v[136:139]
	v_mfma_f32_16x16x4_f32 v[140:143], v113, v129, v[140:143]
	s_add_u32 s14, s6, 0x440000
	s_addc_u32 s15, s7, 0
	global_load_dword v220, v12, s[14:15] offset:0
	global_load_dword v221, v12, s[14:15] offset:256
	global_load_dword v222, v12, s[14:15] offset:512
	global_load_dword v223, v12, s[14:15] offset:768
	s_waitcnt lgkmcnt(10)
	v_mfma_f32_16x16x4_f32 v[136:139], v114, v130, v[136:139]
	v_mfma_f32_16x16x4_f32 v[140:143], v115, v131, v[140:143]
	s_waitcnt vmcnt(58)
	ds_write_b128 v2, v[52:55] offset:0
	ds_write_b128 v2, v[56:59] offset:10240
	s_add_u32 s10, s0, 0x480000
	s_addc_u32 s11, s1, 0
	global_load_dwordx4 v[52:55], v0, s[10:11]
	global_load_dwordx4 v[56:59], v1, s[10:11]
	s_waitcnt lgkmcnt(11)
	v_mfma_f32_16x16x4_f32 v[136:139], v116, v132, v[136:139]
	v_mfma_f32_16x16x4_f32 v[140:143], v117, v133, v[140:143]
	s_waitcnt lgkmcnt(10)
	v_mfma_f32_16x16x4_f32 v[136:139], v118, v134, v[136:139]
	v_mfma_f32_16x16x4_f32 v[140:143], v119, v135, v[140:143]
	s_add_u32 s16, s8, 0x3a0000
	s_addc_u32 s17, s9, 0
	s_nop 9
	v_add_f32_e32 v136, v136, v140
	v_add_f32_e32 v137, v137, v141
	v_add_f32_e32 v138, v138, v142
	v_add_f32_e32 v139, v139, v143
	ds_write_b32 v13, v136 offset:2176
	ds_write_b32 v13, v137 offset:2448
	ds_write_b32 v13, v138 offset:2720
	ds_write_b32 v13, v139 offset:2992
	global_store_dword v12, v136, s[16:17] offset:0
	global_store_dword v12, v137, s[16:17] offset:256
	global_store_dword v12, v138, s[16:17] offset:512
	global_store_dword v12, v139, s[16:17] offset:768
	s_waitcnt lgkmcnt(0)
	s_barrier
; #define LAS __attribute__((address_space(3)))
; __device__ __forceinline__ void scan_combine(LAS unsigned char* lds, CArgsP a) {
;     ...
;     for (int g = 1; g <= GL; ++g) {
;         const bool pf = (g + 2 <= GL);
;         float u3 = 0.f;
;         if (pf) { const f32x4* Pn = (const f32x4*)(PM + (size_t)((g + 2) * 8 + h) * 4096); pa = Pn[tid]; pb = Pn[512 + tid]; u3 = UM[((size_t)((g + 2) * 8 + h) * 64 + v) * 64 + kq]; }
;         asm volatile("s_waitcnt lgkmcnt(0)\n\ts_barrier" ::: "memory");
;         const LAS float* Pg = Pl + (g % 3) * 4096 + kq;
;         float acc0 = u1, acc1 = 0.f, acc2 = 0.f, acc3 = 0.f;
;         const int curi = __builtin_bit_cast(int, cur);
; #pragma unroll
;         for (int k = 0; k < 64; k += 4) {
;             const float s0 = __builtin_bit_cast(float, __builtin_amdgcn_readlane(curi, k)), s1 = __builtin_bit_cast(float, __builtin_amdgcn_readlane(curi, k + 1));
;             const float s2 = __builtin_bit_cast(float, __builtin_amdgcn_readlane(curi, k + 2)), s3 = __builtin_bit_cast(float, __builtin_amdgcn_readlane(curi, k + 3));
;             acc0 += s0 * Pg[(k + 0) * 64]; acc1 += s1 * Pg[(k + 1) * 64]; acc2 += s2 * Pg[(k + 2) * 64]; acc3 += s3 * Pg[(k + 3) * 64];
;         }
;         cur = (acc0 + acc1) + (acc2 + acc3);
;         SS[((size_t)((g + 1) * 8 + h) * 64 + v) * 64 + kq] = cur;
;         if (pf) { LAS float* dst = Pl + ((g + 2) % 3) * 4096; *(LAS f32x4*)(dst + 4 * tid) = pa; *(LAS f32x4*)(dst + 2048 + 4 * tid) = pb; }
;         u1 = u2; u2 = u3;
	ds_read2_b32 v[104:105], v9 offset0:0 offset1:4
	ds_read2_b32 v[106:107], v9 offset0:8 offset1:12
	ds_read2_b32 v[108:109], v9 offset0:16 offset1:20
	ds_read2_b32 v[110:111], v9 offset0:24 offset1:28
	ds_read2_b32 v[112:113], v9 offset0:32 offset1:36
	ds_read2_b32 v[114:115], v9 offset0:40 offset1:44
	ds_read2_b32 v[116:117], v9 offset0:48 offset1:52
	ds_read2_b32 v[118:119], v9 offset0:56 offset1:60
	s_waitcnt vmcnt(56)
	s_waitcnt lgkmcnt(7)
	v_mfma_f32_16x16x4_f32 v[136:139], v104, v228, v[224:227]
	v_mfma_f32_16x16x4_f32 v[140:143], v105, v229, 0
	ds_read2st64_b32 v[120:121], v10 offset0:0 offset1:5
	ds_read2st64_b32 v[122:123], v10 offset0:10 offset1:15
	s_waitcnt lgkmcnt(8)
	v_mfma_f32_16x16x4_f32 v[136:139], v106, v230, v[136:139]
	v_mfma_f32_16x16x4_f32 v[140:143], v107, v231, v[140:143]
	ds_read2st64_b32 v[124:125], v10 offset0:20 offset1:25
	ds_read2st64_b32 v[126:127], v10 offset0:30 offset1:35
	s_waitcnt lgkmcnt(9)
	v_mfma_f32_16x16x4_f32 v[136:139], v108, v232, v[136:139]
	v_mfma_f32_16x16x4_f32 v[140:143], v109, v233, v[140:143]
	ds_read2st64_b32 v[128:129], v10 offset0:40 offset1:45
	ds_read2st64_b32 v[130:131], v10 offset0:50 offset1:55
	s_waitcnt lgkmcnt(10)
	v_mfma_f32_16x16x4_f32 v[136:139], v110, v234, v[136:139]
	v_mfma_f32_16x16x4_f32 v[140:143], v111, v235, v[140:143]
	ds_read2st64_b32 v[132:133], v10 offset0:60 offset1:65
	ds_read2st64_b32 v[134:135], v10 offset0:70 offset1:75
	s_waitcnt lgkmcnt(11)
	v_mfma_f32_16x16x4_f32 v[136:139], v112, v236, v[136:139]
	v_mfma_f32_16x16x4_f32 v[140:143], v113, v237, v[140:143]
	s_add_u32 s14, s6, 0x460000
	s_addc_u32 s15, s7, 0
	global_load_dword v224, v12, s[14:15] offset:0
	global_load_dword v225, v12, s[14:15] offset:256
	global_load_dword v226, v12, s[14:15] offset:512
	global_load_dword v227, v12, s[14:15] offset:768
	s_waitcnt lgkmcnt(10)
	v_mfma_f32_16x16x4_f32 v[136:139], v114, v238, v[136:139]
	v_mfma_f32_16x16x4_f32 v[140:143], v115, v239, v[140:143]
	s_waitcnt vmcnt(58)
	ds_write_b128 v2, v[60:63] offset:20480
	ds_write_b128 v2, v[64:67] offset:30720
	s_add_u32 s10, s0, 0x4a0000
	s_addc_u32 s11, s1, 0
	global_load_dwordx4 v[60:63], v0, s[10:11]
	global_load_dwordx4 v[64:67], v1, s[10:11]
	s_waitcnt lgkmcnt(11)
	v_mfma_f32_16x16x4_f32 v[136:139], v116, v240, v[136:139]
	v_mfma_f32_16x16x4_f32 v[140:143], v117, v241, v[140:143]
	s_waitcnt lgkmcnt(10)
	v_mfma_f32_16x16x4_f32 v[136:139], v118, v242, v[136:139]
	v_mfma_f32_16x16x4_f32 v[140:143], v119, v243, v[140:143]
	s_add_u32 s16, s8, 0x3c0000
	s_addc_u32 s17, s9, 0
	s_nop 9
	v_add_f32_e32 v136, v136, v140
	v_add_f32_e32 v137, v137, v141
	v_add_f32_e32 v138, v138, v142
	v_add_f32_e32 v139, v139, v143
	ds_write_b32 v13, v136 offset:0
	ds_write_b32 v13, v137 offset:272
	ds_write_b32 v13, v138 offset:544
	ds_write_b32 v13, v139 offset:816
	global_store_dword v12, v136, s[16:17] offset:0
	global_store_dword v12, v137, s[16:17] offset:256
	global_store_dword v12, v138, s[16:17] offset:512
	global_store_dword v12, v139, s[16:17] offset:768
	s_waitcnt lgkmcnt(0)
	s_barrier
	ds_read2_b32 v[104:105], v8 offset0:0 offset1:4
	ds_read2_b32 v[106:107], v8 offset0:8 offset1:12
	ds_read2_b32 v[108:109], v8 offset0:16 offset1:20
	ds_read2_b32 v[110:111], v8 offset0:24 offset1:28
	ds_read2_b32 v[112:113], v8 offset0:32 offset1:36
	ds_read2_b32 v[114:115], v8 offset0:40 offset1:44
	ds_read2_b32 v[116:117], v8 offset0:48 offset1:52
	ds_read2_b32 v[118:119], v8 offset0:56 offset1:60
	s_waitcnt vmcnt(56)
	s_waitcnt lgkmcnt(7)
	v_mfma_f32_16x16x4_f32 v[136:139], v104, v120, v[204:207]
	v_mfma_f32_16x16x4_f32 v[140:143], v105, v121, 0
	ds_read2st64_b32 v[228:229], v11 offset0:0 offset1:5
	ds_read2st64_b32 v[230:231], v11 offset0:10 offset1:15
	s_waitcnt lgkmcnt(8)
	v_mfma_f32_16x16x4_f32 v[136:139], v106, v122, v[136:139]
	v_mfma_f32_16x16x4_f32 v[140:143], v107, v123, v[140:143]
	ds_read2st64_b32 v[232:233], v11 offset0:20 offset1:25
	ds_read2st64_b32 v[234:235], v11 offset0:30 offset1:35
	s_waitcnt lgkmcnt(9)
	v_mfma_f32_16x16x4_f32 v[136:139], v108, v124, v[136:139]
	v_mfma_f32_16x16x4_f32 v[140:143], v109, v125, v[140:143]
	ds_read2st64_b32 v[236:237], v11 offset0:40 offset1:45
	ds_read2st64_b32 v[238:239], v11 offset0:50 offset1:55
	s_waitcnt lgkmcnt(10)
	v_mfma_f32_16x16x4_f32 v[136:139], v110, v126, v[136:139]
	v_mfma_f32_16x16x4_f32 v[140:143], v111, v127, v[140:143]
	ds_read2st64_b32 v[240:241], v11 offset0:60 offset1:65
	ds_read2st64_b32 v[242:243], v11 offset0:70 offset1:75
	s_waitcnt lgkmcnt(11)
	v_mfma_f32_16x16x4_f32 v[136:139], v112, v128, v[136:139]
	v_mfma_f32_16x16x4_f32 v[140:143], v113, v129, v[140:143]
	s_add_u32 s14, s6, 0x480000
	s_addc_u32 s15, s7, 0
	global_load_dword v204, v12, s[14:15] offset:0
	global_load_dword v205, v12, s[14:15] offset:256
	global_load_dword v206, v12, s[14:15] offset:512
	global_load_dword v207, v12, s[14:15] offset:768
	s_waitcnt lgkmcnt(10)
	v_mfma_f32_16x16x4_f32 v[136:139], v114, v130, v[136:139]
	v_mfma_f32_16x16x4_f32 v[140:143], v115, v131, v[140:143]
	s_waitcnt vmcnt(58)
	ds_write_b128 v2, v[68:71] offset:0
	ds_write_b128 v2, v[72:75] offset:10240
	s_add_u32 s10, s0, 0x4c0000
	s_addc_u32 s11, s1, 0
	global_load_dwordx4 v[68:71], v0, s[10:11]
	global_load_dwordx4 v[72:75], v1, s[10:11]
	s_waitcnt lgkmcnt(11)
	v_mfma_f32_16x16x4_f32 v[136:139], v116, v132, v[136:139]
	v_mfma_f32_16x16x4_f32 v[140:143], v117, v133, v[140:143]
	s_waitcnt lgkmcnt(10)
	v_mfma_f32_16x16x4_f32 v[136:139], v118, v134, v[136:139]
	v_mfma_f32_16x16x4_f32 v[140:143], v119, v135, v[140:143]
	s_add_u32 s16, s8, 0x3e0000
	s_addc_u32 s17, s9, 0
	s_nop 9
	v_add_f32_e32 v136, v136, v140
	v_add_f32_e32 v137, v137, v141
	v_add_f32_e32 v138, v138, v142
	v_add_f32_e32 v139, v139, v143
	ds_write_b32 v13, v136 offset:2176
	ds_write_b32 v13, v137 offset:2448
	ds_write_b32 v13, v138 offset:2720
	ds_write_b32 v13, v139 offset:2992
	global_store_dword v12, v136, s[16:17] offset:0
	global_store_dword v12, v137, s[16:17] offset:256
	global_store_dword v12, v138, s[16:17] offset:512
	global_store_dword v12, v139, s[16:17] offset:768
	s_waitcnt lgkmcnt(0)
	s_barrier
; #define LAS __attribute__((address_space(3)))
; __device__ __forceinline__ void scan_combine(LAS unsigned char* lds, CArgsP a) {
;     ...
;     for (int g = 1; g <= GL; ++g) {
;         const bool pf = (g + 2 <= GL);
;         float u3 = 0.f;
;         if (pf) { const f32x4* Pn = (const f32x4*)(PM + (size_t)((g + 2) * 8 + h) * 4096); pa = Pn[tid]; pb = Pn[512 + tid]; u3 = UM[((size_t)((g + 2) * 8 + h) * 64 + v) * 64 + kq]; }
;         asm volatile("s_waitcnt lgkmcnt(0)\n\ts_barrier" ::: "memory");
;         const LAS float* Pg = Pl + (g % 3) * 4096 + kq;
;         float acc0 = u1, acc1 = 0.f, acc2 = 0.f, acc3 = 0.f;
;         const int curi = __builtin_bit_cast(int, cur);
; #pragma unroll
;         for (int k = 0; k < 64; k += 4) {
;             const float s0 = __builtin_bit_cast(float, __builtin_amdgcn_readlane(curi, k)), s1 = __builtin_bit_cast(float, __builtin_amdgcn_readlane(curi, k + 1));
;             const float s2 = __builtin_bit_cast(float, __builtin_amdgcn_readlane(curi, k + 2)), s3 = __builtin_bit_cast(float, __builtin_amdgcn_readlane(curi, k + 3));
;             acc0 += s0 * Pg[(k + 0) * 64]; acc1 += s1 * Pg[(k + 1) * 64]; acc2 += s2 * Pg[(k + 2) * 64]; acc3 += s3 * Pg[(k + 3) * 64];
;         }
;         cur = (acc0 + acc1) + (acc2 + acc3);
;         SS[((size_t)((g + 1) * 8 + h) * 64 + v) * 64 + kq] = cur;
;         if (pf) { LAS float* dst = Pl + ((g + 2) % 3) * 4096; *(LAS f32x4*)(dst + 4 * tid) = pa; *(LAS f32x4*)(dst + 2048 + 4 * tid) = pb; }
;         u1 = u2; u2 = u3;
	ds_read2_b32 v[104:105], v9 offset0:0 offset1:4
	ds_read2_b32 v[106:107], v9 offset0:8 offset1:12
	ds_read2_b32 v[108:109], v9 offset0:16 offset1:20
	ds_read2_b32 v[110:111], v9 offset0:24 offset1:28
	ds_read2_b32 v[112:113], v9 offset0:32 offset1:36
	ds_read2_b32 v[114:115], v9 offset0:40 offset1:44
	ds_read2_b32 v[116:117], v9 offset0:48 offset1:52
	ds_read2_b32 v[118:119], v9 offset0:56 offset1:60
	s_waitcnt vmcnt(56)
	s_waitcnt lgkmcnt(7)
	v_mfma_f32_16x16x4_f32 v[136:139], v104, v228, v[208:211]
	v_mfma_f32_16x16x4_f32 v[140:143], v105, v229, 0
	ds_read2st64_b32 v[120:121], v10 offset0:0 offset1:5
	ds_read2st64_b32 v[122:123], v10 offset0:10 offset1:15
	s_waitcnt lgkmcnt(8)
	v_mfma_f32_16x16x4_f32 v[136:139], v106, v230, v[136:139]
	v_mfma_f32_16x16x4_f32 v[140:143], v107, v231, v[140:143]
	ds_read2st64_b32 v[124:125], v10 offset0:20 offset1:25
	ds_read2st64_b32 v[126:127], v10 offset0:30 offset1:35
	s_waitcnt lgkmcnt(9)
	v_mfma_f32_16x16x4_f32 v[136:139], v108, v232, v[136:139]
	v_mfma_f32_16x16x4_f32 v[140:143], v109, v233, v[140:143]
	ds_read2st64_b32 v[128:129], v10 offset0:40 offset1:45
	ds_read2st64_b32 v[130:131], v10 offset0:50 offset1:55
	s_waitcnt lgkmcnt(10)
	v_mfma_f32_16x16x4_f32 v[136:139], v110, v234, v[136:139]
	v_mfma_f32_16x16x4_f32 v[140:143], v111, v235, v[140:143]
	ds_read2st64_b32 v[132:133], v10 offset0:60 offset1:65
	ds_read2st64_b32 v[134:135], v10 offset0:70 offset1:75
	s_waitcnt lgkmcnt(11)
	v_mfma_f32_16x16x4_f32 v[136:139], v112, v236, v[136:139]
	v_mfma_f32_16x16x4_f32 v[140:143], v113, v237, v[140:143]
	s_add_u32 s14, s6, 0x4a0000
	s_addc_u32 s15, s7, 0
	global_load_dword v208, v12, s[14:15] offset:0
	global_load_dword v209, v12, s[14:15] offset:256
	global_load_dword v210, v12, s[14:15] offset:512
	global_load_dword v211, v12, s[14:15] offset:768
	s_waitcnt lgkmcnt(10)
	v_mfma_f32_16x16x4_f32 v[136:139], v114, v238, v[136:139]
	v_mfma_f32_16x16x4_f32 v[140:143], v115, v239, v[140:143]
	s_waitcnt vmcnt(58)
	ds_write_b128 v2, v[76:79] offset:20480
	ds_write_b128 v2, v[80:83] offset:30720
	s_add_u32 s10, s0, 0x4e0000
	s_addc_u32 s11, s1, 0
	global_load_dwordx4 v[76:79], v0, s[10:11]
	global_load_dwordx4 v[80:83], v1, s[10:11]
	s_waitcnt lgkmcnt(11)
	v_mfma_f32_16x16x4_f32 v[136:139], v116, v240, v[136:139]
	v_mfma_f32_16x16x4_f32 v[140:143], v117, v241, v[140:143]
	s_waitcnt lgkmcnt(10)
	v_mfma_f32_16x16x4_f32 v[136:139], v118, v242, v[136:139]
	v_mfma_f32_16x16x4_f32 v[140:143], v119, v243, v[140:143]
	s_add_u32 s16, s8, 0x400000
	s_addc_u32 s17, s9, 0
	s_nop 9
	v_add_f32_e32 v136, v136, v140
	v_add_f32_e32 v137, v137, v141
	v_add_f32_e32 v138, v138, v142
	v_add_f32_e32 v139, v139, v143
	ds_write_b32 v13, v136 offset:0
	ds_write_b32 v13, v137 offset:272
	ds_write_b32 v13, v138 offset:544
	ds_write_b32 v13, v139 offset:816
	global_store_dword v12, v136, s[16:17] offset:0
	global_store_dword v12, v137, s[16:17] offset:256
	global_store_dword v12, v138, s[16:17] offset:512
	global_store_dword v12, v139, s[16:17] offset:768
	s_waitcnt lgkmcnt(0)
	s_barrier
	ds_read2_b32 v[104:105], v8 offset0:0 offset1:4
	ds_read2_b32 v[106:107], v8 offset0:8 offset1:12
	ds_read2_b32 v[108:109], v8 offset0:16 offset1:20
	ds_read2_b32 v[110:111], v8 offset0:24 offset1:28
	ds_read2_b32 v[112:113], v8 offset0:32 offset1:36
	ds_read2_b32 v[114:115], v8 offset0:40 offset1:44
	ds_read2_b32 v[116:117], v8 offset0:48 offset1:52
	ds_read2_b32 v[118:119], v8 offset0:56 offset1:60
	s_waitcnt vmcnt(56)
	s_waitcnt lgkmcnt(7)
	v_mfma_f32_16x16x4_f32 v[136:139], v104, v120, v[212:215]
	v_mfma_f32_16x16x4_f32 v[140:143], v105, v121, 0
	ds_read2st64_b32 v[228:229], v11 offset0:0 offset1:5
	ds_read2st64_b32 v[230:231], v11 offset0:10 offset1:15
	s_waitcnt lgkmcnt(8)
	v_mfma_f32_16x16x4_f32 v[136:139], v106, v122, v[136:139]
	v_mfma_f32_16x16x4_f32 v[140:143], v107, v123, v[140:143]
	ds_read2st64_b32 v[232:233], v11 offset0:20 offset1:25
	ds_read2st64_b32 v[234:235], v11 offset0:30 offset1:35
	s_waitcnt lgkmcnt(9)
	v_mfma_f32_16x16x4_f32 v[136:139], v108, v124, v[136:139]
	v_mfma_f32_16x16x4_f32 v[140:143], v109, v125, v[140:143]
	ds_read2st64_b32 v[236:237], v11 offset0:40 offset1:45
	ds_read2st64_b32 v[238:239], v11 offset0:50 offset1:55
	s_waitcnt lgkmcnt(10)
	v_mfma_f32_16x16x4_f32 v[136:139], v110, v126, v[136:139]
	v_mfma_f32_16x16x4_f32 v[140:143], v111, v127, v[140:143]
	ds_read2st64_b32 v[240:241], v11 offset0:60 offset1:65
	ds_read2st64_b32 v[242:243], v11 offset0:70 offset1:75
	s_waitcnt lgkmcnt(11)
	v_mfma_f32_16x16x4_f32 v[136:139], v112, v128, v[136:139]
	v_mfma_f32_16x16x4_f32 v[140:143], v113, v129, v[140:143]
	s_add_u32 s14, s6, 0x4c0000
	s_addc_u32 s15, s7, 0
	global_load_dword v212, v12, s[14:15] offset:0
	global_load_dword v213, v12, s[14:15] offset:256
	global_load_dword v214, v12, s[14:15] offset:512
	global_load_dword v215, v12, s[14:15] offset:768
	s_waitcnt lgkmcnt(10)
	v_mfma_f32_16x16x4_f32 v[136:139], v114, v130, v[136:139]
	v_mfma_f32_16x16x4_f32 v[140:143], v115, v131, v[140:143]
	s_waitcnt vmcnt(58)
	ds_write_b128 v2, v[84:87] offset:0
	ds_write_b128 v2, v[88:91] offset:10240
	s_add_u32 s10, s0, 0x500000
	s_addc_u32 s11, s1, 0
	global_load_dwordx4 v[84:87], v0, s[10:11]
	global_load_dwordx4 v[88:91], v1, s[10:11]
	s_waitcnt lgkmcnt(11)
	v_mfma_f32_16x16x4_f32 v[136:139], v116, v132, v[136:139]
	v_mfma_f32_16x16x4_f32 v[140:143], v117, v133, v[140:143]
	s_waitcnt lgkmcnt(10)
	v_mfma_f32_16x16x4_f32 v[136:139], v118, v134, v[136:139]
	v_mfma_f32_16x16x4_f32 v[140:143], v119, v135, v[140:143]
	s_add_u32 s16, s8, 0x420000
	s_addc_u32 s17, s9, 0
	s_nop 9
	v_add_f32_e32 v136, v136, v140
	v_add_f32_e32 v137, v137, v141
	v_add_f32_e32 v138, v138, v142
	v_add_f32_e32 v139, v139, v143
	ds_write_b32 v13, v136 offset:2176
	ds_write_b32 v13, v137 offset:2448
	ds_write_b32 v13, v138 offset:2720
	ds_write_b32 v13, v139 offset:2992
	global_store_dword v12, v136, s[16:17] offset:0
	global_store_dword v12, v137, s[16:17] offset:256
	global_store_dword v12, v138, s[16:17] offset:512
	global_store_dword v12, v139, s[16:17] offset:768
	s_waitcnt lgkmcnt(0)
	s_barrier
; #define LAS __attribute__((address_space(3)))
; __device__ __forceinline__ void scan_combine(LAS unsigned char* lds, CArgsP a) {
;     ...
;     for (int g = 1; g <= GL; ++g) {
;         const bool pf = (g + 2 <= GL);
;         float u3 = 0.f;
;         if (pf) { const f32x4* Pn = (const f32x4*)(PM + (size_t)((g + 2) * 8 + h) * 4096); pa = Pn[tid]; pb = Pn[512 + tid]; u3 = UM[((size_t)((g + 2) * 8 + h) * 64 + v) * 64 + kq]; }
;         asm volatile("s_waitcnt lgkmcnt(0)\n\ts_barrier" ::: "memory");
;         const LAS float* Pg = Pl + (g % 3) * 4096 + kq;
;         float acc0 = u1, acc1 = 0.f, acc2 = 0.f, acc3 = 0.f;
;         const int curi = __builtin_bit_cast(int, cur);
; #pragma unroll
;         for (int k = 0; k < 64; k += 4) {
;             const float s0 = __builtin_bit_cast(float, __builtin_amdgcn_readlane(curi, k)), s1 = __builtin_bit_cast(float, __builtin_amdgcn_readlane(curi, k + 1));
;             const float s2 = __builtin_bit_cast(float, __builtin_amdgcn_readlane(curi, k + 2)), s3 = __builtin_bit_cast(float, __builtin_amdgcn_readlane(curi, k + 3));
;             acc0 += s0 * Pg[(k + 0) * 64]; acc1 += s1 * Pg[(k + 1) * 64]; acc2 += s2 * Pg[(k + 2) * 64]; acc3 += s3 * Pg[(k + 3) * 64];
;         }
;         cur = (acc0 + acc1) + (acc2 + acc3);
;         SS[((size_t)((g + 1) * 8 + h) * 64 + v) * 64 + kq] = cur;
;         if (pf) { LAS float* dst = Pl + ((g + 2) % 3) * 4096; *(LAS f32x4*)(dst + 4 * tid) = pa; *(LAS f32x4*)(dst + 2048 + 4 * tid) = pb; }
;         u1 = u2; u2 = u3;
	ds_read2_b32 v[104:105], v9 offset0:0 offset1:4
	ds_read2_b32 v[106:107], v9 offset0:8 offset1:12
	ds_read2_b32 v[108:109], v9 offset0:16 offset1:20
	ds_read2_b32 v[110:111], v9 offset0:24 offset1:28
	ds_read2_b32 v[112:113], v9 offset0:32 offset1:36
	ds_read2_b32 v[114:115], v9 offset0:40 offset1:44
	ds_read2_b32 v[116:117], v9 offset0:48 offset1:52
	ds_read2_b32 v[118:119], v9 offset0:56 offset1:60
	s_waitcnt vmcnt(56)
	s_waitcnt lgkmcnt(7)
	v_mfma_f32_16x16x4_f32 v[136:139], v104, v228, v[216:219]
	v_mfma_f32_16x16x4_f32 v[140:143], v105, v229, 0
	ds_read2st64_b32 v[120:121], v10 offset0:0 offset1:5
	ds_read2st64_b32 v[122:123], v10 offset0:10 offset1:15
	s_waitcnt lgkmcnt(8)
	v_mfma_f32_16x16x4_f32 v[136:139], v106, v230, v[136:139]
	v_mfma_f32_16x16x4_f32 v[140:143], v107, v231, v[140:143]
	ds_read2st64_b32 v[124:125], v10 offset0:20 offset1:25
	ds_read2st64_b32 v[126:127], v10 offset0:30 offset1:35
	s_waitcnt lgkmcnt(9)
	v_mfma_f32_16x16x4_f32 v[136:139], v108, v232, v[136:139]
	v_mfma_f32_16x16x4_f32 v[140:143], v109, v233, v[140:143]
	ds_read2st64_b32 v[128:129], v10 offset0:40 offset1:45
	ds_read2st64_b32 v[130:131], v10 offset0:50 offset1:55
	s_waitcnt lgkmcnt(10)
	v_mfma_f32_16x16x4_f32 v[136:139], v110, v234, v[136:139]
	v_mfma_f32_16x16x4_f32 v[140:143], v111, v235, v[140:143]
	ds_read2st64_b32 v[132:133], v10 offset0:60 offset1:65
	ds_read2st64_b32 v[134:135], v10 offset0:70 offset1:75
	s_waitcnt lgkmcnt(11)
	v_mfma_f32_16x16x4_f32 v[136:139], v112, v236, v[136:139]
	v_mfma_f32_16x16x4_f32 v[140:143], v113, v237, v[140:143]
	s_add_u32 s14, s6, 0x4e0000
	s_addc_u32 s15, s7, 0
	global_load_dword v216, v12, s[14:15] offset:0
	global_load_dword v217, v12, s[14:15] offset:256
	global_load_dword v218, v12, s[14:15] offset:512
	global_load_dword v219, v12, s[14:15] offset:768
	s_waitcnt lgkmcnt(10)
	v_mfma_f32_16x16x4_f32 v[136:139], v114, v238, v[136:139]
	v_mfma_f32_16x16x4_f32 v[140:143], v115, v239, v[140:143]
	s_waitcnt vmcnt(58)
	ds_write_b128 v2, v[92:95] offset:20480
	ds_write_b128 v2, v[96:99] offset:30720
	s_add_u32 s10, s0, 0x520000
	s_addc_u32 s11, s1, 0
	global_load_dwordx4 v[92:95], v0, s[10:11]
	global_load_dwordx4 v[96:99], v1, s[10:11]
	s_waitcnt lgkmcnt(11)
	v_mfma_f32_16x16x4_f32 v[136:139], v116, v240, v[136:139]
	v_mfma_f32_16x16x4_f32 v[140:143], v117, v241, v[140:143]
	s_waitcnt lgkmcnt(10)
	v_mfma_f32_16x16x4_f32 v[136:139], v118, v242, v[136:139]
	v_mfma_f32_16x16x4_f32 v[140:143], v119, v243, v[140:143]
	s_add_u32 s16, s8, 0x440000
	s_addc_u32 s17, s9, 0
	s_nop 9
	v_add_f32_e32 v136, v136, v140
	v_add_f32_e32 v137, v137, v141
	v_add_f32_e32 v138, v138, v142
	v_add_f32_e32 v139, v139, v143
	ds_write_b32 v13, v136 offset:0
	ds_write_b32 v13, v137 offset:272
	ds_write_b32 v13, v138 offset:544
	ds_write_b32 v13, v139 offset:816
	global_store_dword v12, v136, s[16:17] offset:0
	global_store_dword v12, v137, s[16:17] offset:256
	global_store_dword v12, v138, s[16:17] offset:512
	global_store_dword v12, v139, s[16:17] offset:768
	s_waitcnt lgkmcnt(0)
	s_barrier
	ds_read2_b32 v[104:105], v8 offset0:0 offset1:4
	ds_read2_b32 v[106:107], v8 offset0:8 offset1:12
	ds_read2_b32 v[108:109], v8 offset0:16 offset1:20
	ds_read2_b32 v[110:111], v8 offset0:24 offset1:28
	ds_read2_b32 v[112:113], v8 offset0:32 offset1:36
	ds_read2_b32 v[114:115], v8 offset0:40 offset1:44
	ds_read2_b32 v[116:117], v8 offset0:48 offset1:52
	ds_read2_b32 v[118:119], v8 offset0:56 offset1:60
	s_waitcnt vmcnt(56)
	s_waitcnt lgkmcnt(7)
	v_mfma_f32_16x16x4_f32 v[136:139], v104, v120, v[220:223]
	v_mfma_f32_16x16x4_f32 v[140:143], v105, v121, 0
	ds_read2st64_b32 v[228:229], v11 offset0:0 offset1:5
	ds_read2st64_b32 v[230:231], v11 offset0:10 offset1:15
	s_waitcnt lgkmcnt(8)
	v_mfma_f32_16x16x4_f32 v[136:139], v106, v122, v[136:139]
	v_mfma_f32_16x16x4_f32 v[140:143], v107, v123, v[140:143]
	ds_read2st64_b32 v[232:233], v11 offset0:20 offset1:25
	ds_read2st64_b32 v[234:235], v11 offset0:30 offset1:35
	s_waitcnt lgkmcnt(9)
	v_mfma_f32_16x16x4_f32 v[136:139], v108, v124, v[136:139]
	v_mfma_f32_16x16x4_f32 v[140:143], v109, v125, v[140:143]
	ds_read2st64_b32 v[236:237], v11 offset0:40 offset1:45
	ds_read2st64_b32 v[238:239], v11 offset0:50 offset1:55
	s_waitcnt lgkmcnt(10)
	v_mfma_f32_16x16x4_f32 v[136:139], v110, v126, v[136:139]
	v_mfma_f32_16x16x4_f32 v[140:143], v111, v127, v[140:143]
	ds_read2st64_b32 v[240:241], v11 offset0:60 offset1:65
	ds_read2st64_b32 v[242:243], v11 offset0:70 offset1:75
	s_waitcnt lgkmcnt(11)
	v_mfma_f32_16x16x4_f32 v[136:139], v112, v128, v[136:139]
	v_mfma_f32_16x16x4_f32 v[140:143], v113, v129, v[140:143]
	s_add_u32 s14, s6, 0x500000
	s_addc_u32 s15, s7, 0
	global_load_dword v220, v12, s[14:15] offset:0
	global_load_dword v221, v12, s[14:15] offset:256
	global_load_dword v222, v12, s[14:15] offset:512
	global_load_dword v223, v12, s[14:15] offset:768
	s_waitcnt lgkmcnt(10)
	v_mfma_f32_16x16x4_f32 v[136:139], v114, v130, v[136:139]
	v_mfma_f32_16x16x4_f32 v[140:143], v115, v131, v[140:143]
	s_waitcnt vmcnt(58)
	ds_write_b128 v2, v[52:55] offset:0
	ds_write_b128 v2, v[56:59] offset:10240
	s_add_u32 s10, s0, 0x540000
	s_addc_u32 s11, s1, 0
	global_load_dwordx4 v[52:55], v0, s[10:11]
	global_load_dwordx4 v[56:59], v1, s[10:11]
	s_waitcnt lgkmcnt(11)
	v_mfma_f32_16x16x4_f32 v[136:139], v116, v132, v[136:139]
	v_mfma_f32_16x16x4_f32 v[140:143], v117, v133, v[140:143]
	s_waitcnt lgkmcnt(10)
	v_mfma_f32_16x16x4_f32 v[136:139], v118, v134, v[136:139]
	v_mfma_f32_16x16x4_f32 v[140:143], v119, v135, v[140:143]
	s_add_u32 s16, s8, 0x460000
	s_addc_u32 s17, s9, 0
	s_nop 9
	v_add_f32_e32 v136, v136, v140
	v_add_f32_e32 v137, v137, v141
	v_add_f32_e32 v138, v138, v142
	v_add_f32_e32 v139, v139, v143
	ds_write_b32 v13, v136 offset:2176
	ds_write_b32 v13, v137 offset:2448
	ds_write_b32 v13, v138 offset:2720
	ds_write_b32 v13, v139 offset:2992
	global_store_dword v12, v136, s[16:17] offset:0
	global_store_dword v12, v137, s[16:17] offset:256
	global_store_dword v12, v138, s[16:17] offset:512
	global_store_dword v12, v139, s[16:17] offset:768
	s_waitcnt lgkmcnt(0)
	s_barrier
; #define LAS __attribute__((address_space(3)))
; __device__ __forceinline__ void scan_combine(LAS unsigned char* lds, CArgsP a) {
;     ...
;     for (int g = 1; g <= GL; ++g) {
;         const bool pf = (g + 2 <= GL);
;         float u3 = 0.f;
;         if (pf) { const f32x4* Pn = (const f32x4*)(PM + (size_t)((g + 2) * 8 + h) * 4096); pa = Pn[tid]; pb = Pn[512 + tid]; u3 = UM[((size_t)((g + 2) * 8 + h) * 64 + v) * 64 + kq]; }
;         asm volatile("s_waitcnt lgkmcnt(0)\n\ts_barrier" ::: "memory");
;         const LAS float* Pg = Pl + (g % 3) * 4096 + kq;
;         float acc0 = u1, acc1 = 0.f, acc2 = 0.f, acc3 = 0.f;
;         const int curi = __builtin_bit_cast(int, cur);
; #pragma unroll
;         for (int k = 0; k < 64; k += 4) {
;             const float s0 = __builtin_bit_cast(float, __builtin_amdgcn_readlane(curi, k)), s1 = __builtin_bit_cast(float, __builtin_amdgcn_readlane(curi, k + 1));
;             const float s2 = __builtin_bit_cast(float, __builtin_amdgcn_readlane(curi, k + 2)), s3 = __builtin_bit_cast(float, __builtin_amdgcn_readlane(curi, k + 3));
;             acc0 += s0 * Pg[(k + 0) * 64]; acc1 += s1 * Pg[(k + 1) * 64]; acc2 += s2 * Pg[(k + 2) * 64]; acc3 += s3 * Pg[(k + 3) * 64];
;         }
;         cur = (acc0 + acc1) + (acc2 + acc3);
;         SS[((size_t)((g + 1) * 8 + h) * 64 + v) * 64 + kq] = cur;
;         if (pf) { LAS float* dst = Pl + ((g + 2) % 3) * 4096; *(LAS f32x4*)(dst + 4 * tid) = pa; *(LAS f32x4*)(dst + 2048 + 4 * tid) = pb; }
;         u1 = u2; u2 = u3;
	ds_read2_b32 v[104:105], v9 offset0:0 offset1:4
	ds_read2_b32 v[106:107], v9 offset0:8 offset1:12
	ds_read2_b32 v[108:109], v9 offset0:16 offset1:20
	ds_read2_b32 v[110:111], v9 offset0:24 offset1:28
	ds_read2_b32 v[112:113], v9 offset0:32 offset1:36
	ds_read2_b32 v[114:115], v9 offset0:40 offset1:44
	ds_read2_b32 v[116:117], v9 offset0:48 offset1:52
	ds_read2_b32 v[118:119], v9 offset0:56 offset1:60
	s_waitcnt vmcnt(56)
	s_waitcnt lgkmcnt(7)
	v_mfma_f32_16x16x4_f32 v[136:139], v104, v228, v[224:227]
	v_mfma_f32_16x16x4_f32 v[140:143], v105, v229, 0
	ds_read2st64_b32 v[120:121], v10 offset0:0 offset1:5
	ds_read2st64_b32 v[122:123], v10 offset0:10 offset1:15
	s_waitcnt lgkmcnt(8)
	v_mfma_f32_16x16x4_f32 v[136:139], v106, v230, v[136:139]
	v_mfma_f32_16x16x4_f32 v[140:143], v107, v231, v[140:143]
	ds_read2st64_b32 v[124:125], v10 offset0:20 offset1:25
	ds_read2st64_b32 v[126:127], v10 offset0:30 offset1:35
	s_waitcnt lgkmcnt(9)
	v_mfma_f32_16x16x4_f32 v[136:139], v108, v232, v[136:139]
	v_mfma_f32_16x16x4_f32 v[140:143], v109, v233, v[140:143]
	ds_read2st64_b32 v[128:129], v10 offset0:40 offset1:45
	ds_read2st64_b32 v[130:131], v10 offset0:50 offset1:55
	s_waitcnt lgkmcnt(10)
	v_mfma_f32_16x16x4_f32 v[136:139], v110, v234, v[136:139]
	v_mfma_f32_16x16x4_f32 v[140:143], v111, v235, v[140:143]
	ds_read2st64_b32 v[132:133], v10 offset0:60 offset1:65
	ds_read2st64_b32 v[134:135], v10 offset0:70 offset1:75
	s_waitcnt lgkmcnt(11)
	v_mfma_f32_16x16x4_f32 v[136:139], v112, v236, v[136:139]
	v_mfma_f32_16x16x4_f32 v[140:143], v113, v237, v[140:143]
	s_add_u32 s14, s6, 0x520000
	s_addc_u32 s15, s7, 0
	global_load_dword v224, v12, s[14:15] offset:0
	global_load_dword v225, v12, s[14:15] offset:256
	global_load_dword v226, v12, s[14:15] offset:512
	global_load_dword v227, v12, s[14:15] offset:768
	s_waitcnt lgkmcnt(10)
	v_mfma_f32_16x16x4_f32 v[136:139], v114, v238, v[136:139]
	v_mfma_f32_16x16x4_f32 v[140:143], v115, v239, v[140:143]
	s_waitcnt vmcnt(58)
	ds_write_b128 v2, v[60:63] offset:20480
	ds_write_b128 v2, v[64:67] offset:30720
	s_add_u32 s10, s0, 0x560000
	s_addc_u32 s11, s1, 0
	global_load_dwordx4 v[60:63], v0, s[10:11]
	global_load_dwordx4 v[64:67], v1, s[10:11]
	s_waitcnt lgkmcnt(11)
	v_mfma_f32_16x16x4_f32 v[136:139], v116, v240, v[136:139]
	v_mfma_f32_16x16x4_f32 v[140:143], v117, v241, v[140:143]
	s_waitcnt lgkmcnt(10)
	v_mfma_f32_16x16x4_f32 v[136:139], v118, v242, v[136:139]
	v_mfma_f32_16x16x4_f32 v[140:143], v119, v243, v[140:143]
	s_add_u32 s16, s8, 0x480000
	s_addc_u32 s17, s9, 0
	s_nop 9
	v_add_f32_e32 v136, v136, v140
	v_add_f32_e32 v137, v137, v141
	v_add_f32_e32 v138, v138, v142
	v_add_f32_e32 v139, v139, v143
	ds_write_b32 v13, v136 offset:0
	ds_write_b32 v13, v137 offset:272
	ds_write_b32 v13, v138 offset:544
	ds_write_b32 v13, v139 offset:816
	global_store_dword v12, v136, s[16:17] offset:0
	global_store_dword v12, v137, s[16:17] offset:256
	global_store_dword v12, v138, s[16:17] offset:512
	global_store_dword v12, v139, s[16:17] offset:768
	s_waitcnt lgkmcnt(0)
	s_barrier
	ds_read2_b32 v[104:105], v8 offset0:0 offset1:4
	ds_read2_b32 v[106:107], v8 offset0:8 offset1:12
	ds_read2_b32 v[108:109], v8 offset0:16 offset1:20
	ds_read2_b32 v[110:111], v8 offset0:24 offset1:28
	ds_read2_b32 v[112:113], v8 offset0:32 offset1:36
	ds_read2_b32 v[114:115], v8 offset0:40 offset1:44
	ds_read2_b32 v[116:117], v8 offset0:48 offset1:52
	ds_read2_b32 v[118:119], v8 offset0:56 offset1:60
	s_waitcnt vmcnt(56)
	s_waitcnt lgkmcnt(7)
	v_mfma_f32_16x16x4_f32 v[136:139], v104, v120, v[204:207]
	v_mfma_f32_16x16x4_f32 v[140:143], v105, v121, 0
	ds_read2st64_b32 v[228:229], v11 offset0:0 offset1:5
	ds_read2st64_b32 v[230:231], v11 offset0:10 offset1:15
	s_waitcnt lgkmcnt(8)
	v_mfma_f32_16x16x4_f32 v[136:139], v106, v122, v[136:139]
	v_mfma_f32_16x16x4_f32 v[140:143], v107, v123, v[140:143]
	ds_read2st64_b32 v[232:233], v11 offset0:20 offset1:25
	ds_read2st64_b32 v[234:235], v11 offset0:30 offset1:35
	s_waitcnt lgkmcnt(9)
	v_mfma_f32_16x16x4_f32 v[136:139], v108, v124, v[136:139]
	v_mfma_f32_16x16x4_f32 v[140:143], v109, v125, v[140:143]
	ds_read2st64_b32 v[236:237], v11 offset0:40 offset1:45
	ds_read2st64_b32 v[238:239], v11 offset0:50 offset1:55
	s_waitcnt lgkmcnt(10)
	v_mfma_f32_16x16x4_f32 v[136:139], v110, v126, v[136:139]
	v_mfma_f32_16x16x4_f32 v[140:143], v111, v127, v[140:143]
	ds_read2st64_b32 v[240:241], v11 offset0:60 offset1:65
	ds_read2st64_b32 v[242:243], v11 offset0:70 offset1:75
	s_waitcnt lgkmcnt(11)
	v_mfma_f32_16x16x4_f32 v[136:139], v112, v128, v[136:139]
	v_mfma_f32_16x16x4_f32 v[140:143], v113, v129, v[140:143]
	s_add_u32 s14, s6, 0x540000
	s_addc_u32 s15, s7, 0
	global_load_dword v204, v12, s[14:15] offset:0
	global_load_dword v205, v12, s[14:15] offset:256
	global_load_dword v206, v12, s[14:15] offset:512
	global_load_dword v207, v12, s[14:15] offset:768
	s_waitcnt lgkmcnt(10)
	v_mfma_f32_16x16x4_f32 v[136:139], v114, v130, v[136:139]
	v_mfma_f32_16x16x4_f32 v[140:143], v115, v131, v[140:143]
	s_waitcnt vmcnt(58)
	ds_write_b128 v2, v[68:71] offset:0
	ds_write_b128 v2, v[72:75] offset:10240
	s_add_u32 s10, s0, 0x580000
	s_addc_u32 s11, s1, 0
	global_load_dwordx4 v[68:71], v0, s[10:11]
	global_load_dwordx4 v[72:75], v1, s[10:11]
	s_waitcnt lgkmcnt(11)
	v_mfma_f32_16x16x4_f32 v[136:139], v116, v132, v[136:139]
	v_mfma_f32_16x16x4_f32 v[140:143], v117, v133, v[140:143]
	s_waitcnt lgkmcnt(10)
	v_mfma_f32_16x16x4_f32 v[136:139], v118, v134, v[136:139]
	v_mfma_f32_16x16x4_f32 v[140:143], v119, v135, v[140:143]
	s_add_u32 s16, s8, 0x4a0000
	s_addc_u32 s17, s9, 0
	s_nop 9
	v_add_f32_e32 v136, v136, v140
	v_add_f32_e32 v137, v137, v141
	v_add_f32_e32 v138, v138, v142
	v_add_f32_e32 v139, v139, v143
	ds_write_b32 v13, v136 offset:2176
	ds_write_b32 v13, v137 offset:2448
	ds_write_b32 v13, v138 offset:2720
	ds_write_b32 v13, v139 offset:2992
	global_store_dword v12, v136, s[16:17] offset:0
	global_store_dword v12, v137, s[16:17] offset:256
	global_store_dword v12, v138, s[16:17] offset:512
	global_store_dword v12, v139, s[16:17] offset:768
	s_waitcnt lgkmcnt(0)
	s_barrier
; #define LAS __attribute__((address_space(3)))
; __device__ __forceinline__ void scan_combine(LAS unsigned char* lds, CArgsP a) {
;     ...
;     for (int g = 1; g <= GL; ++g) {
;         const bool pf = (g + 2 <= GL);
;         float u3 = 0.f;
;         if (pf) { const f32x4* Pn = (const f32x4*)(PM + (size_t)((g + 2) * 8 + h) * 4096); pa = Pn[tid]; pb = Pn[512 + tid]; u3 = UM[((size_t)((g + 2) * 8 + h) * 64 + v) * 64 + kq]; }
;         asm volatile("s_waitcnt lgkmcnt(0)\n\ts_barrier" ::: "memory");
;         const LAS float* Pg = Pl + (g % 3) * 4096 + kq;
;         float acc0 = u1, acc1 = 0.f, acc2 = 0.f, acc3 = 0.f;
;         const int curi = __builtin_bit_cast(int, cur);
; #pragma unroll
;         for (int k = 0; k < 64; k += 4) {
;             const float s0 = __builtin_bit_cast(float, __builtin_amdgcn_readlane(curi, k)), s1 = __builtin_bit_cast(float, __builtin_amdgcn_readlane(curi, k + 1));
;             const float s2 = __builtin_bit_cast(float, __builtin_amdgcn_readlane(curi, k + 2)), s3 = __builtin_bit_cast(float, __builtin_amdgcn_readlane(curi, k + 3));
;             acc0 += s0 * Pg[(k + 0) * 64]; acc1 += s1 * Pg[(k + 1) * 64]; acc2 += s2 * Pg[(k + 2) * 64]; acc3 += s3 * Pg[(k + 3) * 64];
;         }
;         cur = (acc0 + acc1) + (acc2 + acc3);
;         SS[((size_t)((g + 1) * 8 + h) * 64 + v) * 64 + kq] = cur;
;         if (pf) { LAS float* dst = Pl + ((g + 2) % 3) * 4096; *(LAS f32x4*)(dst + 4 * tid) = pa; *(LAS f32x4*)(dst + 2048 + 4 * tid) = pb; }
;         u1 = u2; u2 = u3;
	ds_read2_b32 v[104:105], v9 offset0:0 offset1:4
	ds_read2_b32 v[106:107], v9 offset0:8 offset1:12
	ds_read2_b32 v[108:109], v9 offset0:16 offset1:20
	ds_read2_b32 v[110:111], v9 offset0:24 offset1:28
	ds_read2_b32 v[112:113], v9 offset0:32 offset1:36
	ds_read2_b32 v[114:115], v9 offset0:40 offset1:44
	ds_read2_b32 v[116:117], v9 offset0:48 offset1:52
	ds_read2_b32 v[118:119], v9 offset0:56 offset1:60
	s_waitcnt vmcnt(56)
	s_waitcnt lgkmcnt(7)
	v_mfma_f32_16x16x4_f32 v[136:139], v104, v228, v[208:211]
	v_mfma_f32_16x16x4_f32 v[140:143], v105, v229, 0
	ds_read2st64_b32 v[120:121], v10 offset0:0 offset1:5
	ds_read2st64_b32 v[122:123], v10 offset0:10 offset1:15
	s_waitcnt lgkmcnt(8)
	v_mfma_f32_16x16x4_f32 v[136:139], v106, v230, v[136:139]
	v_mfma_f32_16x16x4_f32 v[140:143], v107, v231, v[140:143]
	ds_read2st64_b32 v[124:125], v10 offset0:20 offset1:25
	ds_read2st64_b32 v[126:127], v10 offset0:30 offset1:35
	s_waitcnt lgkmcnt(9)
	v_mfma_f32_16x16x4_f32 v[136:139], v108, v232, v[136:139]
	v_mfma_f32_16x16x4_f32 v[140:143], v109, v233, v[140:143]
	ds_read2st64_b32 v[128:129], v10 offset0:40 offset1:45
	ds_read2st64_b32 v[130:131], v10 offset0:50 offset1:55
	s_waitcnt lgkmcnt(10)
	v_mfma_f32_16x16x4_f32 v[136:139], v110, v234, v[136:139]
	v_mfma_f32_16x16x4_f32 v[140:143], v111, v235, v[140:143]
	ds_read2st64_b32 v[132:133], v10 offset0:60 offset1:65
	ds_read2st64_b32 v[134:135], v10 offset0:70 offset1:75
	s_waitcnt lgkmcnt(11)
	v_mfma_f32_16x16x4_f32 v[136:139], v112, v236, v[136:139]
	v_mfma_f32_16x16x4_f32 v[140:143], v113, v237, v[140:143]
	s_add_u32 s14, s6, 0x560000
	s_addc_u32 s15, s7, 0
	global_load_dword v208, v12, s[14:15] offset:0
	global_load_dword v209, v12, s[14:15] offset:256
	global_load_dword v210, v12, s[14:15] offset:512
	global_load_dword v211, v12, s[14:15] offset:768
	s_waitcnt lgkmcnt(10)
	v_mfma_f32_16x16x4_f32 v[136:139], v114, v238, v[136:139]
	v_mfma_f32_16x16x4_f32 v[140:143], v115, v239, v[140:143]
	s_waitcnt vmcnt(58)
	ds_write_b128 v2, v[76:79] offset:20480
	ds_write_b128 v2, v[80:83] offset:30720
	s_add_u32 s10, s0, 0x5a0000
	s_addc_u32 s11, s1, 0
	global_load_dwordx4 v[76:79], v0, s[10:11]
	global_load_dwordx4 v[80:83], v1, s[10:11]
	s_waitcnt lgkmcnt(11)
	v_mfma_f32_16x16x4_f32 v[136:139], v116, v240, v[136:139]
	v_mfma_f32_16x16x4_f32 v[140:143], v117, v241, v[140:143]
	s_waitcnt lgkmcnt(10)
	v_mfma_f32_16x16x4_f32 v[136:139], v118, v242, v[136:139]
	v_mfma_f32_16x16x4_f32 v[140:143], v119, v243, v[140:143]
	s_add_u32 s16, s8, 0x4c0000
	s_addc_u32 s17, s9, 0
	s_nop 9
	v_add_f32_e32 v136, v136, v140
	v_add_f32_e32 v137, v137, v141
	v_add_f32_e32 v138, v138, v142
	v_add_f32_e32 v139, v139, v143
	ds_write_b32 v13, v136 offset:0
	ds_write_b32 v13, v137 offset:272
	ds_write_b32 v13, v138 offset:544
	ds_write_b32 v13, v139 offset:816
	global_store_dword v12, v136, s[16:17] offset:0
	global_store_dword v12, v137, s[16:17] offset:256
	global_store_dword v12, v138, s[16:17] offset:512
	global_store_dword v12, v139, s[16:17] offset:768
	s_waitcnt lgkmcnt(0)
	s_barrier
	ds_read2_b32 v[104:105], v8 offset0:0 offset1:4
	ds_read2_b32 v[106:107], v8 offset0:8 offset1:12
	ds_read2_b32 v[108:109], v8 offset0:16 offset1:20
	ds_read2_b32 v[110:111], v8 offset0:24 offset1:28
	ds_read2_b32 v[112:113], v8 offset0:32 offset1:36
	ds_read2_b32 v[114:115], v8 offset0:40 offset1:44
	ds_read2_b32 v[116:117], v8 offset0:48 offset1:52
	ds_read2_b32 v[118:119], v8 offset0:56 offset1:60
	s_waitcnt vmcnt(56)
	s_waitcnt lgkmcnt(7)
	v_mfma_f32_16x16x4_f32 v[136:139], v104, v120, v[212:215]
	v_mfma_f32_16x16x4_f32 v[140:143], v105, v121, 0
	ds_read2st64_b32 v[228:229], v11 offset0:0 offset1:5
	ds_read2st64_b32 v[230:231], v11 offset0:10 offset1:15
	s_waitcnt lgkmcnt(8)
	v_mfma_f32_16x16x4_f32 v[136:139], v106, v122, v[136:139]
	v_mfma_f32_16x16x4_f32 v[140:143], v107, v123, v[140:143]
	ds_read2st64_b32 v[232:233], v11 offset0:20 offset1:25
	ds_read2st64_b32 v[234:235], v11 offset0:30 offset1:35
	s_waitcnt lgkmcnt(9)
	v_mfma_f32_16x16x4_f32 v[136:139], v108, v124, v[136:139]
	v_mfma_f32_16x16x4_f32 v[140:143], v109, v125, v[140:143]
	ds_read2st64_b32 v[236:237], v11 offset0:40 offset1:45
	ds_read2st64_b32 v[238:239], v11 offset0:50 offset1:55
	s_waitcnt lgkmcnt(10)
	v_mfma_f32_16x16x4_f32 v[136:139], v110, v126, v[136:139]
	v_mfma_f32_16x16x4_f32 v[140:143], v111, v127, v[140:143]
	ds_read2st64_b32 v[240:241], v11 offset0:60 offset1:65
	ds_read2st64_b32 v[242:243], v11 offset0:70 offset1:75
	s_waitcnt lgkmcnt(11)
	v_mfma_f32_16x16x4_f32 v[136:139], v112, v128, v[136:139]
	v_mfma_f32_16x16x4_f32 v[140:143], v113, v129, v[140:143]
	s_add_u32 s14, s6, 0x580000
	s_addc_u32 s15, s7, 0
	global_load_dword v212, v12, s[14:15] offset:0
	global_load_dword v213, v12, s[14:15] offset:256
	global_load_dword v214, v12, s[14:15] offset:512
	global_load_dword v215, v12, s[14:15] offset:768
	s_waitcnt lgkmcnt(10)
	v_mfma_f32_16x16x4_f32 v[136:139], v114, v130, v[136:139]
	v_mfma_f32_16x16x4_f32 v[140:143], v115, v131, v[140:143]
	s_waitcnt vmcnt(58)
	ds_write_b128 v2, v[84:87] offset:0
	ds_write_b128 v2, v[88:91] offset:10240
	s_add_u32 s10, s0, 0x5c0000
	s_addc_u32 s11, s1, 0
	global_load_dwordx4 v[84:87], v0, s[10:11]
	global_load_dwordx4 v[88:91], v1, s[10:11]
	s_waitcnt lgkmcnt(11)
	v_mfma_f32_16x16x4_f32 v[136:139], v116, v132, v[136:139]
	v_mfma_f32_16x16x4_f32 v[140:143], v117, v133, v[140:143]
	s_waitcnt lgkmcnt(10)
	v_mfma_f32_16x16x4_f32 v[136:139], v118, v134, v[136:139]
	v_mfma_f32_16x16x4_f32 v[140:143], v119, v135, v[140:143]
	s_add_u32 s16, s8, 0x4e0000
	s_addc_u32 s17, s9, 0
	s_nop 9
	v_add_f32_e32 v136, v136, v140
	v_add_f32_e32 v137, v137, v141
	v_add_f32_e32 v138, v138, v142
	v_add_f32_e32 v139, v139, v143
	ds_write_b32 v13, v136 offset:2176
	ds_write_b32 v13, v137 offset:2448
	ds_write_b32 v13, v138 offset:2720
	ds_write_b32 v13, v139 offset:2992
	global_store_dword v12, v136, s[16:17] offset:0
	global_store_dword v12, v137, s[16:17] offset:256
	global_store_dword v12, v138, s[16:17] offset:512
	global_store_dword v12, v139, s[16:17] offset:768
	s_waitcnt lgkmcnt(0)
	s_barrier
; #define LAS __attribute__((address_space(3)))
; __device__ __forceinline__ void scan_combine(LAS unsigned char* lds, CArgsP a) {
;     ...
;     for (int g = 1; g <= GL; ++g) {
;         const bool pf = (g + 2 <= GL);
;         float u3 = 0.f;
;         if (pf) { const f32x4* Pn = (const f32x4*)(PM + (size_t)((g + 2) * 8 + h) * 4096); pa = Pn[tid]; pb = Pn[512 + tid]; u3 = UM[((size_t)((g + 2) * 8 + h) * 64 + v) * 64 + kq]; }
;         asm volatile("s_waitcnt lgkmcnt(0)\n\ts_barrier" ::: "memory");
;         const LAS float* Pg = Pl + (g % 3) * 4096 + kq;
;         float acc0 = u1, acc1 = 0.f, acc2 = 0.f, acc3 = 0.f;
;         const int curi = __builtin_bit_cast(int, cur);
; #pragma unroll
;         for (int k = 0; k < 64; k += 4) {
;             const float s0 = __builtin_bit_cast(float, __builtin_amdgcn_readlane(curi, k)), s1 = __builtin_bit_cast(float, __builtin_amdgcn_readlane(curi, k + 1));
;             const float s2 = __builtin_bit_cast(float, __builtin_amdgcn_readlane(curi, k + 2)), s3 = __builtin_bit_cast(float, __builtin_amdgcn_readlane(curi, k + 3));
;             acc0 += s0 * Pg[(k + 0) * 64]; acc1 += s1 * Pg[(k + 1) * 64]; acc2 += s2 * Pg[(k + 2) * 64]; acc3 += s3 * Pg[(k + 3) * 64];
;         }
;         cur = (acc0 + acc1) + (acc2 + acc3);
;         SS[((size_t)((g + 1) * 8 + h) * 64 + v) * 64 + kq] = cur;
;         if (pf) { LAS float* dst = Pl + ((g + 2) % 3) * 4096; *(LAS f32x4*)(dst + 4 * tid) = pa; *(LAS f32x4*)(dst + 2048 + 4 * tid) = pb; }
;         u1 = u2; u2 = u3;
	ds_read2_b32 v[104:105], v9 offset0:0 offset1:4
	ds_read2_b32 v[106:107], v9 offset0:8 offset1:12
	ds_read2_b32 v[108:109], v9 offset0:16 offset1:20
	ds_read2_b32 v[110:111], v9 offset0:24 offset1:28
	ds_read2_b32 v[112:113], v9 offset0:32 offset1:36
	ds_read2_b32 v[114:115], v9 offset0:40 offset1:44
	ds_read2_b32 v[116:117], v9 offset0:48 offset1:52
	ds_read2_b32 v[118:119], v9 offset0:56 offset1:60
	s_waitcnt vmcnt(56)
	s_waitcnt lgkmcnt(7)
	v_mfma_f32_16x16x4_f32 v[136:139], v104, v228, v[216:219]
	v_mfma_f32_16x16x4_f32 v[140:143], v105, v229, 0
	ds_read2st64_b32 v[120:121], v10 offset0:0 offset1:5
	ds_read2st64_b32 v[122:123], v10 offset0:10 offset1:15
	s_waitcnt lgkmcnt(8)
	v_mfma_f32_16x16x4_f32 v[136:139], v106, v230, v[136:139]
	v_mfma_f32_16x16x4_f32 v[140:143], v107, v231, v[140:143]
	ds_read2st64_b32 v[124:125], v10 offset0:20 offset1:25
	ds_read2st64_b32 v[126:127], v10 offset0:30 offset1:35
	s_waitcnt lgkmcnt(9)
	v_mfma_f32_16x16x4_f32 v[136:139], v108, v232, v[136:139]
	v_mfma_f32_16x16x4_f32 v[140:143], v109, v233, v[140:143]
	ds_read2st64_b32 v[128:129], v10 offset0:40 offset1:45
	ds_read2st64_b32 v[130:131], v10 offset0:50 offset1:55
	s_waitcnt lgkmcnt(10)
	v_mfma_f32_16x16x4_f32 v[136:139], v110, v234, v[136:139]
	v_mfma_f32_16x16x4_f32 v[140:143], v111, v235, v[140:143]
	ds_read2st64_b32 v[132:133], v10 offset0:60 offset1:65
	ds_read2st64_b32 v[134:135], v10 offset0:70 offset1:75
	s_waitcnt lgkmcnt(11)
	v_mfma_f32_16x16x4_f32 v[136:139], v112, v236, v[136:139]
	v_mfma_f32_16x16x4_f32 v[140:143], v113, v237, v[140:143]
	s_add_u32 s14, s6, 0x5a0000
	s_addc_u32 s15, s7, 0
	global_load_dword v216, v12, s[14:15] offset:0
	global_load_dword v217, v12, s[14:15] offset:256
	global_load_dword v218, v12, s[14:15] offset:512
	global_load_dword v219, v12, s[14:15] offset:768
	s_waitcnt lgkmcnt(10)
	v_mfma_f32_16x16x4_f32 v[136:139], v114, v238, v[136:139]
	v_mfma_f32_16x16x4_f32 v[140:143], v115, v239, v[140:143]
	s_waitcnt vmcnt(58)
	ds_write_b128 v2, v[92:95] offset:20480
	ds_write_b128 v2, v[96:99] offset:30720
	s_add_u32 s10, s0, 0x5e0000
	s_addc_u32 s11, s1, 0
	global_load_dwordx4 v[92:95], v0, s[10:11]
	global_load_dwordx4 v[96:99], v1, s[10:11]
	s_waitcnt lgkmcnt(11)
	v_mfma_f32_16x16x4_f32 v[136:139], v116, v240, v[136:139]
	v_mfma_f32_16x16x4_f32 v[140:143], v117, v241, v[140:143]
	s_waitcnt lgkmcnt(10)
	v_mfma_f32_16x16x4_f32 v[136:139], v118, v242, v[136:139]
	v_mfma_f32_16x16x4_f32 v[140:143], v119, v243, v[140:143]
	s_add_u32 s16, s8, 0x500000
	s_addc_u32 s17, s9, 0
	s_nop 9
	v_add_f32_e32 v136, v136, v140
	v_add_f32_e32 v137, v137, v141
	v_add_f32_e32 v138, v138, v142
	v_add_f32_e32 v139, v139, v143
	ds_write_b32 v13, v136 offset:0
	ds_write_b32 v13, v137 offset:272
	ds_write_b32 v13, v138 offset:544
	ds_write_b32 v13, v139 offset:816
	global_store_dword v12, v136, s[16:17] offset:0
	global_store_dword v12, v137, s[16:17] offset:256
	global_store_dword v12, v138, s[16:17] offset:512
	global_store_dword v12, v139, s[16:17] offset:768
	s_waitcnt lgkmcnt(0)
	s_barrier
	ds_read2_b32 v[104:105], v8 offset0:0 offset1:4
	ds_read2_b32 v[106:107], v8 offset0:8 offset1:12
	ds_read2_b32 v[108:109], v8 offset0:16 offset1:20
	ds_read2_b32 v[110:111], v8 offset0:24 offset1:28
	ds_read2_b32 v[112:113], v8 offset0:32 offset1:36
	ds_read2_b32 v[114:115], v8 offset0:40 offset1:44
	ds_read2_b32 v[116:117], v8 offset0:48 offset1:52
	ds_read2_b32 v[118:119], v8 offset0:56 offset1:60
	s_waitcnt vmcnt(56)
	s_waitcnt lgkmcnt(7)
	v_mfma_f32_16x16x4_f32 v[136:139], v104, v120, v[220:223]
	v_mfma_f32_16x16x4_f32 v[140:143], v105, v121, 0
	ds_read2st64_b32 v[228:229], v11 offset0:0 offset1:5
	ds_read2st64_b32 v[230:231], v11 offset0:10 offset1:15
	s_waitcnt lgkmcnt(8)
	v_mfma_f32_16x16x4_f32 v[136:139], v106, v122, v[136:139]
	v_mfma_f32_16x16x4_f32 v[140:143], v107, v123, v[140:143]
	ds_read2st64_b32 v[232:233], v11 offset0:20 offset1:25
	ds_read2st64_b32 v[234:235], v11 offset0:30 offset1:35
	s_waitcnt lgkmcnt(9)
	v_mfma_f32_16x16x4_f32 v[136:139], v108, v124, v[136:139]
	v_mfma_f32_16x16x4_f32 v[140:143], v109, v125, v[140:143]
	ds_read2st64_b32 v[236:237], v11 offset0:40 offset1:45
	ds_read2st64_b32 v[238:239], v11 offset0:50 offset1:55
	s_waitcnt lgkmcnt(10)
	v_mfma_f32_16x16x4_f32 v[136:139], v110, v126, v[136:139]
	v_mfma_f32_16x16x4_f32 v[140:143], v111, v127, v[140:143]
	ds_read2st64_b32 v[240:241], v11 offset0:60 offset1:65
	ds_read2st64_b32 v[242:243], v11 offset0:70 offset1:75
	s_waitcnt lgkmcnt(11)
	v_mfma_f32_16x16x4_f32 v[136:139], v112, v128, v[136:139]
	v_mfma_f32_16x16x4_f32 v[140:143], v113, v129, v[140:143]
	s_add_u32 s14, s6, 0x5c0000
	s_addc_u32 s15, s7, 0
	global_load_dword v220, v12, s[14:15] offset:0
	global_load_dword v221, v12, s[14:15] offset:256
	global_load_dword v222, v12, s[14:15] offset:512
	global_load_dword v223, v12, s[14:15] offset:768
	s_waitcnt lgkmcnt(10)
	v_mfma_f32_16x16x4_f32 v[136:139], v114, v130, v[136:139]
	v_mfma_f32_16x16x4_f32 v[140:143], v115, v131, v[140:143]
	s_waitcnt vmcnt(58)
	ds_write_b128 v2, v[52:55] offset:0
	ds_write_b128 v2, v[56:59] offset:10240
	s_add_u32 s10, s0, 0x600000
	s_addc_u32 s11, s1, 0
	global_load_dwordx4 v[52:55], v0, s[10:11]
	global_load_dwordx4 v[56:59], v1, s[10:11]
	s_waitcnt lgkmcnt(11)
	v_mfma_f32_16x16x4_f32 v[136:139], v116, v132, v[136:139]
	v_mfma_f32_16x16x4_f32 v[140:143], v117, v133, v[140:143]
	s_waitcnt lgkmcnt(10)
	v_mfma_f32_16x16x4_f32 v[136:139], v118, v134, v[136:139]
	v_mfma_f32_16x16x4_f32 v[140:143], v119, v135, v[140:143]
	s_add_u32 s16, s8, 0x520000
	s_addc_u32 s17, s9, 0
	s_nop 9
	v_add_f32_e32 v136, v136, v140
	v_add_f32_e32 v137, v137, v141
	v_add_f32_e32 v138, v138, v142
	v_add_f32_e32 v139, v139, v143
	ds_write_b32 v13, v136 offset:2176
	ds_write_b32 v13, v137 offset:2448
	ds_write_b32 v13, v138 offset:2720
	ds_write_b32 v13, v139 offset:2992
	global_store_dword v12, v136, s[16:17] offset:0
	global_store_dword v12, v137, s[16:17] offset:256
	global_store_dword v12, v138, s[16:17] offset:512
	global_store_dword v12, v139, s[16:17] offset:768
	s_waitcnt lgkmcnt(0)
	s_barrier
; #define LAS __attribute__((address_space(3)))
; __device__ __forceinline__ void scan_combine(LAS unsigned char* lds, CArgsP a) {
;     ...
;     for (int g = 1; g <= GL; ++g) {
;         const bool pf = (g + 2 <= GL);
;         float u3 = 0.f;
;         if (pf) { const f32x4* Pn = (const f32x4*)(PM + (size_t)((g + 2) * 8 + h) * 4096); pa = Pn[tid]; pb = Pn[512 + tid]; u3 = UM[((size_t)((g + 2) * 8 + h) * 64 + v) * 64 + kq]; }
;         asm volatile("s_waitcnt lgkmcnt(0)\n\ts_barrier" ::: "memory");
;         const LAS float* Pg = Pl + (g % 3) * 4096 + kq;
;         float acc0 = u1, acc1 = 0.f, acc2 = 0.f, acc3 = 0.f;
;         const int curi = __builtin_bit_cast(int, cur);
; #pragma unroll
;         for (int k = 0; k < 64; k += 4) {
;             const float s0 = __builtin_bit_cast(float, __builtin_amdgcn_readlane(curi, k)), s1 = __builtin_bit_cast(float, __builtin_amdgcn_readlane(curi, k + 1));
;             const float s2 = __builtin_bit_cast(float, __builtin_amdgcn_readlane(curi, k + 2)), s3 = __builtin_bit_cast(float, __builtin_amdgcn_readlane(curi, k + 3));
;             acc0 += s0 * Pg[(k + 0) * 64]; acc1 += s1 * Pg[(k + 1) * 64]; acc2 += s2 * Pg[(k + 2) * 64]; acc3 += s3 * Pg[(k + 3) * 64];
;         }
;         cur = (acc0 + acc1) + (acc2 + acc3);
;         SS[((size_t)((g + 1) * 8 + h) * 64 + v) * 64 + kq] = cur;
;         if (pf) { LAS float* dst = Pl + ((g + 2) % 3) * 4096; *(LAS f32x4*)(dst + 4 * tid) = pa; *(LAS f32x4*)(dst + 2048 + 4 * tid) = pb; }
;         u1 = u2; u2 = u3;
	ds_read2_b32 v[104:105], v9 offset0:0 offset1:4
	ds_read2_b32 v[106:107], v9 offset0:8 offset1:12
	ds_read2_b32 v[108:109], v9 offset0:16 offset1:20
	ds_read2_b32 v[110:111], v9 offset0:24 offset1:28
	ds_read2_b32 v[112:113], v9 offset0:32 offset1:36
	ds_read2_b32 v[114:115], v9 offset0:40 offset1:44
	ds_read2_b32 v[116:117], v9 offset0:48 offset1:52
	ds_read2_b32 v[118:119], v9 offset0:56 offset1:60
	s_waitcnt vmcnt(56)
	s_waitcnt lgkmcnt(7)
	v_mfma_f32_16x16x4_f32 v[136:139], v104, v228, v[224:227]
	v_mfma_f32_16x16x4_f32 v[140:143], v105, v229, 0
	ds_read2st64_b32 v[120:121], v10 offset0:0 offset1:5
	ds_read2st64_b32 v[122:123], v10 offset0:10 offset1:15
	s_waitcnt lgkmcnt(8)
	v_mfma_f32_16x16x4_f32 v[136:139], v106, v230, v[136:139]
	v_mfma_f32_16x16x4_f32 v[140:143], v107, v231, v[140:143]
	ds_read2st64_b32 v[124:125], v10 offset0:20 offset1:25
	ds_read2st64_b32 v[126:127], v10 offset0:30 offset1:35
	s_waitcnt lgkmcnt(9)
	v_mfma_f32_16x16x4_f32 v[136:139], v108, v232, v[136:139]
	v_mfma_f32_16x16x4_f32 v[140:143], v109, v233, v[140:143]
	ds_read2st64_b32 v[128:129], v10 offset0:40 offset1:45
	ds_read2st64_b32 v[130:131], v10 offset0:50 offset1:55
	s_waitcnt lgkmcnt(10)
	v_mfma_f32_16x16x4_f32 v[136:139], v110, v234, v[136:139]
	v_mfma_f32_16x16x4_f32 v[140:143], v111, v235, v[140:143]
	ds_read2st64_b32 v[132:133], v10 offset0:60 offset1:65
	ds_read2st64_b32 v[134:135], v10 offset0:70 offset1:75
	s_waitcnt lgkmcnt(11)
	v_mfma_f32_16x16x4_f32 v[136:139], v112, v236, v[136:139]
	v_mfma_f32_16x16x4_f32 v[140:143], v113, v237, v[140:143]
	s_add_u32 s14, s6, 0x5e0000
	s_addc_u32 s15, s7, 0
	global_load_dword v224, v12, s[14:15] offset:0
	global_load_dword v225, v12, s[14:15] offset:256
	global_load_dword v226, v12, s[14:15] offset:512
	global_load_dword v227, v12, s[14:15] offset:768
	s_waitcnt lgkmcnt(10)
	v_mfma_f32_16x16x4_f32 v[136:139], v114, v238, v[136:139]
	v_mfma_f32_16x16x4_f32 v[140:143], v115, v239, v[140:143]
	s_waitcnt vmcnt(58)
	ds_write_b128 v2, v[60:63] offset:20480
	ds_write_b128 v2, v[64:67] offset:30720
	s_add_u32 s10, s0, 0x620000
	s_addc_u32 s11, s1, 0
	global_load_dwordx4 v[60:63], v0, s[10:11]
	global_load_dwordx4 v[64:67], v1, s[10:11]
	s_waitcnt lgkmcnt(11)
	v_mfma_f32_16x16x4_f32 v[136:139], v116, v240, v[136:139]
	v_mfma_f32_16x16x4_f32 v[140:143], v117, v241, v[140:143]
	s_waitcnt lgkmcnt(10)
	v_mfma_f32_16x16x4_f32 v[136:139], v118, v242, v[136:139]
	v_mfma_f32_16x16x4_f32 v[140:143], v119, v243, v[140:143]
	s_add_u32 s16, s8, 0x540000
	s_addc_u32 s17, s9, 0
	s_nop 9
	v_add_f32_e32 v136, v136, v140
	v_add_f32_e32 v137, v137, v141
	v_add_f32_e32 v138, v138, v142
	v_add_f32_e32 v139, v139, v143
	ds_write_b32 v13, v136 offset:0
	ds_write_b32 v13, v137 offset:272
	ds_write_b32 v13, v138 offset:544
	ds_write_b32 v13, v139 offset:816
	global_store_dword v12, v136, s[16:17] offset:0
	global_store_dword v12, v137, s[16:17] offset:256
	global_store_dword v12, v138, s[16:17] offset:512
	global_store_dword v12, v139, s[16:17] offset:768
	s_waitcnt lgkmcnt(0)
	s_barrier
	ds_read2_b32 v[104:105], v8 offset0:0 offset1:4
	ds_read2_b32 v[106:107], v8 offset0:8 offset1:12
	ds_read2_b32 v[108:109], v8 offset0:16 offset1:20
	ds_read2_b32 v[110:111], v8 offset0:24 offset1:28
	ds_read2_b32 v[112:113], v8 offset0:32 offset1:36
	ds_read2_b32 v[114:115], v8 offset0:40 offset1:44
	ds_read2_b32 v[116:117], v8 offset0:48 offset1:52
	ds_read2_b32 v[118:119], v8 offset0:56 offset1:60
	s_waitcnt vmcnt(56)
	s_waitcnt lgkmcnt(7)
	v_mfma_f32_16x16x4_f32 v[136:139], v104, v120, v[204:207]
	v_mfma_f32_16x16x4_f32 v[140:143], v105, v121, 0
	ds_read2st64_b32 v[228:229], v11 offset0:0 offset1:5
	ds_read2st64_b32 v[230:231], v11 offset0:10 offset1:15
	s_waitcnt lgkmcnt(8)
	v_mfma_f32_16x16x4_f32 v[136:139], v106, v122, v[136:139]
	v_mfma_f32_16x16x4_f32 v[140:143], v107, v123, v[140:143]
	ds_read2st64_b32 v[232:233], v11 offset0:20 offset1:25
	ds_read2st64_b32 v[234:235], v11 offset0:30 offset1:35
	s_waitcnt lgkmcnt(9)
	v_mfma_f32_16x16x4_f32 v[136:139], v108, v124, v[136:139]
	v_mfma_f32_16x16x4_f32 v[140:143], v109, v125, v[140:143]
	ds_read2st64_b32 v[236:237], v11 offset0:40 offset1:45
	ds_read2st64_b32 v[238:239], v11 offset0:50 offset1:55
	s_waitcnt lgkmcnt(10)
	v_mfma_f32_16x16x4_f32 v[136:139], v110, v126, v[136:139]
	v_mfma_f32_16x16x4_f32 v[140:143], v111, v127, v[140:143]
	ds_read2st64_b32 v[240:241], v11 offset0:60 offset1:65
	ds_read2st64_b32 v[242:243], v11 offset0:70 offset1:75
	s_waitcnt lgkmcnt(11)
	v_mfma_f32_16x16x4_f32 v[136:139], v112, v128, v[136:139]
	v_mfma_f32_16x16x4_f32 v[140:143], v113, v129, v[140:143]
	s_add_u32 s14, s6, 0x600000
	s_addc_u32 s15, s7, 0
	global_load_dword v204, v12, s[14:15] offset:0
	global_load_dword v205, v12, s[14:15] offset:256
	global_load_dword v206, v12, s[14:15] offset:512
	global_load_dword v207, v12, s[14:15] offset:768
	s_waitcnt lgkmcnt(10)
	v_mfma_f32_16x16x4_f32 v[136:139], v114, v130, v[136:139]
	v_mfma_f32_16x16x4_f32 v[140:143], v115, v131, v[140:143]
	s_waitcnt vmcnt(58)
	ds_write_b128 v2, v[68:71] offset:0
	ds_write_b128 v2, v[72:75] offset:10240
	s_add_u32 s10, s0, 0x640000
	s_addc_u32 s11, s1, 0
	global_load_dwordx4 v[68:71], v0, s[10:11]
	global_load_dwordx4 v[72:75], v1, s[10:11]
	s_waitcnt lgkmcnt(11)
	v_mfma_f32_16x16x4_f32 v[136:139], v116, v132, v[136:139]
	v_mfma_f32_16x16x4_f32 v[140:143], v117, v133, v[140:143]
	s_waitcnt lgkmcnt(10)
	v_mfma_f32_16x16x4_f32 v[136:139], v118, v134, v[136:139]
	v_mfma_f32_16x16x4_f32 v[140:143], v119, v135, v[140:143]
	s_add_u32 s16, s8, 0x560000
	s_addc_u32 s17, s9, 0
	s_nop 9
	v_add_f32_e32 v136, v136, v140
	v_add_f32_e32 v137, v137, v141
	v_add_f32_e32 v138, v138, v142
	v_add_f32_e32 v139, v139, v143
	ds_write_b32 v13, v136 offset:2176
	ds_write_b32 v13, v137 offset:2448
	ds_write_b32 v13, v138 offset:2720
	ds_write_b32 v13, v139 offset:2992
	global_store_dword v12, v136, s[16:17] offset:0
	global_store_dword v12, v137, s[16:17] offset:256
	global_store_dword v12, v138, s[16:17] offset:512
	global_store_dword v12, v139, s[16:17] offset:768
	s_waitcnt lgkmcnt(0)
	s_barrier
; #define LAS __attribute__((address_space(3)))
; __device__ __forceinline__ void scan_combine(LAS unsigned char* lds, CArgsP a) {
;     ...
;     for (int g = 1; g <= GL; ++g) {
;         const bool pf = (g + 2 <= GL);
;         float u3 = 0.f;
;         if (pf) { const f32x4* Pn = (const f32x4*)(PM + (size_t)((g + 2) * 8 + h) * 4096); pa = Pn[tid]; pb = Pn[512 + tid]; u3 = UM[((size_t)((g + 2) * 8 + h) * 64 + v) * 64 + kq]; }
;         asm volatile("s_waitcnt lgkmcnt(0)\n\ts_barrier" ::: "memory");
;         const LAS float* Pg = Pl + (g % 3) * 4096 + kq;
;         float acc0 = u1, acc1 = 0.f, acc2 = 0.f, acc3 = 0.f;
;         const int curi = __builtin_bit_cast(int, cur);
; #pragma unroll
;         for (int k = 0; k < 64; k += 4) {
;             const float s0 = __builtin_bit_cast(float, __builtin_amdgcn_readlane(curi, k)), s1 = __builtin_bit_cast(float, __builtin_amdgcn_readlane(curi, k + 1));
;             const float s2 = __builtin_bit_cast(float, __builtin_amdgcn_readlane(curi, k + 2)), s3 = __builtin_bit_cast(float, __builtin_amdgcn_readlane(curi, k + 3));
;             acc0 += s0 * Pg[(k + 0) * 64]; acc1 += s1 * Pg[(k + 1) * 64]; acc2 += s2 * Pg[(k + 2) * 64]; acc3 += s3 * Pg[(k + 3) * 64];
;         }
;         cur = (acc0 + acc1) + (acc2 + acc3);
;         SS[((size_t)((g + 1) * 8 + h) * 64 + v) * 64 + kq] = cur;
;         if (pf) { LAS float* dst = Pl + ((g + 2) % 3) * 4096; *(LAS f32x4*)(dst + 4 * tid) = pa; *(LAS f32x4*)(dst + 2048 + 4 * tid) = pb; }
;         u1 = u2; u2 = u3;
;     }
	ds_read2_b32 v[104:105], v9 offset0:0 offset1:4
	ds_read2_b32 v[106:107], v9 offset0:8 offset1:12
	ds_read2_b32 v[108:109], v9 offset0:16 offset1:20
	ds_read2_b32 v[110:111], v9 offset0:24 offset1:28
	ds_read2_b32 v[112:113], v9 offset0:32 offset1:36
	ds_read2_b32 v[114:115], v9 offset0:40 offset1:44
	ds_read2_b32 v[116:117], v9 offset0:48 offset1:52
	ds_read2_b32 v[118:119], v9 offset0:56 offset1:60
	s_waitcnt vmcnt(56)
	s_waitcnt lgkmcnt(7)
	v_mfma_f32_16x16x4_f32 v[136:139], v104, v228, v[208:211]
	v_mfma_f32_16x16x4_f32 v[140:143], v105, v229, 0
	ds_read2st64_b32 v[120:121], v10 offset0:0 offset1:5
	ds_read2st64_b32 v[122:123], v10 offset0:10 offset1:15
	s_waitcnt lgkmcnt(8)
	v_mfma_f32_16x16x4_f32 v[136:139], v106, v230, v[136:139]
	v_mfma_f32_16x16x4_f32 v[140:143], v107, v231, v[140:143]
	ds_read2st64_b32 v[124:125], v10 offset0:20 offset1:25
	ds_read2st64_b32 v[126:127], v10 offset0:30 offset1:35
	s_waitcnt lgkmcnt(9)
	v_mfma_f32_16x16x4_f32 v[136:139], v108, v232, v[136:139]
	v_mfma_f32_16x16x4_f32 v[140:143], v109, v233, v[140:143]
	ds_read2st64_b32 v[128:129], v10 offset0:40 offset1:45
	ds_read2st64_b32 v[130:131], v10 offset0:50 offset1:55
	s_waitcnt lgkmcnt(10)
	v_mfma_f32_16x16x4_f32 v[136:139], v110, v234, v[136:139]
	v_mfma_f32_16x16x4_f32 v[140:143], v111, v235, v[140:143]
	ds_read2st64_b32 v[132:133], v10 offset0:60 offset1:65
	ds_read2st64_b32 v[134:135], v10 offset0:70 offset1:75
	s_waitcnt lgkmcnt(11)
	v_mfma_f32_16x16x4_f32 v[136:139], v112, v236, v[136:139]
	v_mfma_f32_16x16x4_f32 v[140:143], v113, v237, v[140:143]
	s_add_u32 s14, s6, 0x620000
	s_addc_u32 s15, s7, 0
	global_load_dword v208, v12, s[14:15] offset:0
	global_load_dword v209, v12, s[14:15] offset:256
	global_load_dword v210, v12, s[14:15] offset:512
	global_load_dword v211, v12, s[14:15] offset:768
	s_waitcnt lgkmcnt(10)
	v_mfma_f32_16x16x4_f32 v[136:139], v114, v238, v[136:139]
	v_mfma_f32_16x16x4_f32 v[140:143], v115, v239, v[140:143]
	s_waitcnt vmcnt(58)
	ds_write_b128 v2, v[76:79] offset:20480
	ds_write_b128 v2, v[80:83] offset:30720
	s_add_u32 s10, s0, 0x660000
	s_addc_u32 s11, s1, 0
	global_load_dwordx4 v[76:79], v0, s[10:11]
	global_load_dwordx4 v[80:83], v1, s[10:11]
	s_waitcnt lgkmcnt(11)
	v_mfma_f32_16x16x4_f32 v[136:139], v116, v240, v[136:139]
	v_mfma_f32_16x16x4_f32 v[140:143], v117, v241, v[140:143]
	s_waitcnt lgkmcnt(10)
	v_mfma_f32_16x16x4_f32 v[136:139], v118, v242, v[136:139]
	v_mfma_f32_16x16x4_f32 v[140:143], v119, v243, v[140:143]
	s_add_u32 s16, s8, 0x580000
	s_addc_u32 s17, s9, 0
	s_nop 9
	v_add_f32_e32 v136, v136, v140
	v_add_f32_e32 v137, v137, v141
	v_add_f32_e32 v138, v138, v142
	v_add_f32_e32 v139, v139, v143
	ds_write_b32 v13, v136 offset:0
	ds_write_b32 v13, v137 offset:272
	ds_write_b32 v13, v138 offset:544
	ds_write_b32 v13, v139 offset:816
	global_store_dword v12, v136, s[16:17] offset:0
	global_store_dword v12, v137, s[16:17] offset:256
	global_store_dword v12, v138, s[16:17] offset:512
	global_store_dword v12, v139, s[16:17] offset:768
	s_waitcnt lgkmcnt(0)
	s_barrier
	ds_read2_b32 v[104:105], v8 offset0:0 offset1:4
	ds_read2_b32 v[106:107], v8 offset0:8 offset1:12
	ds_read2_b32 v[108:109], v8 offset0:16 offset1:20
	ds_read2_b32 v[110:111], v8 offset0:24 offset1:28
	ds_read2_b32 v[112:113], v8 offset0:32 offset1:36
	ds_read2_b32 v[114:115], v8 offset0:40 offset1:44
	ds_read2_b32 v[116:117], v8 offset0:48 offset1:52
	ds_read2_b32 v[118:119], v8 offset0:56 offset1:60
	s_waitcnt vmcnt(56)
	s_waitcnt lgkmcnt(7)
	v_mfma_f32_16x16x4_f32 v[136:139], v104, v120, v[212:215]
	v_mfma_f32_16x16x4_f32 v[140:143], v105, v121, 0
	ds_read2st64_b32 v[228:229], v11 offset0:0 offset1:5
	ds_read2st64_b32 v[230:231], v11 offset0:10 offset1:15
	s_waitcnt lgkmcnt(8)
	v_mfma_f32_16x16x4_f32 v[136:139], v106, v122, v[136:139]
	v_mfma_f32_16x16x4_f32 v[140:143], v107, v123, v[140:143]
	ds_read2st64_b32 v[232:233], v11 offset0:20 offset1:25
	ds_read2st64_b32 v[234:235], v11 offset0:30 offset1:35
	s_waitcnt lgkmcnt(9)
	v_mfma_f32_16x16x4_f32 v[136:139], v108, v124, v[136:139]
	v_mfma_f32_16x16x4_f32 v[140:143], v109, v125, v[140:143]
	ds_read2st64_b32 v[236:237], v11 offset0:40 offset1:45
	ds_read2st64_b32 v[238:239], v11 offset0:50 offset1:55
	s_waitcnt lgkmcnt(10)
	v_mfma_f32_16x16x4_f32 v[136:139], v110, v126, v[136:139]
	v_mfma_f32_16x16x4_f32 v[140:143], v111, v127, v[140:143]
	ds_read2st64_b32 v[240:241], v11 offset0:60 offset1:65
	ds_read2st64_b32 v[242:243], v11 offset0:70 offset1:75
	s_waitcnt lgkmcnt(11)
	v_mfma_f32_16x16x4_f32 v[136:139], v112, v128, v[136:139]
	v_mfma_f32_16x16x4_f32 v[140:143], v113, v129, v[140:143]
	s_add_u32 s14, s6, 0x640000
	s_addc_u32 s15, s7, 0
	global_load_dword v212, v12, s[14:15] offset:0
	global_load_dword v213, v12, s[14:15] offset:256
	global_load_dword v214, v12, s[14:15] offset:512
	global_load_dword v215, v12, s[14:15] offset:768
	s_waitcnt lgkmcnt(10)
	v_mfma_f32_16x16x4_f32 v[136:139], v114, v130, v[136:139]
	v_mfma_f32_16x16x4_f32 v[140:143], v115, v131, v[140:143]
	s_waitcnt vmcnt(58)
	ds_write_b128 v2, v[84:87] offset:0
	ds_write_b128 v2, v[88:91] offset:10240
	s_add_u32 s10, s0, 0x680000
	s_addc_u32 s11, s1, 0
	global_load_dwordx4 v[84:87], v0, s[10:11]
	global_load_dwordx4 v[88:91], v1, s[10:11]
	s_waitcnt lgkmcnt(11)
	v_mfma_f32_16x16x4_f32 v[136:139], v116, v132, v[136:139]
	v_mfma_f32_16x16x4_f32 v[140:143], v117, v133, v[140:143]
	s_waitcnt lgkmcnt(10)
	v_mfma_f32_16x16x4_f32 v[136:139], v118, v134, v[136:139]
	v_mfma_f32_16x16x4_f32 v[140:143], v119, v135, v[140:143]
	s_add_u32 s16, s8, 0x5a0000
	s_addc_u32 s17, s9, 0
	s_nop 9
	v_add_f32_e32 v136, v136, v140
	v_add_f32_e32 v137, v137, v141
	v_add_f32_e32 v138, v138, v142
	v_add_f32_e32 v139, v139, v143
	ds_write_b32 v13, v136 offset:2176
	ds_write_b32 v13, v137 offset:2448
	ds_write_b32 v13, v138 offset:2720
	ds_write_b32 v13, v139 offset:2992
	global_store_dword v12, v136, s[16:17] offset:0
	global_store_dword v12, v137, s[16:17] offset:256
	global_store_dword v12, v138, s[16:17] offset:512
	global_store_dword v12, v139, s[16:17] offset:768
	s_waitcnt lgkmcnt(0)
	s_barrier
; #define LAS __attribute__((address_space(3)))
; __device__ __forceinline__ void scan_combine(LAS unsigned char* lds, CArgsP a) {
;     ...
;     for (int g = 1; g <= GL; ++g) {
;         const bool pf = (g + 2 <= GL);
;         float u3 = 0.f;
;         if (pf) { const f32x4* Pn = (const f32x4*)(PM + (size_t)((g + 2) * 8 + h) * 4096); pa = Pn[tid]; pb = Pn[512 + tid]; u3 = UM[((size_t)((g + 2) * 8 + h) * 64 + v) * 64 + kq]; }
;         asm volatile("s_waitcnt lgkmcnt(0)\n\ts_barrier" ::: "memory");
;         const LAS float* Pg = Pl + (g % 3) * 4096 + kq;
;         float acc0 = u1, acc1 = 0.f, acc2 = 0.f, acc3 = 0.f;
;         const int curi = __builtin_bit_cast(int, cur);
; #pragma unroll
;         for (int k = 0; k < 64; k += 4) {
;             const float s0 = __builtin_bit_cast(float, __builtin_amdgcn_readlane(curi, k)), s1 = __builtin_bit_cast(float, __builtin_amdgcn_readlane(curi, k + 1));
;             const float s2 = __builtin_bit_cast(float, __builtin_amdgcn_readlane(curi, k + 2)), s3 = __builtin_bit_cast(float, __builtin_amdgcn_readlane(curi, k + 3));
;             acc0 += s0 * Pg[(k + 0) * 64]; acc1 += s1 * Pg[(k + 1) * 64]; acc2 += s2 * Pg[(k + 2) * 64]; acc3 += s3 * Pg[(k + 3) * 64];
;         }
;         cur = (acc0 + acc1) + (acc2 + acc3);
;         SS[((size_t)((g + 1) * 8 + h) * 64 + v) * 64 + kq] = cur;
;         if (pf) { LAS float* dst = Pl + ((g + 2) % 3) * 4096; *(LAS f32x4*)(dst + 4 * tid) = pa; *(LAS f32x4*)(dst + 2048 + 4 * tid) = pb; }
;         u1 = u2; u2 = u3;
;     }
	ds_read2_b32 v[104:105], v9 offset0:0 offset1:4
	ds_read2_b32 v[106:107], v9 offset0:8 offset1:12
	ds_read2_b32 v[108:109], v9 offset0:16 offset1:20
	ds_read2_b32 v[110:111], v9 offset0:24 offset1:28
	ds_read2_b32 v[112:113], v9 offset0:32 offset1:36
	ds_read2_b32 v[114:115], v9 offset0:40 offset1:44
	ds_read2_b32 v[116:117], v9 offset0:48 offset1:52
	ds_read2_b32 v[118:119], v9 offset0:56 offset1:60
	s_waitcnt vmcnt(56)
	s_waitcnt lgkmcnt(7)
	v_mfma_f32_16x16x4_f32 v[136:139], v104, v228, v[216:219]
	v_mfma_f32_16x16x4_f32 v[140:143], v105, v229, 0
	ds_read2st64_b32 v[120:121], v10 offset0:0 offset1:5
	ds_read2st64_b32 v[122:123], v10 offset0:10 offset1:15
	s_waitcnt lgkmcnt(8)
	v_mfma_f32_16x16x4_f32 v[136:139], v106, v230, v[136:139]
	v_mfma_f32_16x16x4_f32 v[140:143], v107, v231, v[140:143]
	ds_read2st64_b32 v[124:125], v10 offset0:20 offset1:25
	ds_read2st64_b32 v[126:127], v10 offset0:30 offset1:35
	s_waitcnt lgkmcnt(9)
	v_mfma_f32_16x16x4_f32 v[136:139], v108, v232, v[136:139]
	v_mfma_f32_16x16x4_f32 v[140:143], v109, v233, v[140:143]
	ds_read2st64_b32 v[128:129], v10 offset0:40 offset1:45
	ds_read2st64_b32 v[130:131], v10 offset0:50 offset1:55
	s_waitcnt lgkmcnt(10)
	v_mfma_f32_16x16x4_f32 v[136:139], v110, v234, v[136:139]
	v_mfma_f32_16x16x4_f32 v[140:143], v111, v235, v[140:143]
	ds_read2st64_b32 v[132:133], v10 offset0:60 offset1:65
	ds_read2st64_b32 v[134:135], v10 offset0:70 offset1:75
	s_waitcnt lgkmcnt(11)
	v_mfma_f32_16x16x4_f32 v[136:139], v112, v236, v[136:139]
	v_mfma_f32_16x16x4_f32 v[140:143], v113, v237, v[140:143]
	s_add_u32 s14, s6, 0x660000
	s_addc_u32 s15, s7, 0
	global_load_dword v216, v12, s[14:15] offset:0
	global_load_dword v217, v12, s[14:15] offset:256
	global_load_dword v218, v12, s[14:15] offset:512
	global_load_dword v219, v12, s[14:15] offset:768
	s_waitcnt lgkmcnt(10)
	v_mfma_f32_16x16x4_f32 v[136:139], v114, v238, v[136:139]
	v_mfma_f32_16x16x4_f32 v[140:143], v115, v239, v[140:143]
	s_waitcnt vmcnt(58)
	ds_write_b128 v2, v[92:95] offset:20480
	ds_write_b128 v2, v[96:99] offset:30720
	s_add_u32 s10, s0, 0x6a0000
	s_addc_u32 s11, s1, 0
	global_load_dwordx4 v[92:95], v0, s[10:11]
	global_load_dwordx4 v[96:99], v1, s[10:11]
	s_waitcnt lgkmcnt(11)
	v_mfma_f32_16x16x4_f32 v[136:139], v116, v240, v[136:139]
	v_mfma_f32_16x16x4_f32 v[140:143], v117, v241, v[140:143]
	s_waitcnt lgkmcnt(10)
	v_mfma_f32_16x16x4_f32 v[136:139], v118, v242, v[136:139]
	v_mfma_f32_16x16x4_f32 v[140:143], v119, v243, v[140:143]
	s_add_u32 s16, s8, 0x5c0000
	s_addc_u32 s17, s9, 0
	s_nop 9
	v_add_f32_e32 v136, v136, v140
	v_add_f32_e32 v137, v137, v141
	v_add_f32_e32 v138, v138, v142
	v_add_f32_e32 v139, v139, v143
	ds_write_b32 v13, v136 offset:0
	ds_write_b32 v13, v137 offset:272
	ds_write_b32 v13, v138 offset:544
	ds_write_b32 v13, v139 offset:816
	global_store_dword v12, v136, s[16:17] offset:0
	global_store_dword v12, v137, s[16:17] offset:256
	global_store_dword v12, v138, s[16:17] offset:512
	global_store_dword v12, v139, s[16:17] offset:768
	s_waitcnt lgkmcnt(0)
	s_barrier
	ds_read2_b32 v[104:105], v8 offset0:0 offset1:4
	ds_read2_b32 v[106:107], v8 offset0:8 offset1:12
	ds_read2_b32 v[108:109], v8 offset0:16 offset1:20
	ds_read2_b32 v[110:111], v8 offset0:24 offset1:28
	ds_read2_b32 v[112:113], v8 offset0:32 offset1:36
	ds_read2_b32 v[114:115], v8 offset0:40 offset1:44
	ds_read2_b32 v[116:117], v8 offset0:48 offset1:52
	ds_read2_b32 v[118:119], v8 offset0:56 offset1:60
	s_waitcnt vmcnt(56)
	s_waitcnt lgkmcnt(7)
	v_mfma_f32_16x16x4_f32 v[136:139], v104, v120, v[220:223]
	v_mfma_f32_16x16x4_f32 v[140:143], v105, v121, 0
	ds_read2st64_b32 v[228:229], v11 offset0:0 offset1:5
	ds_read2st64_b32 v[230:231], v11 offset0:10 offset1:15
	s_waitcnt lgkmcnt(8)
	v_mfma_f32_16x16x4_f32 v[136:139], v106, v122, v[136:139]
	v_mfma_f32_16x16x4_f32 v[140:143], v107, v123, v[140:143]
	ds_read2st64_b32 v[232:233], v11 offset0:20 offset1:25
	ds_read2st64_b32 v[234:235], v11 offset0:30 offset1:35
	s_waitcnt lgkmcnt(9)
	v_mfma_f32_16x16x4_f32 v[136:139], v108, v124, v[136:139]
	v_mfma_f32_16x16x4_f32 v[140:143], v109, v125, v[140:143]
	ds_read2st64_b32 v[236:237], v11 offset0:40 offset1:45
	ds_read2st64_b32 v[238:239], v11 offset0:50 offset1:55
	s_waitcnt lgkmcnt(10)
	v_mfma_f32_16x16x4_f32 v[136:139], v110, v126, v[136:139]
	v_mfma_f32_16x16x4_f32 v[140:143], v111, v127, v[140:143]
	ds_read2st64_b32 v[240:241], v11 offset0:60 offset1:65
	ds_read2st64_b32 v[242:243], v11 offset0:70 offset1:75
	s_waitcnt lgkmcnt(11)
	v_mfma_f32_16x16x4_f32 v[136:139], v112, v128, v[136:139]
	v_mfma_f32_16x16x4_f32 v[140:143], v113, v129, v[140:143]
	s_add_u32 s14, s6, 0x680000
	s_addc_u32 s15, s7, 0
	global_load_dword v220, v12, s[14:15] offset:0
	global_load_dword v221, v12, s[14:15] offset:256
	global_load_dword v222, v12, s[14:15] offset:512
	global_load_dword v223, v12, s[14:15] offset:768
	s_waitcnt lgkmcnt(10)
	v_mfma_f32_16x16x4_f32 v[136:139], v114, v130, v[136:139]
	v_mfma_f32_16x16x4_f32 v[140:143], v115, v131, v[140:143]
	s_waitcnt vmcnt(58)
	ds_write_b128 v2, v[52:55] offset:0
	ds_write_b128 v2, v[56:59] offset:10240
	s_add_u32 s10, s0, 0x6c0000
	s_addc_u32 s11, s1, 0
	global_load_dwordx4 v[52:55], v0, s[10:11]
	global_load_dwordx4 v[56:59], v1, s[10:11]
	s_waitcnt lgkmcnt(11)
	v_mfma_f32_16x16x4_f32 v[136:139], v116, v132, v[136:139]
	v_mfma_f32_16x16x4_f32 v[140:143], v117, v133, v[140:143]
	s_waitcnt lgkmcnt(10)
	v_mfma_f32_16x16x4_f32 v[136:139], v118, v134, v[136:139]
	v_mfma_f32_16x16x4_f32 v[140:143], v119, v135, v[140:143]
	s_add_u32 s16, s8, 0x5e0000
	s_addc_u32 s17, s9, 0
	s_nop 9
	v_add_f32_e32 v136, v136, v140
	v_add_f32_e32 v137, v137, v141
	v_add_f32_e32 v138, v138, v142
	v_add_f32_e32 v139, v139, v143
	ds_write_b32 v13, v136 offset:2176
	ds_write_b32 v13, v137 offset:2448
	ds_write_b32 v13, v138 offset:2720
	ds_write_b32 v13, v139 offset:2992
	global_store_dword v12, v136, s[16:17] offset:0
	global_store_dword v12, v137, s[16:17] offset:256
	global_store_dword v12, v138, s[16:17] offset:512
	global_store_dword v12, v139, s[16:17] offset:768
	s_waitcnt lgkmcnt(0)
	s_barrier
; #define LAS __attribute__((address_space(3)))
; __device__ __forceinline__ void scan_combine(LAS unsigned char* lds, CArgsP a) {
;     ...
;     for (int g = 1; g <= GL; ++g) {
;         const bool pf = (g + 2 <= GL);
;         float u3 = 0.f;
;         if (pf) { const f32x4* Pn = (const f32x4*)(PM + (size_t)((g + 2) * 8 + h) * 4096); pa = Pn[tid]; pb = Pn[512 + tid]; u3 = UM[((size_t)((g + 2) * 8 + h) * 64 + v) * 64 + kq]; }
;         asm volatile("s_waitcnt lgkmcnt(0)\n\ts_barrier" ::: "memory");
;         const LAS float* Pg = Pl + (g % 3) * 4096 + kq;
;         float acc0 = u1, acc1 = 0.f, acc2 = 0.f, acc3 = 0.f;
;         const int curi = __builtin_bit_cast(int, cur);
; #pragma unroll
;         for (int k = 0; k < 64; k += 4) {
;             const float s0 = __builtin_bit_cast(float, __builtin_amdgcn_readlane(curi, k)), s1 = __builtin_bit_cast(float, __builtin_amdgcn_readlane(curi, k + 1));
;             const float s2 = __builtin_bit_cast(float, __builtin_amdgcn_readlane(curi, k + 2)), s3 = __builtin_bit_cast(float, __builtin_amdgcn_readlane(curi, k + 3));
;             acc0 += s0 * Pg[(k + 0) * 64]; acc1 += s1 * Pg[(k + 1) * 64]; acc2 += s2 * Pg[(k + 2) * 64]; acc3 += s3 * Pg[(k + 3) * 64];
;         }
;         cur = (acc0 + acc1) + (acc2 + acc3);
;         SS[((size_t)((g + 1) * 8 + h) * 64 + v) * 64 + kq] = cur;
;         if (pf) { LAS float* dst = Pl + ((g + 2) % 3) * 4096; *(LAS f32x4*)(dst + 4 * tid) = pa; *(LAS f32x4*)(dst + 2048 + 4 * tid) = pb; }
;         u1 = u2; u2 = u3;
;     }
	ds_read2_b32 v[104:105], v9 offset0:0 offset1:4
	ds_read2_b32 v[106:107], v9 offset0:8 offset1:12
	ds_read2_b32 v[108:109], v9 offset0:16 offset1:20
	ds_read2_b32 v[110:111], v9 offset0:24 offset1:28
	ds_read2_b32 v[112:113], v9 offset0:32 offset1:36
	ds_read2_b32 v[114:115], v9 offset0:40 offset1:44
	ds_read2_b32 v[116:117], v9 offset0:48 offset1:52
	ds_read2_b32 v[118:119], v9 offset0:56 offset1:60
	s_waitcnt vmcnt(56)
	s_waitcnt lgkmcnt(7)
	v_mfma_f32_16x16x4_f32 v[136:139], v104, v228, v[224:227]
	v_mfma_f32_16x16x4_f32 v[140:143], v105, v229, 0
	ds_read2st64_b32 v[120:121], v10 offset0:0 offset1:5
	ds_read2st64_b32 v[122:123], v10 offset0:10 offset1:15
	s_waitcnt lgkmcnt(8)
	v_mfma_f32_16x16x4_f32 v[136:139], v106, v230, v[136:139]
	v_mfma_f32_16x16x4_f32 v[140:143], v107, v231, v[140:143]
	ds_read2st64_b32 v[124:125], v10 offset0:20 offset1:25
	ds_read2st64_b32 v[126:127], v10 offset0:30 offset1:35
	s_waitcnt lgkmcnt(9)
	v_mfma_f32_16x16x4_f32 v[136:139], v108, v232, v[136:139]
	v_mfma_f32_16x16x4_f32 v[140:143], v109, v233, v[140:143]
	ds_read2st64_b32 v[128:129], v10 offset0:40 offset1:45
	ds_read2st64_b32 v[130:131], v10 offset0:50 offset1:55
	s_waitcnt lgkmcnt(10)
	v_mfma_f32_16x16x4_f32 v[136:139], v110, v234, v[136:139]
	v_mfma_f32_16x16x4_f32 v[140:143], v111, v235, v[140:143]
	ds_read2st64_b32 v[132:133], v10 offset0:60 offset1:65
	ds_read2st64_b32 v[134:135], v10 offset0:70 offset1:75
	s_waitcnt lgkmcnt(11)
	v_mfma_f32_16x16x4_f32 v[136:139], v112, v236, v[136:139]
	v_mfma_f32_16x16x4_f32 v[140:143], v113, v237, v[140:143]
	s_add_u32 s14, s6, 0x6a0000
	s_addc_u32 s15, s7, 0
	global_load_dword v224, v12, s[14:15] offset:0
	global_load_dword v225, v12, s[14:15] offset:256
	global_load_dword v226, v12, s[14:15] offset:512
	global_load_dword v227, v12, s[14:15] offset:768
	s_waitcnt lgkmcnt(10)
	v_mfma_f32_16x16x4_f32 v[136:139], v114, v238, v[136:139]
	v_mfma_f32_16x16x4_f32 v[140:143], v115, v239, v[140:143]
	s_waitcnt vmcnt(58)
	ds_write_b128 v2, v[60:63] offset:20480
	ds_write_b128 v2, v[64:67] offset:30720
	s_add_u32 s10, s0, 0x6e0000
	s_addc_u32 s11, s1, 0
	global_load_dwordx4 v[60:63], v0, s[10:11]
	global_load_dwordx4 v[64:67], v1, s[10:11]
	s_waitcnt lgkmcnt(11)
	v_mfma_f32_16x16x4_f32 v[136:139], v116, v240, v[136:139]
	v_mfma_f32_16x16x4_f32 v[140:143], v117, v241, v[140:143]
	s_waitcnt lgkmcnt(10)
	v_mfma_f32_16x16x4_f32 v[136:139], v118, v242, v[136:139]
	v_mfma_f32_16x16x4_f32 v[140:143], v119, v243, v[140:143]
	s_add_u32 s16, s8, 0x600000
	s_addc_u32 s17, s9, 0
	s_nop 9
	v_add_f32_e32 v136, v136, v140
	v_add_f32_e32 v137, v137, v141
	v_add_f32_e32 v138, v138, v142
	v_add_f32_e32 v139, v139, v143
	ds_write_b32 v13, v136 offset:0
	ds_write_b32 v13, v137 offset:272
	ds_write_b32 v13, v138 offset:544
	ds_write_b32 v13, v139 offset:816
	global_store_dword v12, v136, s[16:17] offset:0
	global_store_dword v12, v137, s[16:17] offset:256
	global_store_dword v12, v138, s[16:17] offset:512
	global_store_dword v12, v139, s[16:17] offset:768
	s_waitcnt lgkmcnt(0)
	s_barrier
	ds_read2_b32 v[104:105], v8 offset0:0 offset1:4
	ds_read2_b32 v[106:107], v8 offset0:8 offset1:12
	ds_read2_b32 v[108:109], v8 offset0:16 offset1:20
	ds_read2_b32 v[110:111], v8 offset0:24 offset1:28
	ds_read2_b32 v[112:113], v8 offset0:32 offset1:36
	ds_read2_b32 v[114:115], v8 offset0:40 offset1:44
	ds_read2_b32 v[116:117], v8 offset0:48 offset1:52
	ds_read2_b32 v[118:119], v8 offset0:56 offset1:60
	s_waitcnt vmcnt(56)
	s_waitcnt lgkmcnt(7)
	v_mfma_f32_16x16x4_f32 v[136:139], v104, v120, v[204:207]
	v_mfma_f32_16x16x4_f32 v[140:143], v105, v121, 0
	ds_read2st64_b32 v[228:229], v11 offset0:0 offset1:5
	ds_read2st64_b32 v[230:231], v11 offset0:10 offset1:15
	s_waitcnt lgkmcnt(8)
	v_mfma_f32_16x16x4_f32 v[136:139], v106, v122, v[136:139]
	v_mfma_f32_16x16x4_f32 v[140:143], v107, v123, v[140:143]
	ds_read2st64_b32 v[232:233], v11 offset0:20 offset1:25
	ds_read2st64_b32 v[234:235], v11 offset0:30 offset1:35
	s_waitcnt lgkmcnt(9)
	v_mfma_f32_16x16x4_f32 v[136:139], v108, v124, v[136:139]
	v_mfma_f32_16x16x4_f32 v[140:143], v109, v125, v[140:143]
	ds_read2st64_b32 v[236:237], v11 offset0:40 offset1:45
	ds_read2st64_b32 v[238:239], v11 offset0:50 offset1:55
	s_waitcnt lgkmcnt(10)
	v_mfma_f32_16x16x4_f32 v[136:139], v110, v126, v[136:139]
	v_mfma_f32_16x16x4_f32 v[140:143], v111, v127, v[140:143]
	ds_read2st64_b32 v[240:241], v11 offset0:60 offset1:65
	ds_read2st64_b32 v[242:243], v11 offset0:70 offset1:75
	s_waitcnt lgkmcnt(11)
	v_mfma_f32_16x16x4_f32 v[136:139], v112, v128, v[136:139]
	v_mfma_f32_16x16x4_f32 v[140:143], v113, v129, v[140:143]
	s_add_u32 s14, s6, 0x6c0000
	s_addc_u32 s15, s7, 0
	global_load_dword v204, v12, s[14:15] offset:0
	global_load_dword v205, v12, s[14:15] offset:256
	global_load_dword v206, v12, s[14:15] offset:512
	global_load_dword v207, v12, s[14:15] offset:768
	s_waitcnt lgkmcnt(10)
	v_mfma_f32_16x16x4_f32 v[136:139], v114, v130, v[136:139]
	v_mfma_f32_16x16x4_f32 v[140:143], v115, v131, v[140:143]
	s_waitcnt vmcnt(58)
	ds_write_b128 v2, v[68:71] offset:0
	ds_write_b128 v2, v[72:75] offset:10240
	s_add_u32 s10, s0, 0x700000
	s_addc_u32 s11, s1, 0
	global_load_dwordx4 v[68:71], v0, s[10:11]
	global_load_dwordx4 v[72:75], v1, s[10:11]
	s_waitcnt lgkmcnt(11)
	v_mfma_f32_16x16x4_f32 v[136:139], v116, v132, v[136:139]
	v_mfma_f32_16x16x4_f32 v[140:143], v117, v133, v[140:143]
	s_waitcnt lgkmcnt(10)
	v_mfma_f32_16x16x4_f32 v[136:139], v118, v134, v[136:139]
	v_mfma_f32_16x16x4_f32 v[140:143], v119, v135, v[140:143]
	s_add_u32 s16, s8, 0x620000
	s_addc_u32 s17, s9, 0
	s_nop 9
	v_add_f32_e32 v136, v136, v140
	v_add_f32_e32 v137, v137, v141
	v_add_f32_e32 v138, v138, v142
	v_add_f32_e32 v139, v139, v143
	ds_write_b32 v13, v136 offset:2176
	ds_write_b32 v13, v137 offset:2448
	ds_write_b32 v13, v138 offset:2720
	ds_write_b32 v13, v139 offset:2992
	global_store_dword v12, v136, s[16:17] offset:0
	global_store_dword v12, v137, s[16:17] offset:256
	global_store_dword v12, v138, s[16:17] offset:512
	global_store_dword v12, v139, s[16:17] offset:768
	s_waitcnt lgkmcnt(0)
	s_barrier
; #define LAS __attribute__((address_space(3)))
; __device__ __forceinline__ void scan_combine(LAS unsigned char* lds, CArgsP a) {
;     ...
;     for (int g = 1; g <= GL; ++g) {
;         const bool pf = (g + 2 <= GL);
;         float u3 = 0.f;
;         if (pf) { const f32x4* Pn = (const f32x4*)(PM + (size_t)((g + 2) * 8 + h) * 4096); pa = Pn[tid]; pb = Pn[512 + tid]; u3 = UM[((size_t)((g + 2) * 8 + h) * 64 + v) * 64 + kq]; }
;         asm volatile("s_waitcnt lgkmcnt(0)\n\ts_barrier" ::: "memory");
;         const LAS float* Pg = Pl + (g % 3) * 4096 + kq;
;         float acc0 = u1, acc1 = 0.f, acc2 = 0.f, acc3 = 0.f;
;         const int curi = __builtin_bit_cast(int, cur);
; #pragma unroll
;         for (int k = 0; k < 64; k += 4) {
;             const float s0 = __builtin_bit_cast(float, __builtin_amdgcn_readlane(curi, k)), s1 = __builtin_bit_cast(float, __builtin_amdgcn_readlane(curi, k + 1));
;             const float s2 = __builtin_bit_cast(float, __builtin_amdgcn_readlane(curi, k + 2)), s3 = __builtin_bit_cast(float, __builtin_amdgcn_readlane(curi, k + 3));
;             acc0 += s0 * Pg[(k + 0) * 64]; acc1 += s1 * Pg[(k + 1) * 64]; acc2 += s2 * Pg[(k + 2) * 64]; acc3 += s3 * Pg[(k + 3) * 64];
;         }
;         cur = (acc0 + acc1) + (acc2 + acc3);
;         SS[((size_t)((g + 1) * 8 + h) * 64 + v) * 64 + kq] = cur;
;         if (pf) { LAS float* dst = Pl + ((g + 2) % 3) * 4096; *(LAS f32x4*)(dst + 4 * tid) = pa; *(LAS f32x4*)(dst + 2048 + 4 * tid) = pb; }
;         u1 = u2; u2 = u3;
;     }
	ds_read2_b32 v[104:105], v9 offset0:0 offset1:4
	ds_read2_b32 v[106:107], v9 offset0:8 offset1:12
	ds_read2_b32 v[108:109], v9 offset0:16 offset1:20
	ds_read2_b32 v[110:111], v9 offset0:24 offset1:28
	ds_read2_b32 v[112:113], v9 offset0:32 offset1:36
	ds_read2_b32 v[114:115], v9 offset0:40 offset1:44
	ds_read2_b32 v[116:117], v9 offset0:48 offset1:52
	ds_read2_b32 v[118:119], v9 offset0:56 offset1:60
	s_waitcnt vmcnt(56)
	s_waitcnt lgkmcnt(7)
	v_mfma_f32_16x16x4_f32 v[136:139], v104, v228, v[208:211]
	v_mfma_f32_16x16x4_f32 v[140:143], v105, v229, 0
	ds_read2st64_b32 v[120:121], v10 offset0:0 offset1:5
	ds_read2st64_b32 v[122:123], v10 offset0:10 offset1:15
	s_waitcnt lgkmcnt(8)
	v_mfma_f32_16x16x4_f32 v[136:139], v106, v230, v[136:139]
	v_mfma_f32_16x16x4_f32 v[140:143], v107, v231, v[140:143]
	ds_read2st64_b32 v[124:125], v10 offset0:20 offset1:25
	ds_read2st64_b32 v[126:127], v10 offset0:30 offset1:35
	s_waitcnt lgkmcnt(9)
	v_mfma_f32_16x16x4_f32 v[136:139], v108, v232, v[136:139]
	v_mfma_f32_16x16x4_f32 v[140:143], v109, v233, v[140:143]
	ds_read2st64_b32 v[128:129], v10 offset0:40 offset1:45
	ds_read2st64_b32 v[130:131], v10 offset0:50 offset1:55
	s_waitcnt lgkmcnt(10)
	v_mfma_f32_16x16x4_f32 v[136:139], v110, v234, v[136:139]
	v_mfma_f32_16x16x4_f32 v[140:143], v111, v235, v[140:143]
	ds_read2st64_b32 v[132:133], v10 offset0:60 offset1:65
	ds_read2st64_b32 v[134:135], v10 offset0:70 offset1:75
	s_waitcnt lgkmcnt(11)
	v_mfma_f32_16x16x4_f32 v[136:139], v112, v236, v[136:139]
	v_mfma_f32_16x16x4_f32 v[140:143], v113, v237, v[140:143]
	s_add_u32 s14, s6, 0x6e0000
	s_addc_u32 s15, s7, 0
	global_load_dword v208, v12, s[14:15] offset:0
	global_load_dword v209, v12, s[14:15] offset:256
	global_load_dword v210, v12, s[14:15] offset:512
	global_load_dword v211, v12, s[14:15] offset:768
	s_waitcnt lgkmcnt(10)
	v_mfma_f32_16x16x4_f32 v[136:139], v114, v238, v[136:139]
	v_mfma_f32_16x16x4_f32 v[140:143], v115, v239, v[140:143]
	s_waitcnt vmcnt(58)
	ds_write_b128 v2, v[76:79] offset:20480
	ds_write_b128 v2, v[80:83] offset:30720
	s_add_u32 s10, s0, 0x720000
	s_addc_u32 s11, s1, 0
	global_load_dwordx4 v[76:79], v0, s[10:11]
	global_load_dwordx4 v[80:83], v1, s[10:11]
	s_waitcnt lgkmcnt(11)
	v_mfma_f32_16x16x4_f32 v[136:139], v116, v240, v[136:139]
	v_mfma_f32_16x16x4_f32 v[140:143], v117, v241, v[140:143]
	s_waitcnt lgkmcnt(10)
	v_mfma_f32_16x16x4_f32 v[136:139], v118, v242, v[136:139]
	v_mfma_f32_16x16x4_f32 v[140:143], v119, v243, v[140:143]
	s_add_u32 s16, s8, 0x640000
	s_addc_u32 s17, s9, 0
	s_nop 9
	v_add_f32_e32 v136, v136, v140
	v_add_f32_e32 v137, v137, v141
	v_add_f32_e32 v138, v138, v142
	v_add_f32_e32 v139, v139, v143
	ds_write_b32 v13, v136 offset:0
	ds_write_b32 v13, v137 offset:272
	ds_write_b32 v13, v138 offset:544
	ds_write_b32 v13, v139 offset:816
	global_store_dword v12, v136, s[16:17] offset:0
	global_store_dword v12, v137, s[16:17] offset:256
	global_store_dword v12, v138, s[16:17] offset:512
	global_store_dword v12, v139, s[16:17] offset:768
	s_waitcnt lgkmcnt(0)
	s_barrier
	ds_read2_b32 v[104:105], v8 offset0:0 offset1:4
	ds_read2_b32 v[106:107], v8 offset0:8 offset1:12
	ds_read2_b32 v[108:109], v8 offset0:16 offset1:20
	ds_read2_b32 v[110:111], v8 offset0:24 offset1:28
	ds_read2_b32 v[112:113], v8 offset0:32 offset1:36
	ds_read2_b32 v[114:115], v8 offset0:40 offset1:44
	ds_read2_b32 v[116:117], v8 offset0:48 offset1:52
	ds_read2_b32 v[118:119], v8 offset0:56 offset1:60
	s_waitcnt vmcnt(56)
	s_waitcnt lgkmcnt(7)
	v_mfma_f32_16x16x4_f32 v[136:139], v104, v120, v[212:215]
	v_mfma_f32_16x16x4_f32 v[140:143], v105, v121, 0
	ds_read2st64_b32 v[228:229], v11 offset0:0 offset1:5
	ds_read2st64_b32 v[230:231], v11 offset0:10 offset1:15
	s_waitcnt lgkmcnt(8)
	v_mfma_f32_16x16x4_f32 v[136:139], v106, v122, v[136:139]
	v_mfma_f32_16x16x4_f32 v[140:143], v107, v123, v[140:143]
	ds_read2st64_b32 v[232:233], v11 offset0:20 offset1:25
	ds_read2st64_b32 v[234:235], v11 offset0:30 offset1:35
	s_waitcnt lgkmcnt(9)
	v_mfma_f32_16x16x4_f32 v[136:139], v108, v124, v[136:139]
	v_mfma_f32_16x16x4_f32 v[140:143], v109, v125, v[140:143]
	ds_read2st64_b32 v[236:237], v11 offset0:40 offset1:45
	ds_read2st64_b32 v[238:239], v11 offset0:50 offset1:55
	s_waitcnt lgkmcnt(10)
	v_mfma_f32_16x16x4_f32 v[136:139], v110, v126, v[136:139]
	v_mfma_f32_16x16x4_f32 v[140:143], v111, v127, v[140:143]
	ds_read2st64_b32 v[240:241], v11 offset0:60 offset1:65
	ds_read2st64_b32 v[242:243], v11 offset0:70 offset1:75
	s_waitcnt lgkmcnt(11)
	v_mfma_f32_16x16x4_f32 v[136:139], v112, v128, v[136:139]
	v_mfma_f32_16x16x4_f32 v[140:143], v113, v129, v[140:143]
	s_add_u32 s14, s6, 0x700000
	s_addc_u32 s15, s7, 0
	global_load_dword v212, v12, s[14:15] offset:0
	global_load_dword v213, v12, s[14:15] offset:256
	global_load_dword v214, v12, s[14:15] offset:512
	global_load_dword v215, v12, s[14:15] offset:768
	s_waitcnt lgkmcnt(10)
	v_mfma_f32_16x16x4_f32 v[136:139], v114, v130, v[136:139]
	v_mfma_f32_16x16x4_f32 v[140:143], v115, v131, v[140:143]
	s_waitcnt vmcnt(58)
	ds_write_b128 v2, v[84:87] offset:0
	ds_write_b128 v2, v[88:91] offset:10240
	s_add_u32 s10, s0, 0x740000
	s_addc_u32 s11, s1, 0
	global_load_dwordx4 v[84:87], v0, s[10:11]
	global_load_dwordx4 v[88:91], v1, s[10:11]
	s_waitcnt lgkmcnt(11)
	v_mfma_f32_16x16x4_f32 v[136:139], v116, v132, v[136:139]
	v_mfma_f32_16x16x4_f32 v[140:143], v117, v133, v[140:143]
	s_waitcnt lgkmcnt(10)
	v_mfma_f32_16x16x4_f32 v[136:139], v118, v134, v[136:139]
	v_mfma_f32_16x16x4_f32 v[140:143], v119, v135, v[140:143]
	s_add_u32 s16, s8, 0x660000
	s_addc_u32 s17, s9, 0
	s_nop 9
	v_add_f32_e32 v136, v136, v140
	v_add_f32_e32 v137, v137, v141
	v_add_f32_e32 v138, v138, v142
	v_add_f32_e32 v139, v139, v143
	ds_write_b32 v13, v136 offset:2176
	ds_write_b32 v13, v137 offset:2448
	ds_write_b32 v13, v138 offset:2720
	ds_write_b32 v13, v139 offset:2992
	global_store_dword v12, v136, s[16:17] offset:0
	global_store_dword v12, v137, s[16:17] offset:256
	global_store_dword v12, v138, s[16:17] offset:512
	global_store_dword v12, v139, s[16:17] offset:768
	s_waitcnt lgkmcnt(0)
	s_barrier
; #define LAS __attribute__((address_space(3)))
; __device__ __forceinline__ void scan_combine(LAS unsigned char* lds, CArgsP a) {
;     ...
;     for (int g = 1; g <= GL; ++g) {
;         const bool pf = (g + 2 <= GL);
;         float u3 = 0.f;
;         if (pf) { const f32x4* Pn = (const f32x4*)(PM + (size_t)((g + 2) * 8 + h) * 4096); pa = Pn[tid]; pb = Pn[512 + tid]; u3 = UM[((size_t)((g + 2) * 8 + h) * 64 + v) * 64 + kq]; }
;         asm volatile("s_waitcnt lgkmcnt(0)\n\ts_barrier" ::: "memory");
;         const LAS float* Pg = Pl + (g % 3) * 4096 + kq;
;         float acc0 = u1, acc1 = 0.f, acc2 = 0.f, acc3 = 0.f;
;         const int curi = __builtin_bit_cast(int, cur);
; #pragma unroll
;         for (int k = 0; k < 64; k += 4) {
;             const float s0 = __builtin_bit_cast(float, __builtin_amdgcn_readlane(curi, k)), s1 = __builtin_bit_cast(float, __builtin_amdgcn_readlane(curi, k + 1));
;             const float s2 = __builtin_bit_cast(float, __builtin_amdgcn_readlane(curi, k + 2)), s3 = __builtin_bit_cast(float, __builtin_amdgcn_readlane(curi, k + 3));
;             acc0 += s0 * Pg[(k + 0) * 64]; acc1 += s1 * Pg[(k + 1) * 64]; acc2 += s2 * Pg[(k + 2) * 64]; acc3 += s3 * Pg[(k + 3) * 64];
;         }
;         cur = (acc0 + acc1) + (acc2 + acc3);
;         SS[((size_t)((g + 1) * 8 + h) * 64 + v) * 64 + kq] = cur;
;         if (pf) { LAS float* dst = Pl + ((g + 2) % 3) * 4096; *(LAS f32x4*)(dst + 4 * tid) = pa; *(LAS f32x4*)(dst + 2048 + 4 * tid) = pb; }
;         u1 = u2; u2 = u3;
;     }
	ds_read2_b32 v[104:105], v9 offset0:0 offset1:4
	ds_read2_b32 v[106:107], v9 offset0:8 offset1:12
	ds_read2_b32 v[108:109], v9 offset0:16 offset1:20
	ds_read2_b32 v[110:111], v9 offset0:24 offset1:28
	ds_read2_b32 v[112:113], v9 offset0:32 offset1:36
	ds_read2_b32 v[114:115], v9 offset0:40 offset1:44
	ds_read2_b32 v[116:117], v9 offset0:48 offset1:52
	ds_read2_b32 v[118:119], v9 offset0:56 offset1:60
	s_waitcnt vmcnt(56)
	s_waitcnt lgkmcnt(7)
	v_mfma_f32_16x16x4_f32 v[136:139], v104, v228, v[216:219]
	v_mfma_f32_16x16x4_f32 v[140:143], v105, v229, 0
	ds_read2st64_b32 v[120:121], v10 offset0:0 offset1:5
	ds_read2st64_b32 v[122:123], v10 offset0:10 offset1:15
	s_waitcnt lgkmcnt(8)
	v_mfma_f32_16x16x4_f32 v[136:139], v106, v230, v[136:139]
	v_mfma_f32_16x16x4_f32 v[140:143], v107, v231, v[140:143]
	ds_read2st64_b32 v[124:125], v10 offset0:20 offset1:25
	ds_read2st64_b32 v[126:127], v10 offset0:30 offset1:35
	s_waitcnt lgkmcnt(9)
	v_mfma_f32_16x16x4_f32 v[136:139], v108, v232, v[136:139]
	v_mfma_f32_16x16x4_f32 v[140:143], v109, v233, v[140:143]
	ds_read2st64_b32 v[128:129], v10 offset0:40 offset1:45
	ds_read2st64_b32 v[130:131], v10 offset0:50 offset1:55
	s_waitcnt lgkmcnt(10)
	v_mfma_f32_16x16x4_f32 v[136:139], v110, v234, v[136:139]
	v_mfma_f32_16x16x4_f32 v[140:143], v111, v235, v[140:143]
	ds_read2st64_b32 v[132:133], v10 offset0:60 offset1:65
	ds_read2st64_b32 v[134:135], v10 offset0:70 offset1:75
	s_waitcnt lgkmcnt(11)
	v_mfma_f32_16x16x4_f32 v[136:139], v112, v236, v[136:139]
	v_mfma_f32_16x16x4_f32 v[140:143], v113, v237, v[140:143]
	s_add_u32 s14, s6, 0x720000
	s_addc_u32 s15, s7, 0
	global_load_dword v216, v12, s[14:15] offset:0
	global_load_dword v217, v12, s[14:15] offset:256
	global_load_dword v218, v12, s[14:15] offset:512
	global_load_dword v219, v12, s[14:15] offset:768
	s_waitcnt lgkmcnt(10)
	v_mfma_f32_16x16x4_f32 v[136:139], v114, v238, v[136:139]
	v_mfma_f32_16x16x4_f32 v[140:143], v115, v239, v[140:143]
	s_waitcnt vmcnt(58)
	ds_write_b128 v2, v[92:95] offset:20480
	ds_write_b128 v2, v[96:99] offset:30720
	s_add_u32 s10, s0, 0x760000
	s_addc_u32 s11, s1, 0
	global_load_dwordx4 v[92:95], v0, s[10:11]
	global_load_dwordx4 v[96:99], v1, s[10:11]
	s_waitcnt lgkmcnt(11)
	v_mfma_f32_16x16x4_f32 v[136:139], v116, v240, v[136:139]
	v_mfma_f32_16x16x4_f32 v[140:143], v117, v241, v[140:143]
	s_waitcnt lgkmcnt(10)
	v_mfma_f32_16x16x4_f32 v[136:139], v118, v242, v[136:139]
	v_mfma_f32_16x16x4_f32 v[140:143], v119, v243, v[140:143]
	s_add_u32 s16, s8, 0x680000
	s_addc_u32 s17, s9, 0
	s_nop 9
	v_add_f32_e32 v136, v136, v140
	v_add_f32_e32 v137, v137, v141
	v_add_f32_e32 v138, v138, v142
	v_add_f32_e32 v139, v139, v143
	ds_write_b32 v13, v136 offset:0
	ds_write_b32 v13, v137 offset:272
	ds_write_b32 v13, v138 offset:544
	ds_write_b32 v13, v139 offset:816
	global_store_dword v12, v136, s[16:17] offset:0
	global_store_dword v12, v137, s[16:17] offset:256
	global_store_dword v12, v138, s[16:17] offset:512
	global_store_dword v12, v139, s[16:17] offset:768
	s_waitcnt lgkmcnt(0)
	s_barrier
	ds_read2_b32 v[104:105], v8 offset0:0 offset1:4
	ds_read2_b32 v[106:107], v8 offset0:8 offset1:12
	ds_read2_b32 v[108:109], v8 offset0:16 offset1:20
	ds_read2_b32 v[110:111], v8 offset0:24 offset1:28
	ds_read2_b32 v[112:113], v8 offset0:32 offset1:36
	ds_read2_b32 v[114:115], v8 offset0:40 offset1:44
	ds_read2_b32 v[116:117], v8 offset0:48 offset1:52
	ds_read2_b32 v[118:119], v8 offset0:56 offset1:60
	s_waitcnt vmcnt(56)
	s_waitcnt lgkmcnt(7)
	v_mfma_f32_16x16x4_f32 v[136:139], v104, v120, v[220:223]
	v_mfma_f32_16x16x4_f32 v[140:143], v105, v121, 0
	ds_read2st64_b32 v[228:229], v11 offset0:0 offset1:5
	ds_read2st64_b32 v[230:231], v11 offset0:10 offset1:15
	s_waitcnt lgkmcnt(8)
	v_mfma_f32_16x16x4_f32 v[136:139], v106, v122, v[136:139]
	v_mfma_f32_16x16x4_f32 v[140:143], v107, v123, v[140:143]
	ds_read2st64_b32 v[232:233], v11 offset0:20 offset1:25
	ds_read2st64_b32 v[234:235], v11 offset0:30 offset1:35
	s_waitcnt lgkmcnt(9)
	v_mfma_f32_16x16x4_f32 v[136:139], v108, v124, v[136:139]
	v_mfma_f32_16x16x4_f32 v[140:143], v109, v125, v[140:143]
	ds_read2st64_b32 v[236:237], v11 offset0:40 offset1:45
	ds_read2st64_b32 v[238:239], v11 offset0:50 offset1:55
	s_waitcnt lgkmcnt(10)
	v_mfma_f32_16x16x4_f32 v[136:139], v110, v126, v[136:139]
	v_mfma_f32_16x16x4_f32 v[140:143], v111, v127, v[140:143]
	ds_read2st64_b32 v[240:241], v11 offset0:60 offset1:65
	ds_read2st64_b32 v[242:243], v11 offset0:70 offset1:75
	s_waitcnt lgkmcnt(11)
	v_mfma_f32_16x16x4_f32 v[136:139], v112, v128, v[136:139]
	v_mfma_f32_16x16x4_f32 v[140:143], v113, v129, v[140:143]
	s_add_u32 s14, s6, 0x740000
	s_addc_u32 s15, s7, 0
	global_load_dword v220, v12, s[14:15] offset:0
	global_load_dword v221, v12, s[14:15] offset:256
	global_load_dword v222, v12, s[14:15] offset:512
	global_load_dword v223, v12, s[14:15] offset:768
	s_waitcnt lgkmcnt(10)
	v_mfma_f32_16x16x4_f32 v[136:139], v114, v130, v[136:139]
	v_mfma_f32_16x16x4_f32 v[140:143], v115, v131, v[140:143]
	s_waitcnt vmcnt(58)
	ds_write_b128 v2, v[52:55] offset:0
	ds_write_b128 v2, v[56:59] offset:10240
	s_add_u32 s10, s0, 0x780000
	s_addc_u32 s11, s1, 0
	global_load_dwordx4 v[52:55], v0, s[10:11]
	global_load_dwordx4 v[56:59], v1, s[10:11]
	s_waitcnt lgkmcnt(11)
	v_mfma_f32_16x16x4_f32 v[136:139], v116, v132, v[136:139]
	v_mfma_f32_16x16x4_f32 v[140:143], v117, v133, v[140:143]
	s_waitcnt lgkmcnt(10)
	v_mfma_f32_16x16x4_f32 v[136:139], v118, v134, v[136:139]
	v_mfma_f32_16x16x4_f32 v[140:143], v119, v135, v[140:143]
	s_add_u32 s16, s8, 0x6a0000
	s_addc_u32 s17, s9, 0
	s_nop 9
	v_add_f32_e32 v136, v136, v140
	v_add_f32_e32 v137, v137, v141
	v_add_f32_e32 v138, v138, v142
	v_add_f32_e32 v139, v139, v143
	ds_write_b32 v13, v136 offset:2176
	ds_write_b32 v13, v137 offset:2448
	ds_write_b32 v13, v138 offset:2720
	ds_write_b32 v13, v139 offset:2992
	global_store_dword v12, v136, s[16:17] offset:0
	global_store_dword v12, v137, s[16:17] offset:256
	global_store_dword v12, v138, s[16:17] offset:512
	global_store_dword v12, v139, s[16:17] offset:768
	s_waitcnt lgkmcnt(0)
	s_barrier
; #define LAS __attribute__((address_space(3)))
; __device__ __forceinline__ void scan_combine(LAS unsigned char* lds, CArgsP a) {
;     ...
;     for (int g = 1; g <= GL; ++g) {
;         const bool pf = (g + 2 <= GL);
;         float u3 = 0.f;
;         if (pf) { const f32x4* Pn = (const f32x4*)(PM + (size_t)((g + 2) * 8 + h) * 4096); pa = Pn[tid]; pb = Pn[512 + tid]; u3 = UM[((size_t)((g + 2) * 8 + h) * 64 + v) * 64 + kq]; }
;         asm volatile("s_waitcnt lgkmcnt(0)\n\ts_barrier" ::: "memory");
;         const LAS float* Pg = Pl + (g % 3) * 4096 + kq;
;         float acc0 = u1, acc1 = 0.f, acc2 = 0.f, acc3 = 0.f;
;         const int curi = __builtin_bit_cast(int, cur);
; #pragma unroll
;         for (int k = 0; k < 64; k += 4) {
;             const float s0 = __builtin_bit_cast(float, __builtin_amdgcn_readlane(curi, k)), s1 = __builtin_bit_cast(float, __builtin_amdgcn_readlane(curi, k + 1));
;             const float s2 = __builtin_bit_cast(float, __builtin_amdgcn_readlane(curi, k + 2)), s3 = __builtin_bit_cast(float, __builtin_amdgcn_readlane(curi, k + 3));
;             acc0 += s0 * Pg[(k + 0) * 64]; acc1 += s1 * Pg[(k + 1) * 64]; acc2 += s2 * Pg[(k + 2) * 64]; acc3 += s3 * Pg[(k + 3) * 64];
;         }
;         cur = (acc0 + acc1) + (acc2 + acc3);
;         SS[((size_t)((g + 1) * 8 + h) * 64 + v) * 64 + kq] = cur;
;         if (pf) { LAS float* dst = Pl + ((g + 2) % 3) * 4096; *(LAS f32x4*)(dst + 4 * tid) = pa; *(LAS f32x4*)(dst + 2048 + 4 * tid) = pb; }
;         u1 = u2; u2 = u3;
;     }
	ds_read2_b32 v[104:105], v9 offset0:0 offset1:4
	ds_read2_b32 v[106:107], v9 offset0:8 offset1:12
	ds_read2_b32 v[108:109], v9 offset0:16 offset1:20
	ds_read2_b32 v[110:111], v9 offset0:24 offset1:28
	ds_read2_b32 v[112:113], v9 offset0:32 offset1:36
	ds_read2_b32 v[114:115], v9 offset0:40 offset1:44
	ds_read2_b32 v[116:117], v9 offset0:48 offset1:52
	ds_read2_b32 v[118:119], v9 offset0:56 offset1:60
	s_waitcnt vmcnt(56)
	s_waitcnt lgkmcnt(7)
	v_mfma_f32_16x16x4_f32 v[136:139], v104, v228, v[224:227]
	v_mfma_f32_16x16x4_f32 v[140:143], v105, v229, 0
	ds_read2st64_b32 v[120:121], v10 offset0:0 offset1:5
	ds_read2st64_b32 v[122:123], v10 offset0:10 offset1:15
	s_waitcnt lgkmcnt(8)
	v_mfma_f32_16x16x4_f32 v[136:139], v106, v230, v[136:139]
	v_mfma_f32_16x16x4_f32 v[140:143], v107, v231, v[140:143]
	ds_read2st64_b32 v[124:125], v10 offset0:20 offset1:25
	ds_read2st64_b32 v[126:127], v10 offset0:30 offset1:35
	s_waitcnt lgkmcnt(9)
	v_mfma_f32_16x16x4_f32 v[136:139], v108, v232, v[136:139]
	v_mfma_f32_16x16x4_f32 v[140:143], v109, v233, v[140:143]
	ds_read2st64_b32 v[128:129], v10 offset0:40 offset1:45
	ds_read2st64_b32 v[130:131], v10 offset0:50 offset1:55
	s_waitcnt lgkmcnt(10)
	v_mfma_f32_16x16x4_f32 v[136:139], v110, v234, v[136:139]
	v_mfma_f32_16x16x4_f32 v[140:143], v111, v235, v[140:143]
	ds_read2st64_b32 v[132:133], v10 offset0:60 offset1:65
	ds_read2st64_b32 v[134:135], v10 offset0:70 offset1:75
	s_waitcnt lgkmcnt(11)
	v_mfma_f32_16x16x4_f32 v[136:139], v112, v236, v[136:139]
	v_mfma_f32_16x16x4_f32 v[140:143], v113, v237, v[140:143]
	s_add_u32 s14, s6, 0x760000
	s_addc_u32 s15, s7, 0
	global_load_dword v224, v12, s[14:15] offset:0
	global_load_dword v225, v12, s[14:15] offset:256
	global_load_dword v226, v12, s[14:15] offset:512
	global_load_dword v227, v12, s[14:15] offset:768
	s_waitcnt lgkmcnt(10)
	v_mfma_f32_16x16x4_f32 v[136:139], v114, v238, v[136:139]
	v_mfma_f32_16x16x4_f32 v[140:143], v115, v239, v[140:143]
	s_waitcnt vmcnt(58)
	ds_write_b128 v2, v[60:63] offset:20480
	ds_write_b128 v2, v[64:67] offset:30720
	s_add_u32 s10, s0, 0x7a0000
	s_addc_u32 s11, s1, 0
	global_load_dwordx4 v[60:63], v0, s[10:11]
	global_load_dwordx4 v[64:67], v1, s[10:11]
	s_waitcnt lgkmcnt(11)
	v_mfma_f32_16x16x4_f32 v[136:139], v116, v240, v[136:139]
	v_mfma_f32_16x16x4_f32 v[140:143], v117, v241, v[140:143]
	s_waitcnt lgkmcnt(10)
	v_mfma_f32_16x16x4_f32 v[136:139], v118, v242, v[136:139]
	v_mfma_f32_16x16x4_f32 v[140:143], v119, v243, v[140:143]
	s_add_u32 s16, s8, 0x6c0000
	s_addc_u32 s17, s9, 0
	s_nop 9
	v_add_f32_e32 v136, v136, v140
	v_add_f32_e32 v137, v137, v141
	v_add_f32_e32 v138, v138, v142
	v_add_f32_e32 v139, v139, v143
	ds_write_b32 v13, v136 offset:0
	ds_write_b32 v13, v137 offset:272
	ds_write_b32 v13, v138 offset:544
	ds_write_b32 v13, v139 offset:816
	global_store_dword v12, v136, s[16:17] offset:0
	global_store_dword v12, v137, s[16:17] offset:256
	global_store_dword v12, v138, s[16:17] offset:512
	global_store_dword v12, v139, s[16:17] offset:768
	s_waitcnt lgkmcnt(0)
	s_barrier
	ds_read2_b32 v[104:105], v8 offset0:0 offset1:4
	ds_read2_b32 v[106:107], v8 offset0:8 offset1:12
	ds_read2_b32 v[108:109], v8 offset0:16 offset1:20
	ds_read2_b32 v[110:111], v8 offset0:24 offset1:28
	ds_read2_b32 v[112:113], v8 offset0:32 offset1:36
	ds_read2_b32 v[114:115], v8 offset0:40 offset1:44
	ds_read2_b32 v[116:117], v8 offset0:48 offset1:52
	ds_read2_b32 v[118:119], v8 offset0:56 offset1:60
	s_waitcnt vmcnt(56)
	s_waitcnt lgkmcnt(7)
	v_mfma_f32_16x16x4_f32 v[136:139], v104, v120, v[204:207]
	v_mfma_f32_16x16x4_f32 v[140:143], v105, v121, 0
	ds_read2st64_b32 v[228:229], v11 offset0:0 offset1:5
	ds_read2st64_b32 v[230:231], v11 offset0:10 offset1:15
	s_waitcnt lgkmcnt(8)
	v_mfma_f32_16x16x4_f32 v[136:139], v106, v122, v[136:139]
	v_mfma_f32_16x16x4_f32 v[140:143], v107, v123, v[140:143]
	ds_read2st64_b32 v[232:233], v11 offset0:20 offset1:25
	ds_read2st64_b32 v[234:235], v11 offset0:30 offset1:35
	s_waitcnt lgkmcnt(9)
	v_mfma_f32_16x16x4_f32 v[136:139], v108, v124, v[136:139]
	v_mfma_f32_16x16x4_f32 v[140:143], v109, v125, v[140:143]
	ds_read2st64_b32 v[236:237], v11 offset0:40 offset1:45
	ds_read2st64_b32 v[238:239], v11 offset0:50 offset1:55
	s_waitcnt lgkmcnt(10)
	v_mfma_f32_16x16x4_f32 v[136:139], v110, v126, v[136:139]
	v_mfma_f32_16x16x4_f32 v[140:143], v111, v127, v[140:143]
	ds_read2st64_b32 v[240:241], v11 offset0:60 offset1:65
	ds_read2st64_b32 v[242:243], v11 offset0:70 offset1:75
	s_waitcnt lgkmcnt(11)
	v_mfma_f32_16x16x4_f32 v[136:139], v112, v128, v[136:139]
	v_mfma_f32_16x16x4_f32 v[140:143], v113, v129, v[140:143]
	s_add_u32 s14, s6, 0x780000
	s_addc_u32 s15, s7, 0
	global_load_dword v204, v12, s[14:15] offset:0
	global_load_dword v205, v12, s[14:15] offset:256
	global_load_dword v206, v12, s[14:15] offset:512
	global_load_dword v207, v12, s[14:15] offset:768
	s_waitcnt lgkmcnt(10)
	v_mfma_f32_16x16x4_f32 v[136:139], v114, v130, v[136:139]
	v_mfma_f32_16x16x4_f32 v[140:143], v115, v131, v[140:143]
	s_waitcnt vmcnt(58)
	ds_write_b128 v2, v[68:71] offset:0
	ds_write_b128 v2, v[72:75] offset:10240
	s_add_u32 s10, s0, 0x7c0000
	s_addc_u32 s11, s1, 0
	global_load_dwordx4 v[68:71], v0, s[10:11]
	global_load_dwordx4 v[72:75], v1, s[10:11]
	s_waitcnt lgkmcnt(11)
	v_mfma_f32_16x16x4_f32 v[136:139], v116, v132, v[136:139]
	v_mfma_f32_16x16x4_f32 v[140:143], v117, v133, v[140:143]
	s_waitcnt lgkmcnt(10)
	v_mfma_f32_16x16x4_f32 v[136:139], v118, v134, v[136:139]
	v_mfma_f32_16x16x4_f32 v[140:143], v119, v135, v[140:143]
	s_add_u32 s16, s8, 0x6e0000
	s_addc_u32 s17, s9, 0
	s_nop 9
	v_add_f32_e32 v136, v136, v140
	v_add_f32_e32 v137, v137, v141
	v_add_f32_e32 v138, v138, v142
	v_add_f32_e32 v139, v139, v143
	ds_write_b32 v13, v136 offset:2176
	ds_write_b32 v13, v137 offset:2448
	ds_write_b32 v13, v138 offset:2720
	ds_write_b32 v13, v139 offset:2992
	global_store_dword v12, v136, s[16:17] offset:0
	global_store_dword v12, v137, s[16:17] offset:256
	global_store_dword v12, v138, s[16:17] offset:512
	global_store_dword v12, v139, s[16:17] offset:768
	s_waitcnt lgkmcnt(0)
	s_barrier
; #define LAS __attribute__((address_space(3)))
; __device__ __forceinline__ void scan_combine(LAS unsigned char* lds, CArgsP a) {
;     ...
;     for (int g = 1; g <= GL; ++g) {
;         const bool pf = (g + 2 <= GL);
;         float u3 = 0.f;
;         if (pf) { const f32x4* Pn = (const f32x4*)(PM + (size_t)((g + 2) * 8 + h) * 4096); pa = Pn[tid]; pb = Pn[512 + tid]; u3 = UM[((size_t)((g + 2) * 8 + h) * 64 + v) * 64 + kq]; }
;         asm volatile("s_waitcnt lgkmcnt(0)\n\ts_barrier" ::: "memory");
;         const LAS float* Pg = Pl + (g % 3) * 4096 + kq;
;         float acc0 = u1, acc1 = 0.f, acc2 = 0.f, acc3 = 0.f;
;         const int curi = __builtin_bit_cast(int, cur);
; #pragma unroll
;         for (int k = 0; k < 64; k += 4) {
;             const float s0 = __builtin_bit_cast(float, __builtin_amdgcn_readlane(curi, k)), s1 = __builtin_bit_cast(float, __builtin_amdgcn_readlane(curi, k + 1));
;             const float s2 = __builtin_bit_cast(float, __builtin_amdgcn_readlane(curi, k + 2)), s3 = __builtin_bit_cast(float, __builtin_amdgcn_readlane(curi, k + 3));
;             acc0 += s0 * Pg[(k + 0) * 64]; acc1 += s1 * Pg[(k + 1) * 64]; acc2 += s2 * Pg[(k + 2) * 64]; acc3 += s3 * Pg[(k + 3) * 64];
;         }
;         cur = (acc0 + acc1) + (acc2 + acc3);
;         SS[((size_t)((g + 1) * 8 + h) * 64 + v) * 64 + kq] = cur;
;         if (pf) { LAS float* dst = Pl + ((g + 2) % 3) * 4096; *(LAS f32x4*)(dst + 4 * tid) = pa; *(LAS f32x4*)(dst + 2048 + 4 * tid) = pb; }
;         u1 = u2; u2 = u3;
;     }
	ds_read2_b32 v[104:105], v9 offset0:0 offset1:4
	ds_read2_b32 v[106:107], v9 offset0:8 offset1:12
	ds_read2_b32 v[108:109], v9 offset0:16 offset1:20
	ds_read2_b32 v[110:111], v9 offset0:24 offset1:28
	ds_read2_b32 v[112:113], v9 offset0:32 offset1:36
	ds_read2_b32 v[114:115], v9 offset0:40 offset1:44
	ds_read2_b32 v[116:117], v9 offset0:48 offset1:52
	ds_read2_b32 v[118:119], v9 offset0:56 offset1:60
	s_waitcnt vmcnt(56)
	s_waitcnt lgkmcnt(7)
	v_mfma_f32_16x16x4_f32 v[136:139], v104, v228, v[208:211]
	v_mfma_f32_16x16x4_f32 v[140:143], v105, v229, 0
	ds_read2st64_b32 v[120:121], v10 offset0:0 offset1:5
	ds_read2st64_b32 v[122:123], v10 offset0:10 offset1:15
	s_waitcnt lgkmcnt(8)
	v_mfma_f32_16x16x4_f32 v[136:139], v106, v230, v[136:139]
	v_mfma_f32_16x16x4_f32 v[140:143], v107, v231, v[140:143]
	ds_read2st64_b32 v[124:125], v10 offset0:20 offset1:25
	ds_read2st64_b32 v[126:127], v10 offset0:30 offset1:35
	s_waitcnt lgkmcnt(9)
	v_mfma_f32_16x16x4_f32 v[136:139], v108, v232, v[136:139]
	v_mfma_f32_16x16x4_f32 v[140:143], v109, v233, v[140:143]
	ds_read2st64_b32 v[128:129], v10 offset0:40 offset1:45
	ds_read2st64_b32 v[130:131], v10 offset0:50 offset1:55
	s_waitcnt lgkmcnt(10)
	v_mfma_f32_16x16x4_f32 v[136:139], v110, v234, v[136:139]
	v_mfma_f32_16x16x4_f32 v[140:143], v111, v235, v[140:143]
	ds_read2st64_b32 v[132:133], v10 offset0:60 offset1:65
	ds_read2st64_b32 v[134:135], v10 offset0:70 offset1:75
	s_waitcnt lgkmcnt(11)
	v_mfma_f32_16x16x4_f32 v[136:139], v112, v236, v[136:139]
	v_mfma_f32_16x16x4_f32 v[140:143], v113, v237, v[140:143]
	s_add_u32 s14, s6, 0x7a0000
	s_addc_u32 s15, s7, 0
	global_load_dword v208, v12, s[14:15] offset:0
	global_load_dword v209, v12, s[14:15] offset:256
	global_load_dword v210, v12, s[14:15] offset:512
	global_load_dword v211, v12, s[14:15] offset:768
	s_waitcnt lgkmcnt(10)
	v_mfma_f32_16x16x4_f32 v[136:139], v114, v238, v[136:139]
	v_mfma_f32_16x16x4_f32 v[140:143], v115, v239, v[140:143]
	s_waitcnt vmcnt(58)
	ds_write_b128 v2, v[76:79] offset:20480
	ds_write_b128 v2, v[80:83] offset:30720
	s_waitcnt lgkmcnt(11)
	v_mfma_f32_16x16x4_f32 v[136:139], v116, v240, v[136:139]
	v_mfma_f32_16x16x4_f32 v[140:143], v117, v241, v[140:143]
	s_waitcnt lgkmcnt(10)
	v_mfma_f32_16x16x4_f32 v[136:139], v118, v242, v[136:139]
	v_mfma_f32_16x16x4_f32 v[140:143], v119, v243, v[140:143]
	s_add_u32 s16, s8, 0x700000
	s_addc_u32 s17, s9, 0
	s_nop 9
	v_add_f32_e32 v136, v136, v140
	v_add_f32_e32 v137, v137, v141
	v_add_f32_e32 v138, v138, v142
	v_add_f32_e32 v139, v139, v143
	ds_write_b32 v13, v136 offset:0
	ds_write_b32 v13, v137 offset:272
	ds_write_b32 v13, v138 offset:544
	ds_write_b32 v13, v139 offset:816
	global_store_dword v12, v136, s[16:17] offset:0
	global_store_dword v12, v137, s[16:17] offset:256
	global_store_dword v12, v138, s[16:17] offset:512
	global_store_dword v12, v139, s[16:17] offset:768
	s_waitcnt lgkmcnt(0)
	s_barrier
	ds_read2_b32 v[104:105], v8 offset0:0 offset1:4
	ds_read2_b32 v[106:107], v8 offset0:8 offset1:12
	ds_read2_b32 v[108:109], v8 offset0:16 offset1:20
	ds_read2_b32 v[110:111], v8 offset0:24 offset1:28
	ds_read2_b32 v[112:113], v8 offset0:32 offset1:36
	ds_read2_b32 v[114:115], v8 offset0:40 offset1:44
	ds_read2_b32 v[116:117], v8 offset0:48 offset1:52
	ds_read2_b32 v[118:119], v8 offset0:56 offset1:60
	s_waitcnt vmcnt(54)
	s_waitcnt lgkmcnt(7)
	v_mfma_f32_16x16x4_f32 v[136:139], v104, v120, v[212:215]
	v_mfma_f32_16x16x4_f32 v[140:143], v105, v121, 0
	ds_read2st64_b32 v[228:229], v11 offset0:0 offset1:5
	ds_read2st64_b32 v[230:231], v11 offset0:10 offset1:15
	s_waitcnt lgkmcnt(8)
	v_mfma_f32_16x16x4_f32 v[136:139], v106, v122, v[136:139]
	v_mfma_f32_16x16x4_f32 v[140:143], v107, v123, v[140:143]
	ds_read2st64_b32 v[232:233], v11 offset0:20 offset1:25
	ds_read2st64_b32 v[234:235], v11 offset0:30 offset1:35
	s_waitcnt lgkmcnt(9)
	v_mfma_f32_16x16x4_f32 v[136:139], v108, v124, v[136:139]
	v_mfma_f32_16x16x4_f32 v[140:143], v109, v125, v[140:143]
	ds_read2st64_b32 v[236:237], v11 offset0:40 offset1:45
	ds_read2st64_b32 v[238:239], v11 offset0:50 offset1:55
	s_waitcnt lgkmcnt(10)
	v_mfma_f32_16x16x4_f32 v[136:139], v110, v126, v[136:139]
	v_mfma_f32_16x16x4_f32 v[140:143], v111, v127, v[140:143]
	ds_read2st64_b32 v[240:241], v11 offset0:60 offset1:65
	ds_read2st64_b32 v[242:243], v11 offset0:70 offset1:75
	s_waitcnt lgkmcnt(11)
	v_mfma_f32_16x16x4_f32 v[136:139], v112, v128, v[136:139]
	v_mfma_f32_16x16x4_f32 v[140:143], v113, v129, v[140:143]
	s_add_u32 s14, s6, 0x7c0000
	s_addc_u32 s15, s7, 0
	global_load_dword v212, v12, s[14:15] offset:0
	global_load_dword v213, v12, s[14:15] offset:256
	global_load_dword v214, v12, s[14:15] offset:512
	global_load_dword v215, v12, s[14:15] offset:768
	s_waitcnt lgkmcnt(10)
	v_mfma_f32_16x16x4_f32 v[136:139], v114, v130, v[136:139]
	v_mfma_f32_16x16x4_f32 v[140:143], v115, v131, v[140:143]
	s_waitcnt vmcnt(56)
	ds_write_b128 v2, v[84:87] offset:0
	ds_write_b128 v2, v[88:91] offset:10240
	s_waitcnt lgkmcnt(11)
	v_mfma_f32_16x16x4_f32 v[136:139], v116, v132, v[136:139]
	v_mfma_f32_16x16x4_f32 v[140:143], v117, v133, v[140:143]
	s_waitcnt lgkmcnt(10)
	v_mfma_f32_16x16x4_f32 v[136:139], v118, v134, v[136:139]
	v_mfma_f32_16x16x4_f32 v[140:143], v119, v135, v[140:143]
	s_add_u32 s16, s8, 0x720000
	s_addc_u32 s17, s9, 0
	s_nop 9
	v_add_f32_e32 v136, v136, v140
	v_add_f32_e32 v137, v137, v141
	v_add_f32_e32 v138, v138, v142
	v_add_f32_e32 v139, v139, v143
	ds_write_b32 v13, v136 offset:2176
	ds_write_b32 v13, v137 offset:2448
	ds_write_b32 v13, v138 offset:2720
	ds_write_b32 v13, v139 offset:2992
	global_store_dword v12, v136, s[16:17] offset:0
	global_store_dword v12, v137, s[16:17] offset:256
	global_store_dword v12, v138, s[16:17] offset:512
	global_store_dword v12, v139, s[16:17] offset:768
	s_waitcnt lgkmcnt(0)
	s_barrier
; #define LAS __attribute__((address_space(3)))
; __device__ __forceinline__ void scan_combine(LAS unsigned char* lds, CArgsP a) {
;     ...
;     for (int g = 1; g <= GL; ++g) {
;         const bool pf = (g + 2 <= GL);
;         float u3 = 0.f;
;         if (pf) { const f32x4* Pn = (const f32x4*)(PM + (size_t)((g + 2) * 8 + h) * 4096); pa = Pn[tid]; pb = Pn[512 + tid]; u3 = UM[((size_t)((g + 2) * 8 + h) * 64 + v) * 64 + kq]; }
;         asm volatile("s_waitcnt lgkmcnt(0)\n\ts_barrier" ::: "memory");
;         const LAS float* Pg = Pl + (g % 3) * 4096 + kq;
;         float acc0 = u1, acc1 = 0.f, acc2 = 0.f, acc3 = 0.f;
;         const int curi = __builtin_bit_cast(int, cur);
; #pragma unroll
;         for (int k = 0; k < 64; k += 4) {
;             const float s0 = __builtin_bit_cast(float, __builtin_amdgcn_readlane(curi, k)), s1 = __builtin_bit_cast(float, __builtin_amdgcn_readlane(curi, k + 1));
;             const float s2 = __builtin_bit_cast(float, __builtin_amdgcn_readlane(curi, k + 2)), s3 = __builtin_bit_cast(float, __builtin_amdgcn_readlane(curi, k + 3));
;             acc0 += s0 * Pg[(k + 0) * 64]; acc1 += s1 * Pg[(k + 1) * 64]; acc2 += s2 * Pg[(k + 2) * 64]; acc3 += s3 * Pg[(k + 3) * 64];
;         }
;         cur = (acc0 + acc1) + (acc2 + acc3);
;         SS[((size_t)((g + 1) * 8 + h) * 64 + v) * 64 + kq] = cur;
;         if (pf) { LAS float* dst = Pl + ((g + 2) % 3) * 4096; *(LAS f32x4*)(dst + 4 * tid) = pa; *(LAS f32x4*)(dst + 2048 + 4 * tid) = pb; }
;         u1 = u2; u2 = u3;
;     }
	ds_read2_b32 v[104:105], v9 offset0:0 offset1:4
	ds_read2_b32 v[106:107], v9 offset0:8 offset1:12
	ds_read2_b32 v[108:109], v9 offset0:16 offset1:20
	ds_read2_b32 v[110:111], v9 offset0:24 offset1:28
	ds_read2_b32 v[112:113], v9 offset0:32 offset1:36
	ds_read2_b32 v[114:115], v9 offset0:40 offset1:44
	ds_read2_b32 v[116:117], v9 offset0:48 offset1:52
	ds_read2_b32 v[118:119], v9 offset0:56 offset1:60
	s_waitcnt vmcnt(52)
	s_waitcnt lgkmcnt(7)
	v_mfma_f32_16x16x4_f32 v[136:139], v104, v228, v[216:219]
	v_mfma_f32_16x16x4_f32 v[140:143], v105, v229, 0
	ds_read2st64_b32 v[120:121], v10 offset0:0 offset1:5
	ds_read2st64_b32 v[122:123], v10 offset0:10 offset1:15
	s_waitcnt lgkmcnt(8)
	v_mfma_f32_16x16x4_f32 v[136:139], v106, v230, v[136:139]
	v_mfma_f32_16x16x4_f32 v[140:143], v107, v231, v[140:143]
	ds_read2st64_b32 v[124:125], v10 offset0:20 offset1:25
	ds_read2st64_b32 v[126:127], v10 offset0:30 offset1:35
	s_waitcnt lgkmcnt(9)
	v_mfma_f32_16x16x4_f32 v[136:139], v108, v232, v[136:139]
	v_mfma_f32_16x16x4_f32 v[140:143], v109, v233, v[140:143]
	ds_read2st64_b32 v[128:129], v10 offset0:40 offset1:45
	ds_read2st64_b32 v[130:131], v10 offset0:50 offset1:55
	s_waitcnt lgkmcnt(10)
	v_mfma_f32_16x16x4_f32 v[136:139], v110, v234, v[136:139]
	v_mfma_f32_16x16x4_f32 v[140:143], v111, v235, v[140:143]
	ds_read2st64_b32 v[132:133], v10 offset0:60 offset1:65
	ds_read2st64_b32 v[134:135], v10 offset0:70 offset1:75
	s_waitcnt lgkmcnt(11)
	v_mfma_f32_16x16x4_f32 v[136:139], v112, v236, v[136:139]
	v_mfma_f32_16x16x4_f32 v[140:143], v113, v237, v[140:143]
	s_waitcnt lgkmcnt(10)
	v_mfma_f32_16x16x4_f32 v[136:139], v114, v238, v[136:139]
	v_mfma_f32_16x16x4_f32 v[140:143], v115, v239, v[140:143]
	s_waitcnt vmcnt(50)
	ds_write_b128 v2, v[92:95] offset:20480
	ds_write_b128 v2, v[96:99] offset:30720
	s_waitcnt lgkmcnt(11)
	v_mfma_f32_16x16x4_f32 v[136:139], v116, v240, v[136:139]
	v_mfma_f32_16x16x4_f32 v[140:143], v117, v241, v[140:143]
	s_waitcnt lgkmcnt(10)
	v_mfma_f32_16x16x4_f32 v[136:139], v118, v242, v[136:139]
	v_mfma_f32_16x16x4_f32 v[140:143], v119, v243, v[140:143]
	s_add_u32 s16, s8, 0x740000
	s_addc_u32 s17, s9, 0
	s_nop 9
	v_add_f32_e32 v136, v136, v140
	v_add_f32_e32 v137, v137, v141
	v_add_f32_e32 v138, v138, v142
	v_add_f32_e32 v139, v139, v143
	ds_write_b32 v13, v136 offset:0
	ds_write_b32 v13, v137 offset:272
	ds_write_b32 v13, v138 offset:544
	ds_write_b32 v13, v139 offset:816
	global_store_dword v12, v136, s[16:17] offset:0
	global_store_dword v12, v137, s[16:17] offset:256
	global_store_dword v12, v138, s[16:17] offset:512
	global_store_dword v12, v139, s[16:17] offset:768
	s_waitcnt lgkmcnt(0)
	s_barrier
	ds_read2_b32 v[104:105], v8 offset0:0 offset1:4
	ds_read2_b32 v[106:107], v8 offset0:8 offset1:12
	ds_read2_b32 v[108:109], v8 offset0:16 offset1:20
	ds_read2_b32 v[110:111], v8 offset0:24 offset1:28
	ds_read2_b32 v[112:113], v8 offset0:32 offset1:36
	ds_read2_b32 v[114:115], v8 offset0:40 offset1:44
	ds_read2_b32 v[116:117], v8 offset0:48 offset1:52
	ds_read2_b32 v[118:119], v8 offset0:56 offset1:60
	s_waitcnt vmcnt(46)
	s_waitcnt lgkmcnt(7)
	v_mfma_f32_16x16x4_f32 v[136:139], v104, v120, v[220:223]
	v_mfma_f32_16x16x4_f32 v[140:143], v105, v121, 0
	ds_read2st64_b32 v[228:229], v11 offset0:0 offset1:5
	ds_read2st64_b32 v[230:231], v11 offset0:10 offset1:15
	s_waitcnt lgkmcnt(8)
	v_mfma_f32_16x16x4_f32 v[136:139], v106, v122, v[136:139]
	v_mfma_f32_16x16x4_f32 v[140:143], v107, v123, v[140:143]
	ds_read2st64_b32 v[232:233], v11 offset0:20 offset1:25
	ds_read2st64_b32 v[234:235], v11 offset0:30 offset1:35
	s_waitcnt lgkmcnt(9)
	v_mfma_f32_16x16x4_f32 v[136:139], v108, v124, v[136:139]
	v_mfma_f32_16x16x4_f32 v[140:143], v109, v125, v[140:143]
	ds_read2st64_b32 v[236:237], v11 offset0:40 offset1:45
	ds_read2st64_b32 v[238:239], v11 offset0:50 offset1:55
	s_waitcnt lgkmcnt(10)
	v_mfma_f32_16x16x4_f32 v[136:139], v110, v126, v[136:139]
	v_mfma_f32_16x16x4_f32 v[140:143], v111, v127, v[140:143]
	ds_read2st64_b32 v[240:241], v11 offset0:60 offset1:65
	ds_read2st64_b32 v[242:243], v11 offset0:70 offset1:75
	s_waitcnt lgkmcnt(11)
	v_mfma_f32_16x16x4_f32 v[136:139], v112, v128, v[136:139]
	v_mfma_f32_16x16x4_f32 v[140:143], v113, v129, v[140:143]
	s_waitcnt lgkmcnt(10)
	v_mfma_f32_16x16x4_f32 v[136:139], v114, v130, v[136:139]
	v_mfma_f32_16x16x4_f32 v[140:143], v115, v131, v[140:143]
	s_waitcnt vmcnt(44)
	ds_write_b128 v2, v[52:55] offset:0
	ds_write_b128 v2, v[56:59] offset:10240
	s_waitcnt lgkmcnt(11)
	v_mfma_f32_16x16x4_f32 v[136:139], v116, v132, v[136:139]
	v_mfma_f32_16x16x4_f32 v[140:143], v117, v133, v[140:143]
	s_waitcnt lgkmcnt(10)
	v_mfma_f32_16x16x4_f32 v[136:139], v118, v134, v[136:139]
	v_mfma_f32_16x16x4_f32 v[140:143], v119, v135, v[140:143]
	s_add_u32 s16, s8, 0x760000
	s_addc_u32 s17, s9, 0
	s_nop 9
	v_add_f32_e32 v136, v136, v140
	v_add_f32_e32 v137, v137, v141
	v_add_f32_e32 v138, v138, v142
	v_add_f32_e32 v139, v139, v143
	ds_write_b32 v13, v136 offset:2176
	ds_write_b32 v13, v137 offset:2448
	ds_write_b32 v13, v138 offset:2720
	ds_write_b32 v13, v139 offset:2992
	global_store_dword v12, v136, s[16:17] offset:0
	global_store_dword v12, v137, s[16:17] offset:256
	global_store_dword v12, v138, s[16:17] offset:512
	global_store_dword v12, v139, s[16:17] offset:768
	s_waitcnt lgkmcnt(0)
	s_barrier
; #define LAS __attribute__((address_space(3)))
; __device__ __forceinline__ void scan_combine(LAS unsigned char* lds, CArgsP a) {
;     ...
;     for (int g = 1; g <= GL; ++g) {
;         const bool pf = (g + 2 <= GL);
;         float u3 = 0.f;
;         if (pf) { const f32x4* Pn = (const f32x4*)(PM + (size_t)((g + 2) * 8 + h) * 4096); pa = Pn[tid]; pb = Pn[512 + tid]; u3 = UM[((size_t)((g + 2) * 8 + h) * 64 + v) * 64 + kq]; }
;         asm volatile("s_waitcnt lgkmcnt(0)\n\ts_barrier" ::: "memory");
;         const LAS float* Pg = Pl + (g % 3) * 4096 + kq;
;         float acc0 = u1, acc1 = 0.f, acc2 = 0.f, acc3 = 0.f;
;         const int curi = __builtin_bit_cast(int, cur);
; #pragma unroll
;         for (int k = 0; k < 64; k += 4) {
;             const float s0 = __builtin_bit_cast(float, __builtin_amdgcn_readlane(curi, k)), s1 = __builtin_bit_cast(float, __builtin_amdgcn_readlane(curi, k + 1));
;             const float s2 = __builtin_bit_cast(float, __builtin_amdgcn_readlane(curi, k + 2)), s3 = __builtin_bit_cast(float, __builtin_amdgcn_readlane(curi, k + 3));
;             acc0 += s0 * Pg[(k + 0) * 64]; acc1 += s1 * Pg[(k + 1) * 64]; acc2 += s2 * Pg[(k + 2) * 64]; acc3 += s3 * Pg[(k + 3) * 64];
;         }
;         cur = (acc0 + acc1) + (acc2 + acc3);
;         SS[((size_t)((g + 1) * 8 + h) * 64 + v) * 64 + kq] = cur;
;         if (pf) { LAS float* dst = Pl + ((g + 2) % 3) * 4096; *(LAS f32x4*)(dst + 4 * tid) = pa; *(LAS f32x4*)(dst + 2048 + 4 * tid) = pb; }
;         u1 = u2; u2 = u3;
;     }
	ds_read2_b32 v[104:105], v9 offset0:0 offset1:4
	ds_read2_b32 v[106:107], v9 offset0:8 offset1:12
	ds_read2_b32 v[108:109], v9 offset0:16 offset1:20
	ds_read2_b32 v[110:111], v9 offset0:24 offset1:28
	ds_read2_b32 v[112:113], v9 offset0:32 offset1:36
	ds_read2_b32 v[114:115], v9 offset0:40 offset1:44
	ds_read2_b32 v[116:117], v9 offset0:48 offset1:52
	ds_read2_b32 v[118:119], v9 offset0:56 offset1:60
	s_waitcnt vmcnt(40)
	s_waitcnt lgkmcnt(7)
	v_mfma_f32_16x16x4_f32 v[136:139], v104, v228, v[224:227]
	v_mfma_f32_16x16x4_f32 v[140:143], v105, v229, 0
	ds_read2st64_b32 v[120:121], v10 offset0:0 offset1:5
	ds_read2st64_b32 v[122:123], v10 offset0:10 offset1:15
	s_waitcnt lgkmcnt(8)
	v_mfma_f32_16x16x4_f32 v[136:139], v106, v230, v[136:139]
	v_mfma_f32_16x16x4_f32 v[140:143], v107, v231, v[140:143]
	ds_read2st64_b32 v[124:125], v10 offset0:20 offset1:25
	ds_read2st64_b32 v[126:127], v10 offset0:30 offset1:35
	s_waitcnt lgkmcnt(9)
	v_mfma_f32_16x16x4_f32 v[136:139], v108, v232, v[136:139]
	v_mfma_f32_16x16x4_f32 v[140:143], v109, v233, v[140:143]
	ds_read2st64_b32 v[128:129], v10 offset0:40 offset1:45
	ds_read2st64_b32 v[130:131], v10 offset0:50 offset1:55
	s_waitcnt lgkmcnt(10)
	v_mfma_f32_16x16x4_f32 v[136:139], v110, v234, v[136:139]
	v_mfma_f32_16x16x4_f32 v[140:143], v111, v235, v[140:143]
	ds_read2st64_b32 v[132:133], v10 offset0:60 offset1:65
	ds_read2st64_b32 v[134:135], v10 offset0:70 offset1:75
	s_waitcnt lgkmcnt(11)
	v_mfma_f32_16x16x4_f32 v[136:139], v112, v236, v[136:139]
	v_mfma_f32_16x16x4_f32 v[140:143], v113, v237, v[140:143]
	s_waitcnt lgkmcnt(10)
	v_mfma_f32_16x16x4_f32 v[136:139], v114, v238, v[136:139]
	v_mfma_f32_16x16x4_f32 v[140:143], v115, v239, v[140:143]
	s_waitcnt vmcnt(38)
	ds_write_b128 v2, v[60:63] offset:20480
	ds_write_b128 v2, v[64:67] offset:30720
	s_waitcnt lgkmcnt(11)
	v_mfma_f32_16x16x4_f32 v[136:139], v116, v240, v[136:139]
	v_mfma_f32_16x16x4_f32 v[140:143], v117, v241, v[140:143]
	s_waitcnt lgkmcnt(10)
	v_mfma_f32_16x16x4_f32 v[136:139], v118, v242, v[136:139]
	v_mfma_f32_16x16x4_f32 v[140:143], v119, v243, v[140:143]
	s_add_u32 s16, s8, 0x780000
	s_addc_u32 s17, s9, 0
	s_nop 9
	v_add_f32_e32 v136, v136, v140
	v_add_f32_e32 v137, v137, v141
	v_add_f32_e32 v138, v138, v142
	v_add_f32_e32 v139, v139, v143
	ds_write_b32 v13, v136 offset:0
	ds_write_b32 v13, v137 offset:272
	ds_write_b32 v13, v138 offset:544
	ds_write_b32 v13, v139 offset:816
	global_store_dword v12, v136, s[16:17] offset:0
	global_store_dword v12, v137, s[16:17] offset:256
	global_store_dword v12, v138, s[16:17] offset:512
	global_store_dword v12, v139, s[16:17] offset:768
	s_waitcnt lgkmcnt(0)
	s_barrier
	ds_read2_b32 v[104:105], v8 offset0:0 offset1:4
	ds_read2_b32 v[106:107], v8 offset0:8 offset1:12
	ds_read2_b32 v[108:109], v8 offset0:16 offset1:20
	ds_read2_b32 v[110:111], v8 offset0:24 offset1:28
	ds_read2_b32 v[112:113], v8 offset0:32 offset1:36
	ds_read2_b32 v[114:115], v8 offset0:40 offset1:44
	ds_read2_b32 v[116:117], v8 offset0:48 offset1:52
	ds_read2_b32 v[118:119], v8 offset0:56 offset1:60
	s_waitcnt vmcnt(34)
	s_waitcnt lgkmcnt(7)
	v_mfma_f32_16x16x4_f32 v[136:139], v104, v120, v[204:207]
	v_mfma_f32_16x16x4_f32 v[140:143], v105, v121, 0
	ds_read2st64_b32 v[228:229], v11 offset0:0 offset1:5
	ds_read2st64_b32 v[230:231], v11 offset0:10 offset1:15
	s_waitcnt lgkmcnt(8)
	v_mfma_f32_16x16x4_f32 v[136:139], v106, v122, v[136:139]
	v_mfma_f32_16x16x4_f32 v[140:143], v107, v123, v[140:143]
	ds_read2st64_b32 v[232:233], v11 offset0:20 offset1:25
	ds_read2st64_b32 v[234:235], v11 offset0:30 offset1:35
	s_waitcnt lgkmcnt(9)
	v_mfma_f32_16x16x4_f32 v[136:139], v108, v124, v[136:139]
	v_mfma_f32_16x16x4_f32 v[140:143], v109, v125, v[140:143]
	ds_read2st64_b32 v[236:237], v11 offset0:40 offset1:45
	ds_read2st64_b32 v[238:239], v11 offset0:50 offset1:55
	s_waitcnt lgkmcnt(10)
	v_mfma_f32_16x16x4_f32 v[136:139], v110, v126, v[136:139]
	v_mfma_f32_16x16x4_f32 v[140:143], v111, v127, v[140:143]
	ds_read2st64_b32 v[240:241], v11 offset0:60 offset1:65
	ds_read2st64_b32 v[242:243], v11 offset0:70 offset1:75
	s_waitcnt lgkmcnt(11)
	v_mfma_f32_16x16x4_f32 v[136:139], v112, v128, v[136:139]
	v_mfma_f32_16x16x4_f32 v[140:143], v113, v129, v[140:143]
	s_waitcnt lgkmcnt(10)
	v_mfma_f32_16x16x4_f32 v[136:139], v114, v130, v[136:139]
	v_mfma_f32_16x16x4_f32 v[140:143], v115, v131, v[140:143]
	s_waitcnt vmcnt(32)
	ds_write_b128 v2, v[68:71] offset:0
	ds_write_b128 v2, v[72:75] offset:10240
	s_waitcnt lgkmcnt(11)
	v_mfma_f32_16x16x4_f32 v[136:139], v116, v132, v[136:139]
	v_mfma_f32_16x16x4_f32 v[140:143], v117, v133, v[140:143]
	s_waitcnt lgkmcnt(10)
	v_mfma_f32_16x16x4_f32 v[136:139], v118, v134, v[136:139]
	v_mfma_f32_16x16x4_f32 v[140:143], v119, v135, v[140:143]
	s_add_u32 s16, s8, 0x7a0000
	s_addc_u32 s17, s9, 0
	s_nop 9
	v_add_f32_e32 v136, v136, v140
	v_add_f32_e32 v137, v137, v141
	v_add_f32_e32 v138, v138, v142
	v_add_f32_e32 v139, v139, v143
	ds_write_b32 v13, v136 offset:2176
	ds_write_b32 v13, v137 offset:2448
	ds_write_b32 v13, v138 offset:2720
	ds_write_b32 v13, v139 offset:2992
	global_store_dword v12, v136, s[16:17] offset:0
	global_store_dword v12, v137, s[16:17] offset:256
	global_store_dword v12, v138, s[16:17] offset:512
	global_store_dword v12, v139, s[16:17] offset:768
	s_waitcnt lgkmcnt(0)
	s_barrier
; #define LAS __attribute__((address_space(3)))
; __device__ __forceinline__ void scan_combine(LAS unsigned char* lds, CArgsP a) {
;     ...
;     for (int g = 1; g <= GL; ++g) {
;         const bool pf = (g + 2 <= GL);
;         float u3 = 0.f;
;         if (pf) { const f32x4* Pn = (const f32x4*)(PM + (size_t)((g + 2) * 8 + h) * 4096); pa = Pn[tid]; pb = Pn[512 + tid]; u3 = UM[((size_t)((g + 2) * 8 + h) * 64 + v) * 64 + kq]; }
;         asm volatile("s_waitcnt lgkmcnt(0)\n\ts_barrier" ::: "memory");
;         const LAS float* Pg = Pl + (g % 3) * 4096 + kq;
;         float acc0 = u1, acc1 = 0.f, acc2 = 0.f, acc3 = 0.f;
;         const int curi = __builtin_bit_cast(int, cur);
; #pragma unroll
;         for (int k = 0; k < 64; k += 4) {
;             const float s0 = __builtin_bit_cast(float, __builtin_amdgcn_readlane(curi, k)), s1 = __builtin_bit_cast(float, __builtin_amdgcn_readlane(curi, k + 1));
;             const float s2 = __builtin_bit_cast(float, __builtin_amdgcn_readlane(curi, k + 2)), s3 = __builtin_bit_cast(float, __builtin_amdgcn_readlane(curi, k + 3));
;             acc0 += s0 * Pg[(k + 0) * 64]; acc1 += s1 * Pg[(k + 1) * 64]; acc2 += s2 * Pg[(k + 2) * 64]; acc3 += s3 * Pg[(k + 3) * 64];
;         }
;         cur = (acc0 + acc1) + (acc2 + acc3);
;         SS[((size_t)((g + 1) * 8 + h) * 64 + v) * 64 + kq] = cur;
;         if (pf) { LAS float* dst = Pl + ((g + 2) % 3) * 4096; *(LAS f32x4*)(dst + 4 * tid) = pa; *(LAS f32x4*)(dst + 2048 + 4 * tid) = pb; }
;         u1 = u2; u2 = u3;
;     }
	ds_read2_b32 v[104:105], v9 offset0:0 offset1:4
	ds_read2_b32 v[106:107], v9 offset0:8 offset1:12
	ds_read2_b32 v[108:109], v9 offset0:16 offset1:20
	ds_read2_b32 v[110:111], v9 offset0:24 offset1:28
	ds_read2_b32 v[112:113], v9 offset0:32 offset1:36
	ds_read2_b32 v[114:115], v9 offset0:40 offset1:44
	ds_read2_b32 v[116:117], v9 offset0:48 offset1:52
	ds_read2_b32 v[118:119], v9 offset0:56 offset1:60
	s_waitcnt vmcnt(28)
	s_waitcnt lgkmcnt(7)
	v_mfma_f32_16x16x4_f32 v[136:139], v104, v228, v[208:211]
	v_mfma_f32_16x16x4_f32 v[140:143], v105, v229, 0
	ds_read2st64_b32 v[120:121], v10 offset0:0 offset1:5
	ds_read2st64_b32 v[122:123], v10 offset0:10 offset1:15
	s_waitcnt lgkmcnt(8)
	v_mfma_f32_16x16x4_f32 v[136:139], v106, v230, v[136:139]
	v_mfma_f32_16x16x4_f32 v[140:143], v107, v231, v[140:143]
	ds_read2st64_b32 v[124:125], v10 offset0:20 offset1:25
	ds_read2st64_b32 v[126:127], v10 offset0:30 offset1:35
	s_waitcnt lgkmcnt(9)
	v_mfma_f32_16x16x4_f32 v[136:139], v108, v232, v[136:139]
	v_mfma_f32_16x16x4_f32 v[140:143], v109, v233, v[140:143]
	ds_read2st64_b32 v[128:129], v10 offset0:40 offset1:45
	ds_read2st64_b32 v[130:131], v10 offset0:50 offset1:55
	s_waitcnt lgkmcnt(10)
	v_mfma_f32_16x16x4_f32 v[136:139], v110, v234, v[136:139]
	v_mfma_f32_16x16x4_f32 v[140:143], v111, v235, v[140:143]
	ds_read2st64_b32 v[132:133], v10 offset0:60 offset1:65
	ds_read2st64_b32 v[134:135], v10 offset0:70 offset1:75
	s_waitcnt lgkmcnt(11)
	v_mfma_f32_16x16x4_f32 v[136:139], v112, v236, v[136:139]
	v_mfma_f32_16x16x4_f32 v[140:143], v113, v237, v[140:143]
	s_waitcnt lgkmcnt(10)
	v_mfma_f32_16x16x4_f32 v[136:139], v114, v238, v[136:139]
	v_mfma_f32_16x16x4_f32 v[140:143], v115, v239, v[140:143]
	s_waitcnt lgkmcnt(9)
	v_mfma_f32_16x16x4_f32 v[136:139], v116, v240, v[136:139]
	v_mfma_f32_16x16x4_f32 v[140:143], v117, v241, v[140:143]
	s_waitcnt lgkmcnt(8)
	v_mfma_f32_16x16x4_f32 v[136:139], v118, v242, v[136:139]
	v_mfma_f32_16x16x4_f32 v[140:143], v119, v243, v[140:143]
	s_add_u32 s16, s8, 0x7c0000
	s_addc_u32 s17, s9, 0
	s_nop 9
	v_add_f32_e32 v136, v136, v140
	v_add_f32_e32 v137, v137, v141
	v_add_f32_e32 v138, v138, v142
	v_add_f32_e32 v139, v139, v143
	ds_write_b32 v13, v136 offset:0
	ds_write_b32 v13, v137 offset:272
	ds_write_b32 v13, v138 offset:544
	ds_write_b32 v13, v139 offset:816
	global_store_dword v12, v136, s[16:17] offset:0
	global_store_dword v12, v137, s[16:17] offset:256
	global_store_dword v12, v138, s[16:17] offset:512
	global_store_dword v12, v139, s[16:17] offset:768
	s_waitcnt lgkmcnt(0)
	s_barrier
	ds_read2_b32 v[104:105], v8 offset0:0 offset1:4
	ds_read2_b32 v[106:107], v8 offset0:8 offset1:12
	ds_read2_b32 v[108:109], v8 offset0:16 offset1:20
	ds_read2_b32 v[110:111], v8 offset0:24 offset1:28
	ds_read2_b32 v[112:113], v8 offset0:32 offset1:36
	ds_read2_b32 v[114:115], v8 offset0:40 offset1:44
	ds_read2_b32 v[116:117], v8 offset0:48 offset1:52
	ds_read2_b32 v[118:119], v8 offset0:56 offset1:60
	s_waitcnt vmcnt(24)
	s_waitcnt lgkmcnt(7)
	v_mfma_f32_16x16x4_f32 v[136:139], v104, v120, v[212:215]
	v_mfma_f32_16x16x4_f32 v[140:143], v105, v121, 0
	s_waitcnt lgkmcnt(6)
	v_mfma_f32_16x16x4_f32 v[136:139], v106, v122, v[136:139]
	v_mfma_f32_16x16x4_f32 v[140:143], v107, v123, v[140:143]
	s_waitcnt lgkmcnt(5)
	v_mfma_f32_16x16x4_f32 v[136:139], v108, v124, v[136:139]
	v_mfma_f32_16x16x4_f32 v[140:143], v109, v125, v[140:143]
	s_waitcnt lgkmcnt(4)
	v_mfma_f32_16x16x4_f32 v[136:139], v110, v126, v[136:139]
	v_mfma_f32_16x16x4_f32 v[140:143], v111, v127, v[140:143]
	s_waitcnt lgkmcnt(3)
	v_mfma_f32_16x16x4_f32 v[136:139], v112, v128, v[136:139]
	v_mfma_f32_16x16x4_f32 v[140:143], v113, v129, v[140:143]
	s_waitcnt lgkmcnt(2)
	v_mfma_f32_16x16x4_f32 v[136:139], v114, v130, v[136:139]
	v_mfma_f32_16x16x4_f32 v[140:143], v115, v131, v[140:143]
	s_waitcnt lgkmcnt(1)
	v_mfma_f32_16x16x4_f32 v[136:139], v116, v132, v[136:139]
	v_mfma_f32_16x16x4_f32 v[140:143], v117, v133, v[140:143]
	s_waitcnt lgkmcnt(0)
	v_mfma_f32_16x16x4_f32 v[136:139], v118, v134, v[136:139]
	v_mfma_f32_16x16x4_f32 v[140:143], v119, v135, v[140:143]
	s_add_u32 s16, s8, 0x7e0000
	s_addc_u32 s17, s9, 0
	s_nop 9
	v_add_f32_e32 v136, v136, v140
	v_add_f32_e32 v137, v137, v141
	v_add_f32_e32 v138, v138, v142
	v_add_f32_e32 v139, v139, v143
	global_store_dword v12, v136, s[16:17] offset:0
	global_store_dword v12, v137, s[16:17] offset:256
	global_store_dword v12, v138, s[16:17] offset:512
	global_store_dword v12, v139, s[16:17] offset:768
	s_branch .Lcmb_done
; #define LAS __attribute__((address_space(3)))
; __device__ __forceinline__ void scan_combine(LAS unsigned char* lds, CArgsP a) {
;     ...
;         if (pf) { const f32x4* Pn = (const f32x4*)(PM + (size_t)((g + 2) * 8 + h) * 4096); pa = Pn[tid]; pb = Pn[512 + tid]; u3 = UM[((size_t)((g + 2) * 8 + h) * 64 + v) * 64 + kq]; }
;         asm volatile("s_waitcnt lgkmcnt(0)\n\ts_barrier" ::: "memory");
;         const LAS float* Pg = Pl + (g % 3) * 4096 + kq;
;         float acc0 = u1, acc1 = 0.f, acc2 = 0.f, acc3 = 0.f;
;         const int curi = __builtin_bit_cast(int, cur);
; #pragma unroll
;         for (int k = 0; k < 64; k += 4) {
;             const float s0 = __builtin_bit_cast(float, __builtin_amdgcn_readlane(curi, k)), s1 = __builtin_bit_cast(float, __builtin_amdgcn_readlane(curi, k + 1));
;             const float s2 = __builtin_bit_cast(float, __builtin_amdgcn_readlane(curi, k + 2)), s3 = __builtin_bit_cast(float, __builtin_amdgcn_readlane(curi, k + 3));
;             acc0 += s0 * Pg[(k + 0) * 64]; acc1 += s1 * Pg[(k + 1) * 64]; acc2 += s2 * Pg[(k + 2) * 64]; acc3 += s3 * Pg[(k + 3) * 64];
;         }
;         cur = (acc0 + acc1) + (acc2 + acc3);
;         SS[((size_t)((g + 1) * 8 + h) * 64 + v) * 64 + kq] = cur;
;         if (pf) { LAS float* dst = Pl + ((g + 2) % 3) * 4096; *(LAS f32x4*)(dst + 4 * tid) = pa; *(LAS f32x4*)(dst + 2048 + 4 * tid) = pb; }
.Lcmb_loader:
	s_waitcnt lgkmcnt(0)
	s_barrier
	s_barrier
	s_waitcnt vmcnt(10)
	ds_write_b128 v2, v[76:79] offset:20480
	ds_write_b128 v2, v[80:83] offset:30720
	s_add_u32 s10, s0, 0x120000
	s_addc_u32 s11, s1, 0
	global_load_dwordx4 v[76:79], v0, s[10:11]
	global_load_dwordx4 v[80:83], v1, s[10:11]
	s_waitcnt lgkmcnt(0)
	s_barrier
	s_waitcnt vmcnt(10)
	ds_write_b128 v2, v[84:87] offset:0
	ds_write_b128 v2, v[88:91] offset:10240
	s_add_u32 s10, s0, 0x140000
	s_addc_u32 s11, s1, 0
	global_load_dwordx4 v[84:87], v0, s[10:11]
	global_load_dwordx4 v[88:91], v1, s[10:11]
	s_waitcnt lgkmcnt(0)
	s_barrier
	s_waitcnt vmcnt(10)
	ds_write_b128 v2, v[92:95] offset:20480
	ds_write_b128 v2, v[96:99] offset:30720
	s_add_u32 s10, s0, 0x160000
	s_addc_u32 s11, s1, 0
	global_load_dwordx4 v[92:95], v0, s[10:11]
	global_load_dwordx4 v[96:99], v1, s[10:11]
	s_waitcnt lgkmcnt(0)
	s_barrier
	s_waitcnt vmcnt(10)
	ds_write_b128 v2, v[52:55] offset:0
	ds_write_b128 v2, v[56:59] offset:10240
	s_add_u32 s10, s0, 0x180000
	s_addc_u32 s11, s1, 0
	global_load_dwordx4 v[52:55], v0, s[10:11]
	global_load_dwordx4 v[56:59], v1, s[10:11]
	s_waitcnt lgkmcnt(0)
	s_barrier
	s_waitcnt vmcnt(10)
	ds_write_b128 v2, v[60:63] offset:20480
	ds_write_b128 v2, v[64:67] offset:30720
	s_add_u32 s10, s0, 0x1a0000
	s_addc_u32 s11, s1, 0
	global_load_dwordx4 v[60:63], v0, s[10:11]
	global_load_dwordx4 v[64:67], v1, s[10:11]
	s_waitcnt lgkmcnt(0)
	s_barrier
	s_waitcnt vmcnt(10)
	ds_write_b128 v2, v[68:71] offset:0
	ds_write_b128 v2, v[72:75] offset:10240
	s_add_u32 s10, s0, 0x1c0000
	s_addc_u32 s11, s1, 0
	global_load_dwordx4 v[68:71], v0, s[10:11]
	global_load_dwordx4 v[72:75], v1, s[10:11]
	s_waitcnt lgkmcnt(0)
	s_barrier
	s_waitcnt vmcnt(10)
	ds_write_b128 v2, v[76:79] offset:20480
	ds_write_b128 v2, v[80:83] offset:30720
	s_add_u32 s10, s0, 0x1e0000
	s_addc_u32 s11, s1, 0
	global_load_dwordx4 v[76:79], v0, s[10:11]
	global_load_dwordx4 v[80:83], v1, s[10:11]
	s_waitcnt lgkmcnt(0)
	s_barrier
	s_waitcnt vmcnt(10)
	ds_write_b128 v2, v[84:87] offset:0
	ds_write_b128 v2, v[88:91] offset:10240
	s_add_u32 s10, s0, 0x200000
	s_addc_u32 s11, s1, 0
	global_load_dwordx4 v[84:87], v0, s[10:11]
	global_load_dwordx4 v[88:91], v1, s[10:11]
	s_waitcnt lgkmcnt(0)
	s_barrier
	s_waitcnt vmcnt(10)
	ds_write_b128 v2, v[92:95] offset:20480
	ds_write_b128 v2, v[96:99] offset:30720
	s_add_u32 s10, s0, 0x220000
	s_addc_u32 s11, s1, 0
	global_load_dwordx4 v[92:95], v0, s[10:11]
	global_load_dwordx4 v[96:99], v1, s[10:11]
	s_waitcnt lgkmcnt(0)
	s_barrier
	s_waitcnt vmcnt(10)
	ds_write_b128 v2, v[52:55] offset:0
	ds_write_b128 v2, v[56:59] offset:10240
	s_add_u32 s10, s0, 0x240000
	s_addc_u32 s11, s1, 0
	global_load_dwordx4 v[52:55], v0, s[10:11]
	global_load_dwordx4 v[56:59], v1, s[10:11]
	s_waitcnt lgkmcnt(0)
	s_barrier
	s_waitcnt vmcnt(10)
	ds_write_b128 v2, v[60:63] offset:20480
	ds_write_b128 v2, v[64:67] offset:30720
	s_add_u32 s10, s0, 0x260000
	s_addc_u32 s11, s1, 0
	global_load_dwordx4 v[60:63], v0, s[10:11]
	global_load_dwordx4 v[64:67], v1, s[10:11]
	s_waitcnt lgkmcnt(0)
	s_barrier
	s_waitcnt vmcnt(10)
	ds_write_b128 v2, v[68:71] offset:0
	ds_write_b128 v2, v[72:75] offset:10240
	s_add_u32 s10, s0, 0x280000
	s_addc_u32 s11, s1, 0
	global_load_dwordx4 v[68:71], v0, s[10:11]
	global_load_dwordx4 v[72:75], v1, s[10:11]
	s_waitcnt lgkmcnt(0)
	s_barrier
	s_waitcnt vmcnt(10)
	ds_write_b128 v2, v[76:79] offset:20480
	ds_write_b128 v2, v[80:83] offset:30720
	s_add_u32 s10, s0, 0x2a0000
	s_addc_u32 s11, s1, 0
	global_load_dwordx4 v[76:79], v0, s[10:11]
	global_load_dwordx4 v[80:83], v1, s[10:11]
	s_waitcnt lgkmcnt(0)
	s_barrier
	s_waitcnt vmcnt(10)
	ds_write_b128 v2, v[84:87] offset:0
	ds_write_b128 v2, v[88:91] offset:10240
	s_add_u32 s10, s0, 0x2c0000
	s_addc_u32 s11, s1, 0
	global_load_dwordx4 v[84:87], v0, s[10:11]
	global_load_dwordx4 v[88:91], v1, s[10:11]
	s_waitcnt lgkmcnt(0)
	s_barrier
	s_waitcnt vmcnt(10)
	ds_write_b128 v2, v[92:95] offset:20480
	ds_write_b128 v2, v[96:99] offset:30720
	s_add_u32 s10, s0, 0x2e0000
	s_addc_u32 s11, s1, 0
	global_load_dwordx4 v[92:95], v0, s[10:11]
	global_load_dwordx4 v[96:99], v1, s[10:11]
	s_waitcnt lgkmcnt(0)
	s_barrier
	s_waitcnt vmcnt(10)
	ds_write_b128 v2, v[52:55] offset:0
	ds_write_b128 v2, v[56:59] offset:10240
	s_add_u32 s10, s0, 0x300000
	s_addc_u32 s11, s1, 0
	global_load_dwordx4 v[52:55], v0, s[10:11]
	global_load_dwordx4 v[56:59], v1, s[10:11]
	s_waitcnt lgkmcnt(0)
	s_barrier
	s_waitcnt vmcnt(10)
	ds_write_b128 v2, v[60:63] offset:20480
	ds_write_b128 v2, v[64:67] offset:30720
	s_add_u32 s10, s0, 0x320000
	s_addc_u32 s11, s1, 0
	global_load_dwordx4 v[60:63], v0, s[10:11]
	global_load_dwordx4 v[64:67], v1, s[10:11]
	s_waitcnt lgkmcnt(0)
	s_barrier
	s_waitcnt vmcnt(10)
	ds_write_b128 v2, v[68:71] offset:0
	ds_write_b128 v2, v[72:75] offset:10240
	s_add_u32 s10, s0, 0x340000
	s_addc_u32 s11, s1, 0
	global_load_dwordx4 v[68:71], v0, s[10:11]
	global_load_dwordx4 v[72:75], v1, s[10:11]
	s_waitcnt lgkmcnt(0)
	s_barrier
	s_waitcnt vmcnt(10)
	ds_write_b128 v2, v[76:79] offset:20480
	ds_write_b128 v2, v[80:83] offset:30720
	s_add_u32 s10, s0, 0x360000
	s_addc_u32 s11, s1, 0
	global_load_dwordx4 v[76:79], v0, s[10:11]
	global_load_dwordx4 v[80:83], v1, s[10:11]
	s_waitcnt lgkmcnt(0)
	s_barrier
	s_waitcnt vmcnt(10)
	ds_write_b128 v2, v[84:87] offset:0
	ds_write_b128 v2, v[88:91] offset:10240
	s_add_u32 s10, s0, 0x380000
	s_addc_u32 s11, s1, 0
	global_load_dwordx4 v[84:87], v0, s[10:11]
	global_load_dwordx4 v[88:91], v1, s[10:11]
	s_waitcnt lgkmcnt(0)
	s_barrier
; #define LAS __attribute__((address_space(3)))
; __device__ __forceinline__ void scan_combine(LAS unsigned char* lds, CArgsP a) {
;     ...
;         if (pf) { const f32x4* Pn = (const f32x4*)(PM + (size_t)((g + 2) * 8 + h) * 4096); pa = Pn[tid]; pb = Pn[512 + tid]; u3 = UM[((size_t)((g + 2) * 8 + h) * 64 + v) * 64 + kq]; }
;         asm volatile("s_waitcnt lgkmcnt(0)\n\ts_barrier" ::: "memory");
;         const LAS float* Pg = Pl + (g % 3) * 4096 + kq;
;         float acc0 = u1, acc1 = 0.f, acc2 = 0.f, acc3 = 0.f;
;         const int curi = __builtin_bit_cast(int, cur);
; #pragma unroll
;         for (int k = 0; k < 64; k += 4) {
;             const float s0 = __builtin_bit_cast(float, __builtin_amdgcn_readlane(curi, k)), s1 = __builtin_bit_cast(float, __builtin_amdgcn_readlane(curi, k + 1));
;             const float s2 = __builtin_bit_cast(float, __builtin_amdgcn_readlane(curi, k + 2)), s3 = __builtin_bit_cast(float, __builtin_amdgcn_readlane(curi, k + 3));
;             acc0 += s0 * Pg[(k + 0) * 64]; acc1 += s1 * Pg[(k + 1) * 64]; acc2 += s2 * Pg[(k + 2) * 64]; acc3 += s3 * Pg[(k + 3) * 64];
;         }
;         cur = (acc0 + acc1) + (acc2 + acc3);
;         SS[((size_t)((g + 1) * 8 + h) * 64 + v) * 64 + kq] = cur;
;         if (pf) { LAS float* dst = Pl + ((g + 2) % 3) * 4096; *(LAS f32x4*)(dst + 4 * tid) = pa; *(LAS f32x4*)(dst + 2048 + 4 * tid) = pb; }
	s_waitcnt vmcnt(10)
	ds_write_b128 v2, v[92:95] offset:20480
	ds_write_b128 v2, v[96:99] offset:30720
	s_add_u32 s10, s0, 0x3a0000
	s_addc_u32 s11, s1, 0
	global_load_dwordx4 v[92:95], v0, s[10:11]
	global_load_dwordx4 v[96:99], v1, s[10:11]
	s_waitcnt lgkmcnt(0)
	s_barrier
	s_waitcnt vmcnt(10)
	ds_write_b128 v2, v[52:55] offset:0
	ds_write_b128 v2, v[56:59] offset:10240
	s_add_u32 s10, s0, 0x3c0000
	s_addc_u32 s11, s1, 0
	global_load_dwordx4 v[52:55], v0, s[10:11]
	global_load_dwordx4 v[56:59], v1, s[10:11]
	s_waitcnt lgkmcnt(0)
	s_barrier
	s_waitcnt vmcnt(10)
	ds_write_b128 v2, v[60:63] offset:20480
	ds_write_b128 v2, v[64:67] offset:30720
	s_add_u32 s10, s0, 0x3e0000
	s_addc_u32 s11, s1, 0
	global_load_dwordx4 v[60:63], v0, s[10:11]
	global_load_dwordx4 v[64:67], v1, s[10:11]
	s_waitcnt lgkmcnt(0)
	s_barrier
	s_waitcnt vmcnt(10)
	ds_write_b128 v2, v[68:71] offset:0
	ds_write_b128 v2, v[72:75] offset:10240
	s_add_u32 s10, s0, 0x400000
	s_addc_u32 s11, s1, 0
	global_load_dwordx4 v[68:71], v0, s[10:11]
	global_load_dwordx4 v[72:75], v1, s[10:11]
	s_waitcnt lgkmcnt(0)
	s_barrier
	s_waitcnt vmcnt(10)
	ds_write_b128 v2, v[76:79] offset:20480
	ds_write_b128 v2, v[80:83] offset:30720
	s_add_u32 s10, s0, 0x420000
	s_addc_u32 s11, s1, 0
	global_load_dwordx4 v[76:79], v0, s[10:11]
	global_load_dwordx4 v[80:83], v1, s[10:11]
	s_waitcnt lgkmcnt(0)
	s_barrier
	s_waitcnt vmcnt(10)
	ds_write_b128 v2, v[84:87] offset:0
	ds_write_b128 v2, v[88:91] offset:10240
	s_add_u32 s10, s0, 0x440000
	s_addc_u32 s11, s1, 0
	global_load_dwordx4 v[84:87], v0, s[10:11]
	global_load_dwordx4 v[88:91], v1, s[10:11]
	s_waitcnt lgkmcnt(0)
	s_barrier
	s_waitcnt vmcnt(10)
	ds_write_b128 v2, v[92:95] offset:20480
	ds_write_b128 v2, v[96:99] offset:30720
	s_add_u32 s10, s0, 0x460000
	s_addc_u32 s11, s1, 0
	global_load_dwordx4 v[92:95], v0, s[10:11]
	global_load_dwordx4 v[96:99], v1, s[10:11]
	s_waitcnt lgkmcnt(0)
	s_barrier
	s_waitcnt vmcnt(10)
	ds_write_b128 v2, v[52:55] offset:0
	ds_write_b128 v2, v[56:59] offset:10240
	s_add_u32 s10, s0, 0x480000
	s_addc_u32 s11, s1, 0
	global_load_dwordx4 v[52:55], v0, s[10:11]
	global_load_dwordx4 v[56:59], v1, s[10:11]
	s_waitcnt lgkmcnt(0)
	s_barrier
	s_waitcnt vmcnt(10)
	ds_write_b128 v2, v[60:63] offset:20480
	ds_write_b128 v2, v[64:67] offset:30720
	s_add_u32 s10, s0, 0x4a0000
	s_addc_u32 s11, s1, 0
	global_load_dwordx4 v[60:63], v0, s[10:11]
	global_load_dwordx4 v[64:67], v1, s[10:11]
	s_waitcnt lgkmcnt(0)
	s_barrier
	s_waitcnt vmcnt(10)
	ds_write_b128 v2, v[68:71] offset:0
	ds_write_b128 v2, v[72:75] offset:10240
	s_add_u32 s10, s0, 0x4c0000
	s_addc_u32 s11, s1, 0
	global_load_dwordx4 v[68:71], v0, s[10:11]
	global_load_dwordx4 v[72:75], v1, s[10:11]
	s_waitcnt lgkmcnt(0)
	s_barrier
	s_waitcnt vmcnt(10)
	ds_write_b128 v2, v[76:79] offset:20480
	ds_write_b128 v2, v[80:83] offset:30720
	s_add_u32 s10, s0, 0x4e0000
	s_addc_u32 s11, s1, 0
	global_load_dwordx4 v[76:79], v0, s[10:11]
	global_load_dwordx4 v[80:83], v1, s[10:11]
	s_waitcnt lgkmcnt(0)
	s_barrier
	s_waitcnt vmcnt(10)
	ds_write_b128 v2, v[84:87] offset:0
	ds_write_b128 v2, v[88:91] offset:10240
	s_add_u32 s10, s0, 0x500000
	s_addc_u32 s11, s1, 0
	global_load_dwordx4 v[84:87], v0, s[10:11]
	global_load_dwordx4 v[88:91], v1, s[10:11]
	s_waitcnt lgkmcnt(0)
	s_barrier
	s_waitcnt vmcnt(10)
	ds_write_b128 v2, v[92:95] offset:20480
	ds_write_b128 v2, v[96:99] offset:30720
	s_add_u32 s10, s0, 0x520000
	s_addc_u32 s11, s1, 0
	global_load_dwordx4 v[92:95], v0, s[10:11]
	global_load_dwordx4 v[96:99], v1, s[10:11]
	s_waitcnt lgkmcnt(0)
	s_barrier
	s_waitcnt vmcnt(10)
	ds_write_b128 v2, v[52:55] offset:0
	ds_write_b128 v2, v[56:59] offset:10240
	s_add_u32 s10, s0, 0x540000
	s_addc_u32 s11, s1, 0
	global_load_dwordx4 v[52:55], v0, s[10:11]
	global_load_dwordx4 v[56:59], v1, s[10:11]
	s_waitcnt lgkmcnt(0)
	s_barrier
	s_waitcnt vmcnt(10)
	ds_write_b128 v2, v[60:63] offset:20480
	ds_write_b128 v2, v[64:67] offset:30720
	s_add_u32 s10, s0, 0x560000
	s_addc_u32 s11, s1, 0
	global_load_dwordx4 v[60:63], v0, s[10:11]
	global_load_dwordx4 v[64:67], v1, s[10:11]
	s_waitcnt lgkmcnt(0)
	s_barrier
	s_waitcnt vmcnt(10)
	ds_write_b128 v2, v[68:71] offset:0
	ds_write_b128 v2, v[72:75] offset:10240
	s_add_u32 s10, s0, 0x580000
	s_addc_u32 s11, s1, 0
	global_load_dwordx4 v[68:71], v0, s[10:11]
	global_load_dwordx4 v[72:75], v1, s[10:11]
	s_waitcnt lgkmcnt(0)
	s_barrier
	s_waitcnt vmcnt(10)
	ds_write_b128 v2, v[76:79] offset:20480
	ds_write_b128 v2, v[80:83] offset:30720
	s_add_u32 s10, s0, 0x5a0000
	s_addc_u32 s11, s1, 0
	global_load_dwordx4 v[76:79], v0, s[10:11]
	global_load_dwordx4 v[80:83], v1, s[10:11]
	s_waitcnt lgkmcnt(0)
	s_barrier
	s_waitcnt vmcnt(10)
	ds_write_b128 v2, v[84:87] offset:0
	ds_write_b128 v2, v[88:91] offset:10240
	s_add_u32 s10, s0, 0x5c0000
	s_addc_u32 s11, s1, 0
	global_load_dwordx4 v[84:87], v0, s[10:11]
	global_load_dwordx4 v[88:91], v1, s[10:11]
	s_waitcnt lgkmcnt(0)
	s_barrier
	s_waitcnt vmcnt(10)
	ds_write_b128 v2, v[92:95] offset:20480
	ds_write_b128 v2, v[96:99] offset:30720
	s_add_u32 s10, s0, 0x5e0000
	s_addc_u32 s11, s1, 0
	global_load_dwordx4 v[92:95], v0, s[10:11]
	global_load_dwordx4 v[96:99], v1, s[10:11]
	s_waitcnt lgkmcnt(0)
	s_barrier
; #define LAS __attribute__((address_space(3)))
; __device__ __forceinline__ void scan_combine(LAS unsigned char* lds, CArgsP a) {
;     ...
;         if (pf) { const f32x4* Pn = (const f32x4*)(PM + (size_t)((g + 2) * 8 + h) * 4096); pa = Pn[tid]; pb = Pn[512 + tid]; u3 = UM[((size_t)((g + 2) * 8 + h) * 64 + v) * 64 + kq]; }
;         asm volatile("s_waitcnt lgkmcnt(0)\n\ts_barrier" ::: "memory");
;         const LAS float* Pg = Pl + (g % 3) * 4096 + kq;
;         float acc0 = u1, acc1 = 0.f, acc2 = 0.f, acc3 = 0.f;
;         const int curi = __builtin_bit_cast(int, cur);
; #pragma unroll
;         for (int k = 0; k < 64; k += 4) {
;             const float s0 = __builtin_bit_cast(float, __builtin_amdgcn_readlane(curi, k)), s1 = __builtin_bit_cast(float, __builtin_amdgcn_readlane(curi, k + 1));
;             const float s2 = __builtin_bit_cast(float, __builtin_amdgcn_readlane(curi, k + 2)), s3 = __builtin_bit_cast(float, __builtin_amdgcn_readlane(curi, k + 3));
;             acc0 += s0 * Pg[(k + 0) * 64]; acc1 += s1 * Pg[(k + 1) * 64]; acc2 += s2 * Pg[(k + 2) * 64]; acc3 += s3 * Pg[(k + 3) * 64];
;         }
;         cur = (acc0 + acc1) + (acc2 + acc3);
;         SS[((size_t)((g + 1) * 8 + h) * 64 + v) * 64 + kq] = cur;
;         if (pf) { LAS float* dst = Pl + ((g + 2) % 3) * 4096; *(LAS f32x4*)(dst + 4 * tid) = pa; *(LAS f32x4*)(dst + 2048 + 4 * tid) = pb; }
	s_waitcnt vmcnt(10)
	ds_write_b128 v2, v[52:55] offset:0
	ds_write_b128 v2, v[56:59] offset:10240
	s_add_u32 s10, s0, 0x600000
	s_addc_u32 s11, s1, 0
	global_load_dwordx4 v[52:55], v0, s[10:11]
	global_load_dwordx4 v[56:59], v1, s[10:11]
	s_waitcnt lgkmcnt(0)
	s_barrier
	s_waitcnt vmcnt(10)
	ds_write_b128 v2, v[60:63] offset:20480
	ds_write_b128 v2, v[64:67] offset:30720
	s_add_u32 s10, s0, 0x620000
	s_addc_u32 s11, s1, 0
	global_load_dwordx4 v[60:63], v0, s[10:11]
	global_load_dwordx4 v[64:67], v1, s[10:11]
	s_waitcnt lgkmcnt(0)
	s_barrier
	s_waitcnt vmcnt(10)
	ds_write_b128 v2, v[68:71] offset:0
	ds_write_b128 v2, v[72:75] offset:10240
	s_add_u32 s10, s0, 0x640000
	s_addc_u32 s11, s1, 0
	global_load_dwordx4 v[68:71], v0, s[10:11]
	global_load_dwordx4 v[72:75], v1, s[10:11]
	s_waitcnt lgkmcnt(0)
	s_barrier
	s_waitcnt vmcnt(10)
	ds_write_b128 v2, v[76:79] offset:20480
	ds_write_b128 v2, v[80:83] offset:30720
	s_add_u32 s10, s0, 0x660000
	s_addc_u32 s11, s1, 0
	global_load_dwordx4 v[76:79], v0, s[10:11]
	global_load_dwordx4 v[80:83], v1, s[10:11]
	s_waitcnt lgkmcnt(0)
	s_barrier
	s_waitcnt vmcnt(10)
	ds_write_b128 v2, v[84:87] offset:0
	ds_write_b128 v2, v[88:91] offset:10240
	s_add_u32 s10, s0, 0x680000
	s_addc_u32 s11, s1, 0
	global_load_dwordx4 v[84:87], v0, s[10:11]
	global_load_dwordx4 v[88:91], v1, s[10:11]
	s_waitcnt lgkmcnt(0)
	s_barrier
	s_waitcnt vmcnt(10)
	ds_write_b128 v2, v[92:95] offset:20480
	ds_write_b128 v2, v[96:99] offset:30720
	s_add_u32 s10, s0, 0x6a0000
	s_addc_u32 s11, s1, 0
	global_load_dwordx4 v[92:95], v0, s[10:11]
	global_load_dwordx4 v[96:99], v1, s[10:11]
	s_waitcnt lgkmcnt(0)
	s_barrier
	s_waitcnt vmcnt(10)
	ds_write_b128 v2, v[52:55] offset:0
	ds_write_b128 v2, v[56:59] offset:10240
	s_add_u32 s10, s0, 0x6c0000
	s_addc_u32 s11, s1, 0
	global_load_dwordx4 v[52:55], v0, s[10:11]
	global_load_dwordx4 v[56:59], v1, s[10:11]
	s_waitcnt lgkmcnt(0)
	s_barrier
	s_waitcnt vmcnt(10)
	ds_write_b128 v2, v[60:63] offset:20480
	ds_write_b128 v2, v[64:67] offset:30720
	s_add_u32 s10, s0, 0x6e0000
	s_addc_u32 s11, s1, 0
	global_load_dwordx4 v[60:63], v0, s[10:11]
	global_load_dwordx4 v[64:67], v1, s[10:11]
	s_waitcnt lgkmcnt(0)
	s_barrier
	s_waitcnt vmcnt(10)
	ds_write_b128 v2, v[68:71] offset:0
	ds_write_b128 v2, v[72:75] offset:10240
	s_add_u32 s10, s0, 0x700000
	s_addc_u32 s11, s1, 0
	global_load_dwordx4 v[68:71], v0, s[10:11]
	global_load_dwordx4 v[72:75], v1, s[10:11]
	s_waitcnt lgkmcnt(0)
	s_barrier
	s_waitcnt vmcnt(10)
	ds_write_b128 v2, v[76:79] offset:20480
	ds_write_b128 v2, v[80:83] offset:30720
	s_add_u32 s10, s0, 0x720000
	s_addc_u32 s11, s1, 0
	global_load_dwordx4 v[76:79], v0, s[10:11]
	global_load_dwordx4 v[80:83], v1, s[10:11]
	s_waitcnt lgkmcnt(0)
	s_barrier
	s_waitcnt vmcnt(10)
	ds_write_b128 v2, v[84:87] offset:0
	ds_write_b128 v2, v[88:91] offset:10240
	s_add_u32 s10, s0, 0x740000
	s_addc_u32 s11, s1, 0
	global_load_dwordx4 v[84:87], v0, s[10:11]
	global_load_dwordx4 v[88:91], v1, s[10:11]
	s_waitcnt lgkmcnt(0)
	s_barrier
	s_waitcnt vmcnt(10)
	ds_write_b128 v2, v[92:95] offset:20480
	ds_write_b128 v2, v[96:99] offset:30720
	s_add_u32 s10, s0, 0x760000
	s_addc_u32 s11, s1, 0
	global_load_dwordx4 v[92:95], v0, s[10:11]
	global_load_dwordx4 v[96:99], v1, s[10:11]
	s_waitcnt lgkmcnt(0)
	s_barrier
	s_waitcnt vmcnt(10)
	ds_write_b128 v2, v[52:55] offset:0
	ds_write_b128 v2, v[56:59] offset:10240
	s_add_u32 s10, s0, 0x780000
	s_addc_u32 s11, s1, 0
	global_load_dwordx4 v[52:55], v0, s[10:11]
	global_load_dwordx4 v[56:59], v1, s[10:11]
	s_waitcnt lgkmcnt(0)
	s_barrier
	s_waitcnt vmcnt(10)
	ds_write_b128 v2, v[60:63] offset:20480
	ds_write_b128 v2, v[64:67] offset:30720
	s_add_u32 s10, s0, 0x7a0000
	s_addc_u32 s11, s1, 0
	global_load_dwordx4 v[60:63], v0, s[10:11]
	global_load_dwordx4 v[64:67], v1, s[10:11]
	s_waitcnt lgkmcnt(0)
	s_barrier
	s_waitcnt vmcnt(10)
	ds_write_b128 v2, v[68:71] offset:0
	ds_write_b128 v2, v[72:75] offset:10240
	s_add_u32 s10, s0, 0x7c0000
	s_addc_u32 s11, s1, 0
	global_load_dwordx4 v[68:71], v0, s[10:11]
	global_load_dwordx4 v[72:75], v1, s[10:11]
	s_waitcnt lgkmcnt(0)
	s_barrier
	s_waitcnt vmcnt(10)
	ds_write_b128 v2, v[76:79] offset:20480
	ds_write_b128 v2, v[80:83] offset:30720
	s_waitcnt lgkmcnt(0)
	s_barrier
	s_waitcnt vmcnt(8)
	ds_write_b128 v2, v[84:87] offset:0
	ds_write_b128 v2, v[88:91] offset:10240
	s_waitcnt lgkmcnt(0)
	s_barrier
	s_waitcnt vmcnt(6)
	ds_write_b128 v2, v[92:95] offset:20480
	ds_write_b128 v2, v[96:99] offset:30720
	s_waitcnt lgkmcnt(0)
	s_barrier
	s_waitcnt vmcnt(4)
	ds_write_b128 v2, v[52:55] offset:0
	ds_write_b128 v2, v[56:59] offset:10240
	s_waitcnt lgkmcnt(0)
	s_barrier
	s_waitcnt vmcnt(2)
	ds_write_b128 v2, v[60:63] offset:20480
	ds_write_b128 v2, v[64:67] offset:30720
	s_waitcnt lgkmcnt(0)
	s_barrier
	s_waitcnt vmcnt(0)
	ds_write_b128 v2, v[68:71] offset:0
	ds_write_b128 v2, v[72:75] offset:10240
	s_waitcnt lgkmcnt(0)
	s_barrier
	s_waitcnt lgkmcnt(0)
	s_barrier

; #define LAS __attribute__((address_space(3)))
; __device__ __forceinline__ void attn_sample_unit(LAS unsigned char* lds, CArgsP a, int b, int h) {
;     ...
;     for (int j = tid; j < SA_NK; j += 512) {
;         const float* kp = j < PAST ? ck + (((size_t)b * PAST + j) * 8 + h) * 64 : nk + (size_t)(16 * b + (j - PAST)) * 512 + h * 64;
;         float acc[16];
; #pragma unroll
;         for (int t = 0; t < 16; ++t) acc[t] = 0.f;
; #pragma unroll
;         for (int hb = 0; hb < 2; ++hb) {
;             f32x4 kr[8];
; #pragma unroll
;             for (int i = 0; i < 8; ++i) kr[i] = *(const f32x4*)(kp + 32 * hb + 4 * i);
; #pragma unroll
;             for (int i = 0; i < 8; ++i) {
;                 asm volatile("" ::: "memory");
;                 const f32x4 k4 = kr[i];
; #pragma unroll
;                 for (int t = 0; t < 16; ++t) { const f32x4 q4 = *(const LAS f32x4*)(Qs + t * 64 + 32 * hb + 4 * i); acc[t] += (q4[0] * k4[0] + q4[1] * k4[1]) + (q4[2] * k4[2] + q4[3] * k4[3]); }
;             }
;         }
;         const float cj = C[j];
; #pragma unroll
;         for (int t = 0; t < 16; ++t) SC[t * SA_NK + j] = acc[t] + (C[PAST + t] - cj) * LOG2E;
;     }
;     ...
;         const float* vp = cv + ((size_t)b * PAST * 8 + h) * 64 + lane;
;         float vv[8], vn8[8];
; #pragma unroll
;         for (int i = 0; i < 8; ++i) vv[i] = vp[(size_t)(wid + 8 * i) * 512];
.LBB0_1348:
	s_or_b64 exec, exec, s[26:27]
	s_lshl_b32 s1, s10, 6
	s_lshl_b32 s3, s10, 8
	s_add_u32 s3, s12, s3
	s_addc_u32 s4, s13, 0
	s_mov_b32 s25, 0
	s_add_u32 s6, s3, 0x81a1c00
	s_addc_u32 s7, s4, 0
	s_lshl_b64 s[4:5], s[24:25], 13
	v_lshl_add_u64 v[0:1], v[0:1], 0, s[4:5]
	v_mov_b32_e32 v151, 0
	v_lshl_add_u64 v[0:1], v[0:1], 0, v[150:151]
	v_lshlrev_b64 v[0:1], 8, v[0:1]
	s_add_i32 s3, s0, 0xfffffc00
	s_mov_b64 s[8:9], 0
	s_movk_i32 s4, 0x3ff
	s_mov_b64 s[10:11], 0x100000
	s_movk_i32 s5, 0x20f
	s_waitcnt lgkmcnt(0)
	s_barrier
	v_lshrrev_b32_e32 v44, 4, v148
	v_and_b32_e32 v45, 15, v148
	v_lshlrev_b32_e32 v137, 8, v45
	v_lshl_add_u32 v137, v44, 4, v137
	v_lshlrev_b32_e32 v46, 4, v44
	ds_read_b128 v[0:3], v137 offset:4352
	ds_read_b128 v[4:7], v137 offset:4416
	ds_read_b128 v[8:11], v137 offset:4480
	ds_read_b128 v[12:15], v137 offset:4544
	ds_read_b128 v[24:27], v46 offset:4096
	s_lshl_b32 s48, s46, 6
	v_lshl_add_u32 v138, v45, 2, s48
	v_mul_u32_u24_e32 v139, 0x4100, v44
	v_add_u32_e32 v139, v139, v138
	v_add_u32_e32 v139, 0x2100, v139
	v_lshlrev_b32_e32 v47, 13, v44
	v_lshl_add_u32 v47, v45, 4, v47
	s_waitcnt vmcnt(0)
	v_mov_b32_e32 v136, v47
	v_add_u32_e32 v137, 0x1000, v47
	s_cmp_lg_u32 s46, 0
	s_cbranch_scc1 .Lqk_noext1
	ds_read_b32 v142, v138 offset:4096
	s_waitcnt lgkmcnt(1)
	v_mfma_f32_16x16x4_f32 v[16:19], v0, v234, 0
	v_mfma_f32_16x16x4_f32 v[16:19], v1, v235, v[16:19]
	v_mfma_f32_16x16x4_f32 v[16:19], v2, v236, v[16:19]
	v_mfma_f32_16x16x4_f32 v[16:19], v3, v237, v[16:19]
	v_mfma_f32_16x16x4_f32 v[16:19], v4, v238, v[16:19]
	v_mfma_f32_16x16x4_f32 v[16:19], v5, v239, v[16:19]
	v_mfma_f32_16x16x4_f32 v[16:19], v6, v240, v[16:19]
	v_mfma_f32_16x16x4_f32 v[16:19], v7, v241, v[16:19]
	v_mfma_f32_16x16x4_f32 v[16:19], v8, v242, v[16:19]
	v_mfma_f32_16x16x4_f32 v[16:19], v9, v243, v[16:19]
	v_mfma_f32_16x16x4_f32 v[16:19], v10, v244, v[16:19]
	v_mfma_f32_16x16x4_f32 v[16:19], v11, v245, v[16:19]
	v_mfma_f32_16x16x4_f32 v[16:19], v12, v246, v[16:19]
	v_mfma_f32_16x16x4_f32 v[16:19], v13, v247, v[16:19]
	v_mfma_f32_16x16x4_f32 v[16:19], v14, v248, v[16:19]
	v_mfma_f32_16x16x4_f32 v[16:19], v15, v249, v[16:19]
	global_load_dwordx4 v[234:237], v136, s[44:45] offset:0
	global_load_dwordx4 v[238:241], v136, s[44:45] offset:2048
	global_load_dwordx4 v[242:245], v137, s[44:45] offset:0
	global_load_dwordx4 v[246:249], v137, s[44:45] offset:2048
	s_waitcnt lgkmcnt(0)
	s_nop 9
	v_sub_f32_e32 v44, v24, v142
	v_sub_f32_e32 v45, v25, v142
	v_sub_f32_e32 v46, v26, v142
	v_sub_f32_e32 v47, v27, v142
	v_fma_f32 v44, v44, s47, v16
	v_fma_f32 v45, v45, s47, v17
	v_fma_f32 v46, v46, s47, v18
	v_fma_f32 v47, v47, s47, v19
	ds_write_b32 v139, v44 offset:4096
	ds_write_b32 v139, v45 offset:8256
	ds_write_b32 v139, v46 offset:12416
	ds_write_b32 v139, v47 offset:16576
.Lqk_noext1:
	ds_read_b32 v140, v138 offset:0
	ds_read_b32 v141, v138 offset:512
	s_waitcnt lgkmcnt(2)
	v_mfma_f32_16x16x4_f32 v[16:19], v0, v28, 0
	v_mfma_f32_16x16x4_f32 v[20:23], v0, v52, 0
	v_mfma_f32_16x16x4_f32 v[16:19], v1, v29, v[16:19]
	v_mfma_f32_16x16x4_f32 v[20:23], v1, v53, v[20:23]
	v_mfma_f32_16x16x4_f32 v[16:19], v2, v30, v[16:19]
	v_mfma_f32_16x16x4_f32 v[20:23], v2, v54, v[20:23]
	v_mfma_f32_16x16x4_f32 v[16:19], v3, v31, v[16:19]
	v_mfma_f32_16x16x4_f32 v[20:23], v3, v55, v[20:23]
	v_mfma_f32_16x16x4_f32 v[16:19], v4, v32, v[16:19]
	v_mfma_f32_16x16x4_f32 v[20:23], v4, v56, v[20:23]
	v_mfma_f32_16x16x4_f32 v[16:19], v5, v33, v[16:19]
	v_mfma_f32_16x16x4_f32 v[20:23], v5, v57, v[20:23]
	v_mfma_f32_16x16x4_f32 v[16:19], v6, v34, v[16:19]
	v_mfma_f32_16x16x4_f32 v[20:23], v6, v58, v[20:23]
	v_mfma_f32_16x16x4_f32 v[16:19], v7, v35, v[16:19]
	v_mfma_f32_16x16x4_f32 v[20:23], v7, v59, v[20:23]
	v_mfma_f32_16x16x4_f32 v[16:19], v8, v36, v[16:19]
	v_mfma_f32_16x16x4_f32 v[20:23], v8, v60, v[20:23]
	v_mfma_f32_16x16x4_f32 v[16:19], v9, v37, v[16:19]
	v_mfma_f32_16x16x4_f32 v[20:23], v9, v61, v[20:23]
	v_mfma_f32_16x16x4_f32 v[16:19], v10, v38, v[16:19]
	v_mfma_f32_16x16x4_f32 v[20:23], v10, v62, v[20:23]
	v_mfma_f32_16x16x4_f32 v[16:19], v11, v39, v[16:19]
	v_mfma_f32_16x16x4_f32 v[20:23], v11, v63, v[20:23]
	v_mfma_f32_16x16x4_f32 v[16:19], v12, v40, v[16:19]
	v_mfma_f32_16x16x4_f32 v[20:23], v12, v64, v[20:23]
	v_mfma_f32_16x16x4_f32 v[16:19], v13, v41, v[16:19]
	v_mfma_f32_16x16x4_f32 v[20:23], v13, v65, v[20:23]
	v_mfma_f32_16x16x4_f32 v[16:19], v14, v42, v[16:19]
	v_mfma_f32_16x16x4_f32 v[20:23], v14, v66, v[20:23]
	v_mfma_f32_16x16x4_f32 v[16:19], v15, v43, v[16:19]
	v_mfma_f32_16x16x4_f32 v[20:23], v15, v67, v[20:23]
	s_add_u32 s48, s42, 0x0
	s_addc_u32 s49, s43, 0
	global_load_dwordx4 v[28:31], v136, s[48:49] offset:0
	global_load_dwordx4 v[32:35], v136, s[48:49] offset:2048
	global_load_dwordx4 v[36:39], v137, s[48:49] offset:0
	global_load_dwordx4 v[40:43], v137, s[48:49] offset:2048
	s_add_u32 s48, s42, 0x40000
	s_addc_u32 s49, s43, 0
	global_load_dwordx4 v[52:55], v136, s[48:49] offset:0
	global_load_dwordx4 v[56:59], v136, s[48:49] offset:2048
	global_load_dwordx4 v[60:63], v137, s[48:49] offset:0
	global_load_dwordx4 v[64:67], v137, s[48:49] offset:2048
	s_waitcnt lgkmcnt(0)
; #define LAS __attribute__((address_space(3)))
; __device__ __forceinline__ void attn_sample_unit(LAS unsigned char* lds, CArgsP a, int b, int h) {
;     ...
;     for (int j = tid; j < SA_NK; j += 512) {
;         const float* kp = j < PAST ? ck + (((size_t)b * PAST + j) * 8 + h) * 64 : nk + (size_t)(16 * b + (j - PAST)) * 512 + h * 64;
;         float acc[16];
; #pragma unroll
;         for (int t = 0; t < 16; ++t) acc[t] = 0.f;
; #pragma unroll
;         for (int hb = 0; hb < 2; ++hb) {
;             f32x4 kr[8];
; #pragma unroll
;             for (int i = 0; i < 8; ++i) kr[i] = *(const f32x4*)(kp + 32 * hb + 4 * i);
; #pragma unroll
;             for (int i = 0; i < 8; ++i) {
;                 asm volatile("" ::: "memory");
;                 const f32x4 k4 = kr[i];
; #pragma unroll
;                 for (int t = 0; t < 16; ++t) { const f32x4 q4 = *(const LAS f32x4*)(Qs + t * 64 + 32 * hb + 4 * i); acc[t] += (q4[0] * k4[0] + q4[1] * k4[1]) + (q4[2] * k4[2] + q4[3] * k4[3]); }
;             }
;         }
;         const float cj = C[j];
; #pragma unroll
;         for (int t = 0; t < 16; ++t) SC[t * SA_NK + j] = acc[t] + (C[PAST + t] - cj) * LOG2E;
;     }
;     ...
;         const float* vp = cv + ((size_t)b * PAST * 8 + h) * 64 + lane;
;         float vv[8], vn8[8];
; #pragma unroll
;         for (int i = 0; i < 8; ++i) vv[i] = vp[(size_t)(wid + 8 * i) * 512];
; #pragma unroll 1
;         for (int j0 = wid; j0 < PAST; j0 += 64) {
;             const int jn = (j0 + 64 < PAST) ? j0 + 64 : j0;
; #pragma unroll
;             for (int i = 0; i < 8; ++i) vn8[i] = vp[(size_t)(jn + 8 * i) * 512];
	s_nop 9
	v_sub_f32_e32 v44, v24, v140
	v_sub_f32_e32 v45, v25, v140
	v_sub_f32_e32 v46, v26, v140
	v_sub_f32_e32 v47, v27, v140
	v_fma_f32 v44, v44, s47, v16
	v_fma_f32 v45, v45, s47, v17
	v_fma_f32 v46, v46, s47, v18
	v_fma_f32 v47, v47, s47, v19
	ds_write_b32 v139, v44 offset:0
	ds_write_b32 v139, v45 offset:4160
	ds_write_b32 v139, v46 offset:8320
	ds_write_b32 v139, v47 offset:12480
	v_sub_f32_e32 v44, v24, v141
	v_sub_f32_e32 v45, v25, v141
	v_sub_f32_e32 v46, v26, v141
	v_sub_f32_e32 v47, v27, v141
	v_fma_f32 v44, v44, s47, v20
	v_fma_f32 v45, v45, s47, v21
	v_fma_f32 v46, v46, s47, v22
	v_fma_f32 v47, v47, s47, v23
	ds_write_b32 v139, v44 offset:512
	ds_write_b32 v139, v45 offset:4672
	ds_write_b32 v139, v46 offset:8832
	ds_write_b32 v139, v47 offset:12992
	ds_read_b32 v140, v138 offset:1024
	ds_read_b32 v141, v138 offset:1536
	v_mfma_f32_16x16x4_f32 v[16:19], v0, v68, 0
	v_mfma_f32_16x16x4_f32 v[20:23], v0, v84, 0
	v_mfma_f32_16x16x4_f32 v[16:19], v1, v69, v[16:19]
	v_mfma_f32_16x16x4_f32 v[20:23], v1, v85, v[20:23]
	v_mfma_f32_16x16x4_f32 v[16:19], v2, v70, v[16:19]
	v_mfma_f32_16x16x4_f32 v[20:23], v2, v86, v[20:23]
	v_mfma_f32_16x16x4_f32 v[16:19], v3, v71, v[16:19]
	v_mfma_f32_16x16x4_f32 v[20:23], v3, v87, v[20:23]
	v_mfma_f32_16x16x4_f32 v[16:19], v4, v72, v[16:19]
	v_mfma_f32_16x16x4_f32 v[20:23], v4, v88, v[20:23]
	v_mfma_f32_16x16x4_f32 v[16:19], v5, v73, v[16:19]
	v_mfma_f32_16x16x4_f32 v[20:23], v5, v89, v[20:23]
	v_mfma_f32_16x16x4_f32 v[16:19], v6, v74, v[16:19]
	v_mfma_f32_16x16x4_f32 v[20:23], v6, v90, v[20:23]
	v_mfma_f32_16x16x4_f32 v[16:19], v7, v75, v[16:19]
	v_mfma_f32_16x16x4_f32 v[20:23], v7, v91, v[20:23]
	v_mfma_f32_16x16x4_f32 v[16:19], v8, v76, v[16:19]
	v_mfma_f32_16x16x4_f32 v[20:23], v8, v92, v[20:23]
	v_mfma_f32_16x16x4_f32 v[16:19], v9, v77, v[16:19]
	v_mfma_f32_16x16x4_f32 v[20:23], v9, v93, v[20:23]
	v_mfma_f32_16x16x4_f32 v[16:19], v10, v78, v[16:19]
	v_mfma_f32_16x16x4_f32 v[20:23], v10, v94, v[20:23]
	v_mfma_f32_16x16x4_f32 v[16:19], v11, v79, v[16:19]
	v_mfma_f32_16x16x4_f32 v[20:23], v11, v95, v[20:23]
	v_mfma_f32_16x16x4_f32 v[16:19], v12, v80, v[16:19]
	v_mfma_f32_16x16x4_f32 v[20:23], v12, v96, v[20:23]
	v_mfma_f32_16x16x4_f32 v[16:19], v13, v81, v[16:19]
	v_mfma_f32_16x16x4_f32 v[20:23], v13, v97, v[20:23]
	v_mfma_f32_16x16x4_f32 v[16:19], v14, v82, v[16:19]
	v_mfma_f32_16x16x4_f32 v[20:23], v14, v98, v[20:23]
	v_mfma_f32_16x16x4_f32 v[16:19], v15, v83, v[16:19]
	v_mfma_f32_16x16x4_f32 v[20:23], v15, v99, v[20:23]
	s_add_u32 s48, s42, 0x80000
	s_addc_u32 s49, s43, 0
	global_load_dwordx4 v[68:71], v136, s[48:49] offset:0
	global_load_dwordx4 v[72:75], v136, s[48:49] offset:2048
	global_load_dwordx4 v[76:79], v137, s[48:49] offset:0
	global_load_dwordx4 v[80:83], v137, s[48:49] offset:2048
	s_add_u32 s48, s42, 0xc0000
	s_addc_u32 s49, s43, 0
	global_load_dwordx4 v[84:87], v136, s[48:49] offset:0
	global_load_dwordx4 v[88:91], v136, s[48:49] offset:2048
	global_load_dwordx4 v[92:95], v137, s[48:49] offset:0
	global_load_dwordx4 v[96:99], v137, s[48:49] offset:2048
	s_waitcnt lgkmcnt(0)
	s_nop 9
	v_sub_f32_e32 v44, v24, v140
	v_sub_f32_e32 v45, v25, v140
	v_sub_f32_e32 v46, v26, v140
	v_sub_f32_e32 v47, v27, v140
	v_fma_f32 v44, v44, s47, v16
	v_fma_f32 v45, v45, s47, v17
	v_fma_f32 v46, v46, s47, v18
	v_fma_f32 v47, v47, s47, v19
	ds_write_b32 v139, v44 offset:1024
	ds_write_b32 v139, v45 offset:5184
	ds_write_b32 v139, v46 offset:9344
	ds_write_b32 v139, v47 offset:13504
	v_sub_f32_e32 v44, v24, v141
	v_sub_f32_e32 v45, v25, v141
	v_sub_f32_e32 v46, v26, v141
	v_sub_f32_e32 v47, v27, v141
	v_fma_f32 v44, v44, s47, v20
	v_fma_f32 v45, v45, s47, v21
	v_fma_f32 v46, v46, s47, v22
	v_fma_f32 v47, v47, s47, v23
	ds_write_b32 v139, v44 offset:1536
	ds_write_b32 v139, v45 offset:5696
	ds_write_b32 v139, v46 offset:9856
	ds_write_b32 v139, v47 offset:14016
	ds_read_b32 v140, v138 offset:2048
	ds_read_b32 v141, v138 offset:2560
	v_mfma_f32_16x16x4_f32 v[16:19], v0, v104, 0
	v_mfma_f32_16x16x4_f32 v[20:23], v0, v120, 0
	v_mfma_f32_16x16x4_f32 v[16:19], v1, v105, v[16:19]
	v_mfma_f32_16x16x4_f32 v[20:23], v1, v121, v[20:23]
	v_mfma_f32_16x16x4_f32 v[16:19], v2, v106, v[16:19]
	v_mfma_f32_16x16x4_f32 v[20:23], v2, v122, v[20:23]
	v_mfma_f32_16x16x4_f32 v[16:19], v3, v107, v[16:19]
	v_mfma_f32_16x16x4_f32 v[20:23], v3, v123, v[20:23]
	v_mfma_f32_16x16x4_f32 v[16:19], v4, v108, v[16:19]
	v_mfma_f32_16x16x4_f32 v[20:23], v4, v124, v[20:23]
	v_mfma_f32_16x16x4_f32 v[16:19], v5, v109, v[16:19]
	v_mfma_f32_16x16x4_f32 v[20:23], v5, v125, v[20:23]
	v_mfma_f32_16x16x4_f32 v[16:19], v6, v110, v[16:19]
	v_mfma_f32_16x16x4_f32 v[20:23], v6, v126, v[20:23]
	v_mfma_f32_16x16x4_f32 v[16:19], v7, v111, v[16:19]
	v_mfma_f32_16x16x4_f32 v[20:23], v7, v127, v[20:23]
	v_mfma_f32_16x16x4_f32 v[16:19], v8, v112, v[16:19]
	v_mfma_f32_16x16x4_f32 v[20:23], v8, v128, v[20:23]
	v_mfma_f32_16x16x4_f32 v[16:19], v9, v113, v[16:19]
	v_mfma_f32_16x16x4_f32 v[20:23], v9, v129, v[20:23]
	v_mfma_f32_16x16x4_f32 v[16:19], v10, v114, v[16:19]
	v_mfma_f32_16x16x4_f32 v[20:23], v10, v130, v[20:23]
	v_mfma_f32_16x16x4_f32 v[16:19], v11, v115, v[16:19]
	v_mfma_f32_16x16x4_f32 v[20:23], v11, v131, v[20:23]
	v_mfma_f32_16x16x4_f32 v[16:19], v12, v116, v[16:19]
	v_mfma_f32_16x16x4_f32 v[20:23], v12, v132, v[20:23]
	v_mfma_f32_16x16x4_f32 v[16:19], v13, v117, v[16:19]
	v_mfma_f32_16x16x4_f32 v[20:23], v13, v133, v[20:23]
	v_mfma_f32_16x16x4_f32 v[16:19], v14, v118, v[16:19]
	v_mfma_f32_16x16x4_f32 v[20:23], v14, v134, v[20:23]
	v_mfma_f32_16x16x4_f32 v[16:19], v15, v119, v[16:19]
	v_mfma_f32_16x16x4_f32 v[20:23], v15, v135, v[20:23]
	s_add_u32 s48, s42, 0x100000
	s_addc_u32 s49, s43, 0
	global_load_dwordx4 v[104:107], v136, s[48:49] offset:0
	global_load_dwordx4 v[108:111], v136, s[48:49] offset:2048
	global_load_dwordx4 v[112:115], v137, s[48:49] offset:0
	global_load_dwordx4 v[116:119], v137, s[48:49] offset:2048
	s_add_u32 s48, s42, 0x140000
	s_addc_u32 s49, s43, 0
	global_load_dwordx4 v[120:123], v136, s[48:49] offset:0
	global_load_dwordx4 v[124:127], v136, s[48:49] offset:2048
	global_load_dwordx4 v[128:131], v137, s[48:49] offset:0
	global_load_dwordx4 v[132:135], v137, s[48:49] offset:2048
	s_waitcnt lgkmcnt(0)
; #define LAS __attribute__((address_space(3)))
; __device__ __forceinline__ void attn_sample_unit(LAS unsigned char* lds, CArgsP a, int b, int h) {
;     ...
;     for (int j = tid; j < SA_NK; j += 512) {
;         const float* kp = j < PAST ? ck + (((size_t)b * PAST + j) * 8 + h) * 64 : nk + (size_t)(16 * b + (j - PAST)) * 512 + h * 64;
;         float acc[16];
; #pragma unroll
;         for (int t = 0; t < 16; ++t) acc[t] = 0.f;
; #pragma unroll
;         for (int hb = 0; hb < 2; ++hb) {
;             f32x4 kr[8];
; #pragma unroll
;             for (int i = 0; i < 8; ++i) kr[i] = *(const f32x4*)(kp + 32 * hb + 4 * i);
; #pragma unroll
;             for (int i = 0; i < 8; ++i) {
;                 asm volatile("" ::: "memory");
;                 const f32x4 k4 = kr[i];
; #pragma unroll
;                 for (int t = 0; t < 16; ++t) { const f32x4 q4 = *(const LAS f32x4*)(Qs + t * 64 + 32 * hb + 4 * i); acc[t] += (q4[0] * k4[0] + q4[1] * k4[1]) + (q4[2] * k4[2] + q4[3] * k4[3]); }
;             }
;         }
;         const float cj = C[j];
; #pragma unroll
;         for (int t = 0; t < 16; ++t) SC[t * SA_NK + j] = acc[t] + (C[PAST + t] - cj) * LOG2E;
;     }
;     __syncthreads();
; #pragma unroll
;     for (int tt = 0; tt < 2; ++tt) {
;         const int t = 2 * wid + tt; LAS float* row = SC + t * SA_NK;
;         float mx = -INFINITY;
;         for (int j = lane; j < SA_NK; j += 64) { if (j > PAST + t) row[j] = -INFINITY; mx = fmaxf(mx, row[j]); }
	s_nop 9
	v_sub_f32_e32 v44, v24, v140
	v_sub_f32_e32 v45, v25, v140
	v_sub_f32_e32 v46, v26, v140
	v_sub_f32_e32 v47, v27, v140
	v_fma_f32 v44, v44, s47, v16
	v_fma_f32 v45, v45, s47, v17
	v_fma_f32 v46, v46, s47, v18
	v_fma_f32 v47, v47, s47, v19
	ds_write_b32 v139, v44 offset:2048
	ds_write_b32 v139, v45 offset:6208
	ds_write_b32 v139, v46 offset:10368
	ds_write_b32 v139, v47 offset:14528
	v_sub_f32_e32 v44, v24, v141
	v_sub_f32_e32 v45, v25, v141
	v_sub_f32_e32 v46, v26, v141
	v_sub_f32_e32 v47, v27, v141
	v_fma_f32 v44, v44, s47, v20
	v_fma_f32 v45, v45, s47, v21
	v_fma_f32 v46, v46, s47, v22
	v_fma_f32 v47, v47, s47, v23
	ds_write_b32 v139, v44 offset:2560
	ds_write_b32 v139, v45 offset:6720
	ds_write_b32 v139, v46 offset:10880
	ds_write_b32 v139, v47 offset:15040
	ds_read_b32 v140, v138 offset:3072
	ds_read_b32 v141, v138 offset:3584
	v_mfma_f32_16x16x4_f32 v[16:19], v0, v202, 0
	v_mfma_f32_16x16x4_f32 v[20:23], v0, v218, 0
	v_mfma_f32_16x16x4_f32 v[16:19], v1, v203, v[16:19]
	v_mfma_f32_16x16x4_f32 v[20:23], v1, v219, v[20:23]
	v_mfma_f32_16x16x4_f32 v[16:19], v2, v204, v[16:19]
	v_mfma_f32_16x16x4_f32 v[20:23], v2, v220, v[20:23]
	v_mfma_f32_16x16x4_f32 v[16:19], v3, v205, v[16:19]
	v_mfma_f32_16x16x4_f32 v[20:23], v3, v221, v[20:23]
	v_mfma_f32_16x16x4_f32 v[16:19], v4, v206, v[16:19]
	v_mfma_f32_16x16x4_f32 v[20:23], v4, v222, v[20:23]
	v_mfma_f32_16x16x4_f32 v[16:19], v5, v207, v[16:19]
	v_mfma_f32_16x16x4_f32 v[20:23], v5, v223, v[20:23]
	v_mfma_f32_16x16x4_f32 v[16:19], v6, v208, v[16:19]
	v_mfma_f32_16x16x4_f32 v[20:23], v6, v224, v[20:23]
	v_mfma_f32_16x16x4_f32 v[16:19], v7, v209, v[16:19]
	v_mfma_f32_16x16x4_f32 v[20:23], v7, v225, v[20:23]
	v_mfma_f32_16x16x4_f32 v[16:19], v8, v210, v[16:19]
	v_mfma_f32_16x16x4_f32 v[20:23], v8, v226, v[20:23]
	v_mfma_f32_16x16x4_f32 v[16:19], v9, v211, v[16:19]
	v_mfma_f32_16x16x4_f32 v[20:23], v9, v227, v[20:23]
	v_mfma_f32_16x16x4_f32 v[16:19], v10, v212, v[16:19]
	v_mfma_f32_16x16x4_f32 v[20:23], v10, v228, v[20:23]
	v_mfma_f32_16x16x4_f32 v[16:19], v11, v213, v[16:19]
	v_mfma_f32_16x16x4_f32 v[20:23], v11, v229, v[20:23]
	v_mfma_f32_16x16x4_f32 v[16:19], v12, v214, v[16:19]
	v_mfma_f32_16x16x4_f32 v[20:23], v12, v230, v[20:23]
	v_mfma_f32_16x16x4_f32 v[16:19], v13, v215, v[16:19]
	v_mfma_f32_16x16x4_f32 v[20:23], v13, v231, v[20:23]
	v_mfma_f32_16x16x4_f32 v[16:19], v14, v216, v[16:19]
	v_mfma_f32_16x16x4_f32 v[20:23], v14, v232, v[20:23]
	v_mfma_f32_16x16x4_f32 v[16:19], v15, v217, v[16:19]
	v_mfma_f32_16x16x4_f32 v[20:23], v15, v233, v[20:23]
	s_add_u32 s48, s42, 0x180000
	s_addc_u32 s49, s43, 0
	global_load_dwordx4 v[202:205], v136, s[48:49] offset:0
	global_load_dwordx4 v[206:209], v136, s[48:49] offset:2048
	global_load_dwordx4 v[210:213], v137, s[48:49] offset:0
	global_load_dwordx4 v[214:217], v137, s[48:49] offset:2048
	s_add_u32 s48, s42, 0x1c0000
	s_addc_u32 s49, s43, 0
	global_load_dwordx4 v[218:221], v136, s[48:49] offset:0
	global_load_dwordx4 v[222:225], v136, s[48:49] offset:2048
	global_load_dwordx4 v[226:229], v137, s[48:49] offset:0
	global_load_dwordx4 v[230:233], v137, s[48:49] offset:2048
	s_waitcnt lgkmcnt(0)
	s_nop 9
	v_sub_f32_e32 v44, v24, v140
	v_sub_f32_e32 v45, v25, v140
	v_sub_f32_e32 v46, v26, v140
	v_sub_f32_e32 v47, v27, v140
	v_fma_f32 v44, v44, s47, v16
	v_fma_f32 v45, v45, s47, v17
	v_fma_f32 v46, v46, s47, v18
	v_fma_f32 v47, v47, s47, v19
	ds_write_b32 v139, v44 offset:3072
	ds_write_b32 v139, v45 offset:7232
	ds_write_b32 v139, v46 offset:11392
	ds_write_b32 v139, v47 offset:15552
	v_sub_f32_e32 v44, v24, v141
	v_sub_f32_e32 v45, v25, v141
	v_sub_f32_e32 v46, v26, v141
	v_sub_f32_e32 v47, v27, v141
	v_fma_f32 v44, v44, s47, v20
	v_fma_f32 v45, v45, s47, v21
	v_fma_f32 v46, v46, s47, v22
	v_fma_f32 v47, v47, s47, v23
	ds_write_b32 v139, v44 offset:3584
	ds_write_b32 v139, v45 offset:7744
	ds_write_b32 v139, v46 offset:11904
	ds_write_b32 v139, v47 offset:16064
	s_movk_i32 s3, 0x2080
	v_mad_u32_u24 v6, v50, s3, v165
	v_add_u32_e32 v7, 0, v6
	v_lshlrev_b32_e32 v8, 1, v50
	v_add_u32_e32 v0, 0x2100, v7
	v_mul_u32_u24_e32 v4, 0x2080, v50
	v_or_b32_e32 v1, 0x400, v8
	v_mov_b32_e32 v2, 0xff800000
	s_mov_b64 s[6:7], 0
	s_movk_i32 s3, 0x3cf
	v_mov_b32_e32 v5, v0
	v_mov_b32_e32 v9, v148
	v_mov_b32_e32 v3, 0xff800000
	s_waitcnt lgkmcnt(0)
	s_barrier
	s_branch .LBB0_1354
